# GEMM mainloops: per-burst s_setprio 1/0 toggles removed (loads of the partner wave issue between MFMAs sooner)
# speedup vs baseline: 1.0138x; 1.0138x over previous
.LBB0_413:
	ds_read_b128 v[128:131], v171
	ds_read_b128 v[132:135], v171 offset:1024
	ds_read_b128 v[136:139], v171 offset:2048
	ds_read_b128 v[152:155], v171 offset:3072
	s_add_u32 s24, s22, 0x100
	s_addc_u32 s25, s23, 0
	s_cmp_eq_u32 s65, 28
	s_cselect_b32 s29, s13, s25
	s_cselect_b32 s28, s61, s24
	s_cselect_b32 s27, s11, s64
	s_cselect_b32 s26, s62, s63
	v_lshl_add_u64 v[194:195], s[22:23], 0, v[144:145]
	s_add_i32 m0, s31, 0xc000
	ds_read_b128 v[156:159], v172
	ds_read_b128 v[160:163], v172 offset:1024
	ds_read_b128 v[164:167], v172 offset:2048
	ds_read_b128 v[174:177], v172 offset:3072
	ds_read_b128 v[178:181], v172 offset:4096
	ds_read_b128 v[182:185], v172 offset:5120
	ds_read_b128 v[186:189], v172 offset:6144
	ds_read_b128 v[190:193], v172 offset:7168
	global_load_lds_dwordx4 v[194:195], off
	v_lshl_add_u64 v[194:195], s[22:23], 0, v[146:147]
	s_add_i32 m0, s31, 0xe000
	s_nop 0
	global_load_lds_dwordx4 v[194:195], off
	s_waitcnt lgkmcnt(8)
	s_barrier
	s_waitcnt lgkmcnt(0)
	s_waitcnt lgkmcnt(0)
	v_mfma_f32_16x16x32_bf16 v[124:127], v[128:131], v[156:159], v[124:127]
	v_mfma_f32_16x16x32_bf16 v[120:123], v[136:139], v[156:159], v[120:123]
	v_mfma_f32_16x16x32_bf16 v[116:119], v[128:131], v[164:167], v[116:119]
	v_mfma_f32_16x16x32_bf16 v[112:115], v[136:139], v[164:167], v[112:115]
	v_mfma_f32_16x16x32_bf16 v[108:111], v[128:131], v[178:181], v[108:111]
	v_mfma_f32_16x16x32_bf16 v[104:107], v[136:139], v[178:181], v[104:107]
	v_mfma_f32_16x16x32_bf16 v[100:103], v[128:131], v[186:189], v[100:103]
	v_mfma_f32_16x16x32_bf16 v[96:99], v[136:139], v[186:189], v[96:99]
	v_mfma_f32_16x16x32_bf16 v[124:127], v[132:135], v[160:163], v[124:127]
	v_mfma_f32_16x16x32_bf16 v[120:123], v[152:155], v[160:163], v[120:123]
	v_mfma_f32_16x16x32_bf16 v[116:119], v[132:135], v[174:177], v[116:119]
	v_mfma_f32_16x16x32_bf16 v[112:115], v[152:155], v[174:177], v[112:115]
	v_mfma_f32_16x16x32_bf16 v[108:111], v[132:135], v[182:185], v[108:111]
	v_mfma_f32_16x16x32_bf16 v[104:107], v[152:155], v[182:185], v[104:107]
	v_mfma_f32_16x16x32_bf16 v[100:103], v[132:135], v[190:193], v[100:103]
	v_mfma_f32_16x16x32_bf16 v[96:99], v[152:155], v[190:193], v[96:99]
	s_barrier
	s_add_i32 s22, s47, s2
	v_lshl_add_u64 v[210:211], s[26:27], 0, v[142:143]
	s_mov_b32 m0, s22
	ds_read_b128 v[194:197], v173
	ds_read_b128 v[198:201], v173 offset:1024
	ds_read_b128 v[202:205], v173 offset:2048
	ds_read_b128 v[206:209], v173 offset:3072
	global_load_lds_dwordx4 v[210:211], off
	v_lshl_add_u64 v[212:213], s[26:27], 0, v[140:141]
	s_add_i32 m0, s22, 0x2000
	s_nop 0
	global_load_lds_dwordx4 v[212:213], off
	s_barrier
	s_waitcnt lgkmcnt(0)
	s_waitcnt lgkmcnt(0)
	v_mfma_f32_16x16x32_bf16 v[64:67], v[194:197], v[156:159], v[64:67]
	v_mfma_f32_16x16x32_bf16 v[68:71], v[202:205], v[156:159], v[68:71]
	v_mfma_f32_16x16x32_bf16 v[48:51], v[194:197], v[164:167], v[48:51]
	v_mfma_f32_16x16x32_bf16 v[52:55], v[202:205], v[164:167], v[52:55]
	v_mfma_f32_16x16x32_bf16 v[40:43], v[194:197], v[178:181], v[40:43]
	v_mfma_f32_16x16x32_bf16 v[44:47], v[202:205], v[178:181], v[44:47]
	v_mfma_f32_16x16x32_bf16 v[32:35], v[194:197], v[186:189], v[32:35]
	v_mfma_f32_16x16x32_bf16 v[36:39], v[202:205], v[186:189], v[36:39]
	v_mfma_f32_16x16x32_bf16 v[64:67], v[198:201], v[160:163], v[64:67]
	v_mfma_f32_16x16x32_bf16 v[68:71], v[206:209], v[160:163], v[68:71]
	v_mfma_f32_16x16x32_bf16 v[48:51], v[198:201], v[174:177], v[48:51]
	v_mfma_f32_16x16x32_bf16 v[52:55], v[206:209], v[174:177], v[52:55]
	v_mfma_f32_16x16x32_bf16 v[40:43], v[198:201], v[182:185], v[40:43]
	v_mfma_f32_16x16x32_bf16 v[44:47], v[206:209], v[182:185], v[44:47]
	v_mfma_f32_16x16x32_bf16 v[32:35], v[198:201], v[190:193], v[32:35]
	v_mfma_f32_16x16x32_bf16 v[36:39], v[206:209], v[190:193], v[36:39]
	s_mov_b32 m0, s31
	v_lshl_add_u64 v[214:215], s[28:29], 0, v[142:143]
	s_barrier
	ds_read_b128 v[156:159], v172 offset:16384
	ds_read_b128 v[160:163], v172 offset:17408
	ds_read_b128 v[164:167], v172 offset:18432
	ds_read_b128 v[174:177], v172 offset:19456
	ds_read_b128 v[178:181], v172 offset:20480
	ds_read_b128 v[182:185], v172 offset:21504
	ds_read_b128 v[186:189], v172 offset:22528
	ds_read_b128 v[190:193], v172 offset:23552
	global_load_lds_dwordx4 v[214:215], off
	v_lshl_add_u64 v[216:217], s[28:29], 0, v[140:141]
	s_mov_b32 m0, s34
	s_nop 0
	global_load_lds_dwordx4 v[216:217], off
	s_barrier
	s_waitcnt lgkmcnt(0)
	s_waitcnt lgkmcnt(0)
	v_mfma_f32_16x16x32_bf16 v[92:95], v[128:131], v[156:159], v[92:95]
	v_mfma_f32_16x16x32_bf16 v[88:91], v[136:139], v[156:159], v[88:91]
	v_mfma_f32_16x16x32_bf16 v[84:87], v[128:131], v[164:167], v[84:87]
	v_mfma_f32_16x16x32_bf16 v[80:83], v[136:139], v[164:167], v[80:83]
	v_mfma_f32_16x16x32_bf16 v[76:79], v[128:131], v[178:181], v[76:79]
	v_mfma_f32_16x16x32_bf16 v[72:75], v[136:139], v[178:181], v[72:75]
	v_mfma_f32_16x16x32_bf16 v[60:63], v[128:131], v[186:189], v[60:63]
	v_mfma_f32_16x16x32_bf16 v[56:59], v[136:139], v[186:189], v[56:59]
	v_mfma_f32_16x16x32_bf16 v[92:95], v[132:135], v[160:163], v[92:95]
	v_mfma_f32_16x16x32_bf16 v[88:91], v[152:155], v[160:163], v[88:91]
	v_mfma_f32_16x16x32_bf16 v[84:87], v[132:135], v[174:177], v[84:87]
	v_mfma_f32_16x16x32_bf16 v[80:83], v[152:155], v[174:177], v[80:83]
	v_mfma_f32_16x16x32_bf16 v[76:79], v[132:135], v[182:185], v[76:79]
	v_mfma_f32_16x16x32_bf16 v[72:75], v[152:155], v[182:185], v[72:75]
	v_mfma_f32_16x16x32_bf16 v[60:63], v[132:135], v[190:193], v[60:63]
	v_mfma_f32_16x16x32_bf16 v[56:59], v[152:155], v[190:193], v[56:59]
	s_barrier
	s_add_u32 s22, s26, 0x80000
	s_addc_u32 s23, s27, 0
	s_add_i32 s66, s60, s2
	v_lshl_add_u64 v[128:129], s[22:23], 0, v[142:143]
	s_mov_b32 m0, s66
	s_nop 0
	global_load_lds_dwordx4 v[128:129], off
	v_lshl_add_u64 v[128:129], s[22:23], 0, v[140:141]
	s_add_i32 m0, s66, 0x2000
	s_nop 0
	global_load_lds_dwordx4 v[128:129], off
	s_waitcnt vmcnt(6)
	s_barrier
	v_mfma_f32_16x16x32_bf16 v[24:27], v[194:197], v[156:159], v[24:27]
	v_mfma_f32_16x16x32_bf16 v[28:31], v[202:205], v[156:159], v[28:31]
	v_mfma_f32_16x16x32_bf16 v[16:19], v[194:197], v[164:167], v[16:19]
	v_mfma_f32_16x16x32_bf16 v[20:23], v[202:205], v[164:167], v[20:23]
	v_mfma_f32_16x16x32_bf16 v[8:11], v[194:197], v[178:181], v[8:11]
	v_mfma_f32_16x16x32_bf16 v[12:15], v[202:205], v[178:181], v[12:15]
	v_mfma_f32_16x16x32_bf16 v[4:7], v[194:197], v[186:189], v[4:7]
	v_mfma_f32_16x16x32_bf16 v[0:3], v[202:205], v[186:189], v[0:3]
	v_mfma_f32_16x16x32_bf16 v[24:27], v[198:201], v[160:163], v[24:27]
	v_mfma_f32_16x16x32_bf16 v[28:31], v[206:209], v[160:163], v[28:31]
	v_mfma_f32_16x16x32_bf16 v[16:19], v[198:201], v[174:177], v[16:19]
	v_mfma_f32_16x16x32_bf16 v[20:23], v[206:209], v[174:177], v[20:23]
	v_mfma_f32_16x16x32_bf16 v[8:11], v[198:201], v[182:185], v[8:11]
	v_mfma_f32_16x16x32_bf16 v[12:15], v[206:209], v[182:185], v[12:15]
	v_mfma_f32_16x16x32_bf16 v[4:7], v[198:201], v[190:193], v[4:7]
	v_mfma_f32_16x16x32_bf16 v[0:3], v[206:209], v[190:193], v[0:3]
	s_add_i32 s66, 0, 0x18000
	v_add_u32_e32 v152, s66, v169
	s_barrier
	ds_read_b128 v[128:131], v152
	ds_read_b128 v[132:135], v152 offset:1024
	ds_read_b128 v[136:139], v152 offset:2048
	ds_read_b128 v[152:155], v152 offset:3072
	s_add_u32 s22, s28, 0x80000
	s_addc_u32 s23, s29, 0
	s_mov_b32 m0, s35
	v_lshl_add_u64 v[194:195], s[22:23], 0, v[142:143]
	ds_read_b128 v[156:159], v172 offset:32768
	ds_read_b128 v[160:163], v172 offset:33792
	ds_read_b128 v[164:167], v172 offset:34816
	ds_read_b128 v[174:177], v172 offset:35840
	ds_read_b128 v[178:181], v172 offset:36864
	ds_read_b128 v[182:185], v172 offset:37888
	ds_read_b128 v[186:189], v172 offset:38912
	ds_read_b128 v[190:193], v172 offset:39936
	global_load_lds_dwordx4 v[194:195], off
	v_lshl_add_u64 v[194:195], s[22:23], 0, v[140:141]
	s_mov_b32 m0, s36
	s_nop 0
	global_load_lds_dwordx4 v[194:195], off
	s_waitcnt lgkmcnt(8)
	s_barrier
	s_waitcnt lgkmcnt(0)
	s_waitcnt lgkmcnt(0)
	v_mfma_f32_16x16x32_bf16 v[124:127], v[128:131], v[156:159], v[124:127]
	v_mfma_f32_16x16x32_bf16 v[120:123], v[136:139], v[156:159], v[120:123]
	v_mfma_f32_16x16x32_bf16 v[116:119], v[128:131], v[164:167], v[116:119]
	v_mfma_f32_16x16x32_bf16 v[112:115], v[136:139], v[164:167], v[112:115]
	v_mfma_f32_16x16x32_bf16 v[108:111], v[128:131], v[178:181], v[108:111]
	v_mfma_f32_16x16x32_bf16 v[104:107], v[136:139], v[178:181], v[104:107]
	v_mfma_f32_16x16x32_bf16 v[100:103], v[128:131], v[186:189], v[100:103]
	v_mfma_f32_16x16x32_bf16 v[96:99], v[136:139], v[186:189], v[96:99]
	v_mfma_f32_16x16x32_bf16 v[124:127], v[132:135], v[160:163], v[124:127]
	v_mfma_f32_16x16x32_bf16 v[120:123], v[152:155], v[160:163], v[120:123]
	v_mfma_f32_16x16x32_bf16 v[116:119], v[132:135], v[174:177], v[116:119]
	v_mfma_f32_16x16x32_bf16 v[112:115], v[152:155], v[174:177], v[112:115]
	v_mfma_f32_16x16x32_bf16 v[108:111], v[132:135], v[182:185], v[108:111]
	v_mfma_f32_16x16x32_bf16 v[104:107], v[152:155], v[182:185], v[104:107]
	v_mfma_f32_16x16x32_bf16 v[100:103], v[132:135], v[190:193], v[100:103]
	v_mfma_f32_16x16x32_bf16 v[96:99], v[152:155], v[190:193], v[96:99]
	s_barrier
	s_add_i32 s28, 0, 0x1c000
	s_add_i32 s22, s66, s2
	v_add_u32_e32 v206, s28, v169
	v_lshl_add_u64 v[210:211], v[210:211], 0, s[6:7]
	s_mov_b32 m0, s22
	ds_read_b128 v[194:197], v206
	ds_read_b128 v[198:201], v206 offset:1024
	ds_read_b128 v[202:205], v206 offset:2048
	ds_read_b128 v[206:209], v206 offset:3072
	global_load_lds_dwordx4 v[210:211], off
	v_lshl_add_u64 v[210:211], v[212:213], 0, s[6:7]
	s_add_i32 m0, s22, 0x2000
	s_nop 0
	global_load_lds_dwordx4 v[210:211], off
	s_barrier
	s_waitcnt lgkmcnt(0)
	s_waitcnt lgkmcnt(0)
	v_mfma_f32_16x16x32_bf16 v[64:67], v[194:197], v[156:159], v[64:67]
	v_mfma_f32_16x16x32_bf16 v[68:71], v[202:205], v[156:159], v[68:71]
	v_mfma_f32_16x16x32_bf16 v[48:51], v[194:197], v[164:167], v[48:51]
	v_mfma_f32_16x16x32_bf16 v[52:55], v[202:205], v[164:167], v[52:55]
	v_mfma_f32_16x16x32_bf16 v[40:43], v[194:197], v[178:181], v[40:43]
	v_mfma_f32_16x16x32_bf16 v[44:47], v[202:205], v[178:181], v[44:47]
	v_mfma_f32_16x16x32_bf16 v[32:35], v[194:197], v[186:189], v[32:35]
	v_mfma_f32_16x16x32_bf16 v[36:39], v[202:205], v[186:189], v[36:39]
	v_mfma_f32_16x16x32_bf16 v[64:67], v[198:201], v[160:163], v[64:67]
	v_mfma_f32_16x16x32_bf16 v[68:71], v[206:209], v[160:163], v[68:71]
	v_mfma_f32_16x16x32_bf16 v[48:51], v[198:201], v[174:177], v[48:51]
	v_mfma_f32_16x16x32_bf16 v[52:55], v[206:209], v[174:177], v[52:55]
	v_mfma_f32_16x16x32_bf16 v[40:43], v[198:201], v[182:185], v[40:43]
	v_mfma_f32_16x16x32_bf16 v[44:47], v[206:209], v[182:185], v[44:47]
	v_mfma_f32_16x16x32_bf16 v[32:35], v[198:201], v[190:193], v[32:35]
	v_mfma_f32_16x16x32_bf16 v[36:39], v[206:209], v[190:193], v[36:39]
	s_mov_b32 m0, s38
	v_lshl_add_u64 v[210:211], v[214:215], 0, s[6:7]
	s_barrier
	ds_read_b128 v[156:159], v172 offset:49152
	ds_read_b128 v[160:163], v172 offset:50176
	ds_read_b128 v[164:167], v172 offset:51200
	ds_read_b128 v[174:177], v172 offset:52224
	ds_read_b128 v[178:181], v172 offset:53248
	ds_read_b128 v[182:185], v172 offset:54272
	ds_read_b128 v[186:189], v172 offset:55296
	ds_read_b128 v[190:193], v172 offset:56320
	global_load_lds_dwordx4 v[210:211], off
	v_lshl_add_u64 v[210:211], v[216:217], 0, s[6:7]
	s_mov_b32 m0, s39
	s_nop 0
	global_load_lds_dwordx4 v[210:211], off
	s_barrier
	s_waitcnt lgkmcnt(0)
	s_waitcnt lgkmcnt(0)
	v_mfma_f32_16x16x32_bf16 v[92:95], v[128:131], v[156:159], v[92:95]
	v_mfma_f32_16x16x32_bf16 v[88:91], v[136:139], v[156:159], v[88:91]
	v_mfma_f32_16x16x32_bf16 v[84:87], v[128:131], v[164:167], v[84:87]
	v_mfma_f32_16x16x32_bf16 v[80:83], v[136:139], v[164:167], v[80:83]
	v_mfma_f32_16x16x32_bf16 v[76:79], v[128:131], v[178:181], v[76:79]
	v_mfma_f32_16x16x32_bf16 v[72:75], v[136:139], v[178:181], v[72:75]
	v_mfma_f32_16x16x32_bf16 v[60:63], v[128:131], v[186:189], v[60:63]
	v_mfma_f32_16x16x32_bf16 v[56:59], v[136:139], v[186:189], v[56:59]
	v_mfma_f32_16x16x32_bf16 v[92:95], v[132:135], v[160:163], v[92:95]
	v_mfma_f32_16x16x32_bf16 v[88:91], v[152:155], v[160:163], v[88:91]
	v_mfma_f32_16x16x32_bf16 v[84:87], v[132:135], v[174:177], v[84:87]
	v_mfma_f32_16x16x32_bf16 v[80:83], v[152:155], v[174:177], v[80:83]
	v_mfma_f32_16x16x32_bf16 v[76:79], v[132:135], v[182:185], v[76:79]
	v_mfma_f32_16x16x32_bf16 v[72:75], v[152:155], v[182:185], v[72:75]
	v_mfma_f32_16x16x32_bf16 v[60:63], v[132:135], v[190:193], v[60:63]
	v_mfma_f32_16x16x32_bf16 v[56:59], v[152:155], v[190:193], v[56:59]
	s_barrier
	s_add_u32 s22, s26, 0x80080
	s_addc_u32 s23, s27, 0
	s_add_i32 s26, s28, s2
	v_lshl_add_u64 v[128:129], s[22:23], 0, v[142:143]
	s_mov_b32 m0, s26
	s_nop 0
	global_load_lds_dwordx4 v[128:129], off
	v_lshl_add_u64 v[128:129], s[22:23], 0, v[140:141]
	s_add_i32 m0, s26, 0x2000
	s_nop 0
	global_load_lds_dwordx4 v[128:129], off
	s_waitcnt vmcnt(6)
	s_barrier
	v_mfma_f32_16x16x32_bf16 v[24:27], v[194:197], v[156:159], v[24:27]
	v_mfma_f32_16x16x32_bf16 v[28:31], v[202:205], v[156:159], v[28:31]
	v_mfma_f32_16x16x32_bf16 v[16:19], v[194:197], v[164:167], v[16:19]
	v_mfma_f32_16x16x32_bf16 v[20:23], v[202:205], v[164:167], v[20:23]
	v_mfma_f32_16x16x32_bf16 v[8:11], v[194:197], v[178:181], v[8:11]
	v_mfma_f32_16x16x32_bf16 v[12:15], v[202:205], v[178:181], v[12:15]
	v_mfma_f32_16x16x32_bf16 v[4:7], v[194:197], v[186:189], v[4:7]
	v_mfma_f32_16x16x32_bf16 v[0:3], v[202:205], v[186:189], v[0:3]
	v_mfma_f32_16x16x32_bf16 v[24:27], v[198:201], v[160:163], v[24:27]
	v_mfma_f32_16x16x32_bf16 v[28:31], v[206:209], v[160:163], v[28:31]
	v_mfma_f32_16x16x32_bf16 v[16:19], v[198:201], v[174:177], v[16:19]
	v_mfma_f32_16x16x32_bf16 v[20:23], v[206:209], v[174:177], v[20:23]
	v_mfma_f32_16x16x32_bf16 v[8:11], v[198:201], v[182:185], v[8:11]
	v_mfma_f32_16x16x32_bf16 v[12:15], v[206:209], v[182:185], v[12:15]
	v_mfma_f32_16x16x32_bf16 v[4:7], v[198:201], v[190:193], v[4:7]
	v_mfma_f32_16x16x32_bf16 v[0:3], v[206:209], v[190:193], v[0:3]
	s_add_i32 s65, s65, 2
	s_add_u32 s63, s63, 0x100
	s_addc_u32 s64, s64, 0
	s_cmp_gt_u32 s65, 29
	s_mov_b64 s[22:23], s[24:25]
	s_barrier
	s_cbranch_scc0 .LBB0_413
	v_lshl_or_b32 v154, s19, 7, v170
	v_ashrrev_i32_e32 v155, 31, v154
	v_lshlrev_b64 v[184:185], 2, v[154:155]
	v_readlane_b32 s64, v240, 49
	v_lshl_add_u64 v[128:129], s[8:9], 0, v[184:185]
	v_readlane_b32 s72, v240, 57
	v_readlane_b32 s73, v240, 58
	s_nop 1
	v_lshl_add_u64 v[186:187], s[72:73], 0, v[184:185]
	global_load_dwordx4 v[128:131], v[128:129], off
	s_nop 0
	global_load_dwordx4 v[188:191], v[186:187], off
	s_cmp_lt_u32 s18, 32
	s_movk_i32 s11, 0x3000
	s_cselect_b32 s11, s11, 0x6000
	s_cmp_gt_i32 s18, 15
	s_cselect_b32 s11, s11, 0
	v_lshl_add_u32 v166, s18, 8, v168
	s_lshl_b32 s11, s11, 2
	v_readlane_b32 s65, v240, 50
	v_readlane_b32 s66, v240, 51
	v_readlane_b32 s67, v240, 52
	v_readlane_b32 s68, v240, 53
	v_readlane_b32 s69, v240, 54
	v_readlane_b32 s70, v240, 55
	v_readlane_b32 s71, v240, 56
	v_readlane_b32 s74, v240, 59
	v_readlane_b32 s75, v240, 60
	v_readlane_b32 s76, v240, 61
	v_readlane_b32 s77, v240, 62
	v_readlane_b32 s78, v240, 63
	v_readlane_b32 s79, v239, 0
	v_ashrrev_i32_e32 v167, 31, v166
	s_add_u32 s22, s41, s11
	v_lshlrev_b64 v[138:139], 11, v[166:167]
	s_addc_u32 s23, s42, 0
	v_readlane_b32 s64, v239, 3
	v_lshl_add_u64 v[138:139], v[138:139], 0, v[154:155]
	s_nop 1
	v_lshlrev_b64 v[192:193], 2, v[138:139]
	v_lshl_add_u64 v[194:195], s[22:23], 0, v[184:185]
	global_load_dwordx4 v[196:199], v[194:195], off
	s_cmp_lt_i32 s18, 32
	v_readlane_b32 s65, v239, 4
	s_nop 1
	s_cselect_b32 s19, s65, s46
	s_cselect_b32 s18, s64, s43
	s_nop 0
	v_lshl_add_u64 v[184:185], s[18:19], 0, v[192:193]
	global_load_dwordx4 v[200:203], v[184:185], off
	v_readlane_b32 s66, v239, 5
	v_readlane_b32 s67, v239, 6
	v_readlane_b32 s68, v239, 7
	v_readlane_b32 s69, v239, 8
	v_readlane_b32 s70, v239, 9
	v_readlane_b32 s71, v239, 10
	v_readlane_b32 s72, v239, 11
	v_readlane_b32 s73, v239, 12
	v_readlane_b32 s74, v239, 13
	v_readlane_b32 s75, v239, 14
	v_readlane_b32 s76, v239, 15
	v_readlane_b32 s77, v239, 16
	v_readlane_b32 s78, v239, 17
	v_readlane_b32 s79, v239, 18
	v_or_b32_e32 v160, 16, v166
	v_ashrrev_i32_e32 v161, 31, v160
	v_readlane_b32 s64, v240, 22
	v_lshlrev_b64 v[160:161], 11, v[160:161]
	s_nop 1
	v_lshl_add_u64 v[204:205], v[160:161], 0, v[154:155]
	s_nop 1
	v_lshlrev_b64 v[206:207], 2, v[204:205]
	v_lshl_add_u64 v[208:209], s[18:19], 0, v[206:207]
	global_load_dwordx4 v[212:215], v[208:209], off
	v_readlane_b32 s68, v240, 26
	v_readlane_b32 s69, v240, 27
	v_readlane_b32 s70, v240, 28
	v_readlane_b32 s71, v240, 29
	v_readlane_b32 s72, v240, 30
	v_readlane_b32 s73, v240, 31
	v_readlane_b32 s74, v240, 32
	v_readlane_b32 s75, v240, 33
	v_readlane_b32 s76, v240, 34
	v_readlane_b32 s77, v240, 35
	v_readlane_b32 s78, v240, 36
	v_readlane_b32 s79, v240, 37
	s_mov_b64 s[48:49], s[68:69]
	v_lshl_add_u64 v[160:161], s[48:49], 0, v[192:193]
	s_mov_b64 s[22:23], 0x100000
	s_mov_b64 s[24:25], s[16:17]
	s_and_b64 vcc, exec, s[4:5]
	v_readlane_b32 s65, v240, 23
	v_readlane_b32 s66, v240, 24
	v_readlane_b32 s67, v240, 25
	s_mov_b64 s[50:51], s[70:71]
	s_waitcnt vmcnt(4)
	v_add_f32_e32 v167, v120, v128
	v_add_f32_e32 v180, v121, v129
	v_add_f32_e32 v181, v122, v130
	v_add_f32_e32 v182, v123, v131
	s_waitcnt vmcnt(3)
	v_pk_add_f32 v[120:121], v[126:127], v[190:191]
	v_pk_add_f32 v[122:123], v[124:125], v[188:189]
	v_mul_f32_e32 v124, 0xbfb8aa3b, v167
	v_mul_f32_e32 v125, 0xbfb8aa3b, v180
	v_mul_f32_e32 v126, 0xbfb8aa3b, v181
	v_mul_f32_e32 v127, 0xbfb8aa3b, v182
	v_exp_f32_e32 v124, v124
	v_exp_f32_e32 v125, v125
	v_exp_f32_e32 v126, v126
	v_exp_f32_e32 v127, v127
	v_add_f32_e32 v124, 1.0, v124
	v_add_f32_e32 v125, 1.0, v125
	v_add_f32_e32 v126, 1.0, v126
	v_add_f32_e32 v127, 1.0, v127
	v_rcp_f32_e32 v124, v124
	v_rcp_f32_e32 v126, v126
	v_rcp_f32_e32 v127, v127
	v_rcp_f32_e32 v125, v125
	v_add_f32_e32 v167, v112, v128
	s_mov_b64 s[52:53], s[72:73]
	s_mov_b64 s[54:55], s[74:75]
	s_mov_b64 s[56:57], s[76:77]
	s_mov_b64 s[58:59], s[78:79]
	s_waitcnt vmcnt(2)
	v_pk_mul_f32 v[120:121], v[198:199], v[120:121]
	v_pk_mul_f32 v[180:181], v[196:197], v[122:123]
	s_waitcnt vmcnt(1)
	v_pk_fma_f32 v[122:123], v[120:121], v[126:127], v[202:203]
	v_pk_fma_f32 v[120:121], v[180:181], v[124:125], v[200:201]
	global_store_dwordx4 v[160:161], v[120:123], off
	v_add_f32_e32 v176, v113, v129
	s_nop 0
	v_or_b32_e32 v120, 32, v166
	v_ashrrev_i32_e32 v121, 31, v120
	v_lshlrev_b64 v[120:121], 11, v[120:121]
	v_lshl_add_u64 v[120:121], v[120:121], 0, v[154:155]
	v_lshlrev_b64 v[200:201], 2, v[120:121]
	s_nop 1
	v_lshl_add_u64 v[202:203], s[18:19], 0, v[200:201]
	global_load_dwordx4 v[216:219], v[202:203], off
	v_lshl_add_u64 v[120:121], s[48:49], 0, v[206:207]
	v_add_f32_e32 v177, v114, v130
	v_add_f32_e32 v178, v115, v131
	v_pk_add_f32 v[112:113], v[118:119], v[190:191]
	v_pk_add_f32 v[114:115], v[116:117], v[188:189]
	v_mul_f32_e32 v116, 0xbfb8aa3b, v167
	v_mul_f32_e32 v117, 0xbfb8aa3b, v176
	v_mul_f32_e32 v118, 0xbfb8aa3b, v177
	v_mul_f32_e32 v119, 0xbfb8aa3b, v178
	v_exp_f32_e32 v116, v116
	v_exp_f32_e32 v117, v117
	v_exp_f32_e32 v118, v118
	v_exp_f32_e32 v119, v119
	v_add_f32_e32 v116, 1.0, v116
	v_add_f32_e32 v117, 1.0, v117
	v_add_f32_e32 v118, 1.0, v118
	v_add_f32_e32 v119, 1.0, v119
	v_rcp_f32_e32 v116, v116
	v_rcp_f32_e32 v117, v117
	v_rcp_f32_e32 v118, v118
	v_rcp_f32_e32 v119, v119
	v_pk_mul_f32 v[176:177], v[198:199], v[112:113]
	v_pk_mul_f32 v[112:113], v[196:197], v[114:115]
	s_waitcnt vmcnt(2)
	s_nop 0
	v_pk_fma_f32 v[112:113], v[112:113], v[116:117], v[212:213]
	v_pk_fma_f32 v[114:115], v[176:177], v[118:119], v[214:215]
	global_store_dwordx4 v[120:121], v[112:115], off
	v_add_f32_e32 v126, v104, v128
	s_nop 0
	v_or_b32_e32 v112, 48, v166
	v_ashrrev_i32_e32 v113, 31, v112
	v_lshlrev_b64 v[112:113], 11, v[112:113]
	v_lshl_add_u64 v[112:113], v[112:113], 0, v[154:155]
	s_nop 1
	v_lshlrev_b64 v[204:205], 2, v[112:113]
	s_nop 0
	v_lshl_add_u64 v[206:207], s[18:19], 0, v[204:205]
	global_load_dwordx4 v[212:215], v[206:207], off
	v_lshl_add_u64 v[210:211], v[192:193], 0, s[22:23]
	v_add_f32_e32 v127, v105, v129
	v_add_f32_e32 v155, v106, v130
	v_add_f32_e32 v166, v107, v131
	v_pk_add_f32 v[104:105], v[110:111], v[190:191]
	v_pk_add_f32 v[106:107], v[108:109], v[188:189]
	v_mul_f32_e32 v108, 0xbfb8aa3b, v126
	v_mul_f32_e32 v109, 0xbfb8aa3b, v127
	v_mul_f32_e32 v110, 0xbfb8aa3b, v155
	v_mul_f32_e32 v111, 0xbfb8aa3b, v166
	v_exp_f32_e32 v108, v108
	v_exp_f32_e32 v109, v109
	v_exp_f32_e32 v110, v110
	v_exp_f32_e32 v111, v111
	v_add_f32_e32 v108, 1.0, v108
	v_add_f32_e32 v109, 1.0, v109
	v_add_f32_e32 v110, 1.0, v110
	v_add_f32_e32 v111, 1.0, v111
	v_rcp_f32_e32 v108, v108
	v_rcp_f32_e32 v109, v109
	v_rcp_f32_e32 v110, v110
	v_rcp_f32_e32 v111, v111
	v_pk_mul_f32 v[126:127], v[198:199], v[104:105]
	v_pk_mul_f32 v[104:105], v[196:197], v[106:107]
	v_lshl_add_u64 v[112:113], s[48:49], 0, v[200:201]
	v_lshl_add_u64 v[200:201], s[18:19], 0, v[210:211]
	s_waitcnt vmcnt(2)
	v_pk_fma_f32 v[104:105], v[104:105], v[108:109], v[216:217]
	v_pk_fma_f32 v[106:107], v[126:127], v[110:111], v[218:219]
	global_load_dwordx4 v[216:219], v[200:201], off
	global_store_dwordx4 v[112:113], v[104:107], off
	v_add_f32_e32 v118, v96, v128
	s_nop 0
	v_lshl_add_u64 v[104:105], s[48:49], 0, v[204:205]
	v_add_f32_e32 v119, v97, v129
	v_add_f32_e32 v124, v98, v130
	v_add_f32_e32 v125, v99, v131
	v_pk_add_f32 v[96:97], v[102:103], v[190:191]
	v_pk_add_f32 v[98:99], v[100:101], v[188:189]
	v_mul_f32_e32 v100, 0xbfb8aa3b, v118
	v_mul_f32_e32 v101, 0xbfb8aa3b, v119
	v_mul_f32_e32 v102, 0xbfb8aa3b, v124
	v_mul_f32_e32 v103, 0xbfb8aa3b, v125
	v_exp_f32_e32 v100, v100
	v_exp_f32_e32 v101, v101
	v_exp_f32_e32 v102, v102
	v_exp_f32_e32 v103, v103
	v_add_f32_e32 v100, 1.0, v100
	v_add_f32_e32 v101, 1.0, v101
	v_add_f32_e32 v102, 1.0, v102
	v_add_f32_e32 v103, 1.0, v103
	v_rcp_f32_e32 v100, v100
	v_rcp_f32_e32 v101, v101
	v_rcp_f32_e32 v102, v102
	v_rcp_f32_e32 v103, v103
	v_pk_mul_f32 v[118:119], v[198:199], v[96:97]
	v_pk_mul_f32 v[96:97], v[196:197], v[98:99]
	s_mov_b64 s[22:23], 0x120000
	s_nop 0
	v_lshl_add_u64 v[204:205], v[192:193], 0, s[22:23]
	s_waitcnt vmcnt(2)
	v_pk_fma_f32 v[96:97], v[96:97], v[100:101], v[212:213]
	v_pk_fma_f32 v[98:99], v[118:119], v[102:103], v[214:215]
	v_lshl_add_u64 v[212:213], s[18:19], 0, v[204:205]
	global_store_dwordx4 v[104:105], v[96:99], off
	v_add_f32_e32 v110, v88, v128
	s_nop 0
	v_lshl_add_u64 v[96:97], s[48:49], 0, v[210:211]
	global_load_dwordx4 v[220:223], v[212:213], off
	v_add_f32_e32 v111, v89, v129
	v_add_f32_e32 v116, v90, v130
	v_add_f32_e32 v117, v91, v131
	v_pk_add_f32 v[88:89], v[94:95], v[190:191]
	v_pk_add_f32 v[90:91], v[92:93], v[188:189]
	v_mul_f32_e32 v92, 0xbfb8aa3b, v110
	v_mul_f32_e32 v93, 0xbfb8aa3b, v111
	v_mul_f32_e32 v94, 0xbfb8aa3b, v116
	v_mul_f32_e32 v95, 0xbfb8aa3b, v117
	v_exp_f32_e32 v92, v92
	v_exp_f32_e32 v93, v93
	v_exp_f32_e32 v94, v94
	v_exp_f32_e32 v95, v95
	v_add_f32_e32 v92, 1.0, v92
	v_add_f32_e32 v93, 1.0, v93
	v_add_f32_e32 v94, 1.0, v94
	v_add_f32_e32 v95, 1.0, v95
	v_rcp_f32_e32 v92, v92
	v_rcp_f32_e32 v93, v93
	v_rcp_f32_e32 v94, v94
	v_rcp_f32_e32 v95, v95
	v_pk_mul_f32 v[110:111], v[198:199], v[88:89]
	v_pk_mul_f32 v[88:89], v[196:197], v[90:91]
	s_mov_b64 s[22:23], 0x140000
	s_waitcnt vmcnt(3)
	v_pk_fma_f32 v[88:89], v[88:89], v[92:93], v[216:217]
	v_pk_fma_f32 v[90:91], v[110:111], v[94:95], v[218:219]
	v_lshl_add_u64 v[210:211], v[192:193], 0, s[22:23]
	global_store_dwordx4 v[96:97], v[88:91], off
	v_add_f32_e32 v102, v80, v128
	s_nop 0
	v_lshl_add_u64 v[88:89], s[48:49], 0, v[204:205]
	v_lshl_add_u64 v[204:205], s[18:19], 0, v[210:211]
	v_add_f32_e32 v103, v81, v129
	v_add_f32_e32 v108, v82, v130
	v_add_f32_e32 v109, v83, v131
	v_pk_add_f32 v[80:81], v[86:87], v[190:191]
	v_pk_add_f32 v[82:83], v[84:85], v[188:189]
	v_mul_f32_e32 v84, 0xbfb8aa3b, v102
	v_mul_f32_e32 v85, 0xbfb8aa3b, v103
	v_mul_f32_e32 v86, 0xbfb8aa3b, v108
	v_mul_f32_e32 v87, 0xbfb8aa3b, v109
	v_exp_f32_e32 v84, v84
	v_exp_f32_e32 v85, v85
	v_exp_f32_e32 v86, v86
	v_exp_f32_e32 v87, v87
	v_add_f32_e32 v84, 1.0, v84
	v_add_f32_e32 v85, 1.0, v85
	v_add_f32_e32 v86, 1.0, v86
	v_add_f32_e32 v87, 1.0, v87
	v_rcp_f32_e32 v84, v84
	v_rcp_f32_e32 v85, v85
	v_rcp_f32_e32 v86, v86
	v_rcp_f32_e32 v87, v87
	v_pk_mul_f32 v[102:103], v[198:199], v[80:81]
	v_pk_mul_f32 v[80:81], v[196:197], v[82:83]
	s_mov_b64 s[22:23], 0x160000
	s_waitcnt vmcnt(1)
	v_pk_fma_f32 v[80:81], v[80:81], v[84:85], v[220:221]
	v_pk_fma_f32 v[82:83], v[102:103], v[86:87], v[222:223]
	global_load_dwordx4 v[216:219], v[204:205], off
	global_store_dwordx4 v[88:89], v[80:83], off
	v_add_f32_e32 v94, v72, v128
	s_nop 0
	v_lshl_add_u64 v[80:81], s[48:49], 0, v[210:211]
	v_lshl_add_u64 v[210:211], v[192:193], 0, s[22:23]
	v_add_f32_e32 v95, v73, v129
	v_add_f32_e32 v100, v74, v130
	v_add_f32_e32 v101, v75, v131
	v_pk_add_f32 v[72:73], v[78:79], v[190:191]
	v_pk_add_f32 v[74:75], v[76:77], v[188:189]
	v_mul_f32_e32 v76, 0xbfb8aa3b, v94
	v_mul_f32_e32 v77, 0xbfb8aa3b, v95
	v_mul_f32_e32 v78, 0xbfb8aa3b, v100
	v_mul_f32_e32 v79, 0xbfb8aa3b, v101
	v_exp_f32_e32 v76, v76
	v_exp_f32_e32 v77, v77
	v_exp_f32_e32 v78, v78
	v_exp_f32_e32 v79, v79
	v_add_f32_e32 v76, 1.0, v76
	v_add_f32_e32 v77, 1.0, v77
	v_add_f32_e32 v78, 1.0, v78
	v_add_f32_e32 v79, 1.0, v79
	v_rcp_f32_e32 v76, v76
	v_rcp_f32_e32 v77, v77
	v_rcp_f32_e32 v78, v78
	v_rcp_f32_e32 v79, v79
	v_pk_mul_f32 v[94:95], v[198:199], v[72:73]
	v_pk_mul_f32 v[72:73], v[196:197], v[74:75]
	v_lshl_add_u64 v[192:193], s[18:19], 0, v[210:211]
	s_mov_b32 s19, s10
	s_mov_b64 s[22:23], s[14:15]
	s_mov_b32 s18, s12
	s_waitcnt vmcnt(1)
	v_pk_fma_f32 v[72:73], v[72:73], v[76:77], v[216:217]
	v_pk_fma_f32 v[74:75], v[94:95], v[78:79], v[218:219]
	global_load_dwordx4 v[216:219], v[192:193], off
	v_or_b32_e32 v76, 64, v154
	v_ashrrev_i32_e32 v77, 31, v76
	global_store_dwordx4 v[80:81], v[72:75], off
	v_add_f32_e32 v84, v56, v128
	v_add_f32_e32 v85, v57, v129
	v_add_f32_e32 v86, v58, v130
	v_add_f32_e32 v87, v59, v131
	v_pk_add_f32 v[56:57], v[62:63], v[190:191]
	v_pk_add_f32 v[58:59], v[60:61], v[188:189]
	v_lshl_add_u64 v[188:189], v[76:77], 2, s[8:9]
	v_mul_f32_e32 v60, 0xbfb8aa3b, v84
	v_mul_f32_e32 v61, 0xbfb8aa3b, v85
	v_mul_f32_e32 v62, 0xbfb8aa3b, v86
	v_mul_f32_e32 v63, 0xbfb8aa3b, v87
	v_exp_f32_e32 v60, v60
	v_exp_f32_e32 v61, v61
	v_exp_f32_e32 v62, v62
	v_exp_f32_e32 v63, v63
	v_add_f32_e32 v60, 1.0, v60
	v_add_f32_e32 v61, 1.0, v61
	v_add_f32_e32 v62, 1.0, v62
	v_add_f32_e32 v63, 1.0, v63
	v_rcp_f32_e32 v60, v60
	v_rcp_f32_e32 v61, v61
	v_rcp_f32_e32 v62, v62
	v_rcp_f32_e32 v63, v63
	v_pk_mul_f32 v[84:85], v[198:199], v[56:57]
	v_pk_mul_f32 v[56:57], v[196:197], v[58:59]
	global_load_dwordx4 v[196:199], v[188:189], off
	v_lshl_add_u64 v[76:77], s[48:49], 0, v[210:211]
	global_load_dwordx4 v[220:223], v[186:187], off offset:256
	s_waitcnt vmcnt(3)
	v_pk_fma_f32 v[56:57], v[56:57], v[60:61], v[216:217]
	v_pk_fma_f32 v[58:59], v[84:85], v[62:63], v[218:219]
	global_load_dwordx4 v[216:219], v[194:195], off offset:256
	global_store_dwordx4 v[76:77], v[56:59], off
	global_load_dwordx4 v[188:191], v[184:185], off offset:256
	global_load_dwordx4 v[224:227], v[208:209], off offset:256
	global_load_dwordx4 v[184:187], v[202:203], off offset:256
	global_load_dwordx4 v[228:231], v[206:207], off offset:256
	s_waitcnt vmcnt(7)
	v_add_f32_e32 v68, v68, v196
	v_add_f32_e32 v69, v69, v197
	v_add_f32_e32 v70, v70, v198
	v_add_f32_e32 v71, v71, v199
	v_mul_f32_e32 v68, 0xbfb8aa3b, v68
	v_mul_f32_e32 v69, 0xbfb8aa3b, v69
	v_mul_f32_e32 v70, 0xbfb8aa3b, v70
	v_mul_f32_e32 v71, 0xbfb8aa3b, v71
	v_exp_f32_e32 v68, v68
	v_exp_f32_e32 v69, v69
	v_exp_f32_e32 v70, v70
	v_exp_f32_e32 v71, v71
	v_add_f32_e32 v68, 1.0, v68
	v_add_f32_e32 v69, 1.0, v69
	v_add_f32_e32 v70, 1.0, v70
	v_add_f32_e32 v71, 1.0, v71
	v_rcp_f32_e32 v68, v68
	v_rcp_f32_e32 v70, v70
	v_rcp_f32_e32 v71, v71
	v_rcp_f32_e32 v69, v69
	s_waitcnt vmcnt(6)
	v_pk_add_f32 v[66:67], v[66:67], v[222:223]
	v_pk_add_f32 v[64:65], v[64:65], v[220:221]
	s_waitcnt vmcnt(5)
	v_pk_mul_f32 v[66:67], v[218:219], v[66:67]
	v_pk_mul_f32 v[64:65], v[216:217], v[64:65]
	s_waitcnt vmcnt(3)
	v_pk_fma_f32 v[66:67], v[66:67], v[70:71], v[190:191]
	v_pk_fma_f32 v[64:65], v[64:65], v[68:69], v[188:189]
	global_load_dwordx4 v[188:191], v[200:201], off offset:256
	global_store_dwordx4 v[160:161], v[64:67], off offset:256
	v_add_f32_e32 v52, v52, v196
	global_load_dwordx4 v[208:211], v[212:213], off offset:256
	v_add_f32_e32 v53, v53, v197
	v_add_f32_e32 v54, v54, v198
	v_add_f32_e32 v55, v55, v199
	v_mul_f32_e32 v52, 0xbfb8aa3b, v52
	v_mul_f32_e32 v53, 0xbfb8aa3b, v53
	v_mul_f32_e32 v54, 0xbfb8aa3b, v54
	v_mul_f32_e32 v55, 0xbfb8aa3b, v55
	v_exp_f32_e32 v52, v52
	v_exp_f32_e32 v53, v53
	v_exp_f32_e32 v54, v54
	v_exp_f32_e32 v55, v55
	v_add_f32_e32 v52, 1.0, v52
	v_add_f32_e32 v53, 1.0, v53
	v_add_f32_e32 v54, 1.0, v54
	v_add_f32_e32 v55, 1.0, v55
	v_rcp_f32_e32 v52, v52
	v_rcp_f32_e32 v53, v53
	v_rcp_f32_e32 v54, v54
	v_rcp_f32_e32 v55, v55
	v_pk_add_f32 v[50:51], v[50:51], v[222:223]
	v_pk_add_f32 v[48:49], v[48:49], v[220:221]
	v_pk_mul_f32 v[50:51], v[218:219], v[50:51]
	v_pk_mul_f32 v[48:49], v[216:217], v[48:49]
	v_add_f32_e32 v44, v44, v196
	v_add_f32_e32 v45, v45, v197
	v_add_f32_e32 v46, v46, v198
	v_add_f32_e32 v47, v47, v199
	v_mul_f32_e32 v44, 0xbfb8aa3b, v44
	v_mul_f32_e32 v45, 0xbfb8aa3b, v45
	v_mul_f32_e32 v46, 0xbfb8aa3b, v46
	v_mul_f32_e32 v47, 0xbfb8aa3b, v47
	v_exp_f32_e32 v44, v44
	v_exp_f32_e32 v45, v45
	v_exp_f32_e32 v46, v46
	v_exp_f32_e32 v47, v47
	v_add_f32_e32 v44, 1.0, v44
	v_add_f32_e32 v45, 1.0, v45
	v_add_f32_e32 v46, 1.0, v46
	v_add_f32_e32 v47, 1.0, v47
	v_rcp_f32_e32 v44, v44
	v_rcp_f32_e32 v45, v45
	v_rcp_f32_e32 v46, v46
	v_rcp_f32_e32 v47, v47
	v_pk_add_f32 v[42:43], v[42:43], v[222:223]
	v_pk_add_f32 v[40:41], v[40:41], v[220:221]
	v_pk_mul_f32 v[42:43], v[218:219], v[42:43]
	v_pk_mul_f32 v[40:41], v[216:217], v[40:41]
	v_add_f32_e32 v36, v36, v196
	v_add_f32_e32 v37, v37, v197
	v_add_f32_e32 v38, v38, v198
	v_add_f32_e32 v39, v39, v199
	v_mul_f32_e32 v36, 0xbfb8aa3b, v36
	v_mul_f32_e32 v37, 0xbfb8aa3b, v37
	v_mul_f32_e32 v38, 0xbfb8aa3b, v38
	v_mul_f32_e32 v39, 0xbfb8aa3b, v39
	v_exp_f32_e32 v36, v36
	v_exp_f32_e32 v37, v37
	v_exp_f32_e32 v38, v38
	v_exp_f32_e32 v39, v39
	v_add_f32_e32 v36, 1.0, v36
	v_add_f32_e32 v37, 1.0, v37
	v_add_f32_e32 v38, 1.0, v38
	v_add_f32_e32 v39, 1.0, v39
	v_rcp_f32_e32 v36, v36
	v_rcp_f32_e32 v37, v37
	v_rcp_f32_e32 v38, v38
	v_rcp_f32_e32 v39, v39
	v_pk_add_f32 v[34:35], v[34:35], v[222:223]
	v_pk_add_f32 v[32:33], v[32:33], v[220:221]
	v_pk_mul_f32 v[34:35], v[218:219], v[34:35]
	v_pk_mul_f32 v[32:33], v[216:217], v[32:33]
	v_add_f32_e32 v28, v28, v196
	v_add_f32_e32 v29, v29, v197
	v_add_f32_e32 v30, v30, v198
	v_add_f32_e32 v31, v31, v199
	v_mul_f32_e32 v28, 0xbfb8aa3b, v28
	v_mul_f32_e32 v29, 0xbfb8aa3b, v29
	v_mul_f32_e32 v30, 0xbfb8aa3b, v30
	s_waitcnt vmcnt(5)
	v_pk_fma_f32 v[48:49], v[48:49], v[52:53], v[224:225]
	v_pk_fma_f32 v[50:51], v[50:51], v[54:55], v[226:227]
	global_load_dwordx4 v[224:227], v[204:205], off offset:256
	global_store_dwordx4 v[120:121], v[48:51], off offset:256
	v_mul_f32_e32 v31, 0xbfb8aa3b, v31
	global_load_dwordx4 v[232:235], v[192:193], off offset:256
	v_exp_f32_e32 v28, v28
	v_exp_f32_e32 v29, v29
	v_exp_f32_e32 v30, v30
	v_exp_f32_e32 v31, v31
	v_add_f32_e32 v28, 1.0, v28
	v_add_f32_e32 v29, 1.0, v29
	v_add_f32_e32 v30, 1.0, v30
	v_add_f32_e32 v31, 1.0, v31
	v_rcp_f32_e32 v28, v28
	v_rcp_f32_e32 v29, v29
	v_rcp_f32_e32 v30, v30
	v_rcp_f32_e32 v31, v31
	v_pk_add_f32 v[26:27], v[26:27], v[222:223]
	v_pk_add_f32 v[24:25], v[24:25], v[220:221]
	v_pk_mul_f32 v[26:27], v[218:219], v[26:27]
	v_pk_mul_f32 v[24:25], v[216:217], v[24:25]
	v_add_f32_e32 v20, v20, v196
	v_add_f32_e32 v21, v21, v197
	v_add_f32_e32 v22, v22, v198
	v_add_f32_e32 v23, v23, v199
	v_mul_f32_e32 v20, 0xbfb8aa3b, v20
	v_mul_f32_e32 v21, 0xbfb8aa3b, v21
	v_mul_f32_e32 v22, 0xbfb8aa3b, v22
	v_mul_f32_e32 v23, 0xbfb8aa3b, v23
	v_exp_f32_e32 v20, v20
	v_exp_f32_e32 v21, v21
	v_exp_f32_e32 v22, v22
	v_exp_f32_e32 v23, v23
	v_add_f32_e32 v20, 1.0, v20
	v_add_f32_e32 v21, 1.0, v21
	v_add_f32_e32 v22, 1.0, v22
	v_add_f32_e32 v23, 1.0, v23
	v_rcp_f32_e32 v20, v20
	v_rcp_f32_e32 v21, v21
	v_rcp_f32_e32 v22, v22
	v_rcp_f32_e32 v23, v23
	v_pk_add_f32 v[18:19], v[18:19], v[222:223]
	v_pk_add_f32 v[16:17], v[16:17], v[220:221]
	v_pk_mul_f32 v[18:19], v[218:219], v[18:19]
	v_pk_mul_f32 v[16:17], v[216:217], v[16:17]
	v_add_f32_e32 v12, v12, v196
	v_add_f32_e32 v13, v13, v197
	v_add_f32_e32 v14, v14, v198
	v_add_f32_e32 v15, v15, v199
	v_mul_f32_e32 v12, 0xbfb8aa3b, v12
	v_mul_f32_e32 v13, 0xbfb8aa3b, v13
	v_mul_f32_e32 v14, 0xbfb8aa3b, v14
	v_mul_f32_e32 v15, 0xbfb8aa3b, v15
	v_exp_f32_e32 v12, v12
	v_exp_f32_e32 v13, v13
	v_exp_f32_e32 v14, v14
	v_exp_f32_e32 v15, v15
	v_add_f32_e32 v12, 1.0, v12
	v_add_f32_e32 v13, 1.0, v13
	v_add_f32_e32 v14, 1.0, v14
	v_add_f32_e32 v15, 1.0, v15
	v_rcp_f32_e32 v12, v12
	v_rcp_f32_e32 v13, v13
	v_rcp_f32_e32 v14, v14
	v_rcp_f32_e32 v15, v15
	v_pk_add_f32 v[10:11], v[10:11], v[222:223]
	v_pk_add_f32 v[8:9], v[8:9], v[220:221]
	v_pk_mul_f32 v[10:11], v[218:219], v[10:11]
	v_pk_mul_f32 v[8:9], v[216:217], v[8:9]
	s_waitcnt vmcnt(7)
	v_pk_fma_f32 v[40:41], v[40:41], v[44:45], v[184:185]
	v_pk_fma_f32 v[42:43], v[42:43], v[46:47], v[186:187]
	global_store_dwordx4 v[112:113], v[40:43], off offset:256
	s_waitcnt vmcnt(7)
	v_pk_fma_f32 v[32:33], v[32:33], v[36:37], v[228:229]
	v_pk_fma_f32 v[34:35], v[34:35], v[38:39], v[230:231]
	global_store_dwordx4 v[104:105], v[32:35], off offset:256
	s_waitcnt vmcnt(7)
	v_pk_fma_f32 v[24:25], v[24:25], v[28:29], v[188:189]
	v_pk_fma_f32 v[26:27], v[26:27], v[30:31], v[190:191]
	global_store_dwordx4 v[96:97], v[24:27], off offset:256
	s_waitcnt vmcnt(6)
	v_pk_fma_f32 v[16:17], v[16:17], v[20:21], v[208:209]
	v_pk_fma_f32 v[18:19], v[18:19], v[22:23], v[210:211]
	global_store_dwordx4 v[88:89], v[16:19], off offset:256
	s_waitcnt vmcnt(6)
	v_pk_fma_f32 v[8:9], v[8:9], v[12:13], v[224:225]
	v_pk_fma_f32 v[10:11], v[10:11], v[14:15], v[226:227]
	global_store_dwordx4 v[80:81], v[8:11], off offset:256
	v_add_f32_e32 v12, v0, v196
	v_add_f32_e32 v13, v1, v197
	v_add_f32_e32 v14, v2, v198
	v_add_f32_e32 v15, v3, v199
	v_pk_add_f32 v[0:1], v[6:7], v[222:223]
	v_pk_add_f32 v[2:3], v[4:5], v[220:221]
	v_mul_f32_e32 v4, 0xbfb8aa3b, v12
	v_mul_f32_e32 v5, 0xbfb8aa3b, v13
	v_mul_f32_e32 v6, 0xbfb8aa3b, v14
	v_mul_f32_e32 v7, 0xbfb8aa3b, v15
	v_exp_f32_e32 v4, v4
	v_exp_f32_e32 v5, v5
	v_exp_f32_e32 v6, v6
	v_exp_f32_e32 v7, v7
	v_add_f32_e32 v4, 1.0, v4
	v_add_f32_e32 v5, 1.0, v5
	v_add_f32_e32 v6, 1.0, v6
	v_add_f32_e32 v7, 1.0, v7
	v_rcp_f32_e32 v4, v4
	v_rcp_f32_e32 v5, v5
	v_rcp_f32_e32 v6, v6
	v_rcp_f32_e32 v7, v7
	v_pk_mul_f32 v[12:13], v[218:219], v[0:1]
	v_pk_mul_f32 v[0:1], v[216:217], v[2:3]
	s_waitcnt vmcnt(5)
	v_pk_fma_f32 v[2:3], v[12:13], v[6:7], v[234:235]
	v_pk_fma_f32 v[0:1], v[0:1], v[4:5], v[232:233]
	global_store_dwordx4 v[76:77], v[0:3], off offset:256
	s_cbranch_vccz .LBB0_410
	s_waitcnt vmcnt(0)
	s_cmpk_gt_u32 s1, 0xff
	s_cbranch_scc1 .LBB0_417
	s_barrier

.LBB0_606:
	ds_read_b128 v[148:151], v144
	ds_read_b128 v[152:155], v144 offset:1024
	ds_read_b128 v[156:159], v144 offset:2048
	ds_read_b128 v[160:163], v144 offset:3072
	s_add_u32 s22, s20, 0x100
	s_addc_u32 s23, s21, 0
	s_cmp_eq_u32 s47, 28
	s_cselect_b32 s27, s13, s23
	s_cselect_b32 s26, s41, s22
	s_cselect_b32 s25, s11, s46
	s_cselect_b32 s24, s42, s43
	v_lshl_add_u64 v[196:197], s[20:21], 0, v[134:135]
	s_add_i32 m0, s5, 0xc000
	ds_read_b128 v[164:167], v145
	ds_read_b128 v[168:171], v145 offset:1024
	ds_read_b128 v[172:175], v145 offset:2048
	ds_read_b128 v[176:179], v145 offset:3072
	ds_read_b128 v[180:183], v145 offset:4096
	ds_read_b128 v[184:187], v145 offset:5120
	ds_read_b128 v[188:191], v145 offset:6144
	ds_read_b128 v[192:195], v145 offset:7168
	global_load_lds_dwordx4 v[196:197], off
	v_lshl_add_u64 v[196:197], s[20:21], 0, v[136:137]
	s_add_i32 m0, s5, 0xe000
	s_nop 0
	global_load_lds_dwordx4 v[196:197], off
	s_waitcnt lgkmcnt(8)
	s_barrier
	s_waitcnt lgkmcnt(0)
	s_waitcnt lgkmcnt(0)
	v_mfma_f32_16x16x32_bf16 v[124:127], v[148:151], v[164:167], v[124:127]
	v_mfma_f32_16x16x32_bf16 v[120:123], v[156:159], v[164:167], v[120:123]
	v_mfma_f32_16x16x32_bf16 v[108:111], v[148:151], v[172:175], v[108:111]
	v_mfma_f32_16x16x32_bf16 v[104:107], v[156:159], v[172:175], v[104:107]
	v_mfma_f32_16x16x32_bf16 v[92:95], v[148:151], v[180:183], v[92:95]
	v_mfma_f32_16x16x32_bf16 v[88:91], v[156:159], v[180:183], v[88:91]
	v_mfma_f32_16x16x32_bf16 v[76:79], v[148:151], v[188:191], v[76:79]
	v_mfma_f32_16x16x32_bf16 v[72:75], v[156:159], v[188:191], v[72:75]
	v_mfma_f32_16x16x32_bf16 v[124:127], v[152:155], v[168:171], v[124:127]
	v_mfma_f32_16x16x32_bf16 v[120:123], v[160:163], v[168:171], v[120:123]
	v_mfma_f32_16x16x32_bf16 v[108:111], v[152:155], v[176:179], v[108:111]
	v_mfma_f32_16x16x32_bf16 v[104:107], v[160:163], v[176:179], v[104:107]
	v_mfma_f32_16x16x32_bf16 v[92:95], v[152:155], v[184:187], v[92:95]
	v_mfma_f32_16x16x32_bf16 v[88:91], v[160:163], v[184:187], v[88:91]
	v_mfma_f32_16x16x32_bf16 v[76:79], v[152:155], v[192:195], v[76:79]
	v_mfma_f32_16x16x32_bf16 v[72:75], v[160:163], v[192:195], v[72:75]
	s_barrier
	s_add_i32 s20, s38, s2
	v_lshl_add_u64 v[212:213], s[24:25], 0, v[130:131]
	s_mov_b32 m0, s20
	ds_read_b128 v[196:199], v146
	ds_read_b128 v[200:203], v146 offset:1024
	ds_read_b128 v[204:207], v146 offset:2048
	ds_read_b128 v[208:211], v146 offset:3072
	global_load_lds_dwordx4 v[212:213], off
	v_lshl_add_u64 v[214:215], s[24:25], 0, v[128:129]
	s_add_i32 m0, s20, 0x2000
	s_nop 0
	global_load_lds_dwordx4 v[214:215], off
	s_barrier
	s_waitcnt lgkmcnt(0)
	s_waitcnt lgkmcnt(0)
	v_mfma_f32_16x16x32_bf16 v[116:119], v[196:199], v[164:167], v[116:119]
	v_mfma_f32_16x16x32_bf16 v[112:115], v[204:207], v[164:167], v[112:115]
	v_mfma_f32_16x16x32_bf16 v[100:103], v[196:199], v[172:175], v[100:103]
	v_mfma_f32_16x16x32_bf16 v[96:99], v[204:207], v[172:175], v[96:99]
	v_mfma_f32_16x16x32_bf16 v[84:87], v[196:199], v[180:183], v[84:87]
	v_mfma_f32_16x16x32_bf16 v[80:83], v[204:207], v[180:183], v[80:83]
	v_mfma_f32_16x16x32_bf16 v[68:71], v[196:199], v[188:191], v[68:71]
	v_mfma_f32_16x16x32_bf16 v[64:67], v[204:207], v[188:191], v[64:67]
	v_mfma_f32_16x16x32_bf16 v[116:119], v[200:203], v[168:171], v[116:119]
	v_mfma_f32_16x16x32_bf16 v[112:115], v[208:211], v[168:171], v[112:115]
	v_mfma_f32_16x16x32_bf16 v[100:103], v[200:203], v[176:179], v[100:103]
	v_mfma_f32_16x16x32_bf16 v[96:99], v[208:211], v[176:179], v[96:99]
	v_mfma_f32_16x16x32_bf16 v[84:87], v[200:203], v[184:187], v[84:87]
	v_mfma_f32_16x16x32_bf16 v[80:83], v[208:211], v[184:187], v[80:83]
	v_mfma_f32_16x16x32_bf16 v[68:71], v[200:203], v[192:195], v[68:71]
	v_mfma_f32_16x16x32_bf16 v[64:67], v[208:211], v[192:195], v[64:67]
	s_mov_b32 m0, s5
	v_lshl_add_u64 v[216:217], s[26:27], 0, v[130:131]
	s_barrier
	ds_read_b128 v[164:167], v145 offset:16384
	ds_read_b128 v[168:171], v145 offset:17408
	ds_read_b128 v[172:175], v145 offset:18432
	ds_read_b128 v[176:179], v145 offset:19456
	ds_read_b128 v[180:183], v145 offset:20480
	ds_read_b128 v[184:187], v145 offset:21504
	ds_read_b128 v[188:191], v145 offset:22528
	ds_read_b128 v[192:195], v145 offset:23552
	global_load_lds_dwordx4 v[216:217], off
	v_lshl_add_u64 v[218:219], s[26:27], 0, v[128:129]
	s_mov_b32 m0, s28
	s_nop 0
	global_load_lds_dwordx4 v[218:219], off
	s_barrier
	s_waitcnt lgkmcnt(0)
	s_waitcnt lgkmcnt(0)
	v_mfma_f32_16x16x32_bf16 v[60:63], v[148:151], v[164:167], v[60:63]
	v_mfma_f32_16x16x32_bf16 v[56:59], v[156:159], v[164:167], v[56:59]
	v_mfma_f32_16x16x32_bf16 v[44:47], v[148:151], v[172:175], v[44:47]
	v_mfma_f32_16x16x32_bf16 v[40:43], v[156:159], v[172:175], v[40:43]
	v_mfma_f32_16x16x32_bf16 v[28:31], v[148:151], v[180:183], v[28:31]
	v_mfma_f32_16x16x32_bf16 v[24:27], v[156:159], v[180:183], v[24:27]
	v_mfma_f32_16x16x32_bf16 v[12:15], v[148:151], v[188:191], v[12:15]
	v_mfma_f32_16x16x32_bf16 v[8:11], v[156:159], v[188:191], v[8:11]
	v_mfma_f32_16x16x32_bf16 v[60:63], v[152:155], v[168:171], v[60:63]
	v_mfma_f32_16x16x32_bf16 v[56:59], v[160:163], v[168:171], v[56:59]
	v_mfma_f32_16x16x32_bf16 v[44:47], v[152:155], v[176:179], v[44:47]
	v_mfma_f32_16x16x32_bf16 v[40:43], v[160:163], v[176:179], v[40:43]
	v_mfma_f32_16x16x32_bf16 v[28:31], v[152:155], v[184:187], v[28:31]
	v_mfma_f32_16x16x32_bf16 v[24:27], v[160:163], v[184:187], v[24:27]
	v_mfma_f32_16x16x32_bf16 v[12:15], v[152:155], v[192:195], v[12:15]
	v_mfma_f32_16x16x32_bf16 v[8:11], v[160:163], v[192:195], v[8:11]
	s_barrier
	s_add_u32 s20, s24, 0x80000
	s_addc_u32 s21, s25, 0
	s_add_i32 s60, s39, s2
	v_lshl_add_u64 v[148:149], s[20:21], 0, v[130:131]
	s_mov_b32 m0, s60
	s_nop 0
	global_load_lds_dwordx4 v[148:149], off
	v_lshl_add_u64 v[148:149], s[20:21], 0, v[128:129]
	s_add_i32 m0, s60, 0x2000
	s_nop 0
	global_load_lds_dwordx4 v[148:149], off
	s_waitcnt vmcnt(6)
	s_barrier
	v_mfma_f32_16x16x32_bf16 v[52:55], v[196:199], v[164:167], v[52:55]
	v_mfma_f32_16x16x32_bf16 v[48:51], v[204:207], v[164:167], v[48:51]
	v_mfma_f32_16x16x32_bf16 v[36:39], v[196:199], v[172:175], v[36:39]
	v_mfma_f32_16x16x32_bf16 v[32:35], v[204:207], v[172:175], v[32:35]
	v_mfma_f32_16x16x32_bf16 v[20:23], v[196:199], v[180:183], v[20:23]
	v_mfma_f32_16x16x32_bf16 v[16:19], v[204:207], v[180:183], v[16:19]
	v_mfma_f32_16x16x32_bf16 v[4:7], v[196:199], v[188:191], v[4:7]
	v_mfma_f32_16x16x32_bf16 v[0:3], v[204:207], v[188:191], v[0:3]
	v_mfma_f32_16x16x32_bf16 v[52:55], v[200:203], v[168:171], v[52:55]
	v_mfma_f32_16x16x32_bf16 v[48:51], v[208:211], v[168:171], v[48:51]
	v_mfma_f32_16x16x32_bf16 v[36:39], v[200:203], v[176:179], v[36:39]
	v_mfma_f32_16x16x32_bf16 v[32:35], v[208:211], v[176:179], v[32:35]
	v_mfma_f32_16x16x32_bf16 v[20:23], v[200:203], v[184:187], v[20:23]
	v_mfma_f32_16x16x32_bf16 v[16:19], v[208:211], v[184:187], v[16:19]
	v_mfma_f32_16x16x32_bf16 v[4:7], v[200:203], v[192:195], v[4:7]
	v_mfma_f32_16x16x32_bf16 v[0:3], v[208:211], v[192:195], v[0:3]
	s_add_i32 s60, 0, 0x18000
	v_add_u32_e32 v147, s60, v143
	s_barrier
	ds_read_b128 v[148:151], v147
	ds_read_b128 v[152:155], v147 offset:1024
	ds_read_b128 v[156:159], v147 offset:2048
	ds_read_b128 v[160:163], v147 offset:3072
	s_add_u32 s20, s26, 0x80000
	s_addc_u32 s21, s27, 0
	s_mov_b32 m0, s29
	v_lshl_add_u64 v[196:197], s[20:21], 0, v[130:131]
	ds_read_b128 v[164:167], v145 offset:32768
	ds_read_b128 v[168:171], v145 offset:33792
	ds_read_b128 v[172:175], v145 offset:34816
	ds_read_b128 v[176:179], v145 offset:35840
	ds_read_b128 v[180:183], v145 offset:36864
	ds_read_b128 v[184:187], v145 offset:37888
	ds_read_b128 v[188:191], v145 offset:38912
	ds_read_b128 v[192:195], v145 offset:39936
	global_load_lds_dwordx4 v[196:197], off
	v_lshl_add_u64 v[196:197], s[20:21], 0, v[128:129]
	s_mov_b32 m0, s30
	s_nop 0
	global_load_lds_dwordx4 v[196:197], off
	s_waitcnt lgkmcnt(8)
	s_barrier
	s_waitcnt lgkmcnt(0)
	s_waitcnt lgkmcnt(0)
	v_mfma_f32_16x16x32_bf16 v[124:127], v[148:151], v[164:167], v[124:127]
	v_mfma_f32_16x16x32_bf16 v[120:123], v[156:159], v[164:167], v[120:123]
	v_mfma_f32_16x16x32_bf16 v[108:111], v[148:151], v[172:175], v[108:111]
	v_mfma_f32_16x16x32_bf16 v[104:107], v[156:159], v[172:175], v[104:107]
	v_mfma_f32_16x16x32_bf16 v[92:95], v[148:151], v[180:183], v[92:95]
	v_mfma_f32_16x16x32_bf16 v[88:91], v[156:159], v[180:183], v[88:91]
	v_mfma_f32_16x16x32_bf16 v[76:79], v[148:151], v[188:191], v[76:79]
	v_mfma_f32_16x16x32_bf16 v[72:75], v[156:159], v[188:191], v[72:75]
	v_mfma_f32_16x16x32_bf16 v[124:127], v[152:155], v[168:171], v[124:127]
	v_mfma_f32_16x16x32_bf16 v[120:123], v[160:163], v[168:171], v[120:123]
	v_mfma_f32_16x16x32_bf16 v[108:111], v[152:155], v[176:179], v[108:111]
	v_mfma_f32_16x16x32_bf16 v[104:107], v[160:163], v[176:179], v[104:107]
	v_mfma_f32_16x16x32_bf16 v[92:95], v[152:155], v[184:187], v[92:95]
	v_mfma_f32_16x16x32_bf16 v[88:91], v[160:163], v[184:187], v[88:91]
	v_mfma_f32_16x16x32_bf16 v[76:79], v[152:155], v[192:195], v[76:79]
	v_mfma_f32_16x16x32_bf16 v[72:75], v[160:163], v[192:195], v[72:75]
	s_barrier
	s_add_i32 s26, 0, 0x1c000
	s_add_i32 s20, s60, s2
	v_add_u32_e32 v147, s26, v143
	v_lshl_add_u64 v[212:213], v[212:213], 0, s[8:9]
	s_mov_b32 m0, s20
	ds_read_b128 v[196:199], v147
	ds_read_b128 v[200:203], v147 offset:1024
	ds_read_b128 v[204:207], v147 offset:2048
	ds_read_b128 v[208:211], v147 offset:3072
	global_load_lds_dwordx4 v[212:213], off
	v_lshl_add_u64 v[212:213], v[214:215], 0, s[8:9]
	s_add_i32 m0, s20, 0x2000
	s_nop 0
	global_load_lds_dwordx4 v[212:213], off
	s_barrier
	s_waitcnt lgkmcnt(0)
	s_waitcnt lgkmcnt(0)
	v_mfma_f32_16x16x32_bf16 v[116:119], v[196:199], v[164:167], v[116:119]
	v_mfma_f32_16x16x32_bf16 v[112:115], v[204:207], v[164:167], v[112:115]
	v_mfma_f32_16x16x32_bf16 v[100:103], v[196:199], v[172:175], v[100:103]
	v_mfma_f32_16x16x32_bf16 v[96:99], v[204:207], v[172:175], v[96:99]
	v_mfma_f32_16x16x32_bf16 v[84:87], v[196:199], v[180:183], v[84:87]
	v_mfma_f32_16x16x32_bf16 v[80:83], v[204:207], v[180:183], v[80:83]
	v_mfma_f32_16x16x32_bf16 v[68:71], v[196:199], v[188:191], v[68:71]
	v_mfma_f32_16x16x32_bf16 v[64:67], v[204:207], v[188:191], v[64:67]
	v_mfma_f32_16x16x32_bf16 v[116:119], v[200:203], v[168:171], v[116:119]
	v_mfma_f32_16x16x32_bf16 v[112:115], v[208:211], v[168:171], v[112:115]
	v_mfma_f32_16x16x32_bf16 v[100:103], v[200:203], v[176:179], v[100:103]
	v_mfma_f32_16x16x32_bf16 v[96:99], v[208:211], v[176:179], v[96:99]
	v_mfma_f32_16x16x32_bf16 v[84:87], v[200:203], v[184:187], v[84:87]
	v_mfma_f32_16x16x32_bf16 v[80:83], v[208:211], v[184:187], v[80:83]
	v_mfma_f32_16x16x32_bf16 v[68:71], v[200:203], v[192:195], v[68:71]
	v_mfma_f32_16x16x32_bf16 v[64:67], v[208:211], v[192:195], v[64:67]
	s_mov_b32 m0, s34
	v_lshl_add_u64 v[212:213], v[216:217], 0, s[8:9]
	s_barrier
	ds_read_b128 v[164:167], v145 offset:49152
	ds_read_b128 v[168:171], v145 offset:50176
	ds_read_b128 v[172:175], v145 offset:51200
	ds_read_b128 v[176:179], v145 offset:52224
	ds_read_b128 v[180:183], v145 offset:53248
	ds_read_b128 v[184:187], v145 offset:54272
	ds_read_b128 v[188:191], v145 offset:55296
	ds_read_b128 v[192:195], v145 offset:56320
	global_load_lds_dwordx4 v[212:213], off
	v_lshl_add_u64 v[212:213], v[218:219], 0, s[8:9]
	s_mov_b32 m0, s35
	s_nop 0
	global_load_lds_dwordx4 v[212:213], off
	s_barrier
	s_waitcnt lgkmcnt(0)
	s_waitcnt lgkmcnt(0)
	v_mfma_f32_16x16x32_bf16 v[60:63], v[148:151], v[164:167], v[60:63]
	v_mfma_f32_16x16x32_bf16 v[56:59], v[156:159], v[164:167], v[56:59]
	v_mfma_f32_16x16x32_bf16 v[44:47], v[148:151], v[172:175], v[44:47]
	v_mfma_f32_16x16x32_bf16 v[40:43], v[156:159], v[172:175], v[40:43]
	v_mfma_f32_16x16x32_bf16 v[28:31], v[148:151], v[180:183], v[28:31]
	v_mfma_f32_16x16x32_bf16 v[24:27], v[156:159], v[180:183], v[24:27]
	v_mfma_f32_16x16x32_bf16 v[12:15], v[148:151], v[188:191], v[12:15]
	v_mfma_f32_16x16x32_bf16 v[8:11], v[156:159], v[188:191], v[8:11]
	v_mfma_f32_16x16x32_bf16 v[60:63], v[152:155], v[168:171], v[60:63]
	v_mfma_f32_16x16x32_bf16 v[56:59], v[160:163], v[168:171], v[56:59]
	v_mfma_f32_16x16x32_bf16 v[44:47], v[152:155], v[176:179], v[44:47]
	v_mfma_f32_16x16x32_bf16 v[40:43], v[160:163], v[176:179], v[40:43]
	v_mfma_f32_16x16x32_bf16 v[28:31], v[152:155], v[184:187], v[28:31]
	v_mfma_f32_16x16x32_bf16 v[24:27], v[160:163], v[184:187], v[24:27]
	v_mfma_f32_16x16x32_bf16 v[12:15], v[152:155], v[192:195], v[12:15]
	v_mfma_f32_16x16x32_bf16 v[8:11], v[160:163], v[192:195], v[8:11]
	s_barrier
	s_add_u32 s20, s24, 0x80080
	s_addc_u32 s21, s25, 0
	s_add_i32 s24, s26, s2
	v_lshl_add_u64 v[148:149], s[20:21], 0, v[130:131]
	s_mov_b32 m0, s24
	s_nop 0
	global_load_lds_dwordx4 v[148:149], off
	v_lshl_add_u64 v[148:149], s[20:21], 0, v[128:129]
	s_add_i32 m0, s24, 0x2000
	s_nop 0
	global_load_lds_dwordx4 v[148:149], off
	s_waitcnt vmcnt(6)
	s_barrier
	v_mfma_f32_16x16x32_bf16 v[52:55], v[196:199], v[164:167], v[52:55]
	v_mfma_f32_16x16x32_bf16 v[48:51], v[204:207], v[164:167], v[48:51]
	v_mfma_f32_16x16x32_bf16 v[36:39], v[196:199], v[172:175], v[36:39]
	v_mfma_f32_16x16x32_bf16 v[32:35], v[204:207], v[172:175], v[32:35]
	v_mfma_f32_16x16x32_bf16 v[20:23], v[196:199], v[180:183], v[20:23]
	v_mfma_f32_16x16x32_bf16 v[16:19], v[204:207], v[180:183], v[16:19]
	v_mfma_f32_16x16x32_bf16 v[4:7], v[196:199], v[188:191], v[4:7]
	v_mfma_f32_16x16x32_bf16 v[0:3], v[204:207], v[188:191], v[0:3]
	v_mfma_f32_16x16x32_bf16 v[52:55], v[200:203], v[168:171], v[52:55]
	v_mfma_f32_16x16x32_bf16 v[48:51], v[208:211], v[168:171], v[48:51]
	v_mfma_f32_16x16x32_bf16 v[36:39], v[200:203], v[176:179], v[36:39]
	v_mfma_f32_16x16x32_bf16 v[32:35], v[208:211], v[176:179], v[32:35]
	v_mfma_f32_16x16x32_bf16 v[20:23], v[200:203], v[184:187], v[20:23]
	v_mfma_f32_16x16x32_bf16 v[16:19], v[208:211], v[184:187], v[16:19]
	v_mfma_f32_16x16x32_bf16 v[4:7], v[200:203], v[192:195], v[4:7]
	v_mfma_f32_16x16x32_bf16 v[0:3], v[208:211], v[192:195], v[0:3]
	s_add_i32 s47, s47, 2
	s_add_u32 s43, s43, 0x100
	s_addc_u32 s46, s46, 0
	s_cmp_gt_u32 s47, 29
	s_mov_b64 s[20:21], s[22:23]
	s_barrier
	s_cbranch_scc0 .LBB0_606
	v_mul_f32_e32 v150, 0xbfb8aa3b, v124
	v_mul_f32_e32 v151, 0xbfb8aa3b, v125
	v_exp_f32_e32 v150, v150
	v_exp_f32_e32 v151, v151
	s_lshl_b32 s11, s19, 7
	v_lshl_add_u32 v147, s18, 8, v142
	v_add_f32_e32 v150, 1.0, v150
	v_add_f32_e32 v151, 1.0, v151
	v_rcp_f32_e32 v150, v150
	v_rcp_f32_e32 v151, v151
	s_or_b32 s18, s11, s36
	s_ashr_i32 s19, s18, 31
	v_mad_i64_i32 v[148:149], s[20:21], v147, s40, v[132:133]
	v_pk_mul_f32 v[124:125], v[124:125], v[150:151]
	s_lshl_b64 s[18:19], s[18:19], 1
	v_pk_mul_f32 v[120:121], v[120:121], v[124:125]
	s_and_b64 vcc, exec, s[6:7]
	v_cvt_pk_bf16_f32 v120, v120, v121
	v_mul_f32_e32 v121, 0xbfb8aa3b, v126
	v_exp_f32_e32 v121, v121
	s_mov_b64 s[22:23], s[16:17]
	v_add_f32_e32 v121, 1.0, v121
	v_rcp_f32_e32 v124, v121
	v_mul_f32_e32 v121, 0xbfb8aa3b, v127
	v_exp_f32_e32 v121, v121
	s_nop 0
	v_add_f32_e32 v121, 1.0, v121
	v_rcp_f32_e32 v125, v121
	s_nop 0
	v_pk_mul_f32 v[124:125], v[126:127], v[124:125]
	s_nop 0
	v_pk_mul_f32 v[122:123], v[122:123], v[124:125]
	s_nop 0
	v_cvt_pk_bf16_f32 v121, v122, v123
	v_lshl_add_u64 v[122:123], v[148:149], 0, s[18:19]
	global_store_dwordx2 v[122:123], v[120:121], off
	v_mul_f32_e32 v120, 0xbfb8aa3b, v116
	v_mul_f32_e32 v121, 0xbfb8aa3b, v117
	v_exp_f32_e32 v120, v120
	v_exp_f32_e32 v121, v121
	v_add_f32_e32 v120, 1.0, v120
	v_add_f32_e32 v121, 1.0, v121
	v_rcp_f32_e32 v120, v120
	v_rcp_f32_e32 v121, v121
	s_nop 0
	v_pk_mul_f32 v[116:117], v[116:117], v[120:121]
	s_nop 0
	v_pk_mul_f32 v[112:113], v[112:113], v[116:117]
	s_nop 0
	v_cvt_pk_bf16_f32 v112, v112, v113
	v_mul_f32_e32 v113, 0xbfb8aa3b, v118
	v_exp_f32_e32 v113, v113
	s_nop 0
	v_add_f32_e32 v113, 1.0, v113
	v_rcp_f32_e32 v116, v113
	v_mul_f32_e32 v113, 0xbfb8aa3b, v119
	v_exp_f32_e32 v113, v113
	s_nop 0
	v_add_f32_e32 v113, 1.0, v113
	v_rcp_f32_e32 v117, v113
	s_nop 0
	v_pk_mul_f32 v[116:117], v[118:119], v[116:117]
	s_nop 0
	v_pk_mul_f32 v[114:115], v[114:115], v[116:117]
	s_nop 0
	v_cvt_pk_bf16_f32 v113, v114, v115
	v_mul_f32_e32 v114, 0xbfb8aa3b, v108
	v_mul_f32_e32 v115, 0xbfb8aa3b, v109
	v_exp_f32_e32 v114, v114
	v_exp_f32_e32 v115, v115
	global_store_dwordx2 v[122:123], v[112:113], off offset:128
	v_or_b32_e32 v112, 16, v147
	v_add_f32_e32 v114, 1.0, v114
	v_add_f32_e32 v115, 1.0, v115
	v_rcp_f32_e32 v114, v114
	v_rcp_f32_e32 v115, v115
	v_mad_i64_i32 v[112:113], s[20:21], v112, s40, v[132:133]
	v_pk_mul_f32 v[108:109], v[108:109], v[114:115]
	s_nop 0
	v_pk_mul_f32 v[104:105], v[104:105], v[108:109]
	s_nop 0
	v_cvt_pk_bf16_f32 v104, v104, v105
	v_mul_f32_e32 v105, 0xbfb8aa3b, v110
	v_exp_f32_e32 v105, v105
	s_nop 0
	v_add_f32_e32 v105, 1.0, v105
	v_rcp_f32_e32 v108, v105
	v_mul_f32_e32 v105, 0xbfb8aa3b, v111
	v_exp_f32_e32 v105, v105
	s_nop 0
	v_add_f32_e32 v105, 1.0, v105
	v_rcp_f32_e32 v109, v105
	s_nop 0
	v_pk_mul_f32 v[108:109], v[110:111], v[108:109]
	s_nop 0
	v_pk_mul_f32 v[106:107], v[106:107], v[108:109]
	s_nop 0
	v_cvt_pk_bf16_f32 v105, v106, v107
	v_lshl_add_u64 v[106:107], v[112:113], 0, s[18:19]
	global_store_dwordx2 v[106:107], v[104:105], off
	v_mul_f32_e32 v104, 0xbfb8aa3b, v100
	v_mul_f32_e32 v105, 0xbfb8aa3b, v101
	v_exp_f32_e32 v104, v104
	v_exp_f32_e32 v105, v105
	v_add_f32_e32 v104, 1.0, v104
	v_add_f32_e32 v105, 1.0, v105
	v_rcp_f32_e32 v104, v104
	v_rcp_f32_e32 v105, v105
	s_nop 0
	v_pk_mul_f32 v[100:101], v[100:101], v[104:105]
	s_nop 0
	v_pk_mul_f32 v[96:97], v[96:97], v[100:101]
	s_nop 0
	v_cvt_pk_bf16_f32 v96, v96, v97
	v_mul_f32_e32 v97, 0xbfb8aa3b, v102
	v_exp_f32_e32 v97, v97
	s_nop 0
	v_add_f32_e32 v97, 1.0, v97
	v_rcp_f32_e32 v100, v97
	v_mul_f32_e32 v97, 0xbfb8aa3b, v103
	v_exp_f32_e32 v97, v97
	s_nop 0
	v_add_f32_e32 v97, 1.0, v97
	v_rcp_f32_e32 v101, v97
	s_nop 0
	v_pk_mul_f32 v[100:101], v[102:103], v[100:101]
	s_nop 0
	v_pk_mul_f32 v[98:99], v[98:99], v[100:101]
	s_nop 0
	v_cvt_pk_bf16_f32 v97, v98, v99
	v_mul_f32_e32 v98, 0xbfb8aa3b, v92
	v_mul_f32_e32 v99, 0xbfb8aa3b, v93
	v_exp_f32_e32 v98, v98
	v_exp_f32_e32 v99, v99
	global_store_dwordx2 v[106:107], v[96:97], off offset:128
	v_or_b32_e32 v96, 32, v147
	v_add_f32_e32 v98, 1.0, v98
	v_add_f32_e32 v99, 1.0, v99
	v_rcp_f32_e32 v98, v98
	v_rcp_f32_e32 v99, v99
	v_mad_i64_i32 v[96:97], s[20:21], v96, s40, v[132:133]
	v_pk_mul_f32 v[92:93], v[92:93], v[98:99]
	s_nop 0
	v_pk_mul_f32 v[88:89], v[88:89], v[92:93]
	s_nop 0
	v_cvt_pk_bf16_f32 v88, v88, v89
	v_mul_f32_e32 v89, 0xbfb8aa3b, v94
	v_exp_f32_e32 v89, v89
	s_nop 0
	v_add_f32_e32 v89, 1.0, v89
	v_rcp_f32_e32 v92, v89
	v_mul_f32_e32 v89, 0xbfb8aa3b, v95
	v_exp_f32_e32 v89, v89
	s_nop 0
	v_add_f32_e32 v89, 1.0, v89
	v_rcp_f32_e32 v93, v89
	s_nop 0
	v_pk_mul_f32 v[92:93], v[94:95], v[92:93]
	s_nop 0
	v_pk_mul_f32 v[90:91], v[90:91], v[92:93]
	s_nop 0
	v_cvt_pk_bf16_f32 v89, v90, v91
	v_lshl_add_u64 v[90:91], v[96:97], 0, s[18:19]
	global_store_dwordx2 v[90:91], v[88:89], off
	v_mul_f32_e32 v88, 0xbfb8aa3b, v84
	v_mul_f32_e32 v89, 0xbfb8aa3b, v85
	v_exp_f32_e32 v88, v88
	v_exp_f32_e32 v89, v89
	v_add_f32_e32 v88, 1.0, v88
	v_add_f32_e32 v89, 1.0, v89
	v_rcp_f32_e32 v88, v88
	v_rcp_f32_e32 v89, v89
	s_nop 0
	v_pk_mul_f32 v[84:85], v[84:85], v[88:89]
	s_nop 0
	v_pk_mul_f32 v[80:81], v[80:81], v[84:85]
	s_nop 0
	v_cvt_pk_bf16_f32 v80, v80, v81
	v_mul_f32_e32 v81, 0xbfb8aa3b, v86
	v_exp_f32_e32 v81, v81
	s_nop 0
	v_add_f32_e32 v81, 1.0, v81
	v_rcp_f32_e32 v84, v81
	v_mul_f32_e32 v81, 0xbfb8aa3b, v87
	v_exp_f32_e32 v81, v81
	s_nop 0
	v_add_f32_e32 v81, 1.0, v81
	v_rcp_f32_e32 v85, v81
	s_nop 0
	v_pk_mul_f32 v[84:85], v[86:87], v[84:85]
	s_nop 0
	v_pk_mul_f32 v[82:83], v[82:83], v[84:85]
	s_nop 0
	v_cvt_pk_bf16_f32 v81, v82, v83
	v_mul_f32_e32 v82, 0xbfb8aa3b, v76
	v_mul_f32_e32 v83, 0xbfb8aa3b, v77
	v_exp_f32_e32 v82, v82
	v_exp_f32_e32 v83, v83
	global_store_dwordx2 v[90:91], v[80:81], off offset:128
	v_or_b32_e32 v80, 48, v147
	v_add_f32_e32 v82, 1.0, v82
	v_add_f32_e32 v83, 1.0, v83
	v_rcp_f32_e32 v82, v82
	v_rcp_f32_e32 v83, v83
	v_mad_i64_i32 v[80:81], s[20:21], v80, s40, v[132:133]
	v_pk_mul_f32 v[76:77], v[76:77], v[82:83]
	s_nop 0
	v_pk_mul_f32 v[72:73], v[72:73], v[76:77]
	s_nop 0
	v_cvt_pk_bf16_f32 v72, v72, v73
	v_mul_f32_e32 v73, 0xbfb8aa3b, v78
	v_exp_f32_e32 v73, v73
	s_nop 0
	v_add_f32_e32 v73, 1.0, v73
	v_rcp_f32_e32 v76, v73
	v_mul_f32_e32 v73, 0xbfb8aa3b, v79
	v_exp_f32_e32 v73, v73
	s_nop 0
	v_add_f32_e32 v73, 1.0, v73
	v_rcp_f32_e32 v77, v73
	s_nop 0
	v_pk_mul_f32 v[76:77], v[78:79], v[76:77]
	s_nop 0
	v_pk_mul_f32 v[74:75], v[74:75], v[76:77]
	s_nop 0
	v_cvt_pk_bf16_f32 v73, v74, v75
	v_lshl_add_u64 v[74:75], v[80:81], 0, s[18:19]
	global_store_dwordx2 v[74:75], v[72:73], off
	v_mul_f32_e32 v72, 0xbfb8aa3b, v68
	v_mul_f32_e32 v73, 0xbfb8aa3b, v69
	v_exp_f32_e32 v72, v72
	v_exp_f32_e32 v73, v73
	v_add_f32_e32 v72, 1.0, v72
	v_add_f32_e32 v73, 1.0, v73
	v_rcp_f32_e32 v72, v72
	v_rcp_f32_e32 v73, v73
	s_nop 0
	v_pk_mul_f32 v[68:69], v[68:69], v[72:73]
	s_nop 0
	v_pk_mul_f32 v[64:65], v[64:65], v[68:69]
	s_nop 0
	v_cvt_pk_bf16_f32 v64, v64, v65
	v_mul_f32_e32 v65, 0xbfb8aa3b, v70
	v_exp_f32_e32 v65, v65
	s_nop 0
	v_add_f32_e32 v65, 1.0, v65
	v_rcp_f32_e32 v68, v65
	v_mul_f32_e32 v65, 0xbfb8aa3b, v71
	v_exp_f32_e32 v65, v65
	s_nop 0
	v_add_f32_e32 v65, 1.0, v65
	v_rcp_f32_e32 v69, v65
	s_nop 0
	v_pk_mul_f32 v[68:69], v[70:71], v[68:69]
	s_nop 0
	v_pk_mul_f32 v[66:67], v[66:67], v[68:69]
	s_nop 0
	v_cvt_pk_bf16_f32 v65, v66, v67
	v_mul_f32_e32 v66, 0xbfb8aa3b, v60
	v_mul_f32_e32 v67, 0xbfb8aa3b, v61
	v_exp_f32_e32 v66, v66
	v_exp_f32_e32 v67, v67
	global_store_dwordx2 v[74:75], v[64:65], off offset:128
	v_add_u32_e32 v64, 0x80, v147
	v_add_f32_e32 v66, 1.0, v66
	v_add_f32_e32 v67, 1.0, v67
	v_rcp_f32_e32 v66, v66
	v_rcp_f32_e32 v67, v67
	v_mad_i64_i32 v[64:65], s[20:21], v64, s40, v[132:133]
	v_pk_mul_f32 v[60:61], v[60:61], v[66:67]
	s_nop 0
	v_pk_mul_f32 v[56:57], v[56:57], v[60:61]
	s_nop 0
	v_cvt_pk_bf16_f32 v56, v56, v57
	v_mul_f32_e32 v57, 0xbfb8aa3b, v62
	v_exp_f32_e32 v57, v57
	s_nop 0
	v_add_f32_e32 v57, 1.0, v57
	v_rcp_f32_e32 v60, v57
	v_mul_f32_e32 v57, 0xbfb8aa3b, v63
	v_exp_f32_e32 v57, v57
	s_nop 0
	v_add_f32_e32 v57, 1.0, v57
	v_rcp_f32_e32 v61, v57
	s_nop 0
	v_pk_mul_f32 v[60:61], v[62:63], v[60:61]
	s_nop 0
	v_pk_mul_f32 v[58:59], v[58:59], v[60:61]
	s_nop 0
	v_cvt_pk_bf16_f32 v57, v58, v59
	v_lshl_add_u64 v[58:59], v[64:65], 0, s[18:19]
	global_store_dwordx2 v[58:59], v[56:57], off
	v_mul_f32_e32 v56, 0xbfb8aa3b, v52
	v_mul_f32_e32 v57, 0xbfb8aa3b, v53
	v_exp_f32_e32 v56, v56
	v_exp_f32_e32 v57, v57
	v_add_f32_e32 v56, 1.0, v56
	v_add_f32_e32 v57, 1.0, v57
	v_rcp_f32_e32 v56, v56
	v_rcp_f32_e32 v57, v57
	s_nop 0
	v_pk_mul_f32 v[52:53], v[52:53], v[56:57]
	s_nop 0
	v_pk_mul_f32 v[48:49], v[48:49], v[52:53]
	s_nop 0
	v_cvt_pk_bf16_f32 v48, v48, v49
	v_mul_f32_e32 v49, 0xbfb8aa3b, v54
	v_exp_f32_e32 v49, v49
	s_nop 0
	v_add_f32_e32 v49, 1.0, v49
	v_rcp_f32_e32 v52, v49
	v_mul_f32_e32 v49, 0xbfb8aa3b, v55
	v_exp_f32_e32 v49, v49
	s_nop 0
	v_add_f32_e32 v49, 1.0, v49
	v_rcp_f32_e32 v53, v49
	s_nop 0
	v_pk_mul_f32 v[52:53], v[54:55], v[52:53]
	s_nop 0
	v_pk_mul_f32 v[50:51], v[50:51], v[52:53]
	s_nop 0
	v_cvt_pk_bf16_f32 v49, v50, v51
	v_mul_f32_e32 v50, 0xbfb8aa3b, v44
	v_mul_f32_e32 v51, 0xbfb8aa3b, v45
	v_exp_f32_e32 v50, v50
	v_exp_f32_e32 v51, v51
	global_store_dwordx2 v[58:59], v[48:49], off offset:128
	v_add_u32_e32 v48, 0x90, v147
	v_add_f32_e32 v50, 1.0, v50
	v_add_f32_e32 v51, 1.0, v51
	v_rcp_f32_e32 v50, v50
	v_rcp_f32_e32 v51, v51
	v_mad_i64_i32 v[48:49], s[20:21], v48, s40, v[132:133]
	v_pk_mul_f32 v[44:45], v[44:45], v[50:51]
	s_nop 0
	v_pk_mul_f32 v[40:41], v[40:41], v[44:45]
	s_nop 0
	v_cvt_pk_bf16_f32 v40, v40, v41
	v_mul_f32_e32 v41, 0xbfb8aa3b, v46
	v_exp_f32_e32 v41, v41
	s_nop 0
	v_add_f32_e32 v41, 1.0, v41
	v_rcp_f32_e32 v44, v41
	v_mul_f32_e32 v41, 0xbfb8aa3b, v47
	v_exp_f32_e32 v41, v41
	s_nop 0
	v_add_f32_e32 v41, 1.0, v41
	v_rcp_f32_e32 v45, v41
	s_nop 0
	v_pk_mul_f32 v[44:45], v[46:47], v[44:45]
	s_nop 0
	v_pk_mul_f32 v[42:43], v[42:43], v[44:45]
	s_nop 0
	v_cvt_pk_bf16_f32 v41, v42, v43
	v_lshl_add_u64 v[42:43], v[48:49], 0, s[18:19]
	global_store_dwordx2 v[42:43], v[40:41], off
	v_mul_f32_e32 v40, 0xbfb8aa3b, v36
	v_mul_f32_e32 v41, 0xbfb8aa3b, v37
	v_exp_f32_e32 v40, v40
	v_exp_f32_e32 v41, v41
	v_add_f32_e32 v40, 1.0, v40
	v_add_f32_e32 v41, 1.0, v41
	v_rcp_f32_e32 v40, v40
	v_rcp_f32_e32 v41, v41
	s_nop 0
	v_pk_mul_f32 v[36:37], v[36:37], v[40:41]
	s_nop 0
	v_pk_mul_f32 v[32:33], v[32:33], v[36:37]
	s_nop 0
	v_cvt_pk_bf16_f32 v32, v32, v33
	v_mul_f32_e32 v33, 0xbfb8aa3b, v38
	v_exp_f32_e32 v33, v33
	s_nop 0
	v_add_f32_e32 v33, 1.0, v33
	v_rcp_f32_e32 v36, v33
	v_mul_f32_e32 v33, 0xbfb8aa3b, v39
	v_exp_f32_e32 v33, v33
	s_nop 0
	v_add_f32_e32 v33, 1.0, v33
	v_rcp_f32_e32 v37, v33
	s_nop 0
	v_pk_mul_f32 v[36:37], v[38:39], v[36:37]
	s_nop 0
	v_pk_mul_f32 v[34:35], v[34:35], v[36:37]
	s_nop 0
	v_cvt_pk_bf16_f32 v33, v34, v35
	v_mul_f32_e32 v34, 0xbfb8aa3b, v28
	v_mul_f32_e32 v35, 0xbfb8aa3b, v29
	v_exp_f32_e32 v34, v34
	v_exp_f32_e32 v35, v35
	global_store_dwordx2 v[42:43], v[32:33], off offset:128
	v_add_u32_e32 v32, 0xa0, v147
	v_add_f32_e32 v34, 1.0, v34
	v_add_f32_e32 v35, 1.0, v35
	v_rcp_f32_e32 v34, v34
	v_rcp_f32_e32 v35, v35
	v_mad_i64_i32 v[32:33], s[20:21], v32, s40, v[132:133]
	v_pk_mul_f32 v[28:29], v[28:29], v[34:35]
	s_nop 0
	v_pk_mul_f32 v[24:25], v[24:25], v[28:29]
	s_nop 0
	v_cvt_pk_bf16_f32 v24, v24, v25
	v_mul_f32_e32 v25, 0xbfb8aa3b, v30
	v_exp_f32_e32 v25, v25
	s_nop 0
	v_add_f32_e32 v25, 1.0, v25
	v_rcp_f32_e32 v28, v25
	v_mul_f32_e32 v25, 0xbfb8aa3b, v31
	v_exp_f32_e32 v25, v25
	s_nop 0
	v_add_f32_e32 v25, 1.0, v25
	v_rcp_f32_e32 v29, v25
	s_nop 0
	v_pk_mul_f32 v[28:29], v[30:31], v[28:29]
	s_nop 0
	v_pk_mul_f32 v[26:27], v[26:27], v[28:29]
	s_nop 0
	v_cvt_pk_bf16_f32 v25, v26, v27
	v_lshl_add_u64 v[26:27], v[32:33], 0, s[18:19]
	global_store_dwordx2 v[26:27], v[24:25], off
	v_mul_f32_e32 v24, 0xbfb8aa3b, v20
	v_mul_f32_e32 v25, 0xbfb8aa3b, v21
	v_exp_f32_e32 v24, v24
	v_exp_f32_e32 v25, v25
	v_add_f32_e32 v24, 1.0, v24
	v_add_f32_e32 v25, 1.0, v25
	v_rcp_f32_e32 v24, v24
	v_rcp_f32_e32 v25, v25
	s_nop 0
	v_pk_mul_f32 v[20:21], v[20:21], v[24:25]
	s_nop 0
	v_pk_mul_f32 v[16:17], v[16:17], v[20:21]
	s_nop 0
	v_cvt_pk_bf16_f32 v16, v16, v17
	v_mul_f32_e32 v17, 0xbfb8aa3b, v22
	v_exp_f32_e32 v17, v17
	s_nop 0
	v_add_f32_e32 v17, 1.0, v17
	v_rcp_f32_e32 v20, v17
	v_mul_f32_e32 v17, 0xbfb8aa3b, v23
	v_exp_f32_e32 v17, v17
	s_nop 0
	v_add_f32_e32 v17, 1.0, v17
	v_rcp_f32_e32 v21, v17
	s_nop 0
	v_pk_mul_f32 v[20:21], v[22:23], v[20:21]
	s_nop 0
	v_pk_mul_f32 v[18:19], v[18:19], v[20:21]
	s_nop 0
	v_cvt_pk_bf16_f32 v17, v18, v19
	v_mul_f32_e32 v18, 0xbfb8aa3b, v12
	v_mul_f32_e32 v19, 0xbfb8aa3b, v13
	v_exp_f32_e32 v18, v18
	v_exp_f32_e32 v19, v19
	global_store_dwordx2 v[26:27], v[16:17], off offset:128
	v_add_u32_e32 v16, 0xb0, v147
	v_add_f32_e32 v18, 1.0, v18
	v_add_f32_e32 v19, 1.0, v19
	v_rcp_f32_e32 v18, v18
	v_rcp_f32_e32 v19, v19
	v_mad_i64_i32 v[16:17], s[20:21], v16, s40, v[132:133]
	s_mov_b64 s[20:21], s[14:15]
	v_pk_mul_f32 v[12:13], v[12:13], v[18:19]
	s_nop 0
	v_pk_mul_f32 v[8:9], v[8:9], v[12:13]
	s_nop 0
	v_cvt_pk_bf16_f32 v8, v8, v9
	v_mul_f32_e32 v9, 0xbfb8aa3b, v14
	v_exp_f32_e32 v9, v9
	s_nop 0
	v_add_f32_e32 v9, 1.0, v9
	v_rcp_f32_e32 v12, v9
	v_mul_f32_e32 v9, 0xbfb8aa3b, v15
	v_exp_f32_e32 v9, v9
	s_nop 0
	v_add_f32_e32 v9, 1.0, v9
	v_rcp_f32_e32 v13, v9
	s_nop 0
	v_pk_mul_f32 v[12:13], v[14:15], v[12:13]
	s_nop 0
	v_pk_mul_f32 v[10:11], v[10:11], v[12:13]
	s_nop 0
	v_cvt_pk_bf16_f32 v9, v10, v11
	v_lshl_add_u64 v[10:11], v[16:17], 0, s[18:19]
	global_store_dwordx2 v[10:11], v[8:9], off
	v_mul_f32_e32 v8, 0xbfb8aa3b, v4
	v_mul_f32_e32 v9, 0xbfb8aa3b, v5
	v_exp_f32_e32 v8, v8
	v_exp_f32_e32 v9, v9
	s_mov_b32 s19, s10
	s_mov_b32 s18, s12
	v_add_f32_e32 v8, 1.0, v8
	v_add_f32_e32 v9, 1.0, v9
	v_rcp_f32_e32 v8, v8
	v_rcp_f32_e32 v9, v9
	s_nop 0
	v_pk_mul_f32 v[4:5], v[4:5], v[8:9]
	s_nop 0
	v_pk_mul_f32 v[0:1], v[0:1], v[4:5]
	s_nop 0
	v_cvt_pk_bf16_f32 v0, v0, v1
	v_mul_f32_e32 v1, 0xbfb8aa3b, v6
	v_exp_f32_e32 v1, v1
	s_nop 0
	v_add_f32_e32 v1, 1.0, v1
	v_rcp_f32_e32 v4, v1
	v_mul_f32_e32 v1, 0xbfb8aa3b, v7
	v_exp_f32_e32 v1, v1
	s_nop 0
	v_add_f32_e32 v1, 1.0, v1
	v_rcp_f32_e32 v5, v1
	s_nop 0
	v_pk_mul_f32 v[4:5], v[6:7], v[4:5]
	s_nop 0
	v_pk_mul_f32 v[2:3], v[2:3], v[4:5]
	s_nop 0
	v_cvt_pk_bf16_f32 v1, v2, v3
	global_store_dwordx2 v[10:11], v[0:1], off offset:128
	s_cbranch_vccz .LBB0_603
	s_waitcnt vmcnt(0)
	s_cmpk_gt_u32 s1, 0xff
	s_cbranch_scc1 .LBB0_610
	s_barrier

.LBB0_682:
	ds_read_b128 v[128:131], v151
	ds_read_b128 v[144:147], v151 offset:1024
	ds_read_b128 v[154:157], v151 offset:2048
	ds_read_b128 v[158:161], v151 offset:3072
	s_add_u32 s16, s14, 0x100
	s_addc_u32 s17, s15, 0
	s_cmpk_eq_i32 s40, 0x54
	s_cselect_b32 s21, s9, s17
	s_cselect_b32 s20, s8, s16
	s_cselect_b32 s19, s11, s39
	s_cselect_b32 s18, s10, s38
	v_lshl_add_u64 v[194:195], s[14:15], 0, v[136:137]
	s_add_i32 m0, s4, 0xc000
	ds_read_b128 v[162:165], v152
	ds_read_b128 v[166:169], v152 offset:1024
	ds_read_b128 v[170:173], v152 offset:2048
	ds_read_b128 v[174:177], v152 offset:3072
	ds_read_b128 v[178:181], v152 offset:4096
	ds_read_b128 v[182:185], v152 offset:5120
	ds_read_b128 v[186:189], v152 offset:6144
	ds_read_b128 v[190:193], v152 offset:7168
	global_load_lds_dwordx4 v[194:195], off
	v_lshl_add_u64 v[194:195], s[14:15], 0, v[138:139]
	s_add_i32 m0, s4, 0xe000
	s_nop 0
	global_load_lds_dwordx4 v[194:195], off
	s_waitcnt lgkmcnt(8)
	s_barrier
	s_waitcnt lgkmcnt(0)
	s_waitcnt lgkmcnt(0)
	v_mfma_f32_16x16x32_bf16 v[124:127], v[128:131], v[162:165], v[124:127]
	v_mfma_f32_16x16x32_bf16 v[92:95], v[154:157], v[162:165], v[92:95]
	v_mfma_f32_16x16x32_bf16 v[120:123], v[128:131], v[170:173], v[120:123]
	v_mfma_f32_16x16x32_bf16 v[88:91], v[154:157], v[170:173], v[88:91]
	v_mfma_f32_16x16x32_bf16 v[116:119], v[128:131], v[178:181], v[116:119]
	v_mfma_f32_16x16x32_bf16 v[84:87], v[154:157], v[178:181], v[84:87]
	v_mfma_f32_16x16x32_bf16 v[112:115], v[128:131], v[186:189], v[112:115]
	v_mfma_f32_16x16x32_bf16 v[80:83], v[154:157], v[186:189], v[80:83]
	v_mfma_f32_16x16x32_bf16 v[124:127], v[144:147], v[166:169], v[124:127]
	v_mfma_f32_16x16x32_bf16 v[92:95], v[158:161], v[166:169], v[92:95]
	v_mfma_f32_16x16x32_bf16 v[120:123], v[144:147], v[174:177], v[120:123]
	v_mfma_f32_16x16x32_bf16 v[88:91], v[158:161], v[174:177], v[88:91]
	v_mfma_f32_16x16x32_bf16 v[116:119], v[144:147], v[182:185], v[116:119]
	v_mfma_f32_16x16x32_bf16 v[84:87], v[158:161], v[182:185], v[84:87]
	v_mfma_f32_16x16x32_bf16 v[112:115], v[144:147], v[190:193], v[112:115]
	v_mfma_f32_16x16x32_bf16 v[80:83], v[158:161], v[190:193], v[80:83]
	s_barrier
	s_add_i32 s14, s30, s3
	v_lshl_add_u64 v[210:211], s[18:19], 0, v[132:133]
	s_mov_b32 m0, s14
	ds_read_b128 v[194:197], v153
	ds_read_b128 v[198:201], v153 offset:1024
	ds_read_b128 v[202:205], v153 offset:2048
	ds_read_b128 v[206:209], v153 offset:3072
	global_load_lds_dwordx4 v[210:211], off
	v_lshl_add_u64 v[212:213], s[18:19], 0, v[134:135]
	s_add_i32 m0, s14, 0x2000
	s_nop 0
	global_load_lds_dwordx4 v[212:213], off
	s_barrier
	s_waitcnt lgkmcnt(0)
	s_waitcnt lgkmcnt(0)
	v_mfma_f32_16x16x32_bf16 v[76:79], v[194:197], v[162:165], v[76:79]
	v_mfma_f32_16x16x32_bf16 v[48:51], v[202:205], v[162:165], v[48:51]
	v_mfma_f32_16x16x32_bf16 v[68:71], v[194:197], v[170:173], v[68:71]
	v_mfma_f32_16x16x32_bf16 v[40:43], v[202:205], v[170:173], v[40:43]
	v_mfma_f32_16x16x32_bf16 v[60:63], v[194:197], v[178:181], v[60:63]
	v_mfma_f32_16x16x32_bf16 v[36:39], v[202:205], v[178:181], v[36:39]
	v_mfma_f32_16x16x32_bf16 v[52:55], v[194:197], v[186:189], v[52:55]
	v_mfma_f32_16x16x32_bf16 v[28:31], v[202:205], v[186:189], v[28:31]
	v_mfma_f32_16x16x32_bf16 v[76:79], v[198:201], v[166:169], v[76:79]
	v_mfma_f32_16x16x32_bf16 v[48:51], v[206:209], v[166:169], v[48:51]
	v_mfma_f32_16x16x32_bf16 v[68:71], v[198:201], v[174:177], v[68:71]
	v_mfma_f32_16x16x32_bf16 v[40:43], v[206:209], v[174:177], v[40:43]
	v_mfma_f32_16x16x32_bf16 v[60:63], v[198:201], v[182:185], v[60:63]
	v_mfma_f32_16x16x32_bf16 v[36:39], v[206:209], v[182:185], v[36:39]
	v_mfma_f32_16x16x32_bf16 v[52:55], v[198:201], v[190:193], v[52:55]
	v_mfma_f32_16x16x32_bf16 v[28:31], v[206:209], v[190:193], v[28:31]
	s_mov_b32 m0, s4
	v_lshl_add_u64 v[214:215], s[20:21], 0, v[132:133]
	s_barrier
	ds_read_b128 v[162:165], v152 offset:16384
	ds_read_b128 v[166:169], v152 offset:17408
	ds_read_b128 v[170:173], v152 offset:18432
	ds_read_b128 v[174:177], v152 offset:19456
	ds_read_b128 v[178:181], v152 offset:20480
	ds_read_b128 v[182:185], v152 offset:21504
	ds_read_b128 v[186:189], v152 offset:22528
	ds_read_b128 v[190:193], v152 offset:23552
	global_load_lds_dwordx4 v[214:215], off
	v_lshl_add_u64 v[216:217], s[20:21], 0, v[134:135]
	s_mov_b32 m0, s5
	s_nop 0
	global_load_lds_dwordx4 v[216:217], off
	s_barrier
	s_waitcnt lgkmcnt(0)
	s_waitcnt lgkmcnt(0)
	v_mfma_f32_16x16x32_bf16 v[108:111], v[128:131], v[162:165], v[108:111]
	v_mfma_f32_16x16x32_bf16 v[72:75], v[154:157], v[162:165], v[72:75]
	v_mfma_f32_16x16x32_bf16 v[104:107], v[128:131], v[170:173], v[104:107]
	v_mfma_f32_16x16x32_bf16 v[64:67], v[154:157], v[170:173], v[64:67]
	v_mfma_f32_16x16x32_bf16 v[100:103], v[128:131], v[178:181], v[100:103]
	v_mfma_f32_16x16x32_bf16 v[56:59], v[154:157], v[178:181], v[56:59]
	v_mfma_f32_16x16x32_bf16 v[96:99], v[128:131], v[186:189], v[96:99]
	v_mfma_f32_16x16x32_bf16 v[44:47], v[154:157], v[186:189], v[44:47]
	v_mfma_f32_16x16x32_bf16 v[108:111], v[144:147], v[166:169], v[108:111]
	v_mfma_f32_16x16x32_bf16 v[72:75], v[158:161], v[166:169], v[72:75]
	v_mfma_f32_16x16x32_bf16 v[104:107], v[144:147], v[174:177], v[104:107]
	v_mfma_f32_16x16x32_bf16 v[64:67], v[158:161], v[174:177], v[64:67]
	v_mfma_f32_16x16x32_bf16 v[100:103], v[144:147], v[182:185], v[100:103]
	v_mfma_f32_16x16x32_bf16 v[56:59], v[158:161], v[182:185], v[56:59]
	v_mfma_f32_16x16x32_bf16 v[96:99], v[144:147], v[190:193], v[96:99]
	v_mfma_f32_16x16x32_bf16 v[44:47], v[158:161], v[190:193], v[44:47]
	s_barrier
	s_add_u32 s14, s18, 0x160000
	s_addc_u32 s15, s19, 0
	s_add_i32 s41, s31, s3
	v_lshl_add_u64 v[128:129], s[14:15], 0, v[132:133]
	s_mov_b32 m0, s41
	s_nop 0
	global_load_lds_dwordx4 v[128:129], off
	v_lshl_add_u64 v[128:129], s[14:15], 0, v[134:135]
	s_add_i32 m0, s41, 0x2000
	s_nop 0
	global_load_lds_dwordx4 v[128:129], off
	s_waitcnt vmcnt(6)
	s_barrier
	v_mfma_f32_16x16x32_bf16 v[32:35], v[194:197], v[162:165], v[32:35]
	v_mfma_f32_16x16x32_bf16 v[12:15], v[202:205], v[162:165], v[12:15]
	v_mfma_f32_16x16x32_bf16 v[24:27], v[194:197], v[170:173], v[24:27]
	v_mfma_f32_16x16x32_bf16 v[8:11], v[202:205], v[170:173], v[8:11]
	v_mfma_f32_16x16x32_bf16 v[20:23], v[194:197], v[178:181], v[20:23]
	v_mfma_f32_16x16x32_bf16 v[4:7], v[202:205], v[178:181], v[4:7]
	v_mfma_f32_16x16x32_bf16 v[16:19], v[194:197], v[186:189], v[16:19]
	v_mfma_f32_16x16x32_bf16 v[0:3], v[202:205], v[186:189], v[0:3]
	v_mfma_f32_16x16x32_bf16 v[32:35], v[198:201], v[166:169], v[32:35]
	v_mfma_f32_16x16x32_bf16 v[12:15], v[206:209], v[166:169], v[12:15]
	v_mfma_f32_16x16x32_bf16 v[24:27], v[198:201], v[174:177], v[24:27]
	v_mfma_f32_16x16x32_bf16 v[8:11], v[206:209], v[174:177], v[8:11]
	v_mfma_f32_16x16x32_bf16 v[20:23], v[198:201], v[182:185], v[20:23]
	v_mfma_f32_16x16x32_bf16 v[4:7], v[206:209], v[182:185], v[4:7]
	v_mfma_f32_16x16x32_bf16 v[16:19], v[198:201], v[190:193], v[16:19]
	v_mfma_f32_16x16x32_bf16 v[0:3], v[206:209], v[190:193], v[0:3]
	s_add_i32 s41, 0, 0x18000
	v_add_u32_e32 v158, s41, v149
	s_barrier
	ds_read_b128 v[128:131], v158
	ds_read_b128 v[144:147], v158 offset:1024
	ds_read_b128 v[154:157], v158 offset:2048
	ds_read_b128 v[158:161], v158 offset:3072
	s_add_u32 s14, s20, 0x160000
	s_addc_u32 s15, s21, 0
	s_mov_b32 m0, s22
	v_lshl_add_u64 v[194:195], s[14:15], 0, v[132:133]
	ds_read_b128 v[162:165], v152 offset:32768
	ds_read_b128 v[166:169], v152 offset:33792
	ds_read_b128 v[170:173], v152 offset:34816
	ds_read_b128 v[174:177], v152 offset:35840
	ds_read_b128 v[178:181], v152 offset:36864
	ds_read_b128 v[182:185], v152 offset:37888
	ds_read_b128 v[186:189], v152 offset:38912
	ds_read_b128 v[190:193], v152 offset:39936
	global_load_lds_dwordx4 v[194:195], off
	v_lshl_add_u64 v[194:195], s[14:15], 0, v[134:135]
	s_mov_b32 m0, s23
	s_nop 0
	global_load_lds_dwordx4 v[194:195], off
	s_waitcnt lgkmcnt(8)
	s_barrier
	s_waitcnt lgkmcnt(0)
	s_waitcnt lgkmcnt(0)
	v_mfma_f32_16x16x32_bf16 v[124:127], v[128:131], v[162:165], v[124:127]
	v_mfma_f32_16x16x32_bf16 v[92:95], v[154:157], v[162:165], v[92:95]
	v_mfma_f32_16x16x32_bf16 v[120:123], v[128:131], v[170:173], v[120:123]
	v_mfma_f32_16x16x32_bf16 v[88:91], v[154:157], v[170:173], v[88:91]
	v_mfma_f32_16x16x32_bf16 v[116:119], v[128:131], v[178:181], v[116:119]
	v_mfma_f32_16x16x32_bf16 v[84:87], v[154:157], v[178:181], v[84:87]
	v_mfma_f32_16x16x32_bf16 v[112:115], v[128:131], v[186:189], v[112:115]
	v_mfma_f32_16x16x32_bf16 v[80:83], v[154:157], v[186:189], v[80:83]
	v_mfma_f32_16x16x32_bf16 v[124:127], v[144:147], v[166:169], v[124:127]
	v_mfma_f32_16x16x32_bf16 v[92:95], v[158:161], v[166:169], v[92:95]
	v_mfma_f32_16x16x32_bf16 v[120:123], v[144:147], v[174:177], v[120:123]
	v_mfma_f32_16x16x32_bf16 v[88:91], v[158:161], v[174:177], v[88:91]
	v_mfma_f32_16x16x32_bf16 v[116:119], v[144:147], v[182:185], v[116:119]
	v_mfma_f32_16x16x32_bf16 v[84:87], v[158:161], v[182:185], v[84:87]
	v_mfma_f32_16x16x32_bf16 v[112:115], v[144:147], v[190:193], v[112:115]
	v_mfma_f32_16x16x32_bf16 v[80:83], v[158:161], v[190:193], v[80:83]
	s_barrier
	s_add_i32 s20, 0, 0x1c000
	s_add_i32 s14, s41, s3
	v_add_u32_e32 v206, s20, v149
	v_lshl_add_u64 v[210:211], v[210:211], 0, s[12:13]
	s_mov_b32 m0, s14
	ds_read_b128 v[194:197], v206
	ds_read_b128 v[198:201], v206 offset:1024
	ds_read_b128 v[202:205], v206 offset:2048
	ds_read_b128 v[206:209], v206 offset:3072
	global_load_lds_dwordx4 v[210:211], off
	v_lshl_add_u64 v[210:211], v[212:213], 0, s[12:13]
	s_add_i32 m0, s14, 0x2000
	s_nop 0
	global_load_lds_dwordx4 v[210:211], off
	s_barrier
	s_waitcnt lgkmcnt(0)
	s_waitcnt lgkmcnt(0)
	v_mfma_f32_16x16x32_bf16 v[76:79], v[194:197], v[162:165], v[76:79]
	v_mfma_f32_16x16x32_bf16 v[48:51], v[202:205], v[162:165], v[48:51]
	v_mfma_f32_16x16x32_bf16 v[68:71], v[194:197], v[170:173], v[68:71]
	v_mfma_f32_16x16x32_bf16 v[40:43], v[202:205], v[170:173], v[40:43]
	v_mfma_f32_16x16x32_bf16 v[60:63], v[194:197], v[178:181], v[60:63]
	v_mfma_f32_16x16x32_bf16 v[36:39], v[202:205], v[178:181], v[36:39]
	v_mfma_f32_16x16x32_bf16 v[52:55], v[194:197], v[186:189], v[52:55]
	v_mfma_f32_16x16x32_bf16 v[28:31], v[202:205], v[186:189], v[28:31]
	v_mfma_f32_16x16x32_bf16 v[76:79], v[198:201], v[166:169], v[76:79]
	v_mfma_f32_16x16x32_bf16 v[48:51], v[206:209], v[166:169], v[48:51]
	v_mfma_f32_16x16x32_bf16 v[68:71], v[198:201], v[174:177], v[68:71]
	v_mfma_f32_16x16x32_bf16 v[40:43], v[206:209], v[174:177], v[40:43]
	v_mfma_f32_16x16x32_bf16 v[60:63], v[198:201], v[182:185], v[60:63]
	v_mfma_f32_16x16x32_bf16 v[36:39], v[206:209], v[182:185], v[36:39]
	v_mfma_f32_16x16x32_bf16 v[52:55], v[198:201], v[190:193], v[52:55]
	v_mfma_f32_16x16x32_bf16 v[28:31], v[206:209], v[190:193], v[28:31]
	s_mov_b32 m0, s25
	v_lshl_add_u64 v[210:211], v[214:215], 0, s[12:13]
	s_barrier
	ds_read_b128 v[162:165], v152 offset:49152
	ds_read_b128 v[166:169], v152 offset:50176
	ds_read_b128 v[170:173], v152 offset:51200
	ds_read_b128 v[174:177], v152 offset:52224
	ds_read_b128 v[178:181], v152 offset:53248
	ds_read_b128 v[182:185], v152 offset:54272
	ds_read_b128 v[186:189], v152 offset:55296
	ds_read_b128 v[190:193], v152 offset:56320
	global_load_lds_dwordx4 v[210:211], off
	v_lshl_add_u64 v[210:211], v[216:217], 0, s[12:13]
	s_mov_b32 m0, s26
	s_nop 0
	global_load_lds_dwordx4 v[210:211], off
	s_barrier
	s_waitcnt lgkmcnt(0)
	s_waitcnt lgkmcnt(0)
	v_mfma_f32_16x16x32_bf16 v[108:111], v[128:131], v[162:165], v[108:111]
	v_mfma_f32_16x16x32_bf16 v[72:75], v[154:157], v[162:165], v[72:75]
	v_mfma_f32_16x16x32_bf16 v[104:107], v[128:131], v[170:173], v[104:107]
	v_mfma_f32_16x16x32_bf16 v[64:67], v[154:157], v[170:173], v[64:67]
	v_mfma_f32_16x16x32_bf16 v[100:103], v[128:131], v[178:181], v[100:103]
	v_mfma_f32_16x16x32_bf16 v[56:59], v[154:157], v[178:181], v[56:59]
	v_mfma_f32_16x16x32_bf16 v[96:99], v[128:131], v[186:189], v[96:99]
	v_mfma_f32_16x16x32_bf16 v[44:47], v[154:157], v[186:189], v[44:47]
	v_mfma_f32_16x16x32_bf16 v[108:111], v[144:147], v[166:169], v[108:111]
	v_mfma_f32_16x16x32_bf16 v[72:75], v[158:161], v[166:169], v[72:75]
	v_mfma_f32_16x16x32_bf16 v[104:107], v[144:147], v[174:177], v[104:107]
	v_mfma_f32_16x16x32_bf16 v[64:67], v[158:161], v[174:177], v[64:67]
	v_mfma_f32_16x16x32_bf16 v[100:103], v[144:147], v[182:185], v[100:103]
	v_mfma_f32_16x16x32_bf16 v[56:59], v[158:161], v[182:185], v[56:59]
	v_mfma_f32_16x16x32_bf16 v[96:99], v[144:147], v[190:193], v[96:99]
	v_mfma_f32_16x16x32_bf16 v[44:47], v[158:161], v[190:193], v[44:47]
	s_barrier
	s_add_u32 s14, s18, 0x160080
	s_addc_u32 s15, s19, 0
	s_add_i32 s18, s20, s3
	v_lshl_add_u64 v[128:129], s[14:15], 0, v[132:133]
	s_mov_b32 m0, s18
	s_nop 0
	global_load_lds_dwordx4 v[128:129], off
	v_lshl_add_u64 v[128:129], s[14:15], 0, v[134:135]
	s_add_i32 m0, s18, 0x2000
	s_nop 0
	global_load_lds_dwordx4 v[128:129], off
	s_waitcnt vmcnt(6)
	s_barrier
	v_mfma_f32_16x16x32_bf16 v[32:35], v[194:197], v[162:165], v[32:35]
	v_mfma_f32_16x16x32_bf16 v[12:15], v[202:205], v[162:165], v[12:15]
	v_mfma_f32_16x16x32_bf16 v[24:27], v[194:197], v[170:173], v[24:27]
	v_mfma_f32_16x16x32_bf16 v[8:11], v[202:205], v[170:173], v[8:11]
	v_mfma_f32_16x16x32_bf16 v[20:23], v[194:197], v[178:181], v[20:23]
	v_mfma_f32_16x16x32_bf16 v[4:7], v[202:205], v[178:181], v[4:7]
	v_mfma_f32_16x16x32_bf16 v[16:19], v[194:197], v[186:189], v[16:19]
	v_mfma_f32_16x16x32_bf16 v[0:3], v[202:205], v[186:189], v[0:3]
	v_mfma_f32_16x16x32_bf16 v[32:35], v[198:201], v[166:169], v[32:35]
	v_mfma_f32_16x16x32_bf16 v[12:15], v[206:209], v[166:169], v[12:15]
	v_mfma_f32_16x16x32_bf16 v[24:27], v[198:201], v[174:177], v[24:27]
	v_mfma_f32_16x16x32_bf16 v[8:11], v[206:209], v[174:177], v[8:11]
	v_mfma_f32_16x16x32_bf16 v[20:23], v[198:201], v[182:185], v[20:23]
	v_mfma_f32_16x16x32_bf16 v[4:7], v[206:209], v[182:185], v[4:7]
	v_mfma_f32_16x16x32_bf16 v[16:19], v[198:201], v[190:193], v[16:19]
	v_mfma_f32_16x16x32_bf16 v[0:3], v[206:209], v[190:193], v[0:3]
	s_add_i32 s40, s40, 2
	s_add_u32 s38, s38, 0x100
	s_addc_u32 s39, s39, 0
	s_cmpk_gt_u32 s40, 0x55
	s_mov_b64 s[14:15], s[16:17]
	s_barrier
	s_cbranch_scc0 .LBB0_682
	s_cmp_lt_u32 s36, 32
	s_movk_i32 s14, 0x3000
	s_cselect_b32 s14, s14, 0x6000
	s_cmp_gt_i32 s36, 15
	v_lshl_add_u32 v158, s36, 8, v148
	s_cselect_b32 s14, s14, 0
	v_lshl_or_b32 v128, s37, 8, v150
	s_lshl_b32 s14, s14, 2
	v_ashrrev_i32_e32 v159, 31, v158
	s_add_u32 s14, s28, s14
	v_ashrrev_i32_e32 v129, 31, v128
	v_lshlrev_b64 v[146:147], 13, v[158:159]
	s_addc_u32 s15, s29, 0
	v_lshlrev_b64 v[160:161], 2, v[128:129]
	v_lshl_add_u64 v[146:147], s[56:57], 0, v[146:147]
	v_lshl_add_u64 v[144:145], s[14:15], 0, v[160:161]
	v_lshl_add_u64 v[146:147], v[146:147], 0, v[160:161]
	s_mov_b64 s[14:15], 0x100000
	s_mov_b32 s37, s34
	s_mov_b32 s36, s35
	s_mov_b64 s[16:17], s[10:11]
	v_or_b32_e32 v162, 16, v158
	v_ashrrev_i32_e32 v163, 31, v162
	v_lshlrev_b64 v[164:165], 13, v[162:163]
	v_lshl_add_u64 v[162:163], s[56:57], 0, v[164:165]
	v_lshl_add_u64 v[164:165], v[162:163], 0, v[160:161]
	v_or_b32_e32 v162, 32, v158
	v_ashrrev_i32_e32 v163, 31, v162
	v_lshlrev_b64 v[166:167], 13, v[162:163]
	v_lshl_add_u64 v[162:163], s[56:57], 0, v[166:167]
	v_lshl_add_u64 v[166:167], v[162:163], 0, v[160:161]
	v_or_b32_e32 v162, 48, v158
	v_ashrrev_i32_e32 v163, 31, v162
	v_lshlrev_b64 v[168:169], 13, v[162:163]
	v_lshl_add_u64 v[162:163], s[56:57], 0, v[168:169]
	v_lshl_add_u64 v[168:169], v[162:163], 0, v[160:161]
	v_lshl_add_u64 v[162:163], v[146:147], 0, s[14:15]
	s_mov_b32 s14, 0x100000
	v_add_co_u32_e32 v170, vcc, s14, v146
	s_mov_b64 s[14:15], 0x120000
	s_nop 0
	v_addc_co_u32_e32 v171, vcc, 0, v147, vcc
	v_lshl_add_u64 v[172:173], v[146:147], 0, s[14:15]
	s_mov_b32 s14, 0x120000
	v_add_co_u32_e32 v174, vcc, s14, v146
	s_mov_b64 s[14:15], 0x140000
	s_nop 0
	v_addc_co_u32_e32 v175, vcc, 0, v147, vcc
	v_lshl_add_u64 v[176:177], v[146:147], 0, s[14:15]
	s_mov_b32 s14, 0x140000
	v_add_co_u32_e32 v178, vcc, s14, v146
	s_mov_b64 s[14:15], 0x160000
	s_nop 0
	v_addc_co_u32_e32 v179, vcc, 0, v147, vcc
	v_lshl_add_u64 v[180:181], v[146:147], 0, s[14:15]
	s_mov_b32 s14, 0x160000
	v_add_co_u32_e32 v182, vcc, s14, v146
	s_mov_b64 s[14:15], s[8:9]
	s_nop 0
	v_addc_co_u32_e32 v183, vcc, 0, v147, vcc
	s_and_b64 vcc, exec, s[6:7]
	global_load_dwordx4 v[184:187], v[144:145], off
	global_load_dwordx4 v[188:191], v[146:147], off
	v_pk_add_f32 v[126:127], v[126:127], 0 op_sel_hi:[1,0]
	v_pk_add_f32 v[124:125], v[124:125], 0 op_sel_hi:[1,0]
	v_pk_add_f32 v[122:123], v[122:123], 0 op_sel_hi:[1,0]
	v_pk_add_f32 v[120:121], v[120:121], 0 op_sel_hi:[1,0]
	v_pk_add_f32 v[118:119], v[118:119], 0 op_sel_hi:[1,0]
	v_pk_add_f32 v[116:117], v[116:117], 0 op_sel_hi:[1,0]
	v_pk_add_f32 v[114:115], v[114:115], 0 op_sel_hi:[1,0]
	v_pk_add_f32 v[112:113], v[112:113], 0 op_sel_hi:[1,0]
	v_pk_add_f32 v[110:111], v[110:111], 0 op_sel_hi:[1,0]
	v_pk_add_f32 v[108:109], v[108:109], 0 op_sel_hi:[1,0]
	v_pk_add_f32 v[106:107], v[106:107], 0 op_sel_hi:[1,0]
	v_pk_add_f32 v[104:105], v[104:105], 0 op_sel_hi:[1,0]
	v_pk_add_f32 v[102:103], v[102:103], 0 op_sel_hi:[1,0]
	v_pk_add_f32 v[100:101], v[100:101], 0 op_sel_hi:[1,0]
	v_pk_add_f32 v[98:99], v[98:99], 0 op_sel_hi:[1,0]
	v_pk_add_f32 v[96:97], v[96:97], 0 op_sel_hi:[1,0]
	v_pk_add_f32 v[94:95], v[94:95], 0 op_sel_hi:[1,0]
	v_pk_add_f32 v[92:93], v[92:93], 0 op_sel_hi:[1,0]
	v_pk_add_f32 v[90:91], v[90:91], 0 op_sel_hi:[1,0]
	v_pk_add_f32 v[88:89], v[88:89], 0 op_sel_hi:[1,0]
	v_pk_add_f32 v[86:87], v[86:87], 0 op_sel_hi:[1,0]
	v_pk_add_f32 v[84:85], v[84:85], 0 op_sel_hi:[1,0]
	v_pk_add_f32 v[82:83], v[82:83], 0 op_sel_hi:[1,0]
	v_pk_add_f32 v[80:81], v[80:81], 0 op_sel_hi:[1,0]
	v_pk_add_f32 v[74:75], v[74:75], 0 op_sel_hi:[1,0]
	v_pk_add_f32 v[72:73], v[72:73], 0 op_sel_hi:[1,0]
	v_pk_add_f32 v[66:67], v[66:67], 0 op_sel_hi:[1,0]
	v_pk_add_f32 v[64:65], v[64:65], 0 op_sel_hi:[1,0]
	v_pk_add_f32 v[58:59], v[58:59], 0 op_sel_hi:[1,0]
	v_pk_add_f32 v[56:57], v[56:57], 0 op_sel_hi:[1,0]
	v_pk_add_f32 v[46:47], v[46:47], 0 op_sel_hi:[1,0]
	v_pk_add_f32 v[44:45], v[44:45], 0 op_sel_hi:[1,0]
	v_pk_add_f32 v[62:63], v[62:63], 0 op_sel_hi:[1,0]
	v_pk_add_f32 v[60:61], v[60:61], 0 op_sel_hi:[1,0]
	v_pk_add_f32 v[54:55], v[54:55], 0 op_sel_hi:[1,0]
	v_pk_add_f32 v[52:53], v[52:53], 0 op_sel_hi:[1,0]
	v_pk_add_f32 v[34:35], v[34:35], 0 op_sel_hi:[1,0]
	v_pk_add_f32 v[32:33], v[32:33], 0 op_sel_hi:[1,0]
	v_pk_add_f32 v[26:27], v[26:27], 0 op_sel_hi:[1,0]
	v_pk_add_f32 v[24:25], v[24:25], 0 op_sel_hi:[1,0]
	v_pk_add_f32 v[22:23], v[22:23], 0 op_sel_hi:[1,0]
	v_pk_add_f32 v[20:21], v[20:21], 0 op_sel_hi:[1,0]
	v_pk_add_f32 v[18:19], v[18:19], 0 op_sel_hi:[1,0]
	v_pk_add_f32 v[16:17], v[16:17], 0 op_sel_hi:[1,0]
	v_pk_add_f32 v[14:15], v[14:15], 0 op_sel_hi:[1,0]
	v_pk_add_f32 v[12:13], v[12:13], 0 op_sel_hi:[1,0]
	v_pk_add_f32 v[10:11], v[10:11], 0 op_sel_hi:[1,0]
	v_pk_add_f32 v[8:9], v[8:9], 0 op_sel_hi:[1,0]
	v_pk_add_f32 v[6:7], v[6:7], 0 op_sel_hi:[1,0]
	v_pk_add_f32 v[4:5], v[4:5], 0 op_sel_hi:[1,0]
	v_pk_add_f32 v[2:3], v[2:3], 0 op_sel_hi:[1,0]
	v_pk_add_f32 v[0:1], v[0:1], 0 op_sel_hi:[1,0]
	s_waitcnt vmcnt(0)
	v_pk_fma_f32 v[126:127], v[126:127], v[186:187], v[190:191]
	v_pk_fma_f32 v[124:125], v[124:125], v[184:185], v[188:189]
	global_store_dwordx4 v[146:147], v[124:127], off
	global_load_dwordx4 v[188:191], v[164:165], off
	global_load_dwordx4 v[192:195], v[166:167], off
	global_load_dwordx4 v[196:199], v[168:169], off
	global_load_dwordx4 v[200:203], v[170:171], off
	global_load_dwordx4 v[204:207], v[174:175], off
	global_load_dwordx4 v[208:211], v[178:179], off
	global_load_dwordx4 v[212:215], v[182:183], off
	global_load_dwordx4 v[216:219], v[144:145], off offset:64
	global_load_dwordx4 v[220:223], v[146:147], off offset:64
	global_load_dwordx4 v[224:227], v[164:165], off offset:64
	global_load_dwordx4 v[228:231], v[166:167], off offset:64
	global_load_dwordx4 v[232:235], v[168:169], off offset:64
	s_waitcnt vmcnt(11)
	v_pk_fma_f32 v[122:123], v[122:123], v[186:187], v[190:191]
	v_pk_fma_f32 v[120:121], v[120:121], v[184:185], v[188:189]
	global_store_dwordx4 v[164:165], v[120:123], off
	global_load_dwordx4 v[188:191], v[162:163], off offset:64
	s_waitcnt vmcnt(12)
	v_pk_fma_f32 v[118:119], v[118:119], v[186:187], v[194:195]
	v_pk_fma_f32 v[116:117], v[116:117], v[184:185], v[192:193]
	global_store_dwordx4 v[166:167], v[116:119], off
	global_load_dwordx4 v[192:195], v[172:173], off offset:64
	s_waitcnt vmcnt(13)
	v_pk_fma_f32 v[114:115], v[114:115], v[186:187], v[198:199]
	v_pk_fma_f32 v[112:113], v[112:113], v[184:185], v[196:197]
	global_store_dwordx4 v[168:169], v[112:115], off
	global_load_dwordx4 v[196:199], v[176:177], off offset:64
	s_waitcnt vmcnt(14)
	v_pk_fma_f32 v[110:111], v[110:111], v[186:187], v[202:203]
	v_pk_fma_f32 v[108:109], v[108:109], v[184:185], v[200:201]
	global_store_dwordx4 v[170:171], v[108:111], off
	global_load_dwordx4 v[200:203], v[180:181], off offset:64
	s_waitcnt vmcnt(15)
	v_pk_fma_f32 v[106:107], v[106:107], v[186:187], v[206:207]
	v_pk_fma_f32 v[104:105], v[104:105], v[184:185], v[204:205]
	global_store_dwordx4 v[174:175], v[104:107], off
	global_load_dwordx4 v[204:207], v[144:145], off offset:512
	s_waitcnt vmcnt(16)
	v_pk_fma_f32 v[102:103], v[102:103], v[186:187], v[210:211]
	v_pk_fma_f32 v[100:101], v[100:101], v[184:185], v[208:209]
	global_store_dwordx4 v[178:179], v[100:103], off
	global_load_dwordx4 v[208:211], v[146:147], off offset:512
	s_waitcnt vmcnt(17)
	v_pk_fma_f32 v[98:99], v[98:99], v[186:187], v[214:215]
	v_pk_fma_f32 v[96:97], v[96:97], v[184:185], v[212:213]
	global_store_dwordx4 v[182:183], v[96:99], off
	global_load_dwordx4 v[184:187], v[164:165], off offset:512
	s_waitcnt vmcnt(17)
	v_pk_fma_f32 v[94:95], v[94:95], v[218:219], v[222:223]
	v_pk_fma_f32 v[92:93], v[92:93], v[216:217], v[220:221]
	global_store_dwordx4 v[146:147], v[92:95], off offset:64
	global_load_dwordx4 v[212:215], v[166:167], off offset:512
	global_load_dwordx4 v[220:223], v[168:169], off offset:512
	s_waitcnt vmcnt(19)
	v_pk_fma_f32 v[90:91], v[90:91], v[218:219], v[226:227]
	v_pk_fma_f32 v[88:89], v[88:89], v[216:217], v[224:225]
	global_store_dwordx4 v[164:165], v[88:91], off offset:64
	global_load_dwordx4 v[224:227], v[162:163], off offset:512
	s_waitcnt vmcnt(20)
	v_pk_fma_f32 v[86:87], v[86:87], v[218:219], v[230:231]
	v_pk_fma_f32 v[84:85], v[84:85], v[216:217], v[228:229]
	global_store_dwordx4 v[166:167], v[84:87], off offset:64
	global_load_dwordx4 v[228:231], v[172:173], off offset:512
	s_waitcnt vmcnt(21)
	v_pk_fma_f32 v[82:83], v[82:83], v[218:219], v[234:235]
	v_pk_fma_f32 v[80:81], v[80:81], v[216:217], v[232:233]
	global_store_dwordx4 v[168:169], v[80:83], off offset:64
	global_load_dwordx4 v[232:235], v[176:177], off offset:512
	s_waitcnt vmcnt(21)
	v_pk_fma_f32 v[74:75], v[74:75], v[218:219], v[190:191]
	v_pk_fma_f32 v[72:73], v[72:73], v[216:217], v[188:189]
	global_store_dwordx4 v[162:163], v[72:75], off offset:64
	global_load_dwordx4 v[188:191], v[180:181], off offset:512
	s_waitcnt vmcnt(21)
	v_pk_fma_f32 v[66:67], v[66:67], v[218:219], v[194:195]
	v_pk_fma_f32 v[64:65], v[64:65], v[216:217], v[192:193]
	global_store_dwordx4 v[172:173], v[64:67], off offset:64
	global_load_dwordx4 v[192:195], v[144:145], off offset:576
	s_waitcnt vmcnt(21)
	v_pk_fma_f32 v[58:59], v[58:59], v[218:219], v[198:199]
	v_pk_fma_f32 v[56:57], v[56:57], v[216:217], v[196:197]
	global_store_dwordx4 v[176:177], v[56:59], off offset:64
	global_load_dwordx4 v[196:199], v[146:147], off offset:576
	v_pk_add_f32 v[64:65], v[78:79], 0 op_sel_hi:[1,0]
	v_pk_add_f32 v[66:67], v[76:77], 0 op_sel_hi:[1,0]
	s_waitcnt vmcnt(21)
	v_pk_fma_f32 v[46:47], v[46:47], v[218:219], v[202:203]
	v_pk_fma_f32 v[44:45], v[44:45], v[216:217], v[200:201]
	global_store_dwordx4 v[180:181], v[44:47], off offset:64
	global_load_dwordx4 v[200:203], v[164:165], off offset:576
	s_waitcnt vmcnt(19)
	v_pk_fma_f32 v[58:59], v[64:65], v[206:207], v[210:211]
	v_pk_fma_f32 v[56:57], v[66:67], v[204:205], v[208:209]
	global_store_dwordx4 v[146:147], v[56:59], off offset:512
	global_load_dwordx4 v[208:211], v[166:167], off offset:576
	global_load_dwordx4 v[216:219], v[168:169], off offset:576
	v_pk_add_f32 v[64:65], v[70:71], 0 op_sel_hi:[1,0]
	v_pk_add_f32 v[66:67], v[68:69], 0 op_sel_hi:[1,0]
	s_waitcnt vmcnt(20)
	v_pk_fma_f32 v[58:59], v[64:65], v[206:207], v[186:187]
	v_pk_fma_f32 v[56:57], v[66:67], v[204:205], v[184:185]
	global_store_dwordx4 v[164:165], v[56:59], off offset:512
	global_load_dwordx4 v[184:187], v[162:163], off offset:576
	s_waitcnt vmcnt(20)
	v_pk_fma_f32 v[58:59], v[62:63], v[206:207], v[214:215]
	v_pk_fma_f32 v[56:57], v[60:61], v[204:205], v[212:213]
	global_store_dwordx4 v[166:167], v[56:59], off offset:512
	global_load_dwordx4 v[212:215], v[172:173], off offset:576
	s_waitcnt vmcnt(21)
	v_pk_fma_f32 v[54:55], v[54:55], v[206:207], v[222:223]
	v_pk_fma_f32 v[52:53], v[52:53], v[204:205], v[220:221]
	global_store_dwordx4 v[168:169], v[52:55], off offset:512
	global_load_dwordx4 v[220:223], v[176:177], off offset:576
	s_waitcnt vmcnt(21)
	v_pk_fma_f32 v[34:35], v[34:35], v[206:207], v[226:227]
	v_pk_fma_f32 v[32:33], v[32:33], v[204:205], v[224:225]
	global_store_dwordx4 v[162:163], v[32:35], off offset:512
	global_load_dwordx4 v[224:227], v[180:181], off offset:576
	s_waitcnt vmcnt(21)
	v_pk_fma_f32 v[26:27], v[26:27], v[206:207], v[230:231]
	v_pk_fma_f32 v[24:25], v[24:25], v[204:205], v[228:229]
	global_store_dwordx4 v[172:173], v[24:27], off offset:512
	s_waitcnt vmcnt(20)
	v_pk_fma_f32 v[22:23], v[22:23], v[206:207], v[234:235]
	v_pk_fma_f32 v[20:21], v[20:21], v[204:205], v[232:233]
	global_store_dwordx4 v[176:177], v[20:23], off offset:512
	v_pk_add_f32 v[24:25], v[50:51], 0 op_sel_hi:[1,0]
	v_pk_add_f32 v[26:27], v[48:49], 0 op_sel_hi:[1,0]
	s_waitcnt vmcnt(19)
	v_pk_fma_f32 v[18:19], v[18:19], v[206:207], v[190:191]
	v_pk_fma_f32 v[16:17], v[16:17], v[204:205], v[188:189]
	global_store_dwordx4 v[180:181], v[16:19], off offset:512
	s_waitcnt vmcnt(16)
	v_pk_fma_f32 v[22:23], v[24:25], v[194:195], v[198:199]
	v_pk_fma_f32 v[20:21], v[26:27], v[192:193], v[196:197]
	global_store_dwordx4 v[146:147], v[20:23], off offset:576
	v_pk_add_f32 v[24:25], v[42:43], 0 op_sel_hi:[1,0]
	v_pk_add_f32 v[26:27], v[40:41], 0 op_sel_hi:[1,0]
	s_waitcnt vmcnt(15)
	v_pk_fma_f32 v[22:23], v[24:25], v[194:195], v[202:203]
	v_pk_fma_f32 v[20:21], v[26:27], v[192:193], v[200:201]
	global_store_dwordx4 v[164:165], v[20:23], off offset:576
	v_pk_add_f32 v[24:25], v[38:39], 0 op_sel_hi:[1,0]
	v_pk_add_f32 v[26:27], v[36:37], 0 op_sel_hi:[1,0]
	s_waitcnt vmcnt(14)
	v_pk_fma_f32 v[22:23], v[24:25], v[194:195], v[210:211]
	v_pk_fma_f32 v[20:21], v[26:27], v[192:193], v[208:209]
	global_store_dwordx4 v[166:167], v[20:23], off offset:576
	v_pk_add_f32 v[24:25], v[30:31], 0 op_sel_hi:[1,0]
	v_pk_add_f32 v[26:27], v[28:29], 0 op_sel_hi:[1,0]
	s_waitcnt vmcnt(14)
	v_pk_fma_f32 v[22:23], v[24:25], v[194:195], v[218:219]
	v_pk_fma_f32 v[20:21], v[26:27], v[192:193], v[216:217]
	global_store_dwordx4 v[168:169], v[20:23], off offset:576
	s_waitcnt vmcnt(13)
	v_pk_fma_f32 v[14:15], v[14:15], v[194:195], v[186:187]
	v_pk_fma_f32 v[12:13], v[12:13], v[192:193], v[184:185]
	global_store_dwordx4 v[162:163], v[12:15], off offset:576
	s_waitcnt vmcnt(12)
	v_pk_fma_f32 v[10:11], v[10:11], v[194:195], v[214:215]
	v_pk_fma_f32 v[8:9], v[8:9], v[192:193], v[212:213]
	global_store_dwordx4 v[172:173], v[8:11], off offset:576
	s_waitcnt vmcnt(11)
	v_pk_fma_f32 v[6:7], v[6:7], v[194:195], v[222:223]
	v_pk_fma_f32 v[4:5], v[4:5], v[192:193], v[220:221]
	global_store_dwordx4 v[176:177], v[4:7], off offset:576
	s_waitcnt vmcnt(10)
	v_pk_fma_f32 v[2:3], v[2:3], v[194:195], v[226:227]
	v_pk_fma_f32 v[0:1], v[0:1], v[192:193], v[224:225]
	global_store_dwordx4 v[180:181], v[0:3], off offset:576
	s_cbranch_vccz .LBB0_671
	s_waitcnt vmcnt(0)
	s_cmpk_gt_u32 s1, 0xff
	s_cbranch_scc1 .LBB0_686
	s_barrier

.LBB0_698:
	ds_read_b128 v[144:147], v139
	ds_read_b128 v[148:151], v139 offset:1024
	ds_read_b128 v[152:155], v139 offset:2048
	ds_read_b128 v[156:159], v139 offset:3072
	s_add_u32 s16, s14, 0x100
	s_addc_u32 s17, s15, 0
	s_cmp_eq_u32 s43, 4
	s_cselect_b32 s21, s13, s17
	s_cselect_b32 s20, s12, s16
	s_cselect_b32 s19, s7, s42
	s_cselect_b32 s18, s6, s41
	s_mov_b32 m0, s29
	v_lshl_add_u64 v[192:193], s[14:15], 0, v[132:133]
	ds_read_b128 v[160:163], v140
	ds_read_b128 v[164:167], v140 offset:1024
	ds_read_b128 v[168:171], v140 offset:2048
	ds_read_b128 v[172:175], v140 offset:3072
	ds_read_b128 v[176:179], v140 offset:4096
	ds_read_b128 v[180:183], v140 offset:5120
	ds_read_b128 v[184:187], v140 offset:6144
	ds_read_b128 v[188:191], v140 offset:7168
	global_load_lds_dwordx4 v[192:193], off
	v_lshl_add_u64 v[192:193], s[14:15], 0, v[134:135]
	s_mov_b32 m0, s30
	s_nop 0
	global_load_lds_dwordx4 v[192:193], off
	s_waitcnt lgkmcnt(8)
	s_barrier
	s_waitcnt lgkmcnt(0)
	s_waitcnt lgkmcnt(0)
	v_mfma_f32_16x16x32_bf16 v[124:127], v[144:147], v[160:163], v[124:127]
	v_mfma_f32_16x16x32_bf16 v[120:123], v[152:155], v[160:163], v[120:123]
	v_mfma_f32_16x16x32_bf16 v[116:119], v[144:147], v[168:171], v[116:119]
	v_mfma_f32_16x16x32_bf16 v[112:115], v[152:155], v[168:171], v[112:115]
	v_mfma_f32_16x16x32_bf16 v[100:103], v[144:147], v[176:179], v[100:103]
	v_mfma_f32_16x16x32_bf16 v[96:99], v[152:155], v[176:179], v[96:99]
	v_mfma_f32_16x16x32_bf16 v[84:87], v[144:147], v[184:187], v[84:87]
	v_mfma_f32_16x16x32_bf16 v[80:83], v[152:155], v[184:187], v[80:83]
	v_mfma_f32_16x16x32_bf16 v[124:127], v[148:151], v[164:167], v[124:127]
	v_mfma_f32_16x16x32_bf16 v[120:123], v[156:159], v[164:167], v[120:123]
	v_mfma_f32_16x16x32_bf16 v[116:119], v[148:151], v[172:175], v[116:119]
	v_mfma_f32_16x16x32_bf16 v[112:115], v[156:159], v[172:175], v[112:115]
	v_mfma_f32_16x16x32_bf16 v[100:103], v[148:151], v[180:183], v[100:103]
	v_mfma_f32_16x16x32_bf16 v[96:99], v[156:159], v[180:183], v[96:99]
	v_mfma_f32_16x16x32_bf16 v[84:87], v[148:151], v[188:191], v[84:87]
	v_mfma_f32_16x16x32_bf16 v[80:83], v[156:159], v[188:191], v[80:83]
	s_barrier
	s_mov_b32 m0, s31
	v_lshl_add_u64 v[208:209], s[18:19], 0, v[130:131]
	ds_read_b128 v[192:195], v141
	ds_read_b128 v[196:199], v141 offset:1024
	ds_read_b128 v[200:203], v141 offset:2048
	ds_read_b128 v[204:207], v141 offset:3072
	global_load_lds_dwordx4 v[208:209], off
	v_lshl_add_u64 v[210:211], s[18:19], 0, v[128:129]
	s_mov_b32 m0, s34
	s_nop 0
	global_load_lds_dwordx4 v[210:211], off
	s_barrier
	s_waitcnt lgkmcnt(0)
	s_waitcnt lgkmcnt(0)
	v_mfma_f32_16x16x32_bf16 v[108:111], v[192:195], v[160:163], v[108:111]
	v_mfma_f32_16x16x32_bf16 v[104:107], v[200:203], v[160:163], v[104:107]
	v_mfma_f32_16x16x32_bf16 v[92:95], v[192:195], v[168:171], v[92:95]
	v_mfma_f32_16x16x32_bf16 v[88:91], v[200:203], v[168:171], v[88:91]
	v_mfma_f32_16x16x32_bf16 v[76:79], v[192:195], v[176:179], v[76:79]
	v_mfma_f32_16x16x32_bf16 v[72:75], v[200:203], v[176:179], v[72:75]
	v_mfma_f32_16x16x32_bf16 v[68:71], v[192:195], v[184:187], v[68:71]
	v_mfma_f32_16x16x32_bf16 v[64:67], v[200:203], v[184:187], v[64:67]
	v_mfma_f32_16x16x32_bf16 v[108:111], v[196:199], v[164:167], v[108:111]
	v_mfma_f32_16x16x32_bf16 v[104:107], v[204:207], v[164:167], v[104:107]
	v_mfma_f32_16x16x32_bf16 v[92:95], v[196:199], v[172:175], v[92:95]
	v_mfma_f32_16x16x32_bf16 v[88:91], v[204:207], v[172:175], v[88:91]
	v_mfma_f32_16x16x32_bf16 v[76:79], v[196:199], v[180:183], v[76:79]
	v_mfma_f32_16x16x32_bf16 v[72:75], v[204:207], v[180:183], v[72:75]
	v_mfma_f32_16x16x32_bf16 v[68:71], v[196:199], v[188:191], v[68:71]
	v_mfma_f32_16x16x32_bf16 v[64:67], v[204:207], v[188:191], v[64:67]
	s_mov_b32 m0, s3
	v_lshl_add_u64 v[212:213], s[20:21], 0, v[130:131]
	s_barrier
	ds_read_b128 v[160:163], v140 offset:16384
	ds_read_b128 v[164:167], v140 offset:17408
	ds_read_b128 v[168:171], v140 offset:18432
	ds_read_b128 v[172:175], v140 offset:19456
	ds_read_b128 v[176:179], v140 offset:20480
	ds_read_b128 v[180:183], v140 offset:21504
	ds_read_b128 v[184:187], v140 offset:22528
	ds_read_b128 v[188:191], v140 offset:23552
	global_load_lds_dwordx4 v[212:213], off
	v_lshl_add_u64 v[214:215], s[20:21], 0, v[128:129]
	s_mov_b32 m0, s4
	s_nop 0
	global_load_lds_dwordx4 v[214:215], off
	s_barrier
	s_waitcnt lgkmcnt(0)
	s_waitcnt lgkmcnt(0)
	v_mfma_f32_16x16x32_bf16 v[60:63], v[144:147], v[160:163], v[60:63]
	v_mfma_f32_16x16x32_bf16 v[56:59], v[152:155], v[160:163], v[56:59]
	v_mfma_f32_16x16x32_bf16 v[52:55], v[144:147], v[168:171], v[52:55]
	v_mfma_f32_16x16x32_bf16 v[48:51], v[152:155], v[168:171], v[48:51]
	v_mfma_f32_16x16x32_bf16 v[36:39], v[144:147], v[176:179], v[36:39]
	v_mfma_f32_16x16x32_bf16 v[32:35], v[152:155], v[176:179], v[32:35]
	v_mfma_f32_16x16x32_bf16 v[20:23], v[144:147], v[184:187], v[20:23]
	v_mfma_f32_16x16x32_bf16 v[16:19], v[152:155], v[184:187], v[16:19]
	v_mfma_f32_16x16x32_bf16 v[60:63], v[148:151], v[164:167], v[60:63]
	v_mfma_f32_16x16x32_bf16 v[56:59], v[156:159], v[164:167], v[56:59]
	v_mfma_f32_16x16x32_bf16 v[52:55], v[148:151], v[172:175], v[52:55]
	v_mfma_f32_16x16x32_bf16 v[48:51], v[156:159], v[172:175], v[48:51]
	v_mfma_f32_16x16x32_bf16 v[36:39], v[148:151], v[180:183], v[36:39]
	v_mfma_f32_16x16x32_bf16 v[32:35], v[156:159], v[180:183], v[32:35]
	v_mfma_f32_16x16x32_bf16 v[20:23], v[148:151], v[188:191], v[20:23]
	v_mfma_f32_16x16x32_bf16 v[16:19], v[156:159], v[188:191], v[16:19]
	s_barrier
	s_add_u32 s14, s18, 0x160000
	s_addc_u32 s15, s19, 0
	s_mov_b32 m0, s35
	v_lshl_add_u64 v[144:145], s[14:15], 0, v[130:131]
	global_load_lds_dwordx4 v[144:145], off
	v_lshl_add_u64 v[144:145], s[14:15], 0, v[128:129]
	s_mov_b32 m0, s36
	s_nop 0
	global_load_lds_dwordx4 v[144:145], off
	s_waitcnt vmcnt(6)
	s_barrier
	v_mfma_f32_16x16x32_bf16 v[44:47], v[192:195], v[160:163], v[44:47]
	v_mfma_f32_16x16x32_bf16 v[40:43], v[200:203], v[160:163], v[40:43]
	v_mfma_f32_16x16x32_bf16 v[28:31], v[192:195], v[168:171], v[28:31]
	v_mfma_f32_16x16x32_bf16 v[24:27], v[200:203], v[168:171], v[24:27]
	v_mfma_f32_16x16x32_bf16 v[12:15], v[192:195], v[176:179], v[12:15]
	v_mfma_f32_16x16x32_bf16 v[8:11], v[200:203], v[176:179], v[8:11]
	v_mfma_f32_16x16x32_bf16 v[4:7], v[192:195], v[184:187], v[4:7]
	v_mfma_f32_16x16x32_bf16 v[0:3], v[200:203], v[184:187], v[0:3]
	v_mfma_f32_16x16x32_bf16 v[44:47], v[196:199], v[164:167], v[44:47]
	v_mfma_f32_16x16x32_bf16 v[40:43], v[204:207], v[164:167], v[40:43]
	v_mfma_f32_16x16x32_bf16 v[28:31], v[196:199], v[172:175], v[28:31]
	v_mfma_f32_16x16x32_bf16 v[24:27], v[204:207], v[172:175], v[24:27]
	v_mfma_f32_16x16x32_bf16 v[12:15], v[196:199], v[180:183], v[12:15]
	v_mfma_f32_16x16x32_bf16 v[8:11], v[204:207], v[180:183], v[8:11]
	v_mfma_f32_16x16x32_bf16 v[4:7], v[196:199], v[188:191], v[4:7]
	v_mfma_f32_16x16x32_bf16 v[0:3], v[204:207], v[188:191], v[0:3]
	s_barrier
	ds_read_b128 v[144:147], v142
	ds_read_b128 v[148:151], v142 offset:1024
	ds_read_b128 v[152:155], v142 offset:2048
	ds_read_b128 v[156:159], v142 offset:3072
	s_add_u32 s14, s20, 0x160000
	s_addc_u32 s15, s21, 0
	s_mov_b32 m0, s5
	v_lshl_add_u64 v[192:193], s[14:15], 0, v[130:131]
	ds_read_b128 v[160:163], v140 offset:32768
	ds_read_b128 v[164:167], v140 offset:33792
	ds_read_b128 v[168:171], v140 offset:34816
	ds_read_b128 v[172:175], v140 offset:35840
	ds_read_b128 v[176:179], v140 offset:36864
	ds_read_b128 v[180:183], v140 offset:37888
	ds_read_b128 v[184:187], v140 offset:38912
	ds_read_b128 v[188:191], v140 offset:39936
	global_load_lds_dwordx4 v[192:193], off
	v_lshl_add_u64 v[192:193], s[14:15], 0, v[128:129]
	s_mov_b32 m0, s22
	s_nop 0
	global_load_lds_dwordx4 v[192:193], off
	s_waitcnt lgkmcnt(8)
	s_barrier
	s_waitcnt lgkmcnt(0)
	s_waitcnt lgkmcnt(0)
	v_mfma_f32_16x16x32_bf16 v[124:127], v[144:147], v[160:163], v[124:127]
	v_mfma_f32_16x16x32_bf16 v[120:123], v[152:155], v[160:163], v[120:123]
	v_mfma_f32_16x16x32_bf16 v[116:119], v[144:147], v[168:171], v[116:119]
	v_mfma_f32_16x16x32_bf16 v[112:115], v[152:155], v[168:171], v[112:115]
	v_mfma_f32_16x16x32_bf16 v[100:103], v[144:147], v[176:179], v[100:103]
	v_mfma_f32_16x16x32_bf16 v[96:99], v[152:155], v[176:179], v[96:99]
	v_mfma_f32_16x16x32_bf16 v[84:87], v[144:147], v[184:187], v[84:87]
	v_mfma_f32_16x16x32_bf16 v[80:83], v[152:155], v[184:187], v[80:83]
	v_mfma_f32_16x16x32_bf16 v[124:127], v[148:151], v[164:167], v[124:127]
	v_mfma_f32_16x16x32_bf16 v[120:123], v[156:159], v[164:167], v[120:123]
	v_mfma_f32_16x16x32_bf16 v[116:119], v[148:151], v[172:175], v[116:119]
	v_mfma_f32_16x16x32_bf16 v[112:115], v[156:159], v[172:175], v[112:115]
	v_mfma_f32_16x16x32_bf16 v[100:103], v[148:151], v[180:183], v[100:103]
	v_mfma_f32_16x16x32_bf16 v[96:99], v[156:159], v[180:183], v[96:99]
	v_mfma_f32_16x16x32_bf16 v[84:87], v[148:151], v[188:191], v[84:87]
	v_mfma_f32_16x16x32_bf16 v[80:83], v[156:159], v[188:191], v[80:83]
	s_barrier
	s_add_i32 s20, 0, 0x1c000
	s_add_i32 s14, s37, s2
	v_add_u32_e32 v143, s20, v137
	v_lshl_add_u64 v[208:209], v[208:209], 0, s[8:9]
	s_mov_b32 m0, s14
	ds_read_b128 v[192:195], v143
	ds_read_b128 v[196:199], v143 offset:1024
	ds_read_b128 v[200:203], v143 offset:2048
	ds_read_b128 v[204:207], v143 offset:3072
	global_load_lds_dwordx4 v[208:209], off
	v_lshl_add_u64 v[208:209], v[210:211], 0, s[8:9]
	s_add_i32 m0, s14, 0x2000
	s_nop 0
	global_load_lds_dwordx4 v[208:209], off
	s_barrier
	s_waitcnt lgkmcnt(0)
	s_waitcnt lgkmcnt(0)
	v_mfma_f32_16x16x32_bf16 v[108:111], v[192:195], v[160:163], v[108:111]
	v_mfma_f32_16x16x32_bf16 v[104:107], v[200:203], v[160:163], v[104:107]
	v_mfma_f32_16x16x32_bf16 v[92:95], v[192:195], v[168:171], v[92:95]
	v_mfma_f32_16x16x32_bf16 v[88:91], v[200:203], v[168:171], v[88:91]
	v_mfma_f32_16x16x32_bf16 v[76:79], v[192:195], v[176:179], v[76:79]
	v_mfma_f32_16x16x32_bf16 v[72:75], v[200:203], v[176:179], v[72:75]
	v_mfma_f32_16x16x32_bf16 v[68:71], v[192:195], v[184:187], v[68:71]
	v_mfma_f32_16x16x32_bf16 v[64:67], v[200:203], v[184:187], v[64:67]
	v_mfma_f32_16x16x32_bf16 v[108:111], v[196:199], v[164:167], v[108:111]
	v_mfma_f32_16x16x32_bf16 v[104:107], v[204:207], v[164:167], v[104:107]
	v_mfma_f32_16x16x32_bf16 v[92:95], v[196:199], v[172:175], v[92:95]
	v_mfma_f32_16x16x32_bf16 v[88:91], v[204:207], v[172:175], v[88:91]
	v_mfma_f32_16x16x32_bf16 v[76:79], v[196:199], v[180:183], v[76:79]
	v_mfma_f32_16x16x32_bf16 v[72:75], v[204:207], v[180:183], v[72:75]
	v_mfma_f32_16x16x32_bf16 v[68:71], v[196:199], v[188:191], v[68:71]
	v_mfma_f32_16x16x32_bf16 v[64:67], v[204:207], v[188:191], v[64:67]
	s_mov_b32 m0, s27
	v_lshl_add_u64 v[208:209], v[212:213], 0, s[8:9]
	s_barrier
	ds_read_b128 v[160:163], v140 offset:49152
	ds_read_b128 v[164:167], v140 offset:50176
	ds_read_b128 v[168:171], v140 offset:51200
	ds_read_b128 v[172:175], v140 offset:52224
	ds_read_b128 v[176:179], v140 offset:53248
	ds_read_b128 v[180:183], v140 offset:54272
	ds_read_b128 v[184:187], v140 offset:55296
	ds_read_b128 v[188:191], v140 offset:56320
	global_load_lds_dwordx4 v[208:209], off
	v_lshl_add_u64 v[208:209], v[214:215], 0, s[8:9]
	s_mov_b32 m0, s28
	s_nop 0
	global_load_lds_dwordx4 v[208:209], off
	s_barrier
	s_waitcnt lgkmcnt(0)
	s_waitcnt lgkmcnt(0)
	v_mfma_f32_16x16x32_bf16 v[60:63], v[144:147], v[160:163], v[60:63]
	v_mfma_f32_16x16x32_bf16 v[56:59], v[152:155], v[160:163], v[56:59]
	v_mfma_f32_16x16x32_bf16 v[52:55], v[144:147], v[168:171], v[52:55]
	v_mfma_f32_16x16x32_bf16 v[48:51], v[152:155], v[168:171], v[48:51]
	v_mfma_f32_16x16x32_bf16 v[36:39], v[144:147], v[176:179], v[36:39]
	v_mfma_f32_16x16x32_bf16 v[32:35], v[152:155], v[176:179], v[32:35]
	v_mfma_f32_16x16x32_bf16 v[20:23], v[144:147], v[184:187], v[20:23]
	v_mfma_f32_16x16x32_bf16 v[16:19], v[152:155], v[184:187], v[16:19]
	v_mfma_f32_16x16x32_bf16 v[60:63], v[148:151], v[164:167], v[60:63]
	v_mfma_f32_16x16x32_bf16 v[56:59], v[156:159], v[164:167], v[56:59]
	v_mfma_f32_16x16x32_bf16 v[52:55], v[148:151], v[172:175], v[52:55]
	v_mfma_f32_16x16x32_bf16 v[48:51], v[156:159], v[172:175], v[48:51]
	v_mfma_f32_16x16x32_bf16 v[36:39], v[148:151], v[180:183], v[36:39]
	v_mfma_f32_16x16x32_bf16 v[32:35], v[156:159], v[180:183], v[32:35]
	v_mfma_f32_16x16x32_bf16 v[20:23], v[148:151], v[188:191], v[20:23]
	v_mfma_f32_16x16x32_bf16 v[16:19], v[156:159], v[188:191], v[16:19]
	s_barrier
	s_add_u32 s14, s18, 0x160080
	s_addc_u32 s15, s19, 0
	s_add_i32 s18, s20, s2
	v_lshl_add_u64 v[144:145], s[14:15], 0, v[130:131]
	s_mov_b32 m0, s18
	s_nop 0
	global_load_lds_dwordx4 v[144:145], off
	v_lshl_add_u64 v[144:145], s[14:15], 0, v[128:129]
	s_add_i32 m0, s18, 0x2000
	s_nop 0
	global_load_lds_dwordx4 v[144:145], off
	s_waitcnt vmcnt(6)
	s_barrier
	v_mfma_f32_16x16x32_bf16 v[44:47], v[192:195], v[160:163], v[44:47]
	v_mfma_f32_16x16x32_bf16 v[40:43], v[200:203], v[160:163], v[40:43]
	v_mfma_f32_16x16x32_bf16 v[28:31], v[192:195], v[168:171], v[28:31]
	v_mfma_f32_16x16x32_bf16 v[24:27], v[200:203], v[168:171], v[24:27]
	v_mfma_f32_16x16x32_bf16 v[12:15], v[192:195], v[176:179], v[12:15]
	v_mfma_f32_16x16x32_bf16 v[8:11], v[200:203], v[176:179], v[8:11]
	v_mfma_f32_16x16x32_bf16 v[4:7], v[192:195], v[184:187], v[4:7]
	v_mfma_f32_16x16x32_bf16 v[0:3], v[200:203], v[184:187], v[0:3]
	v_mfma_f32_16x16x32_bf16 v[44:47], v[196:199], v[164:167], v[44:47]
	v_mfma_f32_16x16x32_bf16 v[40:43], v[204:207], v[164:167], v[40:43]
	v_mfma_f32_16x16x32_bf16 v[28:31], v[196:199], v[172:175], v[28:31]
	v_mfma_f32_16x16x32_bf16 v[24:27], v[204:207], v[172:175], v[24:27]
	v_mfma_f32_16x16x32_bf16 v[12:15], v[196:199], v[180:183], v[12:15]
	v_mfma_f32_16x16x32_bf16 v[8:11], v[204:207], v[180:183], v[8:11]
	v_mfma_f32_16x16x32_bf16 v[4:7], v[196:199], v[188:191], v[4:7]
	v_mfma_f32_16x16x32_bf16 v[0:3], v[204:207], v[188:191], v[0:3]
	s_add_i32 s43, s43, 2
	s_add_u32 s41, s41, 0x100
	s_addc_u32 s42, s42, 0
	s_cmp_gt_u32 s43, 5
	s_mov_b64 s[14:15], s[16:17]
	s_barrier
	s_cbranch_scc0 .LBB0_698
	s_ashr_i32 s14, s26, 1
	s_and_b32 s14, s14, 0xfffffe00
	s_lshl_b32 s15, s25, 8
	s_add_i32 s15, s15, s14
	v_add_u32_e32 v146, s15, v136
	v_lshl_or_b32 v144, s24, 8, v138
	v_ashrrev_i32_e32 v147, 31, v146
	v_ashrrev_i32_e32 v145, 31, v144
	v_lshlrev_b64 v[148:149], 13, v[146:147]
	v_lshl_add_u64 v[148:149], s[66:67], 0, v[148:149]
	v_lshlrev_b64 v[144:145], 2, v[144:145]
	v_lshl_add_u64 v[148:149], v[148:149], 0, v[144:145]
	global_store_dwordx4 v[148:149], v[124:127], off
	global_store_dwordx4 v[148:149], v[120:123], off offset:64
	global_store_dwordx4 v[148:149], v[108:111], off offset:512
	global_store_dwordx4 v[148:149], v[104:107], off offset:576
	s_mov_b64 s[14:15], 0x100000
	s_mov_b32 s26, s39
	v_or_b32_e32 v104, 16, v146
	v_ashrrev_i32_e32 v105, 31, v104
	v_lshlrev_b64 v[104:105], 13, v[104:105]
	v_lshl_add_u64 v[104:105], s[66:67], 0, v[104:105]
	v_lshl_add_u64 v[104:105], v[104:105], 0, v[144:145]
	global_store_dwordx4 v[104:105], v[116:119], off
	global_store_dwordx4 v[104:105], v[112:115], off offset:64
	global_store_dwordx4 v[104:105], v[92:95], off offset:512
	global_store_dwordx4 v[104:105], v[88:91], off offset:576
	s_mov_b32 s24, s38
	s_mov_b32 s25, s40
	v_or_b32_e32 v88, 32, v146
	v_ashrrev_i32_e32 v89, 31, v88
	v_lshlrev_b64 v[88:89], 13, v[88:89]
	v_lshl_add_u64 v[88:89], s[66:67], 0, v[88:89]
	v_lshl_add_u64 v[88:89], v[88:89], 0, v[144:145]
	global_store_dwordx4 v[88:89], v[100:103], off
	global_store_dwordx4 v[88:89], v[96:99], off offset:64
	global_store_dwordx4 v[88:89], v[76:79], off offset:512
	global_store_dwordx4 v[88:89], v[72:75], off offset:576
	s_mov_b64 s[16:17], s[6:7]
	s_nop 0
	v_or_b32_e32 v72, 48, v146
	v_ashrrev_i32_e32 v73, 31, v72
	v_lshlrev_b64 v[72:73], 13, v[72:73]
	v_lshl_add_u64 v[72:73], s[66:67], 0, v[72:73]
	v_lshl_add_u64 v[72:73], v[72:73], 0, v[144:145]
	global_store_dwordx4 v[72:73], v[84:87], off
	global_store_dwordx4 v[72:73], v[80:83], off offset:64
	global_store_dwordx4 v[72:73], v[68:71], off offset:512
	global_store_dwordx4 v[72:73], v[64:67], off offset:576
	s_nop 1
	v_lshl_add_u64 v[64:65], v[148:149], 0, s[14:15]
	s_mov_b32 s14, 0x100000
	v_add_co_u32_e32 v66, vcc, s14, v148
	s_mov_b64 s[14:15], 0x120000
	s_nop 0
	v_addc_co_u32_e32 v67, vcc, 0, v149, vcc
	global_store_dwordx4 v[66:67], v[60:63], off
	global_store_dwordx4 v[64:65], v[56:59], off offset:64
	global_store_dwordx4 v[64:65], v[44:47], off offset:512
	global_store_dwordx4 v[64:65], v[40:43], off offset:576
	s_nop 1
	v_lshl_add_u64 v[40:41], v[148:149], 0, s[14:15]
	s_mov_b32 s14, 0x120000
	v_add_co_u32_e32 v42, vcc, s14, v148
	s_mov_b64 s[14:15], 0x140000
	s_nop 0
	v_addc_co_u32_e32 v43, vcc, 0, v149, vcc
	global_store_dwordx4 v[42:43], v[52:55], off
	global_store_dwordx4 v[40:41], v[48:51], off offset:64
	global_store_dwordx4 v[40:41], v[28:31], off offset:512
	global_store_dwordx4 v[40:41], v[24:27], off offset:576
	s_nop 1
	v_lshl_add_u64 v[24:25], v[148:149], 0, s[14:15]
	s_mov_b32 s14, 0x140000
	v_add_co_u32_e32 v26, vcc, s14, v148
	s_mov_b64 s[14:15], 0x160000
	s_nop 0
	v_addc_co_u32_e32 v27, vcc, 0, v149, vcc
	global_store_dwordx4 v[26:27], v[36:39], off
	global_store_dwordx4 v[24:25], v[32:35], off offset:64
	global_store_dwordx4 v[24:25], v[12:15], off offset:512
	global_store_dwordx4 v[24:25], v[8:11], off offset:576
	s_nop 1
	v_add_co_u32_e32 v10, vcc, 0x160000, v148
	v_lshl_add_u64 v[8:9], v[148:149], 0, s[14:15]
	s_nop 0
	v_addc_co_u32_e32 v11, vcc, 0, v149, vcc
	s_and_b64 vcc, exec, s[10:11]
	s_mov_b64 s[14:15], s[12:13]
	global_store_dwordx4 v[10:11], v[20:23], off
	global_store_dwordx4 v[8:9], v[16:19], off offset:64
	global_store_dwordx4 v[8:9], v[4:7], off offset:512
	global_store_dwordx4 v[8:9], v[0:3], off offset:576
	s_cbranch_vccz .LBB0_691
	s_waitcnt vmcnt(0)
	s_cmpk_gt_u32 s1, 0xff
	s_cbranch_scc1 .LBB0_702
	s_barrier

.LBB0_924:
	s_add_u32 s21, s12, s20
	s_addc_u32 s29, s13, 0
	s_add_u32 s24, s21, 0x100
	s_addc_u32 s25, s29, 0
	s_and_b64 s[22:23], s[18:19], exec
	s_cselect_b32 s25, s9, s25
	s_cselect_b32 s24, s17, s24
	s_add_u32 s20, s10, s20
	s_addc_u32 s22, s11, 0
	s_add_u32 s20, s20, 0x100
	s_addc_u32 s22, s22, 0
	s_and_b64 s[18:19], s[18:19], exec
	s_cselect_b32 s27, s30, s22
	s_cselect_b32 s26, s31, s20
	s_add_u32 s28, s21, 0x10080
	s_addc_u32 s29, s29, 0
	s_add_i32 s67, s75, s3
	s_add_i32 m0, s4, 0xc000
	s_add_i32 s72, s4, 0xe000
	s_add_i32 s65, s67, 0x2000
	s_add_u32 s22, s26, 0x10000
	s_addc_u32 s23, s27, 0
	s_add_i32 s41, s2, s3
	ds_read_b128 v[144:147], v141
	ds_read_b128 v[148:151], v141 offset:1024
	ds_read_b128 v[152:155], v141 offset:2048
	ds_read_b128 v[156:159], v141 offset:3072
	s_add_i32 s40, s41, 0x2000
	s_add_i32 s39, 0, 0x18000
	s_add_u32 s20, s24, 0x10000
	s_addc_u32 s21, s25, 0
	s_add_i32 s38, s39, s3
	s_add_i32 s37, 0, 0x1c000
	s_add_i32 s36, s38, 0x2000
	s_add_u32 s18, s26, 0x10080
	s_addc_u32 s19, s27, 0
	s_add_i32 s35, s37, s3
	s_add_i32 s34, s35, 0x2000
	v_lshl_add_u64 v[136:137], s[28:29], 0, v[128:129]
	ds_read_b128 v[160:163], v142
	ds_read_b128 v[164:167], v142 offset:1024
	ds_read_b128 v[168:171], v142 offset:2048
	ds_read_b128 v[172:175], v142 offset:3072
	ds_read_b128 v[176:179], v142 offset:4096
	ds_read_b128 v[180:183], v142 offset:5120
	ds_read_b128 v[184:187], v142 offset:6144
	ds_read_b128 v[188:191], v142 offset:7168
	global_load_lds_dwordx4 v[136:137], off
	v_lshl_add_u64 v[136:137], s[28:29], 0, v[130:131]
	s_mov_b32 m0, s72
	s_nop 0
	global_load_lds_dwordx4 v[136:137], off
	s_waitcnt lgkmcnt(8)
	s_barrier
	s_waitcnt lgkmcnt(0)
	s_waitcnt lgkmcnt(0)
	v_mfma_f32_16x16x32_bf16 v[124:127], v[144:147], v[160:163], v[124:127]
	v_mfma_f32_16x16x32_bf16 v[120:123], v[152:155], v[160:163], v[120:123]
	v_mfma_f32_16x16x32_bf16 v[108:111], v[144:147], v[168:171], v[108:111]
	v_mfma_f32_16x16x32_bf16 v[104:107], v[152:155], v[168:171], v[104:107]
	v_mfma_f32_16x16x32_bf16 v[92:95], v[144:147], v[176:179], v[92:95]
	v_mfma_f32_16x16x32_bf16 v[88:91], v[152:155], v[176:179], v[88:91]
	v_mfma_f32_16x16x32_bf16 v[76:79], v[144:147], v[184:187], v[76:79]
	v_mfma_f32_16x16x32_bf16 v[72:75], v[152:155], v[184:187], v[72:75]
	v_mfma_f32_16x16x32_bf16 v[124:127], v[148:151], v[164:167], v[124:127]
	v_mfma_f32_16x16x32_bf16 v[120:123], v[156:159], v[164:167], v[120:123]
	v_mfma_f32_16x16x32_bf16 v[108:111], v[148:151], v[172:175], v[108:111]
	v_mfma_f32_16x16x32_bf16 v[104:107], v[156:159], v[172:175], v[104:107]
	v_mfma_f32_16x16x32_bf16 v[92:95], v[148:151], v[180:183], v[92:95]
	v_mfma_f32_16x16x32_bf16 v[88:91], v[156:159], v[180:183], v[88:91]
	v_mfma_f32_16x16x32_bf16 v[76:79], v[148:151], v[188:191], v[76:79]
	v_mfma_f32_16x16x32_bf16 v[72:75], v[156:159], v[188:191], v[72:75]
	s_barrier
	s_mov_b32 m0, s67
	v_lshl_add_u64 v[136:137], s[26:27], 0, v[128:129]
	ds_read_b128 v[192:195], v143
	ds_read_b128 v[196:199], v143 offset:1024
	ds_read_b128 v[200:203], v143 offset:2048
	ds_read_b128 v[204:207], v143 offset:3072
	global_load_lds_dwordx4 v[136:137], off
	v_lshl_add_u64 v[208:209], s[26:27], 0, v[130:131]
	s_mov_b32 m0, s65
	s_nop 0
	global_load_lds_dwordx4 v[208:209], off
	s_barrier
	s_waitcnt lgkmcnt(0)
	s_waitcnt lgkmcnt(0)
	v_mfma_f32_16x16x32_bf16 v[116:119], v[192:195], v[160:163], v[116:119]
	v_mfma_f32_16x16x32_bf16 v[112:115], v[200:203], v[160:163], v[112:115]
	v_mfma_f32_16x16x32_bf16 v[100:103], v[192:195], v[168:171], v[100:103]
	v_mfma_f32_16x16x32_bf16 v[96:99], v[200:203], v[168:171], v[96:99]
	v_mfma_f32_16x16x32_bf16 v[84:87], v[192:195], v[176:179], v[84:87]
	v_mfma_f32_16x16x32_bf16 v[80:83], v[200:203], v[176:179], v[80:83]
	v_mfma_f32_16x16x32_bf16 v[68:71], v[192:195], v[184:187], v[68:71]
	v_mfma_f32_16x16x32_bf16 v[64:67], v[200:203], v[184:187], v[64:67]
	v_mfma_f32_16x16x32_bf16 v[116:119], v[196:199], v[164:167], v[116:119]
	v_mfma_f32_16x16x32_bf16 v[112:115], v[204:207], v[164:167], v[112:115]
	v_mfma_f32_16x16x32_bf16 v[100:103], v[196:199], v[172:175], v[100:103]
	v_mfma_f32_16x16x32_bf16 v[96:99], v[204:207], v[172:175], v[96:99]
	v_mfma_f32_16x16x32_bf16 v[84:87], v[196:199], v[180:183], v[84:87]
	v_mfma_f32_16x16x32_bf16 v[80:83], v[204:207], v[180:183], v[80:83]
	v_mfma_f32_16x16x32_bf16 v[68:71], v[196:199], v[188:191], v[68:71]
	v_mfma_f32_16x16x32_bf16 v[64:67], v[204:207], v[188:191], v[64:67]
	s_mov_b32 m0, s4
	v_lshl_add_u64 v[210:211], s[24:25], 0, v[128:129]
	s_barrier
	ds_read_b128 v[160:163], v142 offset:16384
	ds_read_b128 v[164:167], v142 offset:17408
	ds_read_b128 v[168:171], v142 offset:18432
	ds_read_b128 v[172:175], v142 offset:19456
	ds_read_b128 v[176:179], v142 offset:20480
	ds_read_b128 v[180:183], v142 offset:21504
	ds_read_b128 v[184:187], v142 offset:22528
	ds_read_b128 v[188:191], v142 offset:23552
	global_load_lds_dwordx4 v[210:211], off
	v_lshl_add_u64 v[212:213], s[24:25], 0, v[130:131]
	s_mov_b32 m0, s5
	s_nop 0
	global_load_lds_dwordx4 v[212:213], off
	s_barrier
	s_waitcnt lgkmcnt(0)
	s_waitcnt lgkmcnt(0)
	v_mfma_f32_16x16x32_bf16 v[60:63], v[144:147], v[160:163], v[60:63]
	v_mfma_f32_16x16x32_bf16 v[56:59], v[152:155], v[160:163], v[56:59]
	v_mfma_f32_16x16x32_bf16 v[44:47], v[144:147], v[168:171], v[44:47]
	v_mfma_f32_16x16x32_bf16 v[40:43], v[152:155], v[168:171], v[40:43]
	v_mfma_f32_16x16x32_bf16 v[28:31], v[144:147], v[176:179], v[28:31]
	v_mfma_f32_16x16x32_bf16 v[24:27], v[152:155], v[176:179], v[24:27]
	v_mfma_f32_16x16x32_bf16 v[12:15], v[144:147], v[184:187], v[12:15]
	v_mfma_f32_16x16x32_bf16 v[8:11], v[152:155], v[184:187], v[8:11]
	v_mfma_f32_16x16x32_bf16 v[60:63], v[148:151], v[164:167], v[60:63]
	v_mfma_f32_16x16x32_bf16 v[56:59], v[156:159], v[164:167], v[56:59]
	v_mfma_f32_16x16x32_bf16 v[44:47], v[148:151], v[172:175], v[44:47]
	v_mfma_f32_16x16x32_bf16 v[40:43], v[156:159], v[172:175], v[40:43]
	v_mfma_f32_16x16x32_bf16 v[28:31], v[148:151], v[180:183], v[28:31]
	v_mfma_f32_16x16x32_bf16 v[24:27], v[156:159], v[180:183], v[24:27]
	v_mfma_f32_16x16x32_bf16 v[12:15], v[148:151], v[188:191], v[12:15]
	v_mfma_f32_16x16x32_bf16 v[8:11], v[156:159], v[188:191], v[8:11]
	s_barrier
	s_mov_b32 m0, s41
	v_lshl_add_u64 v[144:145], s[22:23], 0, v[128:129]
	global_load_lds_dwordx4 v[144:145], off
	v_lshl_add_u64 v[144:145], s[22:23], 0, v[130:131]
	s_mov_b32 m0, s40
	s_nop 0
	global_load_lds_dwordx4 v[144:145], off
	s_waitcnt vmcnt(6)
	s_barrier
	v_mfma_f32_16x16x32_bf16 v[52:55], v[192:195], v[160:163], v[52:55]
	v_mfma_f32_16x16x32_bf16 v[48:51], v[200:203], v[160:163], v[48:51]
	v_mfma_f32_16x16x32_bf16 v[36:39], v[192:195], v[168:171], v[36:39]
	v_mfma_f32_16x16x32_bf16 v[32:35], v[200:203], v[168:171], v[32:35]
	v_mfma_f32_16x16x32_bf16 v[20:23], v[192:195], v[176:179], v[20:23]
	v_mfma_f32_16x16x32_bf16 v[16:19], v[200:203], v[176:179], v[16:19]
	v_mfma_f32_16x16x32_bf16 v[4:7], v[192:195], v[184:187], v[4:7]
	v_mfma_f32_16x16x32_bf16 v[0:3], v[200:203], v[184:187], v[0:3]
	v_mfma_f32_16x16x32_bf16 v[52:55], v[196:199], v[164:167], v[52:55]
	v_mfma_f32_16x16x32_bf16 v[48:51], v[204:207], v[164:167], v[48:51]
	v_mfma_f32_16x16x32_bf16 v[36:39], v[196:199], v[172:175], v[36:39]
	v_mfma_f32_16x16x32_bf16 v[32:35], v[204:207], v[172:175], v[32:35]
	v_mfma_f32_16x16x32_bf16 v[20:23], v[196:199], v[180:183], v[20:23]
	v_mfma_f32_16x16x32_bf16 v[16:19], v[204:207], v[180:183], v[16:19]
	v_mfma_f32_16x16x32_bf16 v[4:7], v[196:199], v[188:191], v[4:7]
	v_mfma_f32_16x16x32_bf16 v[0:3], v[204:207], v[188:191], v[0:3]
	v_add_u32_e32 v156, s39, v139
	s_barrier
	ds_read_b128 v[144:147], v156
	ds_read_b128 v[148:151], v156 offset:1024
	ds_read_b128 v[152:155], v156 offset:2048
	ds_read_b128 v[156:159], v156 offset:3072
	s_mov_b32 m0, s42
	v_lshl_add_u64 v[192:193], s[20:21], 0, v[128:129]
	ds_read_b128 v[160:163], v142 offset:32768
	ds_read_b128 v[164:167], v142 offset:33792
	ds_read_b128 v[168:171], v142 offset:34816
	ds_read_b128 v[172:175], v142 offset:35840
	ds_read_b128 v[176:179], v142 offset:36864
	ds_read_b128 v[180:183], v142 offset:37888
	ds_read_b128 v[184:187], v142 offset:38912
	ds_read_b128 v[188:191], v142 offset:39936
	global_load_lds_dwordx4 v[192:193], off
	v_lshl_add_u64 v[192:193], s[20:21], 0, v[130:131]
	s_mov_b32 m0, s43
	s_nop 0
	global_load_lds_dwordx4 v[192:193], off
	s_waitcnt lgkmcnt(8)
	s_barrier
	s_waitcnt lgkmcnt(0)
	s_waitcnt lgkmcnt(0)
	v_mfma_f32_16x16x32_bf16 v[124:127], v[144:147], v[160:163], v[124:127]
	v_mfma_f32_16x16x32_bf16 v[120:123], v[152:155], v[160:163], v[120:123]
	v_mfma_f32_16x16x32_bf16 v[108:111], v[144:147], v[168:171], v[108:111]
	v_mfma_f32_16x16x32_bf16 v[104:107], v[152:155], v[168:171], v[104:107]
	v_mfma_f32_16x16x32_bf16 v[92:95], v[144:147], v[176:179], v[92:95]
	v_mfma_f32_16x16x32_bf16 v[88:91], v[152:155], v[176:179], v[88:91]
	v_mfma_f32_16x16x32_bf16 v[76:79], v[144:147], v[184:187], v[76:79]
	v_mfma_f32_16x16x32_bf16 v[72:75], v[152:155], v[184:187], v[72:75]
	v_mfma_f32_16x16x32_bf16 v[124:127], v[148:151], v[164:167], v[124:127]
	v_mfma_f32_16x16x32_bf16 v[120:123], v[156:159], v[164:167], v[120:123]
	v_mfma_f32_16x16x32_bf16 v[108:111], v[148:151], v[172:175], v[108:111]
	v_mfma_f32_16x16x32_bf16 v[104:107], v[156:159], v[172:175], v[104:107]
	v_mfma_f32_16x16x32_bf16 v[92:95], v[148:151], v[180:183], v[92:95]
	v_mfma_f32_16x16x32_bf16 v[88:91], v[156:159], v[180:183], v[88:91]
	v_mfma_f32_16x16x32_bf16 v[76:79], v[148:151], v[188:191], v[76:79]
	v_mfma_f32_16x16x32_bf16 v[72:75], v[156:159], v[188:191], v[72:75]
	s_barrier
	s_mov_b32 m0, s38
	v_add_u32_e32 v204, s37, v139
	v_lshl_add_u64 v[136:137], v[136:137], 0, s[62:63]
	ds_read_b128 v[192:195], v204
	ds_read_b128 v[196:199], v204 offset:1024
	ds_read_b128 v[200:203], v204 offset:2048
	ds_read_b128 v[204:207], v204 offset:3072
	global_load_lds_dwordx4 v[136:137], off
	v_lshl_add_u64 v[136:137], v[208:209], 0, s[62:63]
	s_mov_b32 m0, s36
	s_nop 0
	global_load_lds_dwordx4 v[136:137], off
	s_barrier
	s_waitcnt lgkmcnt(0)
	s_waitcnt lgkmcnt(0)
	v_mfma_f32_16x16x32_bf16 v[116:119], v[192:195], v[160:163], v[116:119]
	v_mfma_f32_16x16x32_bf16 v[112:115], v[200:203], v[160:163], v[112:115]
	v_mfma_f32_16x16x32_bf16 v[100:103], v[192:195], v[168:171], v[100:103]
	v_mfma_f32_16x16x32_bf16 v[96:99], v[200:203], v[168:171], v[96:99]
	v_mfma_f32_16x16x32_bf16 v[84:87], v[192:195], v[176:179], v[84:87]
	v_mfma_f32_16x16x32_bf16 v[80:83], v[200:203], v[176:179], v[80:83]
	v_mfma_f32_16x16x32_bf16 v[68:71], v[192:195], v[184:187], v[68:71]
	v_mfma_f32_16x16x32_bf16 v[64:67], v[200:203], v[184:187], v[64:67]
	v_mfma_f32_16x16x32_bf16 v[116:119], v[196:199], v[164:167], v[116:119]
	v_mfma_f32_16x16x32_bf16 v[112:115], v[204:207], v[164:167], v[112:115]
	v_mfma_f32_16x16x32_bf16 v[100:103], v[196:199], v[172:175], v[100:103]
	v_mfma_f32_16x16x32_bf16 v[96:99], v[204:207], v[172:175], v[96:99]
	v_mfma_f32_16x16x32_bf16 v[84:87], v[196:199], v[180:183], v[84:87]
	v_mfma_f32_16x16x32_bf16 v[80:83], v[204:207], v[180:183], v[80:83]
	v_mfma_f32_16x16x32_bf16 v[68:71], v[196:199], v[188:191], v[68:71]
	v_mfma_f32_16x16x32_bf16 v[64:67], v[204:207], v[188:191], v[64:67]
	s_mov_b32 m0, s47
	v_lshl_add_u64 v[136:137], v[210:211], 0, s[62:63]
	s_barrier
	ds_read_b128 v[160:163], v142 offset:49152
	ds_read_b128 v[164:167], v142 offset:50176
	ds_read_b128 v[168:171], v142 offset:51200
	ds_read_b128 v[172:175], v142 offset:52224
	ds_read_b128 v[176:179], v142 offset:53248
	ds_read_b128 v[180:183], v142 offset:54272
	ds_read_b128 v[184:187], v142 offset:55296
	ds_read_b128 v[188:191], v142 offset:56320
	global_load_lds_dwordx4 v[136:137], off
	v_lshl_add_u64 v[136:137], v[212:213], 0, s[62:63]
	s_mov_b32 m0, s74
	s_nop 0
	global_load_lds_dwordx4 v[136:137], off
	s_barrier
	s_waitcnt lgkmcnt(0)
	s_waitcnt lgkmcnt(0)
	v_mfma_f32_16x16x32_bf16 v[60:63], v[144:147], v[160:163], v[60:63]
	v_mfma_f32_16x16x32_bf16 v[56:59], v[152:155], v[160:163], v[56:59]
	v_mfma_f32_16x16x32_bf16 v[44:47], v[144:147], v[168:171], v[44:47]
	v_mfma_f32_16x16x32_bf16 v[40:43], v[152:155], v[168:171], v[40:43]
	v_mfma_f32_16x16x32_bf16 v[28:31], v[144:147], v[176:179], v[28:31]
	v_mfma_f32_16x16x32_bf16 v[24:27], v[152:155], v[176:179], v[24:27]
	v_mfma_f32_16x16x32_bf16 v[12:15], v[144:147], v[184:187], v[12:15]
	v_mfma_f32_16x16x32_bf16 v[8:11], v[152:155], v[184:187], v[8:11]
	v_mfma_f32_16x16x32_bf16 v[60:63], v[148:151], v[164:167], v[60:63]
	v_mfma_f32_16x16x32_bf16 v[56:59], v[156:159], v[164:167], v[56:59]
	v_mfma_f32_16x16x32_bf16 v[44:47], v[148:151], v[172:175], v[44:47]
	v_mfma_f32_16x16x32_bf16 v[40:43], v[156:159], v[172:175], v[40:43]
	v_mfma_f32_16x16x32_bf16 v[28:31], v[148:151], v[180:183], v[28:31]
	v_mfma_f32_16x16x32_bf16 v[24:27], v[156:159], v[180:183], v[24:27]
	v_mfma_f32_16x16x32_bf16 v[12:15], v[148:151], v[188:191], v[12:15]
	v_mfma_f32_16x16x32_bf16 v[8:11], v[156:159], v[188:191], v[8:11]
	s_barrier
	s_mov_b32 m0, s35
	v_lshl_add_u64 v[136:137], s[18:19], 0, v[128:129]
	global_load_lds_dwordx4 v[136:137], off
	v_lshl_add_u64 v[136:137], s[18:19], 0, v[130:131]
	s_mov_b32 m0, s34
	s_nop 0
	global_load_lds_dwordx4 v[136:137], off
	s_waitcnt vmcnt(6)
	s_barrier
	v_mfma_f32_16x16x32_bf16 v[52:55], v[192:195], v[160:163], v[52:55]
	v_mfma_f32_16x16x32_bf16 v[48:51], v[200:203], v[160:163], v[48:51]
	v_mfma_f32_16x16x32_bf16 v[36:39], v[192:195], v[168:171], v[36:39]
	v_mfma_f32_16x16x32_bf16 v[32:35], v[200:203], v[168:171], v[32:35]
	v_mfma_f32_16x16x32_bf16 v[20:23], v[192:195], v[176:179], v[20:23]
	v_mfma_f32_16x16x32_bf16 v[16:19], v[200:203], v[176:179], v[16:19]
	v_mfma_f32_16x16x32_bf16 v[4:7], v[192:195], v[184:187], v[4:7]
	v_mfma_f32_16x16x32_bf16 v[0:3], v[200:203], v[184:187], v[0:3]
	v_mfma_f32_16x16x32_bf16 v[52:55], v[196:199], v[164:167], v[52:55]
	v_mfma_f32_16x16x32_bf16 v[48:51], v[204:207], v[164:167], v[48:51]
	v_mfma_f32_16x16x32_bf16 v[36:39], v[196:199], v[172:175], v[36:39]
	v_mfma_f32_16x16x32_bf16 v[32:35], v[204:207], v[172:175], v[32:35]
	v_mfma_f32_16x16x32_bf16 v[20:23], v[196:199], v[180:183], v[20:23]
	v_mfma_f32_16x16x32_bf16 v[16:19], v[204:207], v[180:183], v[16:19]
	v_mfma_f32_16x16x32_bf16 v[4:7], v[196:199], v[188:191], v[4:7]
	v_mfma_f32_16x16x32_bf16 v[0:3], v[204:207], v[188:191], v[0:3]
	s_movk_i32 s20, 0x100
	s_andn2_b64 vcc, exec, s[14:15]
	s_mov_b64 s[18:19], -1
	s_mov_b64 s[14:15], 0
	s_barrier
	s_cbranch_vccz .LBB0_924
	v_lshl_or_b32 v136, s8, 8, v140
	v_ashrrev_i32_e32 v137, 31, v136
	v_cmp_lt_i32_e64 s[8:9], s1, v136
	v_add_u32_e32 v148, 0xfffff000, v136
	s_and_saveexec_b64 s[10:11], s[8:9]
	s_xor_b64 s[10:11], exec, s[10:11]
	v_cvt_f32_u32_e32 v144, v148
	v_mul_f32_e32 v147, 0x3b808081, v144
	s_or_saveexec_b64 s[10:11], s[10:11]
	v_cvt_f32_i32_e32 v150, v136
	s_xor_b64 exec, exec, s[10:11]
	v_mul_f32_e32 v147, 0x39800801, v150
	s_or_b64 exec, exec, s[10:11]
	v_or_b32_e32 v144, 1, v136
	v_cmp_lt_i32_e64 s[10:11], s1, v144
	v_add_u32_e32 v149, 0xfffff001, v136
	s_and_saveexec_b64 s[12:13], s[10:11]
	s_xor_b64 s[12:13], exec, s[12:13]
	v_cvt_f32_u32_e32 v145, v149
	v_mul_f32_e32 v153, 0x3b808081, v145
	s_or_saveexec_b64 s[12:13], s[12:13]
	v_cvt_f32_i32_e32 v167, v144
	v_mul_f32_e32 v144, 0x39800801, v167
	s_xor_b64 exec, exec, s[12:13]
	v_mul_f32_e32 v153, 0x39800801, v167
	s_or_b64 exec, exec, s[12:13]
	v_or_b32_e32 v145, 2, v136
	v_cmp_lt_i32_e64 s[12:13], s1, v145
	v_add_u32_e32 v151, 0xfffff002, v136
	s_and_saveexec_b64 s[14:15], s[12:13]
	s_xor_b64 s[14:15], exec, s[14:15]
	v_cvt_f32_u32_e32 v146, v151
	v_mul_f32_e32 v154, 0x3b808081, v146
	s_or_saveexec_b64 s[14:15], s[14:15]
	v_cvt_f32_i32_e32 v168, v145
	v_mul_f32_e32 v145, 0x39800801, v168
	s_xor_b64 exec, exec, s[14:15]
	v_mul_f32_e32 v154, 0x39800801, v168
	s_or_b64 exec, exec, s[14:15]
	v_or_b32_e32 v146, 3, v136
	v_cmp_lt_i32_e64 s[14:15], s1, v146
	v_add_u32_e32 v152, 0xfffff003, v136
	s_and_saveexec_b64 s[18:19], s[14:15]
	s_xor_b64 s[18:19], exec, s[18:19]
	v_cvt_f32_u32_e32 v155, v152
	v_mul_f32_e32 v155, 0x3b808081, v155
	s_or_saveexec_b64 s[18:19], s[18:19]
	v_cvt_f32_i32_e32 v169, v146
	v_mul_f32_e32 v146, 0x39800801, v169
	s_xor_b64 exec, exec, s[18:19]
	v_mul_f32_e32 v155, 0x39800801, v169
	s_or_b64 exec, exec, s[18:19]
	v_lshl_add_u32 v156, s16, 8, v138
	v_and_b32_e32 v157, 0x7cf, v156
	v_cvt_f32_u32_e32 v157, v157
	v_mul_f32_e32 v157, 0xc1447cbd, v157
	v_div_scale_f32 v158, s[16:17], s60, s60, v157
	v_rcp_f32_e32 v159, v158
	v_div_scale_f32 v160, vcc, v157, s60, v157
	v_fma_f32 v161, -v158, v159, 1.0
	v_fmac_f32_e32 v159, v161, v159
	v_mul_f32_e32 v161, v160, v159
	v_fma_f32 v162, -v158, v161, v160
	v_fmac_f32_e32 v161, v162, v159
	v_fma_f32 v158, -v158, v161, v160
	v_div_fmas_f32 v158, v158, v159, v161
	v_div_fixup_f32 v157, v158, s60, v157
	v_add_f32_e32 v182, 0xc0447cbd, v157
	v_mul_f32_e64 v154, |v182|, -v154
	v_mul_f32_e32 v154, 0x3fb8aa3b, v154
	v_exp_f32_e32 v154, v154
	v_mul_f32_e64 v147, |v182|, -v147
	v_mul_f32_e64 v153, |v182|, -v153
	v_mul_f32_e32 v147, 0x3fb8aa3b, v147
	v_mul_f32_e32 v153, 0x3fb8aa3b, v153
	v_mul_f32_e32 v160, v126, v154
	v_mul_f32_e64 v126, |v182|, -v155
	v_exp_f32_e32 v147, v147
	v_exp_f32_e32 v153, v153
	v_mul_f32_e32 v126, 0x3fb8aa3b, v126
	v_exp_f32_e32 v126, v126
	v_mul_f32_e32 v158, v124, v147
	v_mul_f32_e32 v159, v125, v153
	v_mov_b64_e32 v[124:125], s[92:93]
	v_mad_i64_i32 v[124:125], s[16:17], v156, s61, v[124:125]
	v_mul_f32_e32 v161, v127, v126
	v_or_b32_e32 v126, 16, v136
	v_lshl_add_u64 v[124:125], v[136:137], 2, v[124:125]
	v_cmp_lt_i32_e64 s[16:17], s1, v126
	v_add_u32_e32 v153, 0xfffff010, v136
	global_store_dwordx4 v[124:125], v[158:161], off
	s_and_saveexec_b64 s[18:19], s[16:17]
	s_xor_b64 s[18:19], exec, s[18:19]
	v_cvt_f32_u32_e32 v127, v153
	v_mul_f32_e32 v159, 0x3b808081, v127
	s_or_saveexec_b64 s[18:19], s[18:19]
	v_cvt_f32_i32_e32 v170, v126
	v_mul_f32_e32 v126, 0x39800801, v170
	s_xor_b64 exec, exec, s[18:19]
	v_mul_f32_e32 v159, 0x39800801, v170
	s_or_b64 exec, exec, s[18:19]
	v_or_b32_e32 v127, 17, v136
	v_cmp_lt_i32_e64 s[18:19], s1, v127
	v_add_u32_e32 v155, 0xfffff011, v136
	s_and_saveexec_b64 s[20:21], s[18:19]
	s_xor_b64 s[20:21], exec, s[20:21]
	v_cvt_f32_u32_e32 v147, v155
	v_mul_f32_e32 v160, 0x3b808081, v147
	s_or_saveexec_b64 s[20:21], s[20:21]
	v_cvt_f32_i32_e32 v171, v127
	v_mul_f32_e32 v127, 0x39800801, v171
	s_xor_b64 exec, exec, s[20:21]
	v_mul_f32_e32 v160, 0x39800801, v171
	s_or_b64 exec, exec, s[20:21]
	v_or_b32_e32 v147, 18, v136
	v_cmp_lt_i32_e64 s[20:21], s1, v147
	v_add_u32_e32 v157, 0xfffff012, v136
	s_and_saveexec_b64 s[22:23], s[20:21]
	s_xor_b64 s[22:23], exec, s[22:23]
	v_cvt_f32_u32_e32 v154, v157
	v_mul_f32_e32 v161, 0x3b808081, v154
	s_or_saveexec_b64 s[22:23], s[22:23]
	v_cvt_f32_i32_e32 v172, v147
	v_mul_f32_e32 v147, 0x39800801, v172
	s_xor_b64 exec, exec, s[22:23]
	v_mul_f32_e32 v161, 0x39800801, v172
	s_or_b64 exec, exec, s[22:23]
	v_or_b32_e32 v154, 19, v136
	v_cmp_lt_i32_e64 s[22:23], s1, v154
	v_add_u32_e32 v158, 0xfffff013, v136
	s_and_saveexec_b64 s[24:25], s[22:23]
	s_xor_b64 s[24:25], exec, s[24:25]
	v_cvt_f32_u32_e32 v162, v158
	v_mul_f32_e32 v162, 0x3b808081, v162
	s_or_saveexec_b64 s[24:25], s[24:25]
	v_cvt_f32_i32_e32 v173, v154
	v_mul_f32_e32 v154, 0x39800801, v173
	s_xor_b64 exec, exec, s[24:25]
	v_mul_f32_e32 v162, 0x39800801, v173
	s_or_b64 exec, exec, s[24:25]
	v_mul_f32_e64 v159, |v182|, -v159
	v_mul_f32_e64 v160, |v182|, -v160
	v_mul_f32_e64 v161, |v182|, -v161
	v_mul_f32_e64 v162, |v182|, -v162
	v_mul_f32_e32 v159, 0x3fb8aa3b, v159
	v_mul_f32_e32 v160, 0x3fb8aa3b, v160
	v_mul_f32_e32 v161, 0x3fb8aa3b, v161
	v_mul_f32_e32 v162, 0x3fb8aa3b, v162
	v_exp_f32_e32 v159, v159
	v_exp_f32_e32 v160, v160
	v_exp_f32_e32 v161, v161
	v_exp_f32_e32 v162, v162
	v_mul_f32_e32 v120, v120, v159
	v_mul_f32_e32 v121, v121, v160
	v_mul_f32_e32 v122, v122, v161
	v_mul_f32_e32 v123, v123, v162
	global_store_dwordx4 v[124:125], v[120:123], off offset:64
	s_nop 1
	v_or_b32_e32 v120, 0x80, v136
	v_cmp_lt_i32_e64 s[24:25], s1, v120
	v_add_u32_e32 v123, 0xfffff080, v136
	s_and_saveexec_b64 s[26:27], s[24:25]
	s_xor_b64 s[26:27], exec, s[26:27]
	v_cvt_f32_u32_e32 v121, v123
	v_mul_f32_e32 v163, 0x3b808081, v121
	s_or_saveexec_b64 s[26:27], s[26:27]
	v_cvt_f32_i32_e32 v174, v120
	v_mul_f32_e32 v120, 0x39800801, v174
	s_xor_b64 exec, exec, s[26:27]
	v_mul_f32_e32 v163, 0x39800801, v174
	s_or_b64 exec, exec, s[26:27]
	v_or_b32_e32 v121, 0x81, v136
	v_cmp_lt_i32_e64 s[26:27], s1, v121
	v_add_u32_e32 v160, 0xfffff081, v136
	s_and_saveexec_b64 s[28:29], s[26:27]
	s_xor_b64 s[28:29], exec, s[28:29]
	v_cvt_f32_u32_e32 v122, v160
	v_mul_f32_e32 v164, 0x3b808081, v122
	s_or_saveexec_b64 s[28:29], s[28:29]
	v_cvt_f32_i32_e32 v175, v121
	v_mul_f32_e32 v121, 0x39800801, v175
	s_xor_b64 exec, exec, s[28:29]
	v_mul_f32_e32 v164, 0x39800801, v175
	s_or_b64 exec, exec, s[28:29]
	v_or_b32_e32 v122, 0x82, v136
	v_cmp_lt_i32_e64 s[28:29], s1, v122
	v_add_u32_e32 v161, 0xfffff082, v136
	s_and_saveexec_b64 s[30:31], s[28:29]
	s_xor_b64 s[30:31], exec, s[30:31]
	v_cvt_f32_u32_e32 v159, v161
	v_mul_f32_e32 v165, 0x3b808081, v159
	s_or_saveexec_b64 s[30:31], s[30:31]
	v_cvt_f32_i32_e32 v176, v122
	v_mul_f32_e32 v122, 0x39800801, v176
	s_xor_b64 exec, exec, s[30:31]
	v_mul_f32_e32 v165, 0x39800801, v176
	s_or_b64 exec, exec, s[30:31]
	v_or_b32_e32 v159, 0x83, v136
	v_cmp_lt_i32_e64 s[30:31], s1, v159
	v_add_u32_e32 v162, 0xfffff083, v136
	s_and_saveexec_b64 s[34:35], s[30:31]
	s_xor_b64 s[34:35], exec, s[34:35]
	v_cvt_f32_u32_e32 v166, v162
	v_mul_f32_e32 v166, 0x3b808081, v166
	s_or_saveexec_b64 s[34:35], s[34:35]
	v_cvt_f32_i32_e32 v177, v159
	v_mul_f32_e32 v159, 0x39800801, v177
	s_xor_b64 exec, exec, s[34:35]
	v_mul_f32_e32 v166, 0x39800801, v177
	s_or_b64 exec, exec, s[34:35]
	v_mul_f32_e64 v163, |v182|, -v163
	v_mul_f32_e64 v164, |v182|, -v164
	v_mul_f32_e64 v165, |v182|, -v165
	v_mul_f32_e64 v166, |v182|, -v166
	v_mul_f32_e32 v163, 0x3fb8aa3b, v163
	v_mul_f32_e32 v164, 0x3fb8aa3b, v164
	v_mul_f32_e32 v165, 0x3fb8aa3b, v165
	v_mul_f32_e32 v166, 0x3fb8aa3b, v166
	v_exp_f32_e32 v163, v163
	v_exp_f32_e32 v164, v164
	v_exp_f32_e32 v165, v165
	v_exp_f32_e32 v166, v166
	v_mul_f32_e32 v116, v116, v163
	v_mul_f32_e32 v117, v117, v164
	v_mul_f32_e32 v118, v118, v165
	v_mul_f32_e32 v119, v119, v166
	global_store_dwordx4 v[124:125], v[116:119], off offset:512
	s_nop 1
	v_or_b32_e32 v116, 0x90, v136
	v_cmp_lt_i32_e64 s[34:35], s1, v116
	v_add_u32_e32 v119, 0xfffff090, v136
	s_and_saveexec_b64 s[36:37], s[34:35]
	s_xor_b64 s[36:37], exec, s[36:37]
	v_cvt_f32_u32_e32 v117, v119
	v_mul_f32_e32 v183, 0x3b808081, v117
	s_or_saveexec_b64 s[36:37], s[36:37]
	v_cvt_f32_i32_e32 v178, v116
	v_mul_f32_e32 v116, 0x39800801, v178
	s_xor_b64 exec, exec, s[36:37]
	v_mul_f32_e32 v183, 0x39800801, v178
	s_or_b64 exec, exec, s[36:37]
	v_or_b32_e32 v117, 0x91, v136
	v_cmp_lt_i32_e64 s[36:37], s1, v117
	v_add_u32_e32 v164, 0xfffff091, v136
	s_and_saveexec_b64 s[38:39], s[36:37]
	s_xor_b64 s[38:39], exec, s[38:39]
	v_cvt_f32_u32_e32 v118, v164
	v_mul_f32_e32 v184, 0x3b808081, v118
	s_or_saveexec_b64 s[38:39], s[38:39]
	v_cvt_f32_i32_e32 v179, v117
	v_mul_f32_e32 v117, 0x39800801, v179
	s_xor_b64 exec, exec, s[38:39]
	v_mul_f32_e32 v184, 0x39800801, v179
	s_or_b64 exec, exec, s[38:39]
	v_or_b32_e32 v118, 0x92, v136
	v_cmp_lt_i32_e64 s[38:39], s1, v118
	v_add_u32_e32 v165, 0xfffff092, v136
	s_and_saveexec_b64 s[40:41], s[38:39]
	s_xor_b64 s[40:41], exec, s[40:41]
	v_cvt_f32_u32_e32 v163, v165
	v_mul_f32_e32 v185, 0x3b808081, v163
	s_or_saveexec_b64 s[40:41], s[40:41]
	v_cvt_f32_i32_e32 v180, v118
	v_mul_f32_e32 v118, 0x39800801, v180
	s_xor_b64 exec, exec, s[40:41]
	v_mul_f32_e32 v185, 0x39800801, v180
	s_or_b64 exec, exec, s[40:41]
	v_or_b32_e32 v163, 0x93, v136
	v_cmp_lt_i32_e64 s[40:41], s1, v163
	v_add_u32_e32 v166, 0xfffff093, v136
	s_and_saveexec_b64 s[72:73], s[40:41]
	s_xor_b64 s[72:73], exec, s[72:73]
	v_cvt_f32_u32_e32 v181, v166
	v_mul_f32_e32 v186, 0x3b808081, v181
	s_or_saveexec_b64 s[72:73], s[72:73]
	v_cvt_f32_i32_e32 v181, v163
	v_mul_f32_e32 v163, 0x39800801, v181
	s_xor_b64 exec, exec, s[72:73]
	v_mul_f32_e32 v186, 0x39800801, v181
	s_or_b64 exec, exec, s[72:73]
	v_mul_f32_e64 v183, |v182|, -v183
	v_mul_f32_e64 v184, |v182|, -v184
	v_mul_f32_e64 v185, |v182|, -v185
	v_mul_f32_e64 v182, |v182|, -v186
	v_mul_f32_e32 v183, 0x3fb8aa3b, v183
	v_mul_f32_e32 v184, 0x3fb8aa3b, v184
	v_mul_f32_e32 v185, 0x3fb8aa3b, v185
	v_mul_f32_e32 v182, 0x3fb8aa3b, v182
	v_exp_f32_e32 v183, v183
	v_exp_f32_e32 v184, v184
	v_exp_f32_e32 v185, v185
	v_exp_f32_e32 v182, v182
	v_mul_f32_e32 v112, v112, v183
	v_mul_f32_e32 v113, v113, v184
	v_mul_f32_e32 v114, v114, v185
	v_mul_f32_e32 v115, v115, v182
	global_store_dwordx4 v[124:125], v[112:115], off offset:576
	s_and_saveexec_b64 s[72:73], s[8:9]
	s_xor_b64 s[72:73], exec, s[72:73]
	s_cbranch_execz .LBB0_991
	v_cvt_f32_u32_e32 v112, v148
	v_mul_f32_e32 v113, 0x3b808081, v112
	s_andn2_saveexec_b64 s[72:73], s[72:73]
	s_branch .LBB0_992

.LBB0_1417:
	ds_read_b128 v[140:143], v151
	ds_read_b128 v[144:147], v151 offset:1024
	ds_read_b128 v[154:157], v151 offset:2048
	ds_read_b128 v[158:161], v151 offset:3072
	s_add_u32 s22, s20, 0x100
	s_addc_u32 s23, s21, 0
	s_cmp_eq_u32 s46, 28
	s_cselect_b32 s27, s13, s23
	s_cselect_b32 s26, s40, s22
	s_cselect_b32 s25, s11, s43
	s_cselect_b32 s24, s41, s42
	v_lshl_add_u64 v[194:195], s[20:21], 0, v[132:133]
	s_add_i32 m0, s5, 0xc000
	ds_read_b128 v[162:165], v152
	ds_read_b128 v[166:169], v152 offset:1024
	ds_read_b128 v[170:173], v152 offset:2048
	ds_read_b128 v[174:177], v152 offset:3072
	ds_read_b128 v[178:181], v152 offset:4096
	ds_read_b128 v[182:185], v152 offset:5120
	ds_read_b128 v[186:189], v152 offset:6144
	ds_read_b128 v[190:193], v152 offset:7168
	global_load_lds_dwordx4 v[194:195], off
	v_lshl_add_u64 v[194:195], s[20:21], 0, v[134:135]
	s_add_i32 m0, s5, 0xe000
	s_nop 0
	global_load_lds_dwordx4 v[194:195], off
	s_waitcnt lgkmcnt(8)
	s_barrier
	s_waitcnt lgkmcnt(0)
	s_waitcnt lgkmcnt(0)
	v_mfma_f32_16x16x32_bf16 v[124:127], v[140:143], v[162:165], v[124:127]
	v_mfma_f32_16x16x32_bf16 v[120:123], v[154:157], v[162:165], v[120:123]
	v_mfma_f32_16x16x32_bf16 v[108:111], v[140:143], v[170:173], v[108:111]
	v_mfma_f32_16x16x32_bf16 v[104:107], v[154:157], v[170:173], v[104:107]
	v_mfma_f32_16x16x32_bf16 v[92:95], v[140:143], v[178:181], v[92:95]
	v_mfma_f32_16x16x32_bf16 v[88:91], v[154:157], v[178:181], v[88:91]
	v_mfma_f32_16x16x32_bf16 v[76:79], v[140:143], v[186:189], v[76:79]
	v_mfma_f32_16x16x32_bf16 v[72:75], v[154:157], v[186:189], v[72:75]
	v_mfma_f32_16x16x32_bf16 v[124:127], v[144:147], v[166:169], v[124:127]
	v_mfma_f32_16x16x32_bf16 v[120:123], v[158:161], v[166:169], v[120:123]
	v_mfma_f32_16x16x32_bf16 v[108:111], v[144:147], v[174:177], v[108:111]
	v_mfma_f32_16x16x32_bf16 v[104:107], v[158:161], v[174:177], v[104:107]
	v_mfma_f32_16x16x32_bf16 v[92:95], v[144:147], v[182:185], v[92:95]
	v_mfma_f32_16x16x32_bf16 v[88:91], v[158:161], v[182:185], v[88:91]
	v_mfma_f32_16x16x32_bf16 v[76:79], v[144:147], v[190:193], v[76:79]
	v_mfma_f32_16x16x32_bf16 v[72:75], v[158:161], v[190:193], v[72:75]
	s_barrier
	s_add_i32 s20, s36, s2
	v_lshl_add_u64 v[210:211], s[24:25], 0, v[130:131]
	s_mov_b32 m0, s20
	ds_read_b128 v[194:197], v153
	ds_read_b128 v[198:201], v153 offset:1024
	ds_read_b128 v[202:205], v153 offset:2048
	ds_read_b128 v[206:209], v153 offset:3072
	global_load_lds_dwordx4 v[210:211], off
	v_lshl_add_u64 v[212:213], s[24:25], 0, v[128:129]
	s_add_i32 m0, s20, 0x2000
	s_nop 0
	global_load_lds_dwordx4 v[212:213], off
	s_barrier
	s_waitcnt lgkmcnt(0)
	s_waitcnt lgkmcnt(0)
	v_mfma_f32_16x16x32_bf16 v[116:119], v[194:197], v[162:165], v[116:119]
	v_mfma_f32_16x16x32_bf16 v[112:115], v[202:205], v[162:165], v[112:115]
	v_mfma_f32_16x16x32_bf16 v[100:103], v[194:197], v[170:173], v[100:103]
	v_mfma_f32_16x16x32_bf16 v[96:99], v[202:205], v[170:173], v[96:99]
	v_mfma_f32_16x16x32_bf16 v[84:87], v[194:197], v[178:181], v[84:87]
	v_mfma_f32_16x16x32_bf16 v[80:83], v[202:205], v[178:181], v[80:83]
	v_mfma_f32_16x16x32_bf16 v[68:71], v[194:197], v[186:189], v[68:71]
	v_mfma_f32_16x16x32_bf16 v[64:67], v[202:205], v[186:189], v[64:67]
	v_mfma_f32_16x16x32_bf16 v[116:119], v[198:201], v[166:169], v[116:119]
	v_mfma_f32_16x16x32_bf16 v[112:115], v[206:209], v[166:169], v[112:115]
	v_mfma_f32_16x16x32_bf16 v[100:103], v[198:201], v[174:177], v[100:103]
	v_mfma_f32_16x16x32_bf16 v[96:99], v[206:209], v[174:177], v[96:99]
	v_mfma_f32_16x16x32_bf16 v[84:87], v[198:201], v[182:185], v[84:87]
	v_mfma_f32_16x16x32_bf16 v[80:83], v[206:209], v[182:185], v[80:83]
	v_mfma_f32_16x16x32_bf16 v[68:71], v[198:201], v[190:193], v[68:71]
	v_mfma_f32_16x16x32_bf16 v[64:67], v[206:209], v[190:193], v[64:67]
	s_mov_b32 m0, s5
	v_lshl_add_u64 v[214:215], s[26:27], 0, v[130:131]
	s_barrier
	ds_read_b128 v[162:165], v152 offset:16384
	ds_read_b128 v[166:169], v152 offset:17408
	ds_read_b128 v[170:173], v152 offset:18432
	ds_read_b128 v[174:177], v152 offset:19456
	ds_read_b128 v[178:181], v152 offset:20480
	ds_read_b128 v[182:185], v152 offset:21504
	ds_read_b128 v[186:189], v152 offset:22528
	ds_read_b128 v[190:193], v152 offset:23552
	global_load_lds_dwordx4 v[214:215], off
	v_lshl_add_u64 v[216:217], s[26:27], 0, v[128:129]
	s_mov_b32 m0, s19
	s_nop 0
	global_load_lds_dwordx4 v[216:217], off
	s_barrier
	s_waitcnt lgkmcnt(0)
	s_waitcnt lgkmcnt(0)
	v_mfma_f32_16x16x32_bf16 v[60:63], v[140:143], v[162:165], v[60:63]
	v_mfma_f32_16x16x32_bf16 v[56:59], v[154:157], v[162:165], v[56:59]
	v_mfma_f32_16x16x32_bf16 v[44:47], v[140:143], v[170:173], v[44:47]
	v_mfma_f32_16x16x32_bf16 v[40:43], v[154:157], v[170:173], v[40:43]
	v_mfma_f32_16x16x32_bf16 v[28:31], v[140:143], v[178:181], v[28:31]
	v_mfma_f32_16x16x32_bf16 v[24:27], v[154:157], v[178:181], v[24:27]
	v_mfma_f32_16x16x32_bf16 v[12:15], v[140:143], v[186:189], v[12:15]
	v_mfma_f32_16x16x32_bf16 v[8:11], v[154:157], v[186:189], v[8:11]
	v_mfma_f32_16x16x32_bf16 v[60:63], v[144:147], v[166:169], v[60:63]
	v_mfma_f32_16x16x32_bf16 v[56:59], v[158:161], v[166:169], v[56:59]
	v_mfma_f32_16x16x32_bf16 v[44:47], v[144:147], v[174:177], v[44:47]
	v_mfma_f32_16x16x32_bf16 v[40:43], v[158:161], v[174:177], v[40:43]
	v_mfma_f32_16x16x32_bf16 v[28:31], v[144:147], v[182:185], v[28:31]
	v_mfma_f32_16x16x32_bf16 v[24:27], v[158:161], v[182:185], v[24:27]
	v_mfma_f32_16x16x32_bf16 v[12:15], v[144:147], v[190:193], v[12:15]
	v_mfma_f32_16x16x32_bf16 v[8:11], v[158:161], v[190:193], v[8:11]
	s_barrier
	s_add_u32 s20, s24, 0x80000
	s_addc_u32 s21, s25, 0
	s_add_i32 s47, s37, s2
	v_lshl_add_u64 v[140:141], s[20:21], 0, v[130:131]
	s_mov_b32 m0, s47
	s_nop 0
	global_load_lds_dwordx4 v[140:141], off
	v_lshl_add_u64 v[140:141], s[20:21], 0, v[128:129]
	s_add_i32 m0, s47, 0x2000
	s_nop 0
	global_load_lds_dwordx4 v[140:141], off
	s_waitcnt vmcnt(6)
	s_barrier
	v_mfma_f32_16x16x32_bf16 v[52:55], v[194:197], v[162:165], v[52:55]
	v_mfma_f32_16x16x32_bf16 v[48:51], v[202:205], v[162:165], v[48:51]
	v_mfma_f32_16x16x32_bf16 v[36:39], v[194:197], v[170:173], v[36:39]
	v_mfma_f32_16x16x32_bf16 v[32:35], v[202:205], v[170:173], v[32:35]
	v_mfma_f32_16x16x32_bf16 v[20:23], v[194:197], v[178:181], v[20:23]
	v_mfma_f32_16x16x32_bf16 v[16:19], v[202:205], v[178:181], v[16:19]
	v_mfma_f32_16x16x32_bf16 v[4:7], v[194:197], v[186:189], v[4:7]
	v_mfma_f32_16x16x32_bf16 v[0:3], v[202:205], v[186:189], v[0:3]
	v_mfma_f32_16x16x32_bf16 v[52:55], v[198:201], v[166:169], v[52:55]
	v_mfma_f32_16x16x32_bf16 v[48:51], v[206:209], v[166:169], v[48:51]
	v_mfma_f32_16x16x32_bf16 v[36:39], v[198:201], v[174:177], v[36:39]
	v_mfma_f32_16x16x32_bf16 v[32:35], v[206:209], v[174:177], v[32:35]
	v_mfma_f32_16x16x32_bf16 v[20:23], v[198:201], v[182:185], v[20:23]
	v_mfma_f32_16x16x32_bf16 v[16:19], v[206:209], v[182:185], v[16:19]
	v_mfma_f32_16x16x32_bf16 v[4:7], v[198:201], v[190:193], v[4:7]
	v_mfma_f32_16x16x32_bf16 v[0:3], v[206:209], v[190:193], v[0:3]
	s_add_i32 s47, 0, 0x18000
	v_add_u32_e32 v158, s47, v149
	s_barrier
	ds_read_b128 v[140:143], v158
	ds_read_b128 v[144:147], v158 offset:1024
	ds_read_b128 v[154:157], v158 offset:2048
	ds_read_b128 v[158:161], v158 offset:3072
	s_add_u32 s20, s26, 0x80000
	s_addc_u32 s21, s27, 0
	s_mov_b32 m0, s28
	v_lshl_add_u64 v[194:195], s[20:21], 0, v[130:131]
	ds_read_b128 v[162:165], v152 offset:32768
	ds_read_b128 v[166:169], v152 offset:33792
	ds_read_b128 v[170:173], v152 offset:34816
	ds_read_b128 v[174:177], v152 offset:35840
	ds_read_b128 v[178:181], v152 offset:36864
	ds_read_b128 v[182:185], v152 offset:37888
	ds_read_b128 v[186:189], v152 offset:38912
	ds_read_b128 v[190:193], v152 offset:39936
	global_load_lds_dwordx4 v[194:195], off
	v_lshl_add_u64 v[194:195], s[20:21], 0, v[128:129]
	s_mov_b32 m0, s29
	s_nop 0
	global_load_lds_dwordx4 v[194:195], off
	s_waitcnt lgkmcnt(8)
	s_barrier
	s_waitcnt lgkmcnt(0)
	s_waitcnt lgkmcnt(0)
	v_mfma_f32_16x16x32_bf16 v[124:127], v[140:143], v[162:165], v[124:127]
	v_mfma_f32_16x16x32_bf16 v[120:123], v[154:157], v[162:165], v[120:123]
	v_mfma_f32_16x16x32_bf16 v[108:111], v[140:143], v[170:173], v[108:111]
	v_mfma_f32_16x16x32_bf16 v[104:107], v[154:157], v[170:173], v[104:107]
	v_mfma_f32_16x16x32_bf16 v[92:95], v[140:143], v[178:181], v[92:95]
	v_mfma_f32_16x16x32_bf16 v[88:91], v[154:157], v[178:181], v[88:91]
	v_mfma_f32_16x16x32_bf16 v[76:79], v[140:143], v[186:189], v[76:79]
	v_mfma_f32_16x16x32_bf16 v[72:75], v[154:157], v[186:189], v[72:75]
	v_mfma_f32_16x16x32_bf16 v[124:127], v[144:147], v[166:169], v[124:127]
	v_mfma_f32_16x16x32_bf16 v[120:123], v[158:161], v[166:169], v[120:123]
	v_mfma_f32_16x16x32_bf16 v[108:111], v[144:147], v[174:177], v[108:111]
	v_mfma_f32_16x16x32_bf16 v[104:107], v[158:161], v[174:177], v[104:107]
	v_mfma_f32_16x16x32_bf16 v[92:95], v[144:147], v[182:185], v[92:95]
	v_mfma_f32_16x16x32_bf16 v[88:91], v[158:161], v[182:185], v[88:91]
	v_mfma_f32_16x16x32_bf16 v[76:79], v[144:147], v[190:193], v[76:79]
	v_mfma_f32_16x16x32_bf16 v[72:75], v[158:161], v[190:193], v[72:75]
	s_barrier
	s_add_i32 s26, 0, 0x1c000
	s_add_i32 s20, s47, s2
	v_add_u32_e32 v206, s26, v149
	v_lshl_add_u64 v[210:211], v[210:211], 0, s[8:9]
	s_mov_b32 m0, s20
	ds_read_b128 v[194:197], v206
	ds_read_b128 v[198:201], v206 offset:1024
	ds_read_b128 v[202:205], v206 offset:2048
	ds_read_b128 v[206:209], v206 offset:3072
	global_load_lds_dwordx4 v[210:211], off
	v_lshl_add_u64 v[210:211], v[212:213], 0, s[8:9]
	s_add_i32 m0, s20, 0x2000
	s_nop 0
	global_load_lds_dwordx4 v[210:211], off
	s_barrier
	s_waitcnt lgkmcnt(0)
	s_waitcnt lgkmcnt(0)
	v_mfma_f32_16x16x32_bf16 v[116:119], v[194:197], v[162:165], v[116:119]
	v_mfma_f32_16x16x32_bf16 v[112:115], v[202:205], v[162:165], v[112:115]
	v_mfma_f32_16x16x32_bf16 v[100:103], v[194:197], v[170:173], v[100:103]
	v_mfma_f32_16x16x32_bf16 v[96:99], v[202:205], v[170:173], v[96:99]
	v_mfma_f32_16x16x32_bf16 v[84:87], v[194:197], v[178:181], v[84:87]
	v_mfma_f32_16x16x32_bf16 v[80:83], v[202:205], v[178:181], v[80:83]
	v_mfma_f32_16x16x32_bf16 v[68:71], v[194:197], v[186:189], v[68:71]
	v_mfma_f32_16x16x32_bf16 v[64:67], v[202:205], v[186:189], v[64:67]
	v_mfma_f32_16x16x32_bf16 v[116:119], v[198:201], v[166:169], v[116:119]
	v_mfma_f32_16x16x32_bf16 v[112:115], v[206:209], v[166:169], v[112:115]
	v_mfma_f32_16x16x32_bf16 v[100:103], v[198:201], v[174:177], v[100:103]
	v_mfma_f32_16x16x32_bf16 v[96:99], v[206:209], v[174:177], v[96:99]
	v_mfma_f32_16x16x32_bf16 v[84:87], v[198:201], v[182:185], v[84:87]
	v_mfma_f32_16x16x32_bf16 v[80:83], v[206:209], v[182:185], v[80:83]
	v_mfma_f32_16x16x32_bf16 v[68:71], v[198:201], v[190:193], v[68:71]
	v_mfma_f32_16x16x32_bf16 v[64:67], v[206:209], v[190:193], v[64:67]
	s_mov_b32 m0, s31
	v_lshl_add_u64 v[210:211], v[214:215], 0, s[8:9]
	s_barrier
	ds_read_b128 v[162:165], v152 offset:49152
	ds_read_b128 v[166:169], v152 offset:50176
	ds_read_b128 v[170:173], v152 offset:51200
	ds_read_b128 v[174:177], v152 offset:52224
	ds_read_b128 v[178:181], v152 offset:53248
	ds_read_b128 v[182:185], v152 offset:54272
	ds_read_b128 v[186:189], v152 offset:55296
	ds_read_b128 v[190:193], v152 offset:56320
	global_load_lds_dwordx4 v[210:211], off
	v_lshl_add_u64 v[210:211], v[216:217], 0, s[8:9]
	s_mov_b32 m0, s34
	s_nop 0
	global_load_lds_dwordx4 v[210:211], off
	s_barrier
	s_waitcnt lgkmcnt(0)
	s_waitcnt lgkmcnt(0)
	v_mfma_f32_16x16x32_bf16 v[60:63], v[140:143], v[162:165], v[60:63]
	v_mfma_f32_16x16x32_bf16 v[56:59], v[154:157], v[162:165], v[56:59]
	v_mfma_f32_16x16x32_bf16 v[44:47], v[140:143], v[170:173], v[44:47]
	v_mfma_f32_16x16x32_bf16 v[40:43], v[154:157], v[170:173], v[40:43]
	v_mfma_f32_16x16x32_bf16 v[28:31], v[140:143], v[178:181], v[28:31]
	v_mfma_f32_16x16x32_bf16 v[24:27], v[154:157], v[178:181], v[24:27]
	v_mfma_f32_16x16x32_bf16 v[12:15], v[140:143], v[186:189], v[12:15]
	v_mfma_f32_16x16x32_bf16 v[8:11], v[154:157], v[186:189], v[8:11]
	v_mfma_f32_16x16x32_bf16 v[60:63], v[144:147], v[166:169], v[60:63]
	v_mfma_f32_16x16x32_bf16 v[56:59], v[158:161], v[166:169], v[56:59]
	v_mfma_f32_16x16x32_bf16 v[44:47], v[144:147], v[174:177], v[44:47]
	v_mfma_f32_16x16x32_bf16 v[40:43], v[158:161], v[174:177], v[40:43]
	v_mfma_f32_16x16x32_bf16 v[28:31], v[144:147], v[182:185], v[28:31]
	v_mfma_f32_16x16x32_bf16 v[24:27], v[158:161], v[182:185], v[24:27]
	v_mfma_f32_16x16x32_bf16 v[12:15], v[144:147], v[190:193], v[12:15]
	v_mfma_f32_16x16x32_bf16 v[8:11], v[158:161], v[190:193], v[8:11]
	s_barrier
	s_add_u32 s20, s24, 0x80080
	s_addc_u32 s21, s25, 0
	s_add_i32 s24, s26, s2
	v_lshl_add_u64 v[140:141], s[20:21], 0, v[130:131]
	s_mov_b32 m0, s24
	s_nop 0
	global_load_lds_dwordx4 v[140:141], off
	v_lshl_add_u64 v[140:141], s[20:21], 0, v[128:129]
	s_add_i32 m0, s24, 0x2000
	s_nop 0
	global_load_lds_dwordx4 v[140:141], off
	s_waitcnt vmcnt(6)
	s_barrier
	v_mfma_f32_16x16x32_bf16 v[52:55], v[194:197], v[162:165], v[52:55]
	v_mfma_f32_16x16x32_bf16 v[48:51], v[202:205], v[162:165], v[48:51]
	v_mfma_f32_16x16x32_bf16 v[36:39], v[194:197], v[170:173], v[36:39]
	v_mfma_f32_16x16x32_bf16 v[32:35], v[202:205], v[170:173], v[32:35]
	v_mfma_f32_16x16x32_bf16 v[20:23], v[194:197], v[178:181], v[20:23]
	v_mfma_f32_16x16x32_bf16 v[16:19], v[202:205], v[178:181], v[16:19]
	v_mfma_f32_16x16x32_bf16 v[4:7], v[194:197], v[186:189], v[4:7]
	v_mfma_f32_16x16x32_bf16 v[0:3], v[202:205], v[186:189], v[0:3]
	v_mfma_f32_16x16x32_bf16 v[52:55], v[198:201], v[166:169], v[52:55]
	v_mfma_f32_16x16x32_bf16 v[48:51], v[206:209], v[166:169], v[48:51]
	v_mfma_f32_16x16x32_bf16 v[36:39], v[198:201], v[174:177], v[36:39]
	v_mfma_f32_16x16x32_bf16 v[32:35], v[206:209], v[174:177], v[32:35]
	v_mfma_f32_16x16x32_bf16 v[20:23], v[198:201], v[182:185], v[20:23]
	v_mfma_f32_16x16x32_bf16 v[16:19], v[206:209], v[182:185], v[16:19]
	v_mfma_f32_16x16x32_bf16 v[4:7], v[198:201], v[190:193], v[4:7]
	v_mfma_f32_16x16x32_bf16 v[0:3], v[206:209], v[190:193], v[0:3]
	s_add_i32 s46, s46, 2
	s_add_u32 s42, s42, 0x100
	s_addc_u32 s43, s43, 0
	s_cmp_gt_u32 s46, 29
	s_mov_b64 s[20:21], s[22:23]
	s_barrier
	s_cbranch_scc0 .LBB0_1417
	v_lshl_or_b32 v144, s39, 8, v150
	v_lshl_add_u32 v140, s18, 8, v148
	v_ashrrev_i32_e32 v145, 31, v144
	v_mov_b64_e32 v[142:143], s[52:53]
	v_readlane_b32 s60, v240, 49
	v_ashrrev_i32_e32 v141, 31, v140
	v_mad_i64_i32 v[146:147], s[20:21], v140, s38, v[142:143]
	v_lshlrev_b64 v[144:145], 2, v[144:145]
	v_readlane_b32 s72, v240, 61
	v_readlane_b32 s73, v240, 62
	v_lshl_add_u64 v[154:155], v[146:147], 0, v[144:145]
	s_and_b64 vcc, exec, s[6:7]
	v_lshl_add_u64 v[146:147], v[140:141], 2, s[72:73]
	global_load_dword v156, v[146:147], off
	s_mov_b32 s39, s10
	s_mov_b32 s18, s12
	s_mov_b64 s[22:23], s[16:17]
	v_readlane_b32 s61, v240, 50
	v_readlane_b32 s62, v240, 51
	v_readlane_b32 s63, v240, 52
	v_readlane_b32 s64, v240, 53
	v_readlane_b32 s65, v240, 54
	v_readlane_b32 s66, v240, 55
	v_readlane_b32 s67, v240, 56
	v_readlane_b32 s68, v240, 57
	v_readlane_b32 s69, v240, 58
	v_readlane_b32 s70, v240, 59
	v_readlane_b32 s71, v240, 60
	v_readlane_b32 s74, v240, 63
	v_readlane_b32 s75, v239, 0
	s_waitcnt vmcnt(0)
	v_pk_add_f32 v[126:127], v[126:127], v[156:157] op_sel_hi:[1,0]
	v_pk_add_f32 v[124:125], v[124:125], v[156:157] op_sel_hi:[1,0]
	v_pk_add_f32 v[122:123], v[122:123], v[156:157] op_sel_hi:[1,0]
	v_pk_add_f32 v[120:121], v[120:121], v[156:157] op_sel_hi:[1,0]
	v_pk_add_f32 v[118:119], v[118:119], v[156:157] op_sel_hi:[1,0]
	v_pk_add_f32 v[116:117], v[116:117], v[156:157] op_sel_hi:[1,0]
	v_pk_add_f32 v[114:115], v[114:115], v[156:157] op_sel_hi:[1,0]
	v_pk_add_f32 v[112:113], v[112:113], v[156:157] op_sel_hi:[1,0]
	global_store_dwordx4 v[154:155], v[124:127], off
	global_store_dwordx4 v[154:155], v[120:123], off offset:64
	global_store_dwordx4 v[154:155], v[116:119], off offset:512
	global_store_dwordx4 v[154:155], v[112:115], off offset:576
	global_load_dword v114, v[146:147], off offset:64
	s_waitcnt vmcnt(0)
	v_pk_add_f32 v[110:111], v[110:111], v[114:115] op_sel_hi:[1,0]
	v_or_b32_e32 v112, 16, v140
	v_mad_i64_i32 v[112:113], s[20:21], v112, s38, v[142:143]
	v_lshl_add_u64 v[112:113], v[112:113], 0, v[144:145]
	v_pk_add_f32 v[108:109], v[108:109], v[114:115] op_sel_hi:[1,0]
	v_pk_add_f32 v[106:107], v[106:107], v[114:115] op_sel_hi:[1,0]
	v_pk_add_f32 v[104:105], v[104:105], v[114:115] op_sel_hi:[1,0]
	v_pk_add_f32 v[102:103], v[102:103], v[114:115] op_sel_hi:[1,0]
	v_pk_add_f32 v[100:101], v[100:101], v[114:115] op_sel_hi:[1,0]
	v_pk_add_f32 v[98:99], v[98:99], v[114:115] op_sel_hi:[1,0]
	v_pk_add_f32 v[96:97], v[96:97], v[114:115] op_sel_hi:[1,0]
	global_store_dwordx4 v[112:113], v[108:111], off
	global_store_dwordx4 v[112:113], v[104:107], off offset:64
	global_store_dwordx4 v[112:113], v[100:103], off offset:512
	global_store_dwordx4 v[112:113], v[96:99], off offset:576
	global_load_dword v98, v[146:147], off offset:128
	s_waitcnt vmcnt(0)
	v_pk_add_f32 v[94:95], v[94:95], v[98:99] op_sel_hi:[1,0]
	v_or_b32_e32 v96, 32, v140
	v_mad_i64_i32 v[96:97], s[20:21], v96, s38, v[142:143]
	v_lshl_add_u64 v[96:97], v[96:97], 0, v[144:145]
	v_pk_add_f32 v[92:93], v[92:93], v[98:99] op_sel_hi:[1,0]
	v_pk_add_f32 v[90:91], v[90:91], v[98:99] op_sel_hi:[1,0]
	v_pk_add_f32 v[88:89], v[88:89], v[98:99] op_sel_hi:[1,0]
	v_pk_add_f32 v[86:87], v[86:87], v[98:99] op_sel_hi:[1,0]
	v_pk_add_f32 v[84:85], v[84:85], v[98:99] op_sel_hi:[1,0]
	v_pk_add_f32 v[82:83], v[82:83], v[98:99] op_sel_hi:[1,0]
	v_pk_add_f32 v[80:81], v[80:81], v[98:99] op_sel_hi:[1,0]
	global_store_dwordx4 v[96:97], v[92:95], off
	global_store_dwordx4 v[96:97], v[88:91], off offset:64
	global_store_dwordx4 v[96:97], v[84:87], off offset:512
	global_store_dwordx4 v[96:97], v[80:83], off offset:576
	global_load_dword v82, v[146:147], off offset:192
	s_waitcnt vmcnt(0)
	v_pk_add_f32 v[78:79], v[78:79], v[82:83] op_sel_hi:[1,0]
	v_or_b32_e32 v80, 48, v140
	v_mad_i64_i32 v[80:81], s[20:21], v80, s38, v[142:143]
	v_lshl_add_u64 v[80:81], v[80:81], 0, v[144:145]
	v_pk_add_f32 v[76:77], v[76:77], v[82:83] op_sel_hi:[1,0]
	v_pk_add_f32 v[74:75], v[74:75], v[82:83] op_sel_hi:[1,0]
	v_pk_add_f32 v[72:73], v[72:73], v[82:83] op_sel_hi:[1,0]
	v_pk_add_f32 v[70:71], v[70:71], v[82:83] op_sel_hi:[1,0]
	v_pk_add_f32 v[68:69], v[68:69], v[82:83] op_sel_hi:[1,0]
	v_pk_add_f32 v[66:67], v[66:67], v[82:83] op_sel_hi:[1,0]
	v_pk_add_f32 v[64:65], v[64:65], v[82:83] op_sel_hi:[1,0]
	global_store_dwordx4 v[80:81], v[76:79], off
	global_store_dwordx4 v[80:81], v[72:75], off offset:64
	global_store_dwordx4 v[80:81], v[68:71], off offset:512
	global_store_dwordx4 v[80:81], v[64:67], off offset:576
	global_load_dword v66, v[146:147], off offset:512
	s_waitcnt vmcnt(0)
	v_pk_add_f32 v[62:63], v[62:63], v[66:67] op_sel_hi:[1,0]
	v_add_u32_e32 v64, 0x80, v140
	v_mad_i64_i32 v[64:65], s[20:21], v64, s38, v[142:143]
	v_lshl_add_u64 v[64:65], v[64:65], 0, v[144:145]
	v_pk_add_f32 v[60:61], v[60:61], v[66:67] op_sel_hi:[1,0]
	v_pk_add_f32 v[58:59], v[58:59], v[66:67] op_sel_hi:[1,0]
	v_pk_add_f32 v[56:57], v[56:57], v[66:67] op_sel_hi:[1,0]
	v_pk_add_f32 v[54:55], v[54:55], v[66:67] op_sel_hi:[1,0]
	v_pk_add_f32 v[52:53], v[52:53], v[66:67] op_sel_hi:[1,0]
	v_pk_add_f32 v[50:51], v[50:51], v[66:67] op_sel_hi:[1,0]
	v_pk_add_f32 v[48:49], v[48:49], v[66:67] op_sel_hi:[1,0]
	global_store_dwordx4 v[64:65], v[60:63], off
	global_store_dwordx4 v[64:65], v[56:59], off offset:64
	global_store_dwordx4 v[64:65], v[52:55], off offset:512
	global_store_dwordx4 v[64:65], v[48:51], off offset:576
	global_load_dword v50, v[146:147], off offset:576
	s_waitcnt vmcnt(0)
	v_pk_add_f32 v[46:47], v[46:47], v[50:51] op_sel_hi:[1,0]
	v_add_u32_e32 v48, 0x90, v140
	v_mad_i64_i32 v[48:49], s[20:21], v48, s38, v[142:143]
	v_lshl_add_u64 v[48:49], v[48:49], 0, v[144:145]
	v_pk_add_f32 v[44:45], v[44:45], v[50:51] op_sel_hi:[1,0]
	v_pk_add_f32 v[42:43], v[42:43], v[50:51] op_sel_hi:[1,0]
	v_pk_add_f32 v[40:41], v[40:41], v[50:51] op_sel_hi:[1,0]
	v_pk_add_f32 v[38:39], v[38:39], v[50:51] op_sel_hi:[1,0]
	v_pk_add_f32 v[36:37], v[36:37], v[50:51] op_sel_hi:[1,0]
	v_pk_add_f32 v[34:35], v[34:35], v[50:51] op_sel_hi:[1,0]
	v_pk_add_f32 v[32:33], v[32:33], v[50:51] op_sel_hi:[1,0]
	global_store_dwordx4 v[48:49], v[44:47], off
	global_store_dwordx4 v[48:49], v[40:43], off offset:64
	global_store_dwordx4 v[48:49], v[36:39], off offset:512
	global_store_dwordx4 v[48:49], v[32:35], off offset:576
	global_load_dword v34, v[146:147], off offset:640
	s_waitcnt vmcnt(0)
	v_pk_add_f32 v[30:31], v[30:31], v[34:35] op_sel_hi:[1,0]
	v_add_u32_e32 v32, 0xa0, v140
	v_mad_i64_i32 v[32:33], s[20:21], v32, s38, v[142:143]
	v_lshl_add_u64 v[32:33], v[32:33], 0, v[144:145]
	v_pk_add_f32 v[28:29], v[28:29], v[34:35] op_sel_hi:[1,0]
	v_pk_add_f32 v[26:27], v[26:27], v[34:35] op_sel_hi:[1,0]
	v_pk_add_f32 v[24:25], v[24:25], v[34:35] op_sel_hi:[1,0]
	v_pk_add_f32 v[22:23], v[22:23], v[34:35] op_sel_hi:[1,0]
	v_pk_add_f32 v[20:21], v[20:21], v[34:35] op_sel_hi:[1,0]
	v_pk_add_f32 v[18:19], v[18:19], v[34:35] op_sel_hi:[1,0]
	v_pk_add_f32 v[16:17], v[16:17], v[34:35] op_sel_hi:[1,0]
	global_store_dwordx4 v[32:33], v[28:31], off
	global_store_dwordx4 v[32:33], v[24:27], off offset:64
	global_store_dwordx4 v[32:33], v[20:23], off offset:512
	global_store_dwordx4 v[32:33], v[16:19], off offset:576
	global_load_dword v18, v[146:147], off offset:704
	s_waitcnt vmcnt(0)
	v_pk_add_f32 v[14:15], v[14:15], v[18:19] op_sel_hi:[1,0]
	v_add_u32_e32 v16, 0xb0, v140
	v_mad_i64_i32 v[16:17], s[20:21], v16, s38, v[142:143]
	v_lshl_add_u64 v[16:17], v[16:17], 0, v[144:145]
	v_pk_add_f32 v[12:13], v[12:13], v[18:19] op_sel_hi:[1,0]
	v_pk_add_f32 v[10:11], v[10:11], v[18:19] op_sel_hi:[1,0]
	v_pk_add_f32 v[8:9], v[8:9], v[18:19] op_sel_hi:[1,0]
	v_pk_add_f32 v[6:7], v[6:7], v[18:19] op_sel_hi:[1,0]
	v_pk_add_f32 v[4:5], v[4:5], v[18:19] op_sel_hi:[1,0]
	v_pk_add_f32 v[2:3], v[2:3], v[18:19] op_sel_hi:[1,0]
	v_pk_add_f32 v[0:1], v[0:1], v[18:19] op_sel_hi:[1,0]
	s_mov_b64 s[20:21], s[14:15]
	global_store_dwordx4 v[16:17], v[12:15], off
	global_store_dwordx4 v[16:17], v[8:11], off offset:64
	global_store_dwordx4 v[16:17], v[4:7], off offset:512
	global_store_dwordx4 v[16:17], v[0:3], off offset:576
	s_cbranch_vccz .LBB0_1414
	s_waitcnt vmcnt(0)
	s_cmpk_gt_u32 s1, 0xff
	s_cbranch_scc1 .LBB0_1421
	s_barrier

.LBB0_1846:
	ds_read_b128 v[130:133], v159
	ds_read_b128 v[134:137], v159 offset:1024
	ds_read_b128 v[150:153], v159 offset:2048
	ds_read_b128 v[162:165], v159 offset:3072
	s_add_u32 s24, s8, 0x100
	s_addc_u32 s25, s9, 0
	s_cmp_eq_u32 s60, 28
	s_cselect_b32 s29, s17, s25
	s_cselect_b32 s28, s42, s24
	s_cselect_b32 s27, s15, s47
	s_cselect_b32 s26, s43, s46
	v_lshl_add_u64 v[116:117], s[8:9], 0, v[142:143]
	s_add_i32 m0, s4, 0xc000
	ds_read_b128 v[166:169], v160
	ds_read_b128 v[170:173], v160 offset:1024
	ds_read_b128 v[174:177], v160 offset:2048
	ds_read_b128 v[178:181], v160 offset:3072
	ds_read_b128 v[182:185], v160 offset:4096
	ds_read_b128 v[186:189], v160 offset:5120
	ds_read_b128 v[190:193], v160 offset:6144
	ds_read_b128 v[194:197], v160 offset:7168
	global_load_lds_dwordx4 v[116:117], off
	v_lshl_add_u64 v[116:117], s[8:9], 0, v[144:145]
	s_add_i32 m0, s4, 0xe000
	s_nop 0
	global_load_lds_dwordx4 v[116:117], off
	s_waitcnt lgkmcnt(8)
	s_barrier
	s_waitcnt lgkmcnt(0)
	s_waitcnt lgkmcnt(0)
	v_mfma_f32_16x16x32_bf16 v[126:129], v[130:133], v[166:169], v[126:129]
	v_mfma_f32_16x16x32_bf16 v[92:95], v[150:153], v[166:169], v[92:95]
	v_mfma_f32_16x16x32_bf16 v[122:125], v[130:133], v[174:177], v[122:125]
	v_mfma_f32_16x16x32_bf16 v[88:91], v[150:153], v[174:177], v[88:91]
	v_mfma_f32_16x16x32_bf16 v[116:119], v[130:133], v[182:185], v[118:121]
	v_mfma_f32_16x16x32_bf16 v[84:87], v[150:153], v[182:185], v[84:87]
	v_mfma_f32_16x16x32_bf16 v[112:115], v[130:133], v[190:193], v[112:115]
	v_mfma_f32_16x16x32_bf16 v[80:83], v[150:153], v[190:193], v[80:83]
	v_mfma_f32_16x16x32_bf16 v[126:129], v[134:137], v[170:173], v[126:129]
	v_mfma_f32_16x16x32_bf16 v[92:95], v[162:165], v[170:173], v[92:95]
	v_mfma_f32_16x16x32_bf16 v[122:125], v[134:137], v[178:181], v[122:125]
	v_mfma_f32_16x16x32_bf16 v[88:91], v[162:165], v[178:181], v[88:91]
	v_mfma_f32_16x16x32_bf16 v[116:119], v[134:137], v[186:189], v[116:119]
	v_mfma_f32_16x16x32_bf16 v[84:87], v[162:165], v[186:189], v[84:87]
	v_mfma_f32_16x16x32_bf16 v[112:115], v[134:137], v[194:197], v[112:115]
	v_mfma_f32_16x16x32_bf16 v[80:83], v[162:165], v[194:197], v[80:83]
	s_barrier
	s_add_i32 s8, s39, s3
	v_lshl_add_u64 v[154:155], s[26:27], 0, v[138:139]
	s_mov_b32 m0, s8
	ds_read_b128 v[198:201], v161
	ds_read_b128 v[202:205], v161 offset:1024
	ds_read_b128 v[206:209], v161 offset:2048
	ds_read_b128 v[210:213], v161 offset:3072
	global_load_lds_dwordx4 v[154:155], off
	v_lshl_add_u64 v[214:215], s[26:27], 0, v[140:141]
	s_add_i32 m0, s8, 0x2000
	s_nop 0
	global_load_lds_dwordx4 v[214:215], off
	s_barrier
	s_waitcnt lgkmcnt(0)
	s_waitcnt lgkmcnt(0)
	v_mfma_f32_16x16x32_bf16 v[60:63], v[198:201], v[166:169], v[60:63]
	v_mfma_f32_16x16x32_bf16 v[28:31], v[206:209], v[166:169], v[28:31]
	v_mfma_f32_16x16x32_bf16 v[56:59], v[198:201], v[174:177], v[56:59]
	v_mfma_f32_16x16x32_bf16 v[24:27], v[206:209], v[174:177], v[24:27]
	v_mfma_f32_16x16x32_bf16 v[52:55], v[198:201], v[182:185], v[52:55]
	v_mfma_f32_16x16x32_bf16 v[20:23], v[206:209], v[182:185], v[20:23]
	v_mfma_f32_16x16x32_bf16 v[48:51], v[198:201], v[190:193], v[48:51]
	v_mfma_f32_16x16x32_bf16 v[16:19], v[206:209], v[190:193], v[16:19]
	v_mfma_f32_16x16x32_bf16 v[60:63], v[202:205], v[170:173], v[60:63]
	v_mfma_f32_16x16x32_bf16 v[28:31], v[210:213], v[170:173], v[28:31]
	v_mfma_f32_16x16x32_bf16 v[56:59], v[202:205], v[178:181], v[56:59]
	v_mfma_f32_16x16x32_bf16 v[24:27], v[210:213], v[178:181], v[24:27]
	v_mfma_f32_16x16x32_bf16 v[52:55], v[202:205], v[186:189], v[52:55]
	v_mfma_f32_16x16x32_bf16 v[20:23], v[210:213], v[186:189], v[20:23]
	v_mfma_f32_16x16x32_bf16 v[48:51], v[202:205], v[194:197], v[48:51]
	v_mfma_f32_16x16x32_bf16 v[16:19], v[210:213], v[194:197], v[16:19]
	s_mov_b32 m0, s4
	v_lshl_add_u64 v[216:217], s[28:29], 0, v[138:139]
	s_barrier
	ds_read_b128 v[166:169], v160 offset:16384
	ds_read_b128 v[170:173], v160 offset:17408
	ds_read_b128 v[174:177], v160 offset:18432
	ds_read_b128 v[178:181], v160 offset:19456
	ds_read_b128 v[182:185], v160 offset:20480
	ds_read_b128 v[186:189], v160 offset:21504
	ds_read_b128 v[190:193], v160 offset:22528
	ds_read_b128 v[194:197], v160 offset:23552
	global_load_lds_dwordx4 v[216:217], off
	v_lshl_add_u64 v[218:219], s[28:29], 0, v[140:141]
	s_mov_b32 m0, s5
	s_nop 0
	global_load_lds_dwordx4 v[218:219], off
	s_barrier
	s_waitcnt lgkmcnt(0)
	s_waitcnt lgkmcnt(0)
	v_mfma_f32_16x16x32_bf16 v[108:111], v[130:133], v[166:169], v[108:111]
	v_mfma_f32_16x16x32_bf16 v[76:79], v[150:153], v[166:169], v[76:79]
	v_mfma_f32_16x16x32_bf16 v[104:107], v[130:133], v[174:177], v[104:107]
	v_mfma_f32_16x16x32_bf16 v[72:75], v[150:153], v[174:177], v[72:75]
	v_mfma_f32_16x16x32_bf16 v[100:103], v[130:133], v[182:185], v[100:103]
	v_mfma_f32_16x16x32_bf16 v[68:71], v[150:153], v[182:185], v[68:71]
	v_mfma_f32_16x16x32_bf16 v[96:99], v[130:133], v[190:193], v[96:99]
	v_mfma_f32_16x16x32_bf16 v[64:67], v[150:153], v[190:193], v[64:67]
	v_mfma_f32_16x16x32_bf16 v[108:111], v[134:137], v[170:173], v[108:111]
	v_mfma_f32_16x16x32_bf16 v[76:79], v[162:165], v[170:173], v[76:79]
	v_mfma_f32_16x16x32_bf16 v[104:107], v[134:137], v[178:181], v[104:107]
	v_mfma_f32_16x16x32_bf16 v[72:75], v[162:165], v[178:181], v[72:75]
	v_mfma_f32_16x16x32_bf16 v[100:103], v[134:137], v[186:189], v[100:103]
	v_mfma_f32_16x16x32_bf16 v[68:71], v[162:165], v[186:189], v[68:71]
	v_mfma_f32_16x16x32_bf16 v[96:99], v[134:137], v[194:197], v[96:99]
	v_mfma_f32_16x16x32_bf16 v[64:67], v[162:165], v[194:197], v[64:67]
	s_barrier
	s_add_u32 s8, s26, 0x80000
	s_addc_u32 s9, s27, 0
	s_add_i32 s61, s40, s3
	v_lshl_add_u64 v[120:121], s[8:9], 0, v[138:139]
	s_mov_b32 m0, s61
	s_nop 0
	global_load_lds_dwordx4 v[120:121], off
	v_lshl_add_u64 v[120:121], s[8:9], 0, v[140:141]
	s_add_i32 m0, s61, 0x2000
	s_nop 0
	global_load_lds_dwordx4 v[120:121], off
	s_waitcnt vmcnt(6)
	s_barrier
	v_mfma_f32_16x16x32_bf16 v[44:47], v[198:201], v[166:169], v[44:47]
	v_mfma_f32_16x16x32_bf16 v[12:15], v[206:209], v[166:169], v[12:15]
	v_mfma_f32_16x16x32_bf16 v[40:43], v[198:201], v[174:177], v[40:43]
	v_mfma_f32_16x16x32_bf16 v[8:11], v[206:209], v[174:177], v[8:11]
	v_mfma_f32_16x16x32_bf16 v[36:39], v[198:201], v[182:185], v[36:39]
	v_mfma_f32_16x16x32_bf16 v[4:7], v[206:209], v[182:185], v[4:7]
	v_mfma_f32_16x16x32_bf16 v[32:35], v[198:201], v[190:193], v[32:35]
	v_mfma_f32_16x16x32_bf16 v[0:3], v[206:209], v[190:193], v[0:3]
	v_mfma_f32_16x16x32_bf16 v[44:47], v[202:205], v[170:173], v[44:47]
	v_mfma_f32_16x16x32_bf16 v[12:15], v[210:213], v[170:173], v[12:15]
	v_mfma_f32_16x16x32_bf16 v[40:43], v[202:205], v[178:181], v[40:43]
	v_mfma_f32_16x16x32_bf16 v[8:11], v[210:213], v[178:181], v[8:11]
	v_mfma_f32_16x16x32_bf16 v[36:39], v[202:205], v[186:189], v[36:39]
	v_mfma_f32_16x16x32_bf16 v[4:7], v[210:213], v[186:189], v[4:7]
	v_mfma_f32_16x16x32_bf16 v[32:35], v[202:205], v[194:197], v[32:35]
	v_mfma_f32_16x16x32_bf16 v[0:3], v[210:213], v[194:197], v[0:3]
	s_add_i32 s61, 0, 0x18000
	v_add_u32_e32 v120, s61, v157
	s_barrier
	ds_read_b128 v[130:133], v120
	ds_read_b128 v[134:137], v120 offset:1024
	ds_read_b128 v[150:153], v120 offset:2048
	ds_read_b128 v[162:165], v120 offset:3072
	s_add_u32 s8, s28, 0x80000
	s_addc_u32 s9, s29, 0
	s_mov_b32 m0, s23
	v_lshl_add_u64 v[120:121], s[8:9], 0, v[138:139]
	ds_read_b128 v[166:169], v160 offset:32768
	ds_read_b128 v[170:173], v160 offset:33792
	ds_read_b128 v[174:177], v160 offset:34816
	ds_read_b128 v[178:181], v160 offset:35840
	ds_read_b128 v[182:185], v160 offset:36864
	ds_read_b128 v[186:189], v160 offset:37888
	ds_read_b128 v[190:193], v160 offset:38912
	ds_read_b128 v[194:197], v160 offset:39936
	global_load_lds_dwordx4 v[120:121], off
	v_lshl_add_u64 v[120:121], s[8:9], 0, v[140:141]
	s_mov_b32 m0, s30
	s_nop 0
	global_load_lds_dwordx4 v[120:121], off
	s_waitcnt lgkmcnt(8)
	s_barrier
	s_waitcnt lgkmcnt(0)
	s_waitcnt lgkmcnt(0)
	v_mfma_f32_16x16x32_bf16 v[126:129], v[130:133], v[166:169], v[126:129]
	v_mfma_f32_16x16x32_bf16 v[92:95], v[150:153], v[166:169], v[92:95]
	v_mfma_f32_16x16x32_bf16 v[120:123], v[130:133], v[174:177], v[122:125]
	v_mfma_f32_16x16x32_bf16 v[88:91], v[150:153], v[174:177], v[88:91]
	v_mfma_f32_16x16x32_bf16 v[116:119], v[130:133], v[182:185], v[116:119]
	v_mfma_f32_16x16x32_bf16 v[84:87], v[150:153], v[182:185], v[84:87]
	v_mfma_f32_16x16x32_bf16 v[112:115], v[130:133], v[190:193], v[112:115]
	v_mfma_f32_16x16x32_bf16 v[80:83], v[150:153], v[190:193], v[80:83]
	v_mfma_f32_16x16x32_bf16 v[126:129], v[134:137], v[170:173], v[126:129]
	v_mfma_f32_16x16x32_bf16 v[92:95], v[162:165], v[170:173], v[92:95]
	v_mfma_f32_16x16x32_bf16 v[122:125], v[134:137], v[178:181], v[120:123]
	v_mfma_f32_16x16x32_bf16 v[88:91], v[162:165], v[178:181], v[88:91]
	v_mfma_f32_16x16x32_bf16 v[118:121], v[134:137], v[186:189], v[116:119]
	v_mfma_f32_16x16x32_bf16 v[84:87], v[162:165], v[186:189], v[84:87]
	v_mfma_f32_16x16x32_bf16 v[112:115], v[134:137], v[194:197], v[112:115]
	v_mfma_f32_16x16x32_bf16 v[80:83], v[162:165], v[194:197], v[80:83]
	s_barrier
	s_add_i32 s28, 0, 0x1c000
	v_add_u32_e32 v116, s28, v157
	s_add_i32 s8, s61, s3
	ds_read_b128 v[198:201], v116
	ds_read_b128 v[202:205], v116 offset:1024
	ds_read_b128 v[206:209], v116 offset:2048
	ds_read_b128 v[210:213], v116 offset:3072
	v_lshl_add_u64 v[116:117], v[154:155], 0, s[10:11]
	s_mov_b32 m0, s8
	s_nop 0
	global_load_lds_dwordx4 v[116:117], off
	v_lshl_add_u64 v[116:117], v[214:215], 0, s[10:11]
	s_add_i32 m0, s8, 0x2000
	s_nop 0
	global_load_lds_dwordx4 v[116:117], off
	s_barrier
	s_waitcnt lgkmcnt(0)
	s_waitcnt lgkmcnt(0)
	v_mfma_f32_16x16x32_bf16 v[60:63], v[198:201], v[166:169], v[60:63]
	v_mfma_f32_16x16x32_bf16 v[28:31], v[206:209], v[166:169], v[28:31]
	v_mfma_f32_16x16x32_bf16 v[56:59], v[198:201], v[174:177], v[56:59]
	v_mfma_f32_16x16x32_bf16 v[24:27], v[206:209], v[174:177], v[24:27]
	v_mfma_f32_16x16x32_bf16 v[52:55], v[198:201], v[182:185], v[52:55]
	v_mfma_f32_16x16x32_bf16 v[20:23], v[206:209], v[182:185], v[20:23]
	v_mfma_f32_16x16x32_bf16 v[48:51], v[198:201], v[190:193], v[48:51]
	v_mfma_f32_16x16x32_bf16 v[16:19], v[206:209], v[190:193], v[16:19]
	v_mfma_f32_16x16x32_bf16 v[60:63], v[202:205], v[170:173], v[60:63]
	v_mfma_f32_16x16x32_bf16 v[28:31], v[210:213], v[170:173], v[28:31]
	v_mfma_f32_16x16x32_bf16 v[56:59], v[202:205], v[178:181], v[56:59]
	v_mfma_f32_16x16x32_bf16 v[24:27], v[210:213], v[178:181], v[24:27]
	v_mfma_f32_16x16x32_bf16 v[52:55], v[202:205], v[186:189], v[52:55]
	v_mfma_f32_16x16x32_bf16 v[20:23], v[210:213], v[186:189], v[20:23]
	v_mfma_f32_16x16x32_bf16 v[48:51], v[202:205], v[194:197], v[48:51]
	v_mfma_f32_16x16x32_bf16 v[16:19], v[210:213], v[194:197], v[16:19]
	s_mov_b32 m0, s34
	v_lshl_add_u64 v[116:117], v[216:217], 0, s[10:11]
	s_barrier
	ds_read_b128 v[166:169], v160 offset:49152
	ds_read_b128 v[170:173], v160 offset:50176
	ds_read_b128 v[174:177], v160 offset:51200
	ds_read_b128 v[178:181], v160 offset:52224
	ds_read_b128 v[182:185], v160 offset:53248
	ds_read_b128 v[186:189], v160 offset:54272
	ds_read_b128 v[190:193], v160 offset:55296
	ds_read_b128 v[194:197], v160 offset:56320
	global_load_lds_dwordx4 v[116:117], off
	v_lshl_add_u64 v[116:117], v[218:219], 0, s[10:11]
	s_mov_b32 m0, s35
	s_nop 0
	global_load_lds_dwordx4 v[116:117], off
	s_barrier
	s_waitcnt lgkmcnt(0)
	s_waitcnt lgkmcnt(0)
	v_mfma_f32_16x16x32_bf16 v[108:111], v[130:133], v[166:169], v[108:111]
	v_mfma_f32_16x16x32_bf16 v[76:79], v[150:153], v[166:169], v[76:79]
	v_mfma_f32_16x16x32_bf16 v[104:107], v[130:133], v[174:177], v[104:107]
	v_mfma_f32_16x16x32_bf16 v[72:75], v[150:153], v[174:177], v[72:75]
	v_mfma_f32_16x16x32_bf16 v[100:103], v[130:133], v[182:185], v[100:103]
	v_mfma_f32_16x16x32_bf16 v[68:71], v[150:153], v[182:185], v[68:71]
	v_mfma_f32_16x16x32_bf16 v[96:99], v[130:133], v[190:193], v[96:99]
	v_mfma_f32_16x16x32_bf16 v[64:67], v[150:153], v[190:193], v[64:67]
	v_mfma_f32_16x16x32_bf16 v[108:111], v[134:137], v[170:173], v[108:111]
	v_mfma_f32_16x16x32_bf16 v[76:79], v[162:165], v[170:173], v[76:79]
	v_mfma_f32_16x16x32_bf16 v[104:107], v[134:137], v[178:181], v[104:107]
	v_mfma_f32_16x16x32_bf16 v[72:75], v[162:165], v[178:181], v[72:75]
	v_mfma_f32_16x16x32_bf16 v[100:103], v[134:137], v[186:189], v[100:103]
	v_mfma_f32_16x16x32_bf16 v[68:71], v[162:165], v[186:189], v[68:71]
	v_mfma_f32_16x16x32_bf16 v[96:99], v[134:137], v[194:197], v[96:99]
	v_mfma_f32_16x16x32_bf16 v[64:67], v[162:165], v[194:197], v[64:67]
	s_barrier
	s_add_u32 s8, s26, 0x80080
	s_addc_u32 s9, s27, 0
	s_add_i32 s26, s28, s3
	v_lshl_add_u64 v[116:117], s[8:9], 0, v[138:139]
	s_mov_b32 m0, s26
	s_nop 0
	global_load_lds_dwordx4 v[116:117], off
	v_lshl_add_u64 v[116:117], s[8:9], 0, v[140:141]
	s_add_i32 m0, s26, 0x2000
	s_nop 0
	global_load_lds_dwordx4 v[116:117], off
	s_waitcnt vmcnt(6)
	s_barrier
	v_mfma_f32_16x16x32_bf16 v[44:47], v[198:201], v[166:169], v[44:47]
	v_mfma_f32_16x16x32_bf16 v[12:15], v[206:209], v[166:169], v[12:15]
	v_mfma_f32_16x16x32_bf16 v[40:43], v[198:201], v[174:177], v[40:43]
	v_mfma_f32_16x16x32_bf16 v[8:11], v[206:209], v[174:177], v[8:11]
	v_mfma_f32_16x16x32_bf16 v[36:39], v[198:201], v[182:185], v[36:39]
	v_mfma_f32_16x16x32_bf16 v[4:7], v[206:209], v[182:185], v[4:7]
	v_mfma_f32_16x16x32_bf16 v[32:35], v[198:201], v[190:193], v[32:35]
	v_mfma_f32_16x16x32_bf16 v[0:3], v[206:209], v[190:193], v[0:3]
	v_mfma_f32_16x16x32_bf16 v[44:47], v[202:205], v[170:173], v[44:47]
	v_mfma_f32_16x16x32_bf16 v[12:15], v[210:213], v[170:173], v[12:15]
	v_mfma_f32_16x16x32_bf16 v[40:43], v[202:205], v[178:181], v[40:43]
	v_mfma_f32_16x16x32_bf16 v[8:11], v[210:213], v[178:181], v[8:11]
	v_mfma_f32_16x16x32_bf16 v[36:39], v[202:205], v[186:189], v[36:39]
	v_mfma_f32_16x16x32_bf16 v[4:7], v[210:213], v[186:189], v[4:7]
	v_mfma_f32_16x16x32_bf16 v[32:35], v[202:205], v[194:197], v[32:35]
	v_mfma_f32_16x16x32_bf16 v[0:3], v[210:213], v[194:197], v[0:3]
	s_add_i32 s60, s60, 2
	s_add_u32 s46, s46, 0x100
	s_addc_u32 s47, s47, 0
	s_cmp_gt_u32 s60, 29
	s_mov_b64 s[8:9], s[24:25]
	s_barrier
	s_cbranch_scc0 .LBB0_1846
	s_cmp_lt_u32 s22, 32
	s_movk_i32 s8, 0x3000
	s_cselect_b32 s8, s8, 0x6000
	s_cmp_gt_i32 s22, 15
	s_cselect_b32 s8, s8, 0
	s_lshl_b32 s8, s8, 2
	v_lshl_or_b32 v154, s41, 8, v158
	s_add_u32 s8, s37, s8
	s_addc_u32 s9, s38, 0
	v_ashrrev_i32_e32 v155, 31, v154
	v_lshl_add_u64 v[150:151], v[154:155], 2, s[8:9]
	global_load_dwordx4 v[130:133], v[150:151], off
	v_readlane_b32 s60, v239, 35
	v_cndmask_b32_e64 v117, 0, 1, s[12:13]
	v_readlane_b32 s66, v239, 41
	v_readlane_b32 s67, v239, 42
	v_mov_b32_e32 v116, 0
	v_cmp_ne_u32_e64 s[8:9], 1, v117
	s_andn2_b64 vcc, exec, s[12:13]
	v_lshl_add_u64 v[152:153], v[154:155], 2, s[66:67]
	v_mov_b32_e32 v134, 0
	v_mov_b32_e32 v135, 0
	v_mov_b32_e32 v136, 0
	v_mov_b32_e32 v137, 0
	v_readlane_b32 s61, v239, 36
	v_readlane_b32 s62, v239, 37
	v_readlane_b32 s63, v239, 38
	v_readlane_b32 s64, v239, 39
	v_readlane_b32 s65, v239, 40
	v_readlane_b32 s68, v239, 43
	v_readlane_b32 s69, v239, 44
	v_readlane_b32 s70, v239, 45
	v_readlane_b32 s71, v239, 46
	v_readlane_b32 s72, v239, 47
	v_readlane_b32 s73, v239, 48
	v_readlane_b32 s74, v239, 49
	v_readlane_b32 s75, v239, 50
	s_cbranch_vccnz .LBB0_1849
	global_load_dwordx4 v[134:137], v[152:153], off

.LBB0_1865:
	ds_read_b128 v[142:145], v139
	ds_read_b128 v[146:149], v139 offset:1024
	ds_read_b128 v[150:153], v139 offset:2048
	ds_read_b128 v[154:157], v139 offset:3072
	s_add_u32 s24, s22, 0x100
	s_addc_u32 s25, s23, 0
	s_cmp_eq_u32 s46, 4
	s_cselect_b32 s29, s15, s25
	s_cselect_b32 s28, s40, s24
	s_cselect_b32 s27, s13, s43
	s_cselect_b32 s26, s41, s42
	v_lshl_add_u64 v[190:191], s[22:23], 0, v[132:133]
	s_add_i32 m0, s5, 0xc000
	ds_read_b128 v[158:161], v140
	ds_read_b128 v[162:165], v140 offset:1024
	ds_read_b128 v[166:169], v140 offset:2048
	ds_read_b128 v[170:173], v140 offset:3072
	ds_read_b128 v[174:177], v140 offset:4096
	ds_read_b128 v[178:181], v140 offset:5120
	ds_read_b128 v[182:185], v140 offset:6144
	ds_read_b128 v[186:189], v140 offset:7168
	global_load_lds_dwordx4 v[190:191], off
	v_lshl_add_u64 v[190:191], s[22:23], 0, v[134:135]
	s_add_i32 m0, s5, 0xe000
	s_nop 0
	global_load_lds_dwordx4 v[190:191], off
	s_waitcnt lgkmcnt(8)
	s_barrier
	s_waitcnt lgkmcnt(0)
	s_waitcnt lgkmcnt(0)
	v_mfma_f32_16x16x32_bf16 v[124:127], v[142:145], v[158:161], v[124:127]
	v_mfma_f32_16x16x32_bf16 v[120:123], v[150:153], v[158:161], v[120:123]
	v_mfma_f32_16x16x32_bf16 v[116:119], v[142:145], v[166:169], v[116:119]
	v_mfma_f32_16x16x32_bf16 v[112:115], v[150:153], v[166:169], v[112:115]
	v_mfma_f32_16x16x32_bf16 v[100:103], v[142:145], v[174:177], v[100:103]
	v_mfma_f32_16x16x32_bf16 v[96:99], v[150:153], v[174:177], v[96:99]
	v_mfma_f32_16x16x32_bf16 v[84:87], v[142:145], v[182:185], v[84:87]
	v_mfma_f32_16x16x32_bf16 v[80:83], v[150:153], v[182:185], v[80:83]
	v_mfma_f32_16x16x32_bf16 v[124:127], v[146:149], v[162:165], v[124:127]
	v_mfma_f32_16x16x32_bf16 v[120:123], v[154:157], v[162:165], v[120:123]
	v_mfma_f32_16x16x32_bf16 v[116:119], v[146:149], v[170:173], v[116:119]
	v_mfma_f32_16x16x32_bf16 v[112:115], v[154:157], v[170:173], v[112:115]
	v_mfma_f32_16x16x32_bf16 v[100:103], v[146:149], v[178:181], v[100:103]
	v_mfma_f32_16x16x32_bf16 v[96:99], v[154:157], v[178:181], v[96:99]
	v_mfma_f32_16x16x32_bf16 v[84:87], v[146:149], v[186:189], v[84:87]
	v_mfma_f32_16x16x32_bf16 v[80:83], v[154:157], v[186:189], v[80:83]
	s_barrier
	s_add_i32 s22, s37, s4
	v_lshl_add_u64 v[206:207], s[26:27], 0, v[130:131]
	s_mov_b32 m0, s22
	ds_read_b128 v[190:193], v141
	ds_read_b128 v[194:197], v141 offset:1024
	ds_read_b128 v[198:201], v141 offset:2048
	ds_read_b128 v[202:205], v141 offset:3072
	global_load_lds_dwordx4 v[206:207], off
	v_lshl_add_u64 v[208:209], s[26:27], 0, v[128:129]
	s_add_i32 m0, s22, 0x2000
	s_nop 0
	global_load_lds_dwordx4 v[208:209], off
	s_barrier
	s_waitcnt lgkmcnt(0)
	s_waitcnt lgkmcnt(0)
	v_mfma_f32_16x16x32_bf16 v[108:111], v[190:193], v[158:161], v[108:111]
	v_mfma_f32_16x16x32_bf16 v[104:107], v[198:201], v[158:161], v[104:107]
	v_mfma_f32_16x16x32_bf16 v[92:95], v[190:193], v[166:169], v[92:95]
	v_mfma_f32_16x16x32_bf16 v[88:91], v[198:201], v[166:169], v[88:91]
	v_mfma_f32_16x16x32_bf16 v[76:79], v[190:193], v[174:177], v[76:79]
	v_mfma_f32_16x16x32_bf16 v[72:75], v[198:201], v[174:177], v[72:75]
	v_mfma_f32_16x16x32_bf16 v[68:71], v[190:193], v[182:185], v[68:71]
	v_mfma_f32_16x16x32_bf16 v[64:67], v[198:201], v[182:185], v[64:67]
	v_mfma_f32_16x16x32_bf16 v[108:111], v[194:197], v[162:165], v[108:111]
	v_mfma_f32_16x16x32_bf16 v[104:107], v[202:205], v[162:165], v[104:107]
	v_mfma_f32_16x16x32_bf16 v[92:95], v[194:197], v[170:173], v[92:95]
	v_mfma_f32_16x16x32_bf16 v[88:91], v[202:205], v[170:173], v[88:91]
	v_mfma_f32_16x16x32_bf16 v[76:79], v[194:197], v[178:181], v[76:79]
	v_mfma_f32_16x16x32_bf16 v[72:75], v[202:205], v[178:181], v[72:75]
	v_mfma_f32_16x16x32_bf16 v[68:71], v[194:197], v[186:189], v[68:71]
	v_mfma_f32_16x16x32_bf16 v[64:67], v[202:205], v[186:189], v[64:67]
	s_mov_b32 m0, s5
	v_lshl_add_u64 v[210:211], s[28:29], 0, v[130:131]
	s_barrier
	ds_read_b128 v[158:161], v140 offset:16384
	ds_read_b128 v[162:165], v140 offset:17408
	ds_read_b128 v[166:169], v140 offset:18432
	ds_read_b128 v[170:173], v140 offset:19456
	ds_read_b128 v[174:177], v140 offset:20480
	ds_read_b128 v[178:181], v140 offset:21504
	ds_read_b128 v[182:185], v140 offset:22528
	ds_read_b128 v[186:189], v140 offset:23552
	global_load_lds_dwordx4 v[210:211], off
	v_lshl_add_u64 v[212:213], s[28:29], 0, v[128:129]
	s_mov_b32 m0, s7
	s_nop 0
	global_load_lds_dwordx4 v[212:213], off
	s_barrier
	s_waitcnt lgkmcnt(0)
	s_waitcnt lgkmcnt(0)
	v_mfma_f32_16x16x32_bf16 v[60:63], v[142:145], v[158:161], v[60:63]
	v_mfma_f32_16x16x32_bf16 v[56:59], v[150:153], v[158:161], v[56:59]
	v_mfma_f32_16x16x32_bf16 v[52:55], v[142:145], v[166:169], v[52:55]
	v_mfma_f32_16x16x32_bf16 v[48:51], v[150:153], v[166:169], v[48:51]
	v_mfma_f32_16x16x32_bf16 v[36:39], v[142:145], v[174:177], v[36:39]
	v_mfma_f32_16x16x32_bf16 v[32:35], v[150:153], v[174:177], v[32:35]
	v_mfma_f32_16x16x32_bf16 v[20:23], v[142:145], v[182:185], v[20:23]
	v_mfma_f32_16x16x32_bf16 v[16:19], v[150:153], v[182:185], v[16:19]
	v_mfma_f32_16x16x32_bf16 v[60:63], v[146:149], v[162:165], v[60:63]
	v_mfma_f32_16x16x32_bf16 v[56:59], v[154:157], v[162:165], v[56:59]
	v_mfma_f32_16x16x32_bf16 v[52:55], v[146:149], v[170:173], v[52:55]
	v_mfma_f32_16x16x32_bf16 v[48:51], v[154:157], v[170:173], v[48:51]
	v_mfma_f32_16x16x32_bf16 v[36:39], v[146:149], v[178:181], v[36:39]
	v_mfma_f32_16x16x32_bf16 v[32:35], v[154:157], v[178:181], v[32:35]
	v_mfma_f32_16x16x32_bf16 v[20:23], v[146:149], v[186:189], v[20:23]
	v_mfma_f32_16x16x32_bf16 v[16:19], v[154:157], v[186:189], v[16:19]
	s_barrier
	s_add_u32 s22, s26, 0x80000
	s_addc_u32 s23, s27, 0
	s_add_i32 s47, s38, s4
	v_lshl_add_u64 v[142:143], s[22:23], 0, v[130:131]
	s_mov_b32 m0, s47
	s_nop 0
	global_load_lds_dwordx4 v[142:143], off
	v_lshl_add_u64 v[142:143], s[22:23], 0, v[128:129]
	s_add_i32 m0, s47, 0x2000
	s_nop 0
	global_load_lds_dwordx4 v[142:143], off
	s_waitcnt vmcnt(6)
	s_barrier
	v_mfma_f32_16x16x32_bf16 v[44:47], v[190:193], v[158:161], v[44:47]
	v_mfma_f32_16x16x32_bf16 v[40:43], v[198:201], v[158:161], v[40:43]
	v_mfma_f32_16x16x32_bf16 v[28:31], v[190:193], v[166:169], v[28:31]
	v_mfma_f32_16x16x32_bf16 v[24:27], v[198:201], v[166:169], v[24:27]
	v_mfma_f32_16x16x32_bf16 v[12:15], v[190:193], v[174:177], v[12:15]
	v_mfma_f32_16x16x32_bf16 v[8:11], v[198:201], v[174:177], v[8:11]
	v_mfma_f32_16x16x32_bf16 v[4:7], v[190:193], v[182:185], v[4:7]
	v_mfma_f32_16x16x32_bf16 v[0:3], v[198:201], v[182:185], v[0:3]
	v_mfma_f32_16x16x32_bf16 v[44:47], v[194:197], v[162:165], v[44:47]
	v_mfma_f32_16x16x32_bf16 v[40:43], v[202:205], v[162:165], v[40:43]
	v_mfma_f32_16x16x32_bf16 v[28:31], v[194:197], v[170:173], v[28:31]
	v_mfma_f32_16x16x32_bf16 v[24:27], v[202:205], v[170:173], v[24:27]
	v_mfma_f32_16x16x32_bf16 v[12:15], v[194:197], v[178:181], v[12:15]
	v_mfma_f32_16x16x32_bf16 v[8:11], v[202:205], v[178:181], v[8:11]
	v_mfma_f32_16x16x32_bf16 v[4:7], v[194:197], v[186:189], v[4:7]
	v_mfma_f32_16x16x32_bf16 v[0:3], v[202:205], v[186:189], v[0:3]
	s_add_i32 s47, 0, 0x18000
	v_add_u32_e32 v154, s47, v137
	s_barrier
	ds_read_b128 v[142:145], v154
	ds_read_b128 v[146:149], v154 offset:1024
	ds_read_b128 v[150:153], v154 offset:2048
	ds_read_b128 v[154:157], v154 offset:3072
	s_add_u32 s22, s28, 0x80000
	s_addc_u32 s23, s29, 0
	s_mov_b32 m0, s9
	v_lshl_add_u64 v[190:191], s[22:23], 0, v[130:131]
	ds_read_b128 v[158:161], v140 offset:32768
	ds_read_b128 v[162:165], v140 offset:33792
	ds_read_b128 v[166:169], v140 offset:34816
	ds_read_b128 v[170:173], v140 offset:35840
	ds_read_b128 v[174:177], v140 offset:36864
	ds_read_b128 v[178:181], v140 offset:37888
	ds_read_b128 v[182:185], v140 offset:38912
	ds_read_b128 v[186:189], v140 offset:39936
	global_load_lds_dwordx4 v[190:191], off
	v_lshl_add_u64 v[190:191], s[22:23], 0, v[128:129]
	s_mov_b32 m0, s30
	s_nop 0
	global_load_lds_dwordx4 v[190:191], off
	s_waitcnt lgkmcnt(8)
	s_barrier
	s_waitcnt lgkmcnt(0)
	s_waitcnt lgkmcnt(0)
	v_mfma_f32_16x16x32_bf16 v[124:127], v[142:145], v[158:161], v[124:127]
	v_mfma_f32_16x16x32_bf16 v[120:123], v[150:153], v[158:161], v[120:123]
	v_mfma_f32_16x16x32_bf16 v[116:119], v[142:145], v[166:169], v[116:119]
	v_mfma_f32_16x16x32_bf16 v[112:115], v[150:153], v[166:169], v[112:115]
	v_mfma_f32_16x16x32_bf16 v[100:103], v[142:145], v[174:177], v[100:103]
	v_mfma_f32_16x16x32_bf16 v[96:99], v[150:153], v[174:177], v[96:99]
	v_mfma_f32_16x16x32_bf16 v[84:87], v[142:145], v[182:185], v[84:87]
	v_mfma_f32_16x16x32_bf16 v[80:83], v[150:153], v[182:185], v[80:83]
	v_mfma_f32_16x16x32_bf16 v[124:127], v[146:149], v[162:165], v[124:127]
	v_mfma_f32_16x16x32_bf16 v[120:123], v[154:157], v[162:165], v[120:123]
	v_mfma_f32_16x16x32_bf16 v[116:119], v[146:149], v[170:173], v[116:119]
	v_mfma_f32_16x16x32_bf16 v[112:115], v[154:157], v[170:173], v[112:115]
	v_mfma_f32_16x16x32_bf16 v[100:103], v[146:149], v[178:181], v[100:103]
	v_mfma_f32_16x16x32_bf16 v[96:99], v[154:157], v[178:181], v[96:99]
	v_mfma_f32_16x16x32_bf16 v[84:87], v[146:149], v[186:189], v[84:87]
	v_mfma_f32_16x16x32_bf16 v[80:83], v[154:157], v[186:189], v[80:83]
	s_barrier
	s_add_i32 s28, 0, 0x1c000
	s_add_i32 s22, s47, s4
	v_add_u32_e32 v202, s28, v137
	v_lshl_add_u64 v[206:207], v[206:207], 0, s[10:11]
	s_mov_b32 m0, s22
	ds_read_b128 v[190:193], v202
	ds_read_b128 v[194:197], v202 offset:1024
	ds_read_b128 v[198:201], v202 offset:2048
	ds_read_b128 v[202:205], v202 offset:3072
	global_load_lds_dwordx4 v[206:207], off
	v_lshl_add_u64 v[206:207], v[208:209], 0, s[10:11]
	s_add_i32 m0, s22, 0x2000
	s_nop 0
	global_load_lds_dwordx4 v[206:207], off
	s_barrier
	s_waitcnt lgkmcnt(0)
	s_waitcnt lgkmcnt(0)
	v_mfma_f32_16x16x32_bf16 v[108:111], v[190:193], v[158:161], v[108:111]
	v_mfma_f32_16x16x32_bf16 v[104:107], v[198:201], v[158:161], v[104:107]
	v_mfma_f32_16x16x32_bf16 v[92:95], v[190:193], v[166:169], v[92:95]
	v_mfma_f32_16x16x32_bf16 v[88:91], v[198:201], v[166:169], v[88:91]
	v_mfma_f32_16x16x32_bf16 v[76:79], v[190:193], v[174:177], v[76:79]
	v_mfma_f32_16x16x32_bf16 v[72:75], v[198:201], v[174:177], v[72:75]
	v_mfma_f32_16x16x32_bf16 v[68:71], v[190:193], v[182:185], v[68:71]
	v_mfma_f32_16x16x32_bf16 v[64:67], v[198:201], v[182:185], v[64:67]
	v_mfma_f32_16x16x32_bf16 v[108:111], v[194:197], v[162:165], v[108:111]
	v_mfma_f32_16x16x32_bf16 v[104:107], v[202:205], v[162:165], v[104:107]
	v_mfma_f32_16x16x32_bf16 v[92:95], v[194:197], v[170:173], v[92:95]
	v_mfma_f32_16x16x32_bf16 v[88:91], v[202:205], v[170:173], v[88:91]
	v_mfma_f32_16x16x32_bf16 v[76:79], v[194:197], v[178:181], v[76:79]
	v_mfma_f32_16x16x32_bf16 v[72:75], v[202:205], v[178:181], v[72:75]
	v_mfma_f32_16x16x32_bf16 v[68:71], v[194:197], v[186:189], v[68:71]
	v_mfma_f32_16x16x32_bf16 v[64:67], v[202:205], v[186:189], v[64:67]
	s_mov_b32 m0, s35
	v_lshl_add_u64 v[206:207], v[210:211], 0, s[10:11]
	s_barrier
	ds_read_b128 v[158:161], v140 offset:49152
	ds_read_b128 v[162:165], v140 offset:50176
	ds_read_b128 v[166:169], v140 offset:51200
	ds_read_b128 v[170:173], v140 offset:52224
	ds_read_b128 v[174:177], v140 offset:53248
	ds_read_b128 v[178:181], v140 offset:54272
	ds_read_b128 v[182:185], v140 offset:55296
	ds_read_b128 v[186:189], v140 offset:56320
	global_load_lds_dwordx4 v[206:207], off
	v_lshl_add_u64 v[206:207], v[212:213], 0, s[10:11]
	s_mov_b32 m0, s36
	s_nop 0
	global_load_lds_dwordx4 v[206:207], off
	s_barrier
	s_waitcnt lgkmcnt(0)
	s_waitcnt lgkmcnt(0)
	v_mfma_f32_16x16x32_bf16 v[60:63], v[142:145], v[158:161], v[60:63]
	v_mfma_f32_16x16x32_bf16 v[56:59], v[150:153], v[158:161], v[56:59]
	v_mfma_f32_16x16x32_bf16 v[52:55], v[142:145], v[166:169], v[52:55]
	v_mfma_f32_16x16x32_bf16 v[48:51], v[150:153], v[166:169], v[48:51]
	v_mfma_f32_16x16x32_bf16 v[36:39], v[142:145], v[174:177], v[36:39]
	v_mfma_f32_16x16x32_bf16 v[32:35], v[150:153], v[174:177], v[32:35]
	v_mfma_f32_16x16x32_bf16 v[20:23], v[142:145], v[182:185], v[20:23]
	v_mfma_f32_16x16x32_bf16 v[16:19], v[150:153], v[182:185], v[16:19]
	v_mfma_f32_16x16x32_bf16 v[60:63], v[146:149], v[162:165], v[60:63]
	v_mfma_f32_16x16x32_bf16 v[56:59], v[154:157], v[162:165], v[56:59]
	v_mfma_f32_16x16x32_bf16 v[52:55], v[146:149], v[170:173], v[52:55]
	v_mfma_f32_16x16x32_bf16 v[48:51], v[154:157], v[170:173], v[48:51]
	v_mfma_f32_16x16x32_bf16 v[36:39], v[146:149], v[178:181], v[36:39]
	v_mfma_f32_16x16x32_bf16 v[32:35], v[154:157], v[178:181], v[32:35]
	v_mfma_f32_16x16x32_bf16 v[20:23], v[146:149], v[186:189], v[20:23]
	v_mfma_f32_16x16x32_bf16 v[16:19], v[154:157], v[186:189], v[16:19]
	s_barrier
	s_add_u32 s22, s26, 0x80080
	s_addc_u32 s23, s27, 0
	s_add_i32 s26, s28, s4
	v_lshl_add_u64 v[142:143], s[22:23], 0, v[130:131]
	s_mov_b32 m0, s26
	s_nop 0
	global_load_lds_dwordx4 v[142:143], off
	v_lshl_add_u64 v[142:143], s[22:23], 0, v[128:129]
	s_add_i32 m0, s26, 0x2000
	s_nop 0
	global_load_lds_dwordx4 v[142:143], off
	s_waitcnt vmcnt(6)
	s_barrier
	v_mfma_f32_16x16x32_bf16 v[44:47], v[190:193], v[158:161], v[44:47]
	v_mfma_f32_16x16x32_bf16 v[40:43], v[198:201], v[158:161], v[40:43]
	v_mfma_f32_16x16x32_bf16 v[28:31], v[190:193], v[166:169], v[28:31]
	v_mfma_f32_16x16x32_bf16 v[24:27], v[198:201], v[166:169], v[24:27]
	v_mfma_f32_16x16x32_bf16 v[12:15], v[190:193], v[174:177], v[12:15]
	v_mfma_f32_16x16x32_bf16 v[8:11], v[198:201], v[174:177], v[8:11]
	v_mfma_f32_16x16x32_bf16 v[4:7], v[190:193], v[182:185], v[4:7]
	v_mfma_f32_16x16x32_bf16 v[0:3], v[198:201], v[182:185], v[0:3]
	v_mfma_f32_16x16x32_bf16 v[44:47], v[194:197], v[162:165], v[44:47]
	v_mfma_f32_16x16x32_bf16 v[40:43], v[202:205], v[162:165], v[40:43]
	v_mfma_f32_16x16x32_bf16 v[28:31], v[194:197], v[170:173], v[28:31]
	v_mfma_f32_16x16x32_bf16 v[24:27], v[202:205], v[170:173], v[24:27]
	v_mfma_f32_16x16x32_bf16 v[12:15], v[194:197], v[178:181], v[12:15]
	v_mfma_f32_16x16x32_bf16 v[8:11], v[202:205], v[178:181], v[8:11]
	v_mfma_f32_16x16x32_bf16 v[4:7], v[194:197], v[186:189], v[4:7]
	v_mfma_f32_16x16x32_bf16 v[0:3], v[202:205], v[186:189], v[0:3]
	s_add_i32 s46, s46, 2
	s_add_u32 s42, s42, 0x100
	s_addc_u32 s43, s43, 0
	s_cmp_gt_u32 s46, 5
	s_mov_b64 s[22:23], s[24:25]
	s_barrier
	s_cbranch_scc0 .LBB0_1865
	s_ashr_i32 s13, s34, 1
	s_and_b32 s13, s13, 0xfffffe00
	s_lshl_b32 s8, s8, 8
	s_add_i32 s8, s8, s13
	v_add_u32_e32 v144, s8, v136
	v_lshl_or_b32 v142, s6, 8, v138
	v_ashrrev_i32_e32 v145, 31, v144
	v_ashrrev_i32_e32 v143, 31, v142
	v_lshlrev_b64 v[146:147], 13, v[144:145]
	v_lshl_add_u64 v[146:147], s[66:67], 0, v[146:147]
	v_lshlrev_b64 v[142:143], 2, v[142:143]
	v_lshl_add_u64 v[146:147], v[146:147], 0, v[142:143]
	global_store_dwordx4 v[146:147], v[124:127], off
	global_store_dwordx4 v[146:147], v[120:123], off offset:64
	global_store_dwordx4 v[146:147], v[108:111], off offset:512
	global_store_dwordx4 v[146:147], v[104:107], off offset:576
	s_mov_b32 s6, 0x100000
	s_mov_b64 s[22:23], 0x100000
	v_or_b32_e32 v104, 16, v144
	v_ashrrev_i32_e32 v105, 31, v104
	v_lshlrev_b64 v[104:105], 13, v[104:105]
	v_lshl_add_u64 v[104:105], s[66:67], 0, v[104:105]
	v_lshl_add_u64 v[104:105], v[104:105], 0, v[142:143]
	global_store_dwordx4 v[104:105], v[116:119], off
	global_store_dwordx4 v[104:105], v[112:115], off offset:64
	global_store_dwordx4 v[104:105], v[92:95], off offset:512
	global_store_dwordx4 v[104:105], v[88:91], off offset:576
	s_mov_b32 s34, s39
	s_mov_b32 s8, s14
	v_or_b32_e32 v88, 32, v144
	v_ashrrev_i32_e32 v89, 31, v88
	v_lshlrev_b64 v[88:89], 13, v[88:89]
	v_lshl_add_u64 v[88:89], s[66:67], 0, v[88:89]
	v_lshl_add_u64 v[88:89], v[88:89], 0, v[142:143]
	global_store_dwordx4 v[88:89], v[100:103], off
	global_store_dwordx4 v[88:89], v[96:99], off offset:64
	global_store_dwordx4 v[88:89], v[76:79], off offset:512
	global_store_dwordx4 v[88:89], v[72:75], off offset:576
	s_mov_b64 s[24:25], s[20:21]
	s_nop 0
	v_or_b32_e32 v72, 48, v144
	v_ashrrev_i32_e32 v73, 31, v72
	v_lshlrev_b64 v[72:73], 13, v[72:73]
	v_lshl_add_u64 v[72:73], s[66:67], 0, v[72:73]
	v_lshl_add_u64 v[72:73], v[72:73], 0, v[142:143]
	global_store_dwordx4 v[72:73], v[84:87], off
	global_store_dwordx4 v[72:73], v[80:83], off offset:64
	global_store_dwordx4 v[72:73], v[68:71], off offset:512
	global_store_dwordx4 v[72:73], v[64:67], off offset:576
	s_nop 1
	v_add_co_u32_e32 v66, vcc, s6, v146
	s_mov_b32 s6, 0x120000
	s_nop 0
	v_addc_co_u32_e32 v67, vcc, 0, v147, vcc
	v_lshl_add_u64 v[64:65], v[146:147], 0, s[22:23]
	global_store_dwordx4 v[66:67], v[60:63], off
	global_store_dwordx4 v[64:65], v[56:59], off offset:64
	global_store_dwordx4 v[64:65], v[44:47], off offset:512
	global_store_dwordx4 v[64:65], v[40:43], off offset:576
	s_mov_b64 s[22:23], 0x120000
	s_nop 0
	v_add_co_u32_e32 v42, vcc, s6, v146
	s_mov_b32 s6, 0x140000
	s_nop 0
	v_addc_co_u32_e32 v43, vcc, 0, v147, vcc
	v_lshl_add_u64 v[40:41], v[146:147], 0, s[22:23]
	global_store_dwordx4 v[42:43], v[52:55], off
	global_store_dwordx4 v[40:41], v[48:51], off offset:64
	global_store_dwordx4 v[40:41], v[28:31], off offset:512
	global_store_dwordx4 v[40:41], v[24:27], off offset:576
	s_mov_b64 s[22:23], 0x140000
	s_nop 0
	v_add_co_u32_e32 v26, vcc, s6, v146
	v_lshl_add_u64 v[24:25], v[146:147], 0, s[22:23]
	s_nop 0
	v_addc_co_u32_e32 v27, vcc, 0, v147, vcc
	global_store_dwordx4 v[26:27], v[36:39], off
	global_store_dwordx4 v[24:25], v[32:35], off offset:64
	global_store_dwordx4 v[24:25], v[12:15], off offset:512
	global_store_dwordx4 v[24:25], v[8:11], off offset:576
	s_mov_b64 s[22:23], 0x160000
	s_mov_b32 s6, s12
	v_add_co_u32_e32 v10, vcc, 0x160000, v146
	v_lshl_add_u64 v[8:9], v[146:147], 0, s[22:23]
	s_nop 0
	v_addc_co_u32_e32 v11, vcc, 0, v147, vcc
	s_and_b64 vcc, exec, s[16:17]
	s_mov_b64 s[22:23], s[18:19]
	global_store_dwordx4 v[10:11], v[20:23], off
	global_store_dwordx4 v[8:9], v[16:19], off offset:64
	global_store_dwordx4 v[8:9], v[4:7], off offset:512
	global_store_dwordx4 v[8:9], v[0:3], off offset:576
	s_cbranch_vccz .LBB0_1862
	s_waitcnt vmcnt(0)
	s_cmpk_gt_u32 s1, 0xff
	s_cbranch_scc1 .LBB0_1869
	s_barrier

.LBB0_2005:
	ds_read_b128 v[148:151], v144
	ds_read_b128 v[152:155], v144 offset:1024
	ds_read_b128 v[156:159], v144 offset:2048
	ds_read_b128 v[160:163], v144 offset:3072
	s_add_u32 s24, s22, 0x100
	s_addc_u32 s25, s23, 0
	s_cmp_eq_u32 s61, 28
	s_cselect_b32 s29, s15, s25
	s_cselect_b32 s28, s43, s24
	s_cselect_b32 s27, s13, s60
	s_cselect_b32 s26, s46, s47
	v_lshl_add_u64 v[196:197], s[22:23], 0, v[134:135]
	s_add_i32 m0, s5, 0xc000
	ds_read_b128 v[164:167], v145
	ds_read_b128 v[168:171], v145 offset:1024
	ds_read_b128 v[172:175], v145 offset:2048
	ds_read_b128 v[176:179], v145 offset:3072
	ds_read_b128 v[180:183], v145 offset:4096
	ds_read_b128 v[184:187], v145 offset:5120
	ds_read_b128 v[188:191], v145 offset:6144
	ds_read_b128 v[192:195], v145 offset:7168
	global_load_lds_dwordx4 v[196:197], off
	v_lshl_add_u64 v[196:197], s[22:23], 0, v[136:137]
	s_add_i32 m0, s5, 0xe000
	s_nop 0
	global_load_lds_dwordx4 v[196:197], off
	s_waitcnt lgkmcnt(8)
	s_barrier
	s_waitcnt lgkmcnt(0)
	s_waitcnt lgkmcnt(0)
	v_mfma_f32_16x16x32_bf16 v[124:127], v[148:151], v[164:167], v[124:127]
	v_mfma_f32_16x16x32_bf16 v[120:123], v[156:159], v[164:167], v[120:123]
	v_mfma_f32_16x16x32_bf16 v[108:111], v[148:151], v[172:175], v[108:111]
	v_mfma_f32_16x16x32_bf16 v[104:107], v[156:159], v[172:175], v[104:107]
	v_mfma_f32_16x16x32_bf16 v[92:95], v[148:151], v[180:183], v[92:95]
	v_mfma_f32_16x16x32_bf16 v[88:91], v[156:159], v[180:183], v[88:91]
	v_mfma_f32_16x16x32_bf16 v[76:79], v[148:151], v[188:191], v[76:79]
	v_mfma_f32_16x16x32_bf16 v[72:75], v[156:159], v[188:191], v[72:75]
	v_mfma_f32_16x16x32_bf16 v[124:127], v[152:155], v[168:171], v[124:127]
	v_mfma_f32_16x16x32_bf16 v[120:123], v[160:163], v[168:171], v[120:123]
	v_mfma_f32_16x16x32_bf16 v[108:111], v[152:155], v[176:179], v[108:111]
	v_mfma_f32_16x16x32_bf16 v[104:107], v[160:163], v[176:179], v[104:107]
	v_mfma_f32_16x16x32_bf16 v[92:95], v[152:155], v[184:187], v[92:95]
	v_mfma_f32_16x16x32_bf16 v[88:91], v[160:163], v[184:187], v[88:91]
	v_mfma_f32_16x16x32_bf16 v[76:79], v[152:155], v[192:195], v[76:79]
	v_mfma_f32_16x16x32_bf16 v[72:75], v[160:163], v[192:195], v[72:75]
	s_barrier
	s_add_i32 s22, s40, s2
	v_lshl_add_u64 v[212:213], s[26:27], 0, v[130:131]
	s_mov_b32 m0, s22
	ds_read_b128 v[196:199], v146
	ds_read_b128 v[200:203], v146 offset:1024
	ds_read_b128 v[204:207], v146 offset:2048
	ds_read_b128 v[208:211], v146 offset:3072
	global_load_lds_dwordx4 v[212:213], off
	v_lshl_add_u64 v[214:215], s[26:27], 0, v[128:129]
	s_add_i32 m0, s22, 0x2000
	s_nop 0
	global_load_lds_dwordx4 v[214:215], off
	s_barrier
	s_waitcnt lgkmcnt(0)
	s_waitcnt lgkmcnt(0)
	v_mfma_f32_16x16x32_bf16 v[116:119], v[196:199], v[164:167], v[116:119]
	v_mfma_f32_16x16x32_bf16 v[112:115], v[204:207], v[164:167], v[112:115]
	v_mfma_f32_16x16x32_bf16 v[100:103], v[196:199], v[172:175], v[100:103]
	v_mfma_f32_16x16x32_bf16 v[96:99], v[204:207], v[172:175], v[96:99]
	v_mfma_f32_16x16x32_bf16 v[84:87], v[196:199], v[180:183], v[84:87]
	v_mfma_f32_16x16x32_bf16 v[80:83], v[204:207], v[180:183], v[80:83]
	v_mfma_f32_16x16x32_bf16 v[68:71], v[196:199], v[188:191], v[68:71]
	v_mfma_f32_16x16x32_bf16 v[64:67], v[204:207], v[188:191], v[64:67]
	v_mfma_f32_16x16x32_bf16 v[116:119], v[200:203], v[168:171], v[116:119]
	v_mfma_f32_16x16x32_bf16 v[112:115], v[208:211], v[168:171], v[112:115]
	v_mfma_f32_16x16x32_bf16 v[100:103], v[200:203], v[176:179], v[100:103]
	v_mfma_f32_16x16x32_bf16 v[96:99], v[208:211], v[176:179], v[96:99]
	v_mfma_f32_16x16x32_bf16 v[84:87], v[200:203], v[184:187], v[84:87]
	v_mfma_f32_16x16x32_bf16 v[80:83], v[208:211], v[184:187], v[80:83]
	v_mfma_f32_16x16x32_bf16 v[68:71], v[200:203], v[192:195], v[68:71]
	v_mfma_f32_16x16x32_bf16 v[64:67], v[208:211], v[192:195], v[64:67]
	s_mov_b32 m0, s5
	v_lshl_add_u64 v[216:217], s[28:29], 0, v[130:131]
	s_barrier
	ds_read_b128 v[164:167], v145 offset:16384
	ds_read_b128 v[168:171], v145 offset:17408
	ds_read_b128 v[172:175], v145 offset:18432
	ds_read_b128 v[176:179], v145 offset:19456
	ds_read_b128 v[180:183], v145 offset:20480
	ds_read_b128 v[184:187], v145 offset:21504
	ds_read_b128 v[188:191], v145 offset:22528
	ds_read_b128 v[192:195], v145 offset:23552
	global_load_lds_dwordx4 v[216:217], off
	v_lshl_add_u64 v[218:219], s[28:29], 0, v[128:129]
	s_mov_b32 m0, s30
	s_nop 0
	global_load_lds_dwordx4 v[218:219], off
	s_barrier
	s_waitcnt lgkmcnt(0)
	s_waitcnt lgkmcnt(0)
	v_mfma_f32_16x16x32_bf16 v[60:63], v[148:151], v[164:167], v[60:63]
	v_mfma_f32_16x16x32_bf16 v[56:59], v[156:159], v[164:167], v[56:59]
	v_mfma_f32_16x16x32_bf16 v[44:47], v[148:151], v[172:175], v[44:47]
	v_mfma_f32_16x16x32_bf16 v[40:43], v[156:159], v[172:175], v[40:43]
	v_mfma_f32_16x16x32_bf16 v[28:31], v[148:151], v[180:183], v[28:31]
	v_mfma_f32_16x16x32_bf16 v[24:27], v[156:159], v[180:183], v[24:27]
	v_mfma_f32_16x16x32_bf16 v[12:15], v[148:151], v[188:191], v[12:15]
	v_mfma_f32_16x16x32_bf16 v[8:11], v[156:159], v[188:191], v[8:11]
	v_mfma_f32_16x16x32_bf16 v[60:63], v[152:155], v[168:171], v[60:63]
	v_mfma_f32_16x16x32_bf16 v[56:59], v[160:163], v[168:171], v[56:59]
	v_mfma_f32_16x16x32_bf16 v[44:47], v[152:155], v[176:179], v[44:47]
	v_mfma_f32_16x16x32_bf16 v[40:43], v[160:163], v[176:179], v[40:43]
	v_mfma_f32_16x16x32_bf16 v[28:31], v[152:155], v[184:187], v[28:31]
	v_mfma_f32_16x16x32_bf16 v[24:27], v[160:163], v[184:187], v[24:27]
	v_mfma_f32_16x16x32_bf16 v[12:15], v[152:155], v[192:195], v[12:15]
	v_mfma_f32_16x16x32_bf16 v[8:11], v[160:163], v[192:195], v[8:11]
	s_barrier
	s_add_u32 s22, s26, 0x80000
	s_addc_u32 s23, s27, 0
	s_add_i32 s62, s41, s2
	v_lshl_add_u64 v[148:149], s[22:23], 0, v[130:131]
	s_mov_b32 m0, s62
	s_nop 0
	global_load_lds_dwordx4 v[148:149], off
	v_lshl_add_u64 v[148:149], s[22:23], 0, v[128:129]
	s_add_i32 m0, s62, 0x2000
	s_nop 0
	global_load_lds_dwordx4 v[148:149], off
	s_waitcnt vmcnt(6)
	s_barrier
	v_mfma_f32_16x16x32_bf16 v[52:55], v[196:199], v[164:167], v[52:55]
	v_mfma_f32_16x16x32_bf16 v[48:51], v[204:207], v[164:167], v[48:51]
	v_mfma_f32_16x16x32_bf16 v[36:39], v[196:199], v[172:175], v[36:39]
	v_mfma_f32_16x16x32_bf16 v[32:35], v[204:207], v[172:175], v[32:35]
	v_mfma_f32_16x16x32_bf16 v[20:23], v[196:199], v[180:183], v[20:23]
	v_mfma_f32_16x16x32_bf16 v[16:19], v[204:207], v[180:183], v[16:19]
	v_mfma_f32_16x16x32_bf16 v[4:7], v[196:199], v[188:191], v[4:7]
	v_mfma_f32_16x16x32_bf16 v[0:3], v[204:207], v[188:191], v[0:3]
	v_mfma_f32_16x16x32_bf16 v[52:55], v[200:203], v[168:171], v[52:55]
	v_mfma_f32_16x16x32_bf16 v[48:51], v[208:211], v[168:171], v[48:51]
	v_mfma_f32_16x16x32_bf16 v[36:39], v[200:203], v[176:179], v[36:39]
	v_mfma_f32_16x16x32_bf16 v[32:35], v[208:211], v[176:179], v[32:35]
	v_mfma_f32_16x16x32_bf16 v[20:23], v[200:203], v[184:187], v[20:23]
	v_mfma_f32_16x16x32_bf16 v[16:19], v[208:211], v[184:187], v[16:19]
	v_mfma_f32_16x16x32_bf16 v[4:7], v[200:203], v[192:195], v[4:7]
	v_mfma_f32_16x16x32_bf16 v[0:3], v[208:211], v[192:195], v[0:3]
	s_add_i32 s62, 0, 0x18000
	v_add_u32_e32 v147, s62, v143
	s_barrier
	ds_read_b128 v[148:151], v147
	ds_read_b128 v[152:155], v147 offset:1024
	ds_read_b128 v[156:159], v147 offset:2048
	ds_read_b128 v[160:163], v147 offset:3072
	s_add_u32 s22, s28, 0x80000
	s_addc_u32 s23, s29, 0
	s_mov_b32 m0, s31
	v_lshl_add_u64 v[196:197], s[22:23], 0, v[130:131]
	ds_read_b128 v[164:167], v145 offset:32768
	ds_read_b128 v[168:171], v145 offset:33792
	ds_read_b128 v[172:175], v145 offset:34816
	ds_read_b128 v[176:179], v145 offset:35840
	ds_read_b128 v[180:183], v145 offset:36864
	ds_read_b128 v[184:187], v145 offset:37888
	ds_read_b128 v[188:191], v145 offset:38912
	ds_read_b128 v[192:195], v145 offset:39936
	global_load_lds_dwordx4 v[196:197], off
	v_lshl_add_u64 v[196:197], s[22:23], 0, v[128:129]
	s_mov_b32 m0, s34
	s_nop 0
	global_load_lds_dwordx4 v[196:197], off
	s_waitcnt lgkmcnt(8)
	s_barrier
	s_waitcnt lgkmcnt(0)
	s_waitcnt lgkmcnt(0)
	v_mfma_f32_16x16x32_bf16 v[124:127], v[148:151], v[164:167], v[124:127]
	v_mfma_f32_16x16x32_bf16 v[120:123], v[156:159], v[164:167], v[120:123]
	v_mfma_f32_16x16x32_bf16 v[108:111], v[148:151], v[172:175], v[108:111]
	v_mfma_f32_16x16x32_bf16 v[104:107], v[156:159], v[172:175], v[104:107]
	v_mfma_f32_16x16x32_bf16 v[92:95], v[148:151], v[180:183], v[92:95]
	v_mfma_f32_16x16x32_bf16 v[88:91], v[156:159], v[180:183], v[88:91]
	v_mfma_f32_16x16x32_bf16 v[76:79], v[148:151], v[188:191], v[76:79]
	v_mfma_f32_16x16x32_bf16 v[72:75], v[156:159], v[188:191], v[72:75]
	v_mfma_f32_16x16x32_bf16 v[124:127], v[152:155], v[168:171], v[124:127]
	v_mfma_f32_16x16x32_bf16 v[120:123], v[160:163], v[168:171], v[120:123]
	v_mfma_f32_16x16x32_bf16 v[108:111], v[152:155], v[176:179], v[108:111]
	v_mfma_f32_16x16x32_bf16 v[104:107], v[160:163], v[176:179], v[104:107]
	v_mfma_f32_16x16x32_bf16 v[92:95], v[152:155], v[184:187], v[92:95]
	v_mfma_f32_16x16x32_bf16 v[88:91], v[160:163], v[184:187], v[88:91]
	v_mfma_f32_16x16x32_bf16 v[76:79], v[152:155], v[192:195], v[76:79]
	v_mfma_f32_16x16x32_bf16 v[72:75], v[160:163], v[192:195], v[72:75]
	s_barrier
	s_add_i32 s28, 0, 0x1c000
	s_add_i32 s22, s62, s2
	v_add_u32_e32 v147, s28, v143
	v_lshl_add_u64 v[212:213], v[212:213], 0, s[10:11]
	s_mov_b32 m0, s22
	ds_read_b128 v[196:199], v147
	ds_read_b128 v[200:203], v147 offset:1024
	ds_read_b128 v[204:207], v147 offset:2048
	ds_read_b128 v[208:211], v147 offset:3072
	global_load_lds_dwordx4 v[212:213], off
	v_lshl_add_u64 v[212:213], v[214:215], 0, s[10:11]
	s_add_i32 m0, s22, 0x2000
	s_nop 0
	global_load_lds_dwordx4 v[212:213], off
	s_barrier
	s_waitcnt lgkmcnt(0)
	s_waitcnt lgkmcnt(0)
	v_mfma_f32_16x16x32_bf16 v[116:119], v[196:199], v[164:167], v[116:119]
	v_mfma_f32_16x16x32_bf16 v[112:115], v[204:207], v[164:167], v[112:115]
	v_mfma_f32_16x16x32_bf16 v[100:103], v[196:199], v[172:175], v[100:103]
	v_mfma_f32_16x16x32_bf16 v[96:99], v[204:207], v[172:175], v[96:99]
	v_mfma_f32_16x16x32_bf16 v[84:87], v[196:199], v[180:183], v[84:87]
	v_mfma_f32_16x16x32_bf16 v[80:83], v[204:207], v[180:183], v[80:83]
	v_mfma_f32_16x16x32_bf16 v[68:71], v[196:199], v[188:191], v[68:71]
	v_mfma_f32_16x16x32_bf16 v[64:67], v[204:207], v[188:191], v[64:67]
	v_mfma_f32_16x16x32_bf16 v[116:119], v[200:203], v[168:171], v[116:119]
	v_mfma_f32_16x16x32_bf16 v[112:115], v[208:211], v[168:171], v[112:115]
	v_mfma_f32_16x16x32_bf16 v[100:103], v[200:203], v[176:179], v[100:103]
	v_mfma_f32_16x16x32_bf16 v[96:99], v[208:211], v[176:179], v[96:99]
	v_mfma_f32_16x16x32_bf16 v[84:87], v[200:203], v[184:187], v[84:87]
	v_mfma_f32_16x16x32_bf16 v[80:83], v[208:211], v[184:187], v[80:83]
	v_mfma_f32_16x16x32_bf16 v[68:71], v[200:203], v[192:195], v[68:71]
	v_mfma_f32_16x16x32_bf16 v[64:67], v[208:211], v[192:195], v[64:67]
	s_mov_b32 m0, s36
	v_lshl_add_u64 v[212:213], v[216:217], 0, s[10:11]
	s_barrier
	ds_read_b128 v[164:167], v145 offset:49152
	ds_read_b128 v[168:171], v145 offset:50176
	ds_read_b128 v[172:175], v145 offset:51200
	ds_read_b128 v[176:179], v145 offset:52224
	ds_read_b128 v[180:183], v145 offset:53248
	ds_read_b128 v[184:187], v145 offset:54272
	ds_read_b128 v[188:191], v145 offset:55296
	ds_read_b128 v[192:195], v145 offset:56320
	global_load_lds_dwordx4 v[212:213], off
	v_lshl_add_u64 v[212:213], v[218:219], 0, s[10:11]
	s_mov_b32 m0, s37
	s_nop 0
	global_load_lds_dwordx4 v[212:213], off
	s_barrier
	s_waitcnt lgkmcnt(0)
	s_waitcnt lgkmcnt(0)
	v_mfma_f32_16x16x32_bf16 v[60:63], v[148:151], v[164:167], v[60:63]
	v_mfma_f32_16x16x32_bf16 v[56:59], v[156:159], v[164:167], v[56:59]
	v_mfma_f32_16x16x32_bf16 v[44:47], v[148:151], v[172:175], v[44:47]
	v_mfma_f32_16x16x32_bf16 v[40:43], v[156:159], v[172:175], v[40:43]
	v_mfma_f32_16x16x32_bf16 v[28:31], v[148:151], v[180:183], v[28:31]
	v_mfma_f32_16x16x32_bf16 v[24:27], v[156:159], v[180:183], v[24:27]
	v_mfma_f32_16x16x32_bf16 v[12:15], v[148:151], v[188:191], v[12:15]
	v_mfma_f32_16x16x32_bf16 v[8:11], v[156:159], v[188:191], v[8:11]
	v_mfma_f32_16x16x32_bf16 v[60:63], v[152:155], v[168:171], v[60:63]
	v_mfma_f32_16x16x32_bf16 v[56:59], v[160:163], v[168:171], v[56:59]
	v_mfma_f32_16x16x32_bf16 v[44:47], v[152:155], v[176:179], v[44:47]
	v_mfma_f32_16x16x32_bf16 v[40:43], v[160:163], v[176:179], v[40:43]
	v_mfma_f32_16x16x32_bf16 v[28:31], v[152:155], v[184:187], v[28:31]
	v_mfma_f32_16x16x32_bf16 v[24:27], v[160:163], v[184:187], v[24:27]
	v_mfma_f32_16x16x32_bf16 v[12:15], v[152:155], v[192:195], v[12:15]
	v_mfma_f32_16x16x32_bf16 v[8:11], v[160:163], v[192:195], v[8:11]
	s_barrier
	s_add_u32 s22, s26, 0x80080
	s_addc_u32 s23, s27, 0
	s_add_i32 s26, s28, s2
	v_lshl_add_u64 v[148:149], s[22:23], 0, v[130:131]
	s_mov_b32 m0, s26
	s_nop 0
	global_load_lds_dwordx4 v[148:149], off
	v_lshl_add_u64 v[148:149], s[22:23], 0, v[128:129]
	s_add_i32 m0, s26, 0x2000
	s_nop 0
	global_load_lds_dwordx4 v[148:149], off
	s_waitcnt vmcnt(6)
	s_barrier
	v_mfma_f32_16x16x32_bf16 v[52:55], v[196:199], v[164:167], v[52:55]
	v_mfma_f32_16x16x32_bf16 v[48:51], v[204:207], v[164:167], v[48:51]
	v_mfma_f32_16x16x32_bf16 v[36:39], v[196:199], v[172:175], v[36:39]
	v_mfma_f32_16x16x32_bf16 v[32:35], v[204:207], v[172:175], v[32:35]
	v_mfma_f32_16x16x32_bf16 v[20:23], v[196:199], v[180:183], v[20:23]
	v_mfma_f32_16x16x32_bf16 v[16:19], v[204:207], v[180:183], v[16:19]
	v_mfma_f32_16x16x32_bf16 v[4:7], v[196:199], v[188:191], v[4:7]
	v_mfma_f32_16x16x32_bf16 v[0:3], v[204:207], v[188:191], v[0:3]
	v_mfma_f32_16x16x32_bf16 v[52:55], v[200:203], v[168:171], v[52:55]
	v_mfma_f32_16x16x32_bf16 v[48:51], v[208:211], v[168:171], v[48:51]
	v_mfma_f32_16x16x32_bf16 v[36:39], v[200:203], v[176:179], v[36:39]
	v_mfma_f32_16x16x32_bf16 v[32:35], v[208:211], v[176:179], v[32:35]
	v_mfma_f32_16x16x32_bf16 v[20:23], v[200:203], v[184:187], v[20:23]
	v_mfma_f32_16x16x32_bf16 v[16:19], v[208:211], v[184:187], v[16:19]
	v_mfma_f32_16x16x32_bf16 v[4:7], v[200:203], v[192:195], v[4:7]
	v_mfma_f32_16x16x32_bf16 v[0:3], v[208:211], v[192:195], v[0:3]
	s_add_i32 s61, s61, 2
	s_add_u32 s47, s47, 0x100
	s_addc_u32 s60, s60, 0
	s_cmp_gt_u32 s61, 29
	s_mov_b64 s[22:23], s[24:25]
	s_barrier
	s_cbranch_scc0 .LBB0_2005
	v_mul_f32_e32 v150, 0xbfb8aa3b, v124
	v_mul_f32_e32 v151, 0xbfb8aa3b, v125
	v_exp_f32_e32 v150, v150
	v_exp_f32_e32 v151, v151
	s_lshl_b32 s13, s21, 7
	v_lshl_add_u32 v147, s20, 8, v142
	v_add_f32_e32 v150, 1.0, v150
	v_add_f32_e32 v151, 1.0, v151
	v_rcp_f32_e32 v150, v150
	v_rcp_f32_e32 v151, v151
	s_or_b32 s20, s13, s38
	s_ashr_i32 s21, s20, 31
	v_mad_i64_i32 v[148:149], s[22:23], v147, s42, v[132:133]
	v_pk_mul_f32 v[124:125], v[124:125], v[150:151]
	s_lshl_b64 s[20:21], s[20:21], 1
	v_pk_mul_f32 v[120:121], v[120:121], v[124:125]
	s_and_b64 vcc, exec, s[6:7]
	v_cvt_pk_bf16_f32 v120, v120, v121
	v_mul_f32_e32 v121, 0xbfb8aa3b, v126
	v_exp_f32_e32 v121, v121
	s_mov_b64 s[24:25], s[18:19]
	v_add_f32_e32 v121, 1.0, v121
	v_rcp_f32_e32 v124, v121
	v_mul_f32_e32 v121, 0xbfb8aa3b, v127
	v_exp_f32_e32 v121, v121
	s_nop 0
	v_add_f32_e32 v121, 1.0, v121
	v_rcp_f32_e32 v125, v121
	s_nop 0
	v_pk_mul_f32 v[124:125], v[126:127], v[124:125]
	s_nop 0
	v_pk_mul_f32 v[122:123], v[122:123], v[124:125]
	s_nop 0
	v_cvt_pk_bf16_f32 v121, v122, v123
	v_lshl_add_u64 v[122:123], v[148:149], 0, s[20:21]
	global_store_dwordx2 v[122:123], v[120:121], off
	v_mul_f32_e32 v120, 0xbfb8aa3b, v116
	v_mul_f32_e32 v121, 0xbfb8aa3b, v117
	v_exp_f32_e32 v120, v120
	v_exp_f32_e32 v121, v121
	v_add_f32_e32 v120, 1.0, v120
	v_add_f32_e32 v121, 1.0, v121
	v_rcp_f32_e32 v120, v120
	v_rcp_f32_e32 v121, v121
	s_nop 0
	v_pk_mul_f32 v[116:117], v[116:117], v[120:121]
	s_nop 0
	v_pk_mul_f32 v[112:113], v[112:113], v[116:117]
	s_nop 0
	v_cvt_pk_bf16_f32 v112, v112, v113
	v_mul_f32_e32 v113, 0xbfb8aa3b, v118
	v_exp_f32_e32 v113, v113
	s_nop 0
	v_add_f32_e32 v113, 1.0, v113
	v_rcp_f32_e32 v116, v113
	v_mul_f32_e32 v113, 0xbfb8aa3b, v119
	v_exp_f32_e32 v113, v113
	s_nop 0
	v_add_f32_e32 v113, 1.0, v113
	v_rcp_f32_e32 v117, v113
	s_nop 0
	v_pk_mul_f32 v[116:117], v[118:119], v[116:117]
	s_nop 0
	v_pk_mul_f32 v[114:115], v[114:115], v[116:117]
	s_nop 0
	v_cvt_pk_bf16_f32 v113, v114, v115
	v_mul_f32_e32 v114, 0xbfb8aa3b, v108
	v_mul_f32_e32 v115, 0xbfb8aa3b, v109
	v_exp_f32_e32 v114, v114
	v_exp_f32_e32 v115, v115
	global_store_dwordx2 v[122:123], v[112:113], off offset:128
	v_or_b32_e32 v112, 16, v147
	v_add_f32_e32 v114, 1.0, v114
	v_add_f32_e32 v115, 1.0, v115
	v_rcp_f32_e32 v114, v114
	v_rcp_f32_e32 v115, v115
	v_mad_i64_i32 v[112:113], s[22:23], v112, s42, v[132:133]
	v_pk_mul_f32 v[108:109], v[108:109], v[114:115]
	s_nop 0
	v_pk_mul_f32 v[104:105], v[104:105], v[108:109]
	s_nop 0
	v_cvt_pk_bf16_f32 v104, v104, v105
	v_mul_f32_e32 v105, 0xbfb8aa3b, v110
	v_exp_f32_e32 v105, v105
	s_nop 0
	v_add_f32_e32 v105, 1.0, v105
	v_rcp_f32_e32 v108, v105
	v_mul_f32_e32 v105, 0xbfb8aa3b, v111
	v_exp_f32_e32 v105, v105
	s_nop 0
	v_add_f32_e32 v105, 1.0, v105
	v_rcp_f32_e32 v109, v105
	s_nop 0
	v_pk_mul_f32 v[108:109], v[110:111], v[108:109]
	s_nop 0
	v_pk_mul_f32 v[106:107], v[106:107], v[108:109]
	s_nop 0
	v_cvt_pk_bf16_f32 v105, v106, v107
	v_lshl_add_u64 v[106:107], v[112:113], 0, s[20:21]
	global_store_dwordx2 v[106:107], v[104:105], off
	v_mul_f32_e32 v104, 0xbfb8aa3b, v100
	v_mul_f32_e32 v105, 0xbfb8aa3b, v101
	v_exp_f32_e32 v104, v104
	v_exp_f32_e32 v105, v105
	v_add_f32_e32 v104, 1.0, v104
	v_add_f32_e32 v105, 1.0, v105
	v_rcp_f32_e32 v104, v104
	v_rcp_f32_e32 v105, v105
	s_nop 0
	v_pk_mul_f32 v[100:101], v[100:101], v[104:105]
	s_nop 0
	v_pk_mul_f32 v[96:97], v[96:97], v[100:101]
	s_nop 0
	v_cvt_pk_bf16_f32 v96, v96, v97
	v_mul_f32_e32 v97, 0xbfb8aa3b, v102
	v_exp_f32_e32 v97, v97
	s_nop 0
	v_add_f32_e32 v97, 1.0, v97
	v_rcp_f32_e32 v100, v97
	v_mul_f32_e32 v97, 0xbfb8aa3b, v103
	v_exp_f32_e32 v97, v97
	s_nop 0
	v_add_f32_e32 v97, 1.0, v97
	v_rcp_f32_e32 v101, v97
	s_nop 0
	v_pk_mul_f32 v[100:101], v[102:103], v[100:101]
	s_nop 0
	v_pk_mul_f32 v[98:99], v[98:99], v[100:101]
	s_nop 0
	v_cvt_pk_bf16_f32 v97, v98, v99
	v_mul_f32_e32 v98, 0xbfb8aa3b, v92
	v_mul_f32_e32 v99, 0xbfb8aa3b, v93
	v_exp_f32_e32 v98, v98
	v_exp_f32_e32 v99, v99
	global_store_dwordx2 v[106:107], v[96:97], off offset:128
	v_or_b32_e32 v96, 32, v147
	v_add_f32_e32 v98, 1.0, v98
	v_add_f32_e32 v99, 1.0, v99
	v_rcp_f32_e32 v98, v98
	v_rcp_f32_e32 v99, v99
	v_mad_i64_i32 v[96:97], s[22:23], v96, s42, v[132:133]
	v_pk_mul_f32 v[92:93], v[92:93], v[98:99]
	s_nop 0
	v_pk_mul_f32 v[88:89], v[88:89], v[92:93]
	s_nop 0
	v_cvt_pk_bf16_f32 v88, v88, v89
	v_mul_f32_e32 v89, 0xbfb8aa3b, v94
	v_exp_f32_e32 v89, v89
	s_nop 0
	v_add_f32_e32 v89, 1.0, v89
	v_rcp_f32_e32 v92, v89
	v_mul_f32_e32 v89, 0xbfb8aa3b, v95
	v_exp_f32_e32 v89, v89
	s_nop 0
	v_add_f32_e32 v89, 1.0, v89
	v_rcp_f32_e32 v93, v89
	s_nop 0
	v_pk_mul_f32 v[92:93], v[94:95], v[92:93]
	s_nop 0
	v_pk_mul_f32 v[90:91], v[90:91], v[92:93]
	s_nop 0
	v_cvt_pk_bf16_f32 v89, v90, v91
	v_lshl_add_u64 v[90:91], v[96:97], 0, s[20:21]
	global_store_dwordx2 v[90:91], v[88:89], off
	v_mul_f32_e32 v88, 0xbfb8aa3b, v84
	v_mul_f32_e32 v89, 0xbfb8aa3b, v85
	v_exp_f32_e32 v88, v88
	v_exp_f32_e32 v89, v89
	v_add_f32_e32 v88, 1.0, v88
	v_add_f32_e32 v89, 1.0, v89
	v_rcp_f32_e32 v88, v88
	v_rcp_f32_e32 v89, v89
	s_nop 0
	v_pk_mul_f32 v[84:85], v[84:85], v[88:89]
	s_nop 0
	v_pk_mul_f32 v[80:81], v[80:81], v[84:85]
	s_nop 0
	v_cvt_pk_bf16_f32 v80, v80, v81
	v_mul_f32_e32 v81, 0xbfb8aa3b, v86
	v_exp_f32_e32 v81, v81
	s_nop 0
	v_add_f32_e32 v81, 1.0, v81
	v_rcp_f32_e32 v84, v81
	v_mul_f32_e32 v81, 0xbfb8aa3b, v87
	v_exp_f32_e32 v81, v81
	s_nop 0
	v_add_f32_e32 v81, 1.0, v81
	v_rcp_f32_e32 v85, v81
	s_nop 0
	v_pk_mul_f32 v[84:85], v[86:87], v[84:85]
	s_nop 0
	v_pk_mul_f32 v[82:83], v[82:83], v[84:85]
	s_nop 0
	v_cvt_pk_bf16_f32 v81, v82, v83
	v_mul_f32_e32 v82, 0xbfb8aa3b, v76
	v_mul_f32_e32 v83, 0xbfb8aa3b, v77
	v_exp_f32_e32 v82, v82
	v_exp_f32_e32 v83, v83
	global_store_dwordx2 v[90:91], v[80:81], off offset:128
	v_or_b32_e32 v80, 48, v147
	v_add_f32_e32 v82, 1.0, v82
	v_add_f32_e32 v83, 1.0, v83
	v_rcp_f32_e32 v82, v82
	v_rcp_f32_e32 v83, v83
	v_mad_i64_i32 v[80:81], s[22:23], v80, s42, v[132:133]
	v_pk_mul_f32 v[76:77], v[76:77], v[82:83]
	s_nop 0
	v_pk_mul_f32 v[72:73], v[72:73], v[76:77]
	s_nop 0
	v_cvt_pk_bf16_f32 v72, v72, v73
	v_mul_f32_e32 v73, 0xbfb8aa3b, v78
	v_exp_f32_e32 v73, v73
	s_nop 0
	v_add_f32_e32 v73, 1.0, v73
	v_rcp_f32_e32 v76, v73
	v_mul_f32_e32 v73, 0xbfb8aa3b, v79
	v_exp_f32_e32 v73, v73
	s_nop 0
	v_add_f32_e32 v73, 1.0, v73
	v_rcp_f32_e32 v77, v73
	s_nop 0
	v_pk_mul_f32 v[76:77], v[78:79], v[76:77]
	s_nop 0
	v_pk_mul_f32 v[74:75], v[74:75], v[76:77]
	s_nop 0
	v_cvt_pk_bf16_f32 v73, v74, v75
	v_lshl_add_u64 v[74:75], v[80:81], 0, s[20:21]
	global_store_dwordx2 v[74:75], v[72:73], off
	v_mul_f32_e32 v72, 0xbfb8aa3b, v68
	v_mul_f32_e32 v73, 0xbfb8aa3b, v69
	v_exp_f32_e32 v72, v72
	v_exp_f32_e32 v73, v73
	v_add_f32_e32 v72, 1.0, v72
	v_add_f32_e32 v73, 1.0, v73
	v_rcp_f32_e32 v72, v72
	v_rcp_f32_e32 v73, v73
	s_nop 0
	v_pk_mul_f32 v[68:69], v[68:69], v[72:73]
	s_nop 0
	v_pk_mul_f32 v[64:65], v[64:65], v[68:69]
	s_nop 0
	v_cvt_pk_bf16_f32 v64, v64, v65
	v_mul_f32_e32 v65, 0xbfb8aa3b, v70
	v_exp_f32_e32 v65, v65
	s_nop 0
	v_add_f32_e32 v65, 1.0, v65
	v_rcp_f32_e32 v68, v65
	v_mul_f32_e32 v65, 0xbfb8aa3b, v71
	v_exp_f32_e32 v65, v65
	s_nop 0
	v_add_f32_e32 v65, 1.0, v65
	v_rcp_f32_e32 v69, v65
	s_nop 0
	v_pk_mul_f32 v[68:69], v[70:71], v[68:69]
	s_nop 0
	v_pk_mul_f32 v[66:67], v[66:67], v[68:69]
	s_nop 0
	v_cvt_pk_bf16_f32 v65, v66, v67
	v_mul_f32_e32 v66, 0xbfb8aa3b, v60
	v_mul_f32_e32 v67, 0xbfb8aa3b, v61
	v_exp_f32_e32 v66, v66
	v_exp_f32_e32 v67, v67
	global_store_dwordx2 v[74:75], v[64:65], off offset:128
	v_add_u32_e32 v64, 0x80, v147
	v_add_f32_e32 v66, 1.0, v66
	v_add_f32_e32 v67, 1.0, v67
	v_rcp_f32_e32 v66, v66
	v_rcp_f32_e32 v67, v67
	v_mad_i64_i32 v[64:65], s[22:23], v64, s42, v[132:133]
	v_pk_mul_f32 v[60:61], v[60:61], v[66:67]
	s_nop 0
	v_pk_mul_f32 v[56:57], v[56:57], v[60:61]
	s_nop 0
	v_cvt_pk_bf16_f32 v56, v56, v57
	v_mul_f32_e32 v57, 0xbfb8aa3b, v62
	v_exp_f32_e32 v57, v57
	s_nop 0
	v_add_f32_e32 v57, 1.0, v57
	v_rcp_f32_e32 v60, v57
	v_mul_f32_e32 v57, 0xbfb8aa3b, v63
	v_exp_f32_e32 v57, v57
	s_nop 0
	v_add_f32_e32 v57, 1.0, v57
	v_rcp_f32_e32 v61, v57
	s_nop 0
	v_pk_mul_f32 v[60:61], v[62:63], v[60:61]
	s_nop 0
	v_pk_mul_f32 v[58:59], v[58:59], v[60:61]
	s_nop 0
	v_cvt_pk_bf16_f32 v57, v58, v59
	v_lshl_add_u64 v[58:59], v[64:65], 0, s[20:21]
	global_store_dwordx2 v[58:59], v[56:57], off
	v_mul_f32_e32 v56, 0xbfb8aa3b, v52
	v_mul_f32_e32 v57, 0xbfb8aa3b, v53
	v_exp_f32_e32 v56, v56
	v_exp_f32_e32 v57, v57
	v_add_f32_e32 v56, 1.0, v56
	v_add_f32_e32 v57, 1.0, v57
	v_rcp_f32_e32 v56, v56
	v_rcp_f32_e32 v57, v57
	s_nop 0
	v_pk_mul_f32 v[52:53], v[52:53], v[56:57]
	s_nop 0
	v_pk_mul_f32 v[48:49], v[48:49], v[52:53]
	s_nop 0
	v_cvt_pk_bf16_f32 v48, v48, v49
	v_mul_f32_e32 v49, 0xbfb8aa3b, v54
	v_exp_f32_e32 v49, v49
	s_nop 0
	v_add_f32_e32 v49, 1.0, v49
	v_rcp_f32_e32 v52, v49
	v_mul_f32_e32 v49, 0xbfb8aa3b, v55
	v_exp_f32_e32 v49, v49
	s_nop 0
	v_add_f32_e32 v49, 1.0, v49
	v_rcp_f32_e32 v53, v49
	s_nop 0
	v_pk_mul_f32 v[52:53], v[54:55], v[52:53]
	s_nop 0
	v_pk_mul_f32 v[50:51], v[50:51], v[52:53]
	s_nop 0
	v_cvt_pk_bf16_f32 v49, v50, v51
	v_mul_f32_e32 v50, 0xbfb8aa3b, v44
	v_mul_f32_e32 v51, 0xbfb8aa3b, v45
	v_exp_f32_e32 v50, v50
	v_exp_f32_e32 v51, v51
	global_store_dwordx2 v[58:59], v[48:49], off offset:128
	v_add_u32_e32 v48, 0x90, v147
	v_add_f32_e32 v50, 1.0, v50
	v_add_f32_e32 v51, 1.0, v51
	v_rcp_f32_e32 v50, v50
	v_rcp_f32_e32 v51, v51
	v_mad_i64_i32 v[48:49], s[22:23], v48, s42, v[132:133]
	v_pk_mul_f32 v[44:45], v[44:45], v[50:51]
	s_nop 0
	v_pk_mul_f32 v[40:41], v[40:41], v[44:45]
	s_nop 0
	v_cvt_pk_bf16_f32 v40, v40, v41
	v_mul_f32_e32 v41, 0xbfb8aa3b, v46
	v_exp_f32_e32 v41, v41
	s_nop 0
	v_add_f32_e32 v41, 1.0, v41
	v_rcp_f32_e32 v44, v41
	v_mul_f32_e32 v41, 0xbfb8aa3b, v47
	v_exp_f32_e32 v41, v41
	s_nop 0
	v_add_f32_e32 v41, 1.0, v41
	v_rcp_f32_e32 v45, v41
	s_nop 0
	v_pk_mul_f32 v[44:45], v[46:47], v[44:45]
	s_nop 0
	v_pk_mul_f32 v[42:43], v[42:43], v[44:45]
	s_nop 0
	v_cvt_pk_bf16_f32 v41, v42, v43
	v_lshl_add_u64 v[42:43], v[48:49], 0, s[20:21]
	global_store_dwordx2 v[42:43], v[40:41], off
	v_mul_f32_e32 v40, 0xbfb8aa3b, v36
	v_mul_f32_e32 v41, 0xbfb8aa3b, v37
	v_exp_f32_e32 v40, v40
	v_exp_f32_e32 v41, v41
	v_add_f32_e32 v40, 1.0, v40
	v_add_f32_e32 v41, 1.0, v41
	v_rcp_f32_e32 v40, v40
	v_rcp_f32_e32 v41, v41
	s_nop 0
	v_pk_mul_f32 v[36:37], v[36:37], v[40:41]
	s_nop 0
	v_pk_mul_f32 v[32:33], v[32:33], v[36:37]
	s_nop 0
	v_cvt_pk_bf16_f32 v32, v32, v33
	v_mul_f32_e32 v33, 0xbfb8aa3b, v38
	v_exp_f32_e32 v33, v33
	s_nop 0
	v_add_f32_e32 v33, 1.0, v33
	v_rcp_f32_e32 v36, v33
	v_mul_f32_e32 v33, 0xbfb8aa3b, v39
	v_exp_f32_e32 v33, v33
	s_nop 0
	v_add_f32_e32 v33, 1.0, v33
	v_rcp_f32_e32 v37, v33
	s_nop 0
	v_pk_mul_f32 v[36:37], v[38:39], v[36:37]
	s_nop 0
	v_pk_mul_f32 v[34:35], v[34:35], v[36:37]
	s_nop 0
	v_cvt_pk_bf16_f32 v33, v34, v35
	v_mul_f32_e32 v34, 0xbfb8aa3b, v28
	v_mul_f32_e32 v35, 0xbfb8aa3b, v29
	v_exp_f32_e32 v34, v34
	v_exp_f32_e32 v35, v35
	global_store_dwordx2 v[42:43], v[32:33], off offset:128
	v_add_u32_e32 v32, 0xa0, v147
	v_add_f32_e32 v34, 1.0, v34
	v_add_f32_e32 v35, 1.0, v35
	v_rcp_f32_e32 v34, v34
	v_rcp_f32_e32 v35, v35
	v_mad_i64_i32 v[32:33], s[22:23], v32, s42, v[132:133]
	v_pk_mul_f32 v[28:29], v[28:29], v[34:35]
	s_nop 0
	v_pk_mul_f32 v[24:25], v[24:25], v[28:29]
	s_nop 0
	v_cvt_pk_bf16_f32 v24, v24, v25
	v_mul_f32_e32 v25, 0xbfb8aa3b, v30
	v_exp_f32_e32 v25, v25
	s_nop 0
	v_add_f32_e32 v25, 1.0, v25
	v_rcp_f32_e32 v28, v25
	v_mul_f32_e32 v25, 0xbfb8aa3b, v31
	v_exp_f32_e32 v25, v25
	s_nop 0
	v_add_f32_e32 v25, 1.0, v25
	v_rcp_f32_e32 v29, v25
	s_nop 0
	v_pk_mul_f32 v[28:29], v[30:31], v[28:29]
	s_nop 0
	v_pk_mul_f32 v[26:27], v[26:27], v[28:29]
	s_nop 0
	v_cvt_pk_bf16_f32 v25, v26, v27
	v_lshl_add_u64 v[26:27], v[32:33], 0, s[20:21]
	global_store_dwordx2 v[26:27], v[24:25], off
	v_mul_f32_e32 v24, 0xbfb8aa3b, v20
	v_mul_f32_e32 v25, 0xbfb8aa3b, v21
	v_exp_f32_e32 v24, v24
	v_exp_f32_e32 v25, v25
	v_add_f32_e32 v24, 1.0, v24
	v_add_f32_e32 v25, 1.0, v25
	v_rcp_f32_e32 v24, v24
	v_rcp_f32_e32 v25, v25
	s_nop 0
	v_pk_mul_f32 v[20:21], v[20:21], v[24:25]
	s_nop 0
	v_pk_mul_f32 v[16:17], v[16:17], v[20:21]
	s_nop 0
	v_cvt_pk_bf16_f32 v16, v16, v17
	v_mul_f32_e32 v17, 0xbfb8aa3b, v22
	v_exp_f32_e32 v17, v17
	s_nop 0
	v_add_f32_e32 v17, 1.0, v17
	v_rcp_f32_e32 v20, v17
	v_mul_f32_e32 v17, 0xbfb8aa3b, v23
	v_exp_f32_e32 v17, v17
	s_nop 0
	v_add_f32_e32 v17, 1.0, v17
	v_rcp_f32_e32 v21, v17
	s_nop 0
	v_pk_mul_f32 v[20:21], v[22:23], v[20:21]
	s_nop 0
	v_pk_mul_f32 v[18:19], v[18:19], v[20:21]
	s_nop 0
	v_cvt_pk_bf16_f32 v17, v18, v19
	v_mul_f32_e32 v18, 0xbfb8aa3b, v12
	v_mul_f32_e32 v19, 0xbfb8aa3b, v13
	v_exp_f32_e32 v18, v18
	v_exp_f32_e32 v19, v19
	global_store_dwordx2 v[26:27], v[16:17], off offset:128
	v_add_u32_e32 v16, 0xb0, v147
	v_add_f32_e32 v18, 1.0, v18
	v_add_f32_e32 v19, 1.0, v19
	v_rcp_f32_e32 v18, v18
	v_rcp_f32_e32 v19, v19
	v_mad_i64_i32 v[16:17], s[22:23], v16, s42, v[132:133]
	s_mov_b64 s[22:23], s[16:17]
	v_pk_mul_f32 v[12:13], v[12:13], v[18:19]
	s_nop 0
	v_pk_mul_f32 v[8:9], v[8:9], v[12:13]
	s_nop 0
	v_cvt_pk_bf16_f32 v8, v8, v9
	v_mul_f32_e32 v9, 0xbfb8aa3b, v14
	v_exp_f32_e32 v9, v9
	s_nop 0
	v_add_f32_e32 v9, 1.0, v9
	v_rcp_f32_e32 v12, v9
	v_mul_f32_e32 v9, 0xbfb8aa3b, v15
	v_exp_f32_e32 v9, v9
	s_nop 0
	v_add_f32_e32 v9, 1.0, v9
	v_rcp_f32_e32 v13, v9
	s_nop 0
	v_pk_mul_f32 v[12:13], v[14:15], v[12:13]
	s_nop 0
	v_pk_mul_f32 v[10:11], v[10:11], v[12:13]
	s_nop 0
	v_cvt_pk_bf16_f32 v9, v10, v11
	v_lshl_add_u64 v[10:11], v[16:17], 0, s[20:21]
	global_store_dwordx2 v[10:11], v[8:9], off
	v_mul_f32_e32 v8, 0xbfb8aa3b, v4
	v_mul_f32_e32 v9, 0xbfb8aa3b, v5
	v_exp_f32_e32 v8, v8
	v_exp_f32_e32 v9, v9
	s_mov_b32 s21, s12
	s_mov_b32 s20, s14
	v_add_f32_e32 v8, 1.0, v8
	v_add_f32_e32 v9, 1.0, v9
	v_rcp_f32_e32 v8, v8
	v_rcp_f32_e32 v9, v9
	s_nop 0
	v_pk_mul_f32 v[4:5], v[4:5], v[8:9]
	s_nop 0
	v_pk_mul_f32 v[0:1], v[0:1], v[4:5]
	s_nop 0
	v_cvt_pk_bf16_f32 v0, v0, v1
	v_mul_f32_e32 v1, 0xbfb8aa3b, v6
	v_exp_f32_e32 v1, v1
	s_nop 0
	v_add_f32_e32 v1, 1.0, v1
	v_rcp_f32_e32 v4, v1
	v_mul_f32_e32 v1, 0xbfb8aa3b, v7
	v_exp_f32_e32 v1, v1
	s_nop 0
	v_add_f32_e32 v1, 1.0, v1
	v_rcp_f32_e32 v5, v1
	s_nop 0
	v_pk_mul_f32 v[4:5], v[6:7], v[4:5]
	s_nop 0
	v_pk_mul_f32 v[2:3], v[2:3], v[4:5]
	s_nop 0
	v_cvt_pk_bf16_f32 v1, v2, v3
	global_store_dwordx2 v[10:11], v[0:1], off offset:128
	s_cbranch_vccz .LBB0_2002
	s_waitcnt vmcnt(0)
	s_cmpk_gt_u32 s1, 0xff
	s_cbranch_scc1 .LBB0_2009
	s_barrier

.LBB0_2081:
	ds_read_b128 v[128:131], v151
	ds_read_b128 v[144:147], v151 offset:1024
	ds_read_b128 v[154:157], v151 offset:2048
	ds_read_b128 v[158:161], v151 offset:3072
	s_add_u32 s18, s16, 0x100
	s_addc_u32 s19, s17, 0
	s_cmpk_eq_i32 s42, 0x54
	s_cselect_b32 s23, s11, s19
	s_cselect_b32 s22, s10, s18
	s_cselect_b32 s21, s13, s41
	s_cselect_b32 s20, s12, s40
	v_lshl_add_u64 v[194:195], s[16:17], 0, v[136:137]
	s_add_i32 m0, s4, 0xc000
	ds_read_b128 v[162:165], v152
	ds_read_b128 v[166:169], v152 offset:1024
	ds_read_b128 v[170:173], v152 offset:2048
	ds_read_b128 v[174:177], v152 offset:3072
	ds_read_b128 v[178:181], v152 offset:4096
	ds_read_b128 v[182:185], v152 offset:5120
	ds_read_b128 v[186:189], v152 offset:6144
	ds_read_b128 v[190:193], v152 offset:7168
	global_load_lds_dwordx4 v[194:195], off
	v_lshl_add_u64 v[194:195], s[16:17], 0, v[138:139]
	s_add_i32 m0, s4, 0xe000
	s_nop 0
	global_load_lds_dwordx4 v[194:195], off
	s_waitcnt lgkmcnt(8)
	s_barrier
	s_waitcnt lgkmcnt(0)
	s_waitcnt lgkmcnt(0)
	v_mfma_f32_16x16x32_bf16 v[124:127], v[128:131], v[162:165], v[124:127]
	v_mfma_f32_16x16x32_bf16 v[92:95], v[154:157], v[162:165], v[92:95]
	v_mfma_f32_16x16x32_bf16 v[120:123], v[128:131], v[170:173], v[120:123]
	v_mfma_f32_16x16x32_bf16 v[88:91], v[154:157], v[170:173], v[88:91]
	v_mfma_f32_16x16x32_bf16 v[116:119], v[128:131], v[178:181], v[116:119]
	v_mfma_f32_16x16x32_bf16 v[84:87], v[154:157], v[178:181], v[84:87]
	v_mfma_f32_16x16x32_bf16 v[112:115], v[128:131], v[186:189], v[112:115]
	v_mfma_f32_16x16x32_bf16 v[80:83], v[154:157], v[186:189], v[80:83]
	v_mfma_f32_16x16x32_bf16 v[124:127], v[144:147], v[166:169], v[124:127]
	v_mfma_f32_16x16x32_bf16 v[92:95], v[158:161], v[166:169], v[92:95]
	v_mfma_f32_16x16x32_bf16 v[120:123], v[144:147], v[174:177], v[120:123]
	v_mfma_f32_16x16x32_bf16 v[88:91], v[158:161], v[174:177], v[88:91]
	v_mfma_f32_16x16x32_bf16 v[116:119], v[144:147], v[182:185], v[116:119]
	v_mfma_f32_16x16x32_bf16 v[84:87], v[158:161], v[182:185], v[84:87]
	v_mfma_f32_16x16x32_bf16 v[112:115], v[144:147], v[190:193], v[112:115]
	v_mfma_f32_16x16x32_bf16 v[80:83], v[158:161], v[190:193], v[80:83]
	s_barrier
	s_add_i32 s16, s34, s3
	v_lshl_add_u64 v[210:211], s[20:21], 0, v[132:133]
	s_mov_b32 m0, s16
	ds_read_b128 v[194:197], v153
	ds_read_b128 v[198:201], v153 offset:1024
	ds_read_b128 v[202:205], v153 offset:2048
	ds_read_b128 v[206:209], v153 offset:3072
	global_load_lds_dwordx4 v[210:211], off
	v_lshl_add_u64 v[212:213], s[20:21], 0, v[134:135]
	s_add_i32 m0, s16, 0x2000
	s_nop 0
	global_load_lds_dwordx4 v[212:213], off
	s_barrier
	s_waitcnt lgkmcnt(0)
	s_waitcnt lgkmcnt(0)
	v_mfma_f32_16x16x32_bf16 v[76:79], v[194:197], v[162:165], v[76:79]
	v_mfma_f32_16x16x32_bf16 v[48:51], v[202:205], v[162:165], v[48:51]
	v_mfma_f32_16x16x32_bf16 v[68:71], v[194:197], v[170:173], v[68:71]
	v_mfma_f32_16x16x32_bf16 v[40:43], v[202:205], v[170:173], v[40:43]
	v_mfma_f32_16x16x32_bf16 v[60:63], v[194:197], v[178:181], v[60:63]
	v_mfma_f32_16x16x32_bf16 v[36:39], v[202:205], v[178:181], v[36:39]
	v_mfma_f32_16x16x32_bf16 v[52:55], v[194:197], v[186:189], v[52:55]
	v_mfma_f32_16x16x32_bf16 v[28:31], v[202:205], v[186:189], v[28:31]
	v_mfma_f32_16x16x32_bf16 v[76:79], v[198:201], v[166:169], v[76:79]
	v_mfma_f32_16x16x32_bf16 v[48:51], v[206:209], v[166:169], v[48:51]
	v_mfma_f32_16x16x32_bf16 v[68:71], v[198:201], v[174:177], v[68:71]
	v_mfma_f32_16x16x32_bf16 v[40:43], v[206:209], v[174:177], v[40:43]
	v_mfma_f32_16x16x32_bf16 v[60:63], v[198:201], v[182:185], v[60:63]
	v_mfma_f32_16x16x32_bf16 v[36:39], v[206:209], v[182:185], v[36:39]
	v_mfma_f32_16x16x32_bf16 v[52:55], v[198:201], v[190:193], v[52:55]
	v_mfma_f32_16x16x32_bf16 v[28:31], v[206:209], v[190:193], v[28:31]
	s_mov_b32 m0, s4
	v_lshl_add_u64 v[214:215], s[22:23], 0, v[132:133]
	s_barrier
	ds_read_b128 v[162:165], v152 offset:16384
	ds_read_b128 v[166:169], v152 offset:17408
	ds_read_b128 v[170:173], v152 offset:18432
	ds_read_b128 v[174:177], v152 offset:19456
	ds_read_b128 v[178:181], v152 offset:20480
	ds_read_b128 v[182:185], v152 offset:21504
	ds_read_b128 v[186:189], v152 offset:22528
	ds_read_b128 v[190:193], v152 offset:23552
	global_load_lds_dwordx4 v[214:215], off
	v_lshl_add_u64 v[216:217], s[22:23], 0, v[134:135]
	s_mov_b32 m0, s5
	s_nop 0
	global_load_lds_dwordx4 v[216:217], off
	s_barrier
	s_waitcnt lgkmcnt(0)
	s_waitcnt lgkmcnt(0)
	v_mfma_f32_16x16x32_bf16 v[108:111], v[128:131], v[162:165], v[108:111]
	v_mfma_f32_16x16x32_bf16 v[72:75], v[154:157], v[162:165], v[72:75]
	v_mfma_f32_16x16x32_bf16 v[104:107], v[128:131], v[170:173], v[104:107]
	v_mfma_f32_16x16x32_bf16 v[64:67], v[154:157], v[170:173], v[64:67]
	v_mfma_f32_16x16x32_bf16 v[100:103], v[128:131], v[178:181], v[100:103]
	v_mfma_f32_16x16x32_bf16 v[56:59], v[154:157], v[178:181], v[56:59]
	v_mfma_f32_16x16x32_bf16 v[96:99], v[128:131], v[186:189], v[96:99]
	v_mfma_f32_16x16x32_bf16 v[44:47], v[154:157], v[186:189], v[44:47]
	v_mfma_f32_16x16x32_bf16 v[108:111], v[144:147], v[166:169], v[108:111]
	v_mfma_f32_16x16x32_bf16 v[72:75], v[158:161], v[166:169], v[72:75]
	v_mfma_f32_16x16x32_bf16 v[104:107], v[144:147], v[174:177], v[104:107]
	v_mfma_f32_16x16x32_bf16 v[64:67], v[158:161], v[174:177], v[64:67]
	v_mfma_f32_16x16x32_bf16 v[100:103], v[144:147], v[182:185], v[100:103]
	v_mfma_f32_16x16x32_bf16 v[56:59], v[158:161], v[182:185], v[56:59]
	v_mfma_f32_16x16x32_bf16 v[96:99], v[144:147], v[190:193], v[96:99]
	v_mfma_f32_16x16x32_bf16 v[44:47], v[158:161], v[190:193], v[44:47]
	s_barrier
	s_add_u32 s16, s20, 0x160000
	s_addc_u32 s17, s21, 0
	s_add_i32 s43, s35, s3
	v_lshl_add_u64 v[128:129], s[16:17], 0, v[132:133]
	s_mov_b32 m0, s43
	s_nop 0
	global_load_lds_dwordx4 v[128:129], off
	v_lshl_add_u64 v[128:129], s[16:17], 0, v[134:135]
	s_add_i32 m0, s43, 0x2000
	s_nop 0
	global_load_lds_dwordx4 v[128:129], off
	s_waitcnt vmcnt(6)
	s_barrier
	v_mfma_f32_16x16x32_bf16 v[32:35], v[194:197], v[162:165], v[32:35]
	v_mfma_f32_16x16x32_bf16 v[12:15], v[202:205], v[162:165], v[12:15]
	v_mfma_f32_16x16x32_bf16 v[24:27], v[194:197], v[170:173], v[24:27]
	v_mfma_f32_16x16x32_bf16 v[8:11], v[202:205], v[170:173], v[8:11]
	v_mfma_f32_16x16x32_bf16 v[20:23], v[194:197], v[178:181], v[20:23]
	v_mfma_f32_16x16x32_bf16 v[4:7], v[202:205], v[178:181], v[4:7]
	v_mfma_f32_16x16x32_bf16 v[16:19], v[194:197], v[186:189], v[16:19]
	v_mfma_f32_16x16x32_bf16 v[0:3], v[202:205], v[186:189], v[0:3]
	v_mfma_f32_16x16x32_bf16 v[32:35], v[198:201], v[166:169], v[32:35]
	v_mfma_f32_16x16x32_bf16 v[12:15], v[206:209], v[166:169], v[12:15]
	v_mfma_f32_16x16x32_bf16 v[24:27], v[198:201], v[174:177], v[24:27]
	v_mfma_f32_16x16x32_bf16 v[8:11], v[206:209], v[174:177], v[8:11]
	v_mfma_f32_16x16x32_bf16 v[20:23], v[198:201], v[182:185], v[20:23]
	v_mfma_f32_16x16x32_bf16 v[4:7], v[206:209], v[182:185], v[4:7]
	v_mfma_f32_16x16x32_bf16 v[16:19], v[198:201], v[190:193], v[16:19]
	v_mfma_f32_16x16x32_bf16 v[0:3], v[206:209], v[190:193], v[0:3]
	s_add_i32 s43, 0, 0x18000
	v_add_u32_e32 v158, s43, v149
	s_barrier
	ds_read_b128 v[128:131], v158
	ds_read_b128 v[144:147], v158 offset:1024
	ds_read_b128 v[154:157], v158 offset:2048
	ds_read_b128 v[158:161], v158 offset:3072
	s_add_u32 s16, s22, 0x160000
	s_addc_u32 s17, s23, 0
	s_mov_b32 m0, s24
	v_lshl_add_u64 v[194:195], s[16:17], 0, v[132:133]
	ds_read_b128 v[162:165], v152 offset:32768
	ds_read_b128 v[166:169], v152 offset:33792
	ds_read_b128 v[170:173], v152 offset:34816
	ds_read_b128 v[174:177], v152 offset:35840
	ds_read_b128 v[178:181], v152 offset:36864
	ds_read_b128 v[182:185], v152 offset:37888
	ds_read_b128 v[186:189], v152 offset:38912
	ds_read_b128 v[190:193], v152 offset:39936
	global_load_lds_dwordx4 v[194:195], off
	v_lshl_add_u64 v[194:195], s[16:17], 0, v[134:135]
	s_mov_b32 m0, s25
	s_nop 0
	global_load_lds_dwordx4 v[194:195], off
	s_waitcnt lgkmcnt(8)
	s_barrier
	s_waitcnt lgkmcnt(0)
	s_waitcnt lgkmcnt(0)
	v_mfma_f32_16x16x32_bf16 v[124:127], v[128:131], v[162:165], v[124:127]
	v_mfma_f32_16x16x32_bf16 v[92:95], v[154:157], v[162:165], v[92:95]
	v_mfma_f32_16x16x32_bf16 v[120:123], v[128:131], v[170:173], v[120:123]
	v_mfma_f32_16x16x32_bf16 v[88:91], v[154:157], v[170:173], v[88:91]
	v_mfma_f32_16x16x32_bf16 v[116:119], v[128:131], v[178:181], v[116:119]
	v_mfma_f32_16x16x32_bf16 v[84:87], v[154:157], v[178:181], v[84:87]
	v_mfma_f32_16x16x32_bf16 v[112:115], v[128:131], v[186:189], v[112:115]
	v_mfma_f32_16x16x32_bf16 v[80:83], v[154:157], v[186:189], v[80:83]
	v_mfma_f32_16x16x32_bf16 v[124:127], v[144:147], v[166:169], v[124:127]
	v_mfma_f32_16x16x32_bf16 v[92:95], v[158:161], v[166:169], v[92:95]
	v_mfma_f32_16x16x32_bf16 v[120:123], v[144:147], v[174:177], v[120:123]
	v_mfma_f32_16x16x32_bf16 v[88:91], v[158:161], v[174:177], v[88:91]
	v_mfma_f32_16x16x32_bf16 v[116:119], v[144:147], v[182:185], v[116:119]
	v_mfma_f32_16x16x32_bf16 v[84:87], v[158:161], v[182:185], v[84:87]
	v_mfma_f32_16x16x32_bf16 v[112:115], v[144:147], v[190:193], v[112:115]
	v_mfma_f32_16x16x32_bf16 v[80:83], v[158:161], v[190:193], v[80:83]
	s_barrier
	s_add_i32 s22, 0, 0x1c000
	s_add_i32 s16, s43, s3
	v_add_u32_e32 v206, s22, v149
	v_lshl_add_u64 v[210:211], v[210:211], 0, s[14:15]
	s_mov_b32 m0, s16
	ds_read_b128 v[194:197], v206
	ds_read_b128 v[198:201], v206 offset:1024
	ds_read_b128 v[202:205], v206 offset:2048
	ds_read_b128 v[206:209], v206 offset:3072
	global_load_lds_dwordx4 v[210:211], off
	v_lshl_add_u64 v[210:211], v[212:213], 0, s[14:15]
	s_add_i32 m0, s16, 0x2000
	s_nop 0
	global_load_lds_dwordx4 v[210:211], off
	s_barrier
	s_waitcnt lgkmcnt(0)
	s_waitcnt lgkmcnt(0)
	v_mfma_f32_16x16x32_bf16 v[76:79], v[194:197], v[162:165], v[76:79]
	v_mfma_f32_16x16x32_bf16 v[48:51], v[202:205], v[162:165], v[48:51]
	v_mfma_f32_16x16x32_bf16 v[68:71], v[194:197], v[170:173], v[68:71]
	v_mfma_f32_16x16x32_bf16 v[40:43], v[202:205], v[170:173], v[40:43]
	v_mfma_f32_16x16x32_bf16 v[60:63], v[194:197], v[178:181], v[60:63]
	v_mfma_f32_16x16x32_bf16 v[36:39], v[202:205], v[178:181], v[36:39]
	v_mfma_f32_16x16x32_bf16 v[52:55], v[194:197], v[186:189], v[52:55]
	v_mfma_f32_16x16x32_bf16 v[28:31], v[202:205], v[186:189], v[28:31]
	v_mfma_f32_16x16x32_bf16 v[76:79], v[198:201], v[166:169], v[76:79]
	v_mfma_f32_16x16x32_bf16 v[48:51], v[206:209], v[166:169], v[48:51]
	v_mfma_f32_16x16x32_bf16 v[68:71], v[198:201], v[174:177], v[68:71]
	v_mfma_f32_16x16x32_bf16 v[40:43], v[206:209], v[174:177], v[40:43]
	v_mfma_f32_16x16x32_bf16 v[60:63], v[198:201], v[182:185], v[60:63]
	v_mfma_f32_16x16x32_bf16 v[36:39], v[206:209], v[182:185], v[36:39]
	v_mfma_f32_16x16x32_bf16 v[52:55], v[198:201], v[190:193], v[52:55]
	v_mfma_f32_16x16x32_bf16 v[28:31], v[206:209], v[190:193], v[28:31]
	s_mov_b32 m0, s27
	v_lshl_add_u64 v[210:211], v[214:215], 0, s[14:15]
	s_barrier
	ds_read_b128 v[162:165], v152 offset:49152
	ds_read_b128 v[166:169], v152 offset:50176
	ds_read_b128 v[170:173], v152 offset:51200
	ds_read_b128 v[174:177], v152 offset:52224
	ds_read_b128 v[178:181], v152 offset:53248
	ds_read_b128 v[182:185], v152 offset:54272
	ds_read_b128 v[186:189], v152 offset:55296
	ds_read_b128 v[190:193], v152 offset:56320
	global_load_lds_dwordx4 v[210:211], off
	v_lshl_add_u64 v[210:211], v[216:217], 0, s[14:15]
	s_mov_b32 m0, s28
	s_nop 0
	global_load_lds_dwordx4 v[210:211], off
	s_barrier
	s_waitcnt lgkmcnt(0)
	s_waitcnt lgkmcnt(0)
	v_mfma_f32_16x16x32_bf16 v[108:111], v[128:131], v[162:165], v[108:111]
	v_mfma_f32_16x16x32_bf16 v[72:75], v[154:157], v[162:165], v[72:75]
	v_mfma_f32_16x16x32_bf16 v[104:107], v[128:131], v[170:173], v[104:107]
	v_mfma_f32_16x16x32_bf16 v[64:67], v[154:157], v[170:173], v[64:67]
	v_mfma_f32_16x16x32_bf16 v[100:103], v[128:131], v[178:181], v[100:103]
	v_mfma_f32_16x16x32_bf16 v[56:59], v[154:157], v[178:181], v[56:59]
	v_mfma_f32_16x16x32_bf16 v[96:99], v[128:131], v[186:189], v[96:99]
	v_mfma_f32_16x16x32_bf16 v[44:47], v[154:157], v[186:189], v[44:47]
	v_mfma_f32_16x16x32_bf16 v[108:111], v[144:147], v[166:169], v[108:111]
	v_mfma_f32_16x16x32_bf16 v[72:75], v[158:161], v[166:169], v[72:75]
	v_mfma_f32_16x16x32_bf16 v[104:107], v[144:147], v[174:177], v[104:107]
	v_mfma_f32_16x16x32_bf16 v[64:67], v[158:161], v[174:177], v[64:67]
	v_mfma_f32_16x16x32_bf16 v[100:103], v[144:147], v[182:185], v[100:103]
	v_mfma_f32_16x16x32_bf16 v[56:59], v[158:161], v[182:185], v[56:59]
	v_mfma_f32_16x16x32_bf16 v[96:99], v[144:147], v[190:193], v[96:99]
	v_mfma_f32_16x16x32_bf16 v[44:47], v[158:161], v[190:193], v[44:47]
	s_barrier
	s_add_u32 s16, s20, 0x160080
	s_addc_u32 s17, s21, 0
	s_add_i32 s20, s22, s3
	v_lshl_add_u64 v[128:129], s[16:17], 0, v[132:133]
	s_mov_b32 m0, s20
	s_nop 0
	global_load_lds_dwordx4 v[128:129], off
	v_lshl_add_u64 v[128:129], s[16:17], 0, v[134:135]
	s_add_i32 m0, s20, 0x2000
	s_nop 0
	global_load_lds_dwordx4 v[128:129], off
	s_waitcnt vmcnt(6)
	s_barrier
	v_mfma_f32_16x16x32_bf16 v[32:35], v[194:197], v[162:165], v[32:35]
	v_mfma_f32_16x16x32_bf16 v[12:15], v[202:205], v[162:165], v[12:15]
	v_mfma_f32_16x16x32_bf16 v[24:27], v[194:197], v[170:173], v[24:27]
	v_mfma_f32_16x16x32_bf16 v[8:11], v[202:205], v[170:173], v[8:11]
	v_mfma_f32_16x16x32_bf16 v[20:23], v[194:197], v[178:181], v[20:23]
	v_mfma_f32_16x16x32_bf16 v[4:7], v[202:205], v[178:181], v[4:7]
	v_mfma_f32_16x16x32_bf16 v[16:19], v[194:197], v[186:189], v[16:19]
	v_mfma_f32_16x16x32_bf16 v[0:3], v[202:205], v[186:189], v[0:3]
	v_mfma_f32_16x16x32_bf16 v[32:35], v[198:201], v[166:169], v[32:35]
	v_mfma_f32_16x16x32_bf16 v[12:15], v[206:209], v[166:169], v[12:15]
	v_mfma_f32_16x16x32_bf16 v[24:27], v[198:201], v[174:177], v[24:27]
	v_mfma_f32_16x16x32_bf16 v[8:11], v[206:209], v[174:177], v[8:11]
	v_mfma_f32_16x16x32_bf16 v[20:23], v[198:201], v[182:185], v[20:23]
	v_mfma_f32_16x16x32_bf16 v[4:7], v[206:209], v[182:185], v[4:7]
	v_mfma_f32_16x16x32_bf16 v[16:19], v[198:201], v[190:193], v[16:19]
	v_mfma_f32_16x16x32_bf16 v[0:3], v[206:209], v[190:193], v[0:3]
	s_add_i32 s42, s42, 2
	s_add_u32 s40, s40, 0x100
	s_addc_u32 s41, s41, 0
	s_cmpk_gt_u32 s42, 0x55
	s_mov_b64 s[16:17], s[18:19]
	s_barrier
	s_cbranch_scc0 .LBB0_2081
	s_cmp_lt_u32 s38, 32
	s_movk_i32 s16, 0x3000
	s_cselect_b32 s16, s16, 0x6000
	s_cmp_gt_i32 s38, 15
	v_lshl_add_u32 v158, s38, 8, v148
	s_cselect_b32 s16, s16, 0
	v_lshl_or_b32 v128, s39, 8, v150
	s_lshl_b32 s16, s16, 2
	v_ashrrev_i32_e32 v159, 31, v158
	s_add_u32 s16, s30, s16
	v_ashrrev_i32_e32 v129, 31, v128
	v_lshlrev_b64 v[146:147], 13, v[158:159]
	s_addc_u32 s17, s31, 0
	v_lshlrev_b64 v[160:161], 2, v[128:129]
	v_lshl_add_u64 v[146:147], s[56:57], 0, v[146:147]
	v_lshl_add_u64 v[144:145], s[16:17], 0, v[160:161]
	v_lshl_add_u64 v[146:147], v[146:147], 0, v[160:161]
	s_mov_b64 s[16:17], 0x100000
	s_mov_b32 s39, s36
	s_mov_b32 s38, s37
	s_mov_b64 s[18:19], s[12:13]
	v_or_b32_e32 v162, 16, v158
	v_ashrrev_i32_e32 v163, 31, v162
	v_lshlrev_b64 v[164:165], 13, v[162:163]
	v_lshl_add_u64 v[162:163], s[56:57], 0, v[164:165]
	v_lshl_add_u64 v[164:165], v[162:163], 0, v[160:161]
	v_or_b32_e32 v162, 32, v158
	v_ashrrev_i32_e32 v163, 31, v162
	v_lshlrev_b64 v[166:167], 13, v[162:163]
	v_lshl_add_u64 v[162:163], s[56:57], 0, v[166:167]
	v_lshl_add_u64 v[166:167], v[162:163], 0, v[160:161]
	v_or_b32_e32 v162, 48, v158
	v_ashrrev_i32_e32 v163, 31, v162
	v_lshlrev_b64 v[168:169], 13, v[162:163]
	v_lshl_add_u64 v[162:163], s[56:57], 0, v[168:169]
	v_lshl_add_u64 v[168:169], v[162:163], 0, v[160:161]
	v_lshl_add_u64 v[162:163], v[146:147], 0, s[16:17]
	s_mov_b32 s16, 0x100000
	v_add_co_u32_e32 v170, vcc, s16, v146
	s_mov_b64 s[16:17], 0x120000
	s_nop 0
	v_addc_co_u32_e32 v171, vcc, 0, v147, vcc
	v_lshl_add_u64 v[172:173], v[146:147], 0, s[16:17]
	s_mov_b32 s16, 0x120000
	v_add_co_u32_e32 v174, vcc, s16, v146
	s_mov_b64 s[16:17], 0x140000
	s_nop 0
	v_addc_co_u32_e32 v175, vcc, 0, v147, vcc
	v_lshl_add_u64 v[176:177], v[146:147], 0, s[16:17]
	s_mov_b32 s16, 0x140000
	v_add_co_u32_e32 v178, vcc, s16, v146
	s_mov_b64 s[16:17], 0x160000
	s_nop 0
	v_addc_co_u32_e32 v179, vcc, 0, v147, vcc
	v_lshl_add_u64 v[180:181], v[146:147], 0, s[16:17]
	s_mov_b32 s16, 0x160000
	v_add_co_u32_e32 v182, vcc, s16, v146
	s_mov_b64 s[16:17], s[10:11]
	s_nop 0
	v_addc_co_u32_e32 v183, vcc, 0, v147, vcc
	s_and_b64 vcc, exec, s[6:7]
	global_load_dwordx4 v[184:187], v[144:145], off
	global_load_dwordx4 v[188:191], v[146:147], off
	v_pk_add_f32 v[126:127], v[126:127], 0 op_sel_hi:[1,0]
	v_pk_add_f32 v[124:125], v[124:125], 0 op_sel_hi:[1,0]
	v_pk_add_f32 v[122:123], v[122:123], 0 op_sel_hi:[1,0]
	v_pk_add_f32 v[120:121], v[120:121], 0 op_sel_hi:[1,0]
	v_pk_add_f32 v[118:119], v[118:119], 0 op_sel_hi:[1,0]
	v_pk_add_f32 v[116:117], v[116:117], 0 op_sel_hi:[1,0]
	v_pk_add_f32 v[114:115], v[114:115], 0 op_sel_hi:[1,0]
	v_pk_add_f32 v[112:113], v[112:113], 0 op_sel_hi:[1,0]
	v_pk_add_f32 v[110:111], v[110:111], 0 op_sel_hi:[1,0]
	v_pk_add_f32 v[108:109], v[108:109], 0 op_sel_hi:[1,0]
	v_pk_add_f32 v[106:107], v[106:107], 0 op_sel_hi:[1,0]
	v_pk_add_f32 v[104:105], v[104:105], 0 op_sel_hi:[1,0]
	v_pk_add_f32 v[102:103], v[102:103], 0 op_sel_hi:[1,0]
	v_pk_add_f32 v[100:101], v[100:101], 0 op_sel_hi:[1,0]
	v_pk_add_f32 v[98:99], v[98:99], 0 op_sel_hi:[1,0]
	v_pk_add_f32 v[96:97], v[96:97], 0 op_sel_hi:[1,0]
	v_pk_add_f32 v[94:95], v[94:95], 0 op_sel_hi:[1,0]
	v_pk_add_f32 v[92:93], v[92:93], 0 op_sel_hi:[1,0]
	v_pk_add_f32 v[90:91], v[90:91], 0 op_sel_hi:[1,0]
	v_pk_add_f32 v[88:89], v[88:89], 0 op_sel_hi:[1,0]
	v_pk_add_f32 v[86:87], v[86:87], 0 op_sel_hi:[1,0]
	v_pk_add_f32 v[84:85], v[84:85], 0 op_sel_hi:[1,0]
	v_pk_add_f32 v[82:83], v[82:83], 0 op_sel_hi:[1,0]
	v_pk_add_f32 v[80:81], v[80:81], 0 op_sel_hi:[1,0]
	v_pk_add_f32 v[74:75], v[74:75], 0 op_sel_hi:[1,0]
	v_pk_add_f32 v[72:73], v[72:73], 0 op_sel_hi:[1,0]
	v_pk_add_f32 v[66:67], v[66:67], 0 op_sel_hi:[1,0]
	v_pk_add_f32 v[64:65], v[64:65], 0 op_sel_hi:[1,0]
	v_pk_add_f32 v[58:59], v[58:59], 0 op_sel_hi:[1,0]
	v_pk_add_f32 v[56:57], v[56:57], 0 op_sel_hi:[1,0]
	v_pk_add_f32 v[46:47], v[46:47], 0 op_sel_hi:[1,0]
	v_pk_add_f32 v[44:45], v[44:45], 0 op_sel_hi:[1,0]
	v_pk_add_f32 v[62:63], v[62:63], 0 op_sel_hi:[1,0]
	v_pk_add_f32 v[60:61], v[60:61], 0 op_sel_hi:[1,0]
	v_pk_add_f32 v[54:55], v[54:55], 0 op_sel_hi:[1,0]
	v_pk_add_f32 v[52:53], v[52:53], 0 op_sel_hi:[1,0]
	v_pk_add_f32 v[34:35], v[34:35], 0 op_sel_hi:[1,0]
	v_pk_add_f32 v[32:33], v[32:33], 0 op_sel_hi:[1,0]
	v_pk_add_f32 v[26:27], v[26:27], 0 op_sel_hi:[1,0]
	v_pk_add_f32 v[24:25], v[24:25], 0 op_sel_hi:[1,0]
	v_pk_add_f32 v[22:23], v[22:23], 0 op_sel_hi:[1,0]
	v_pk_add_f32 v[20:21], v[20:21], 0 op_sel_hi:[1,0]
	v_pk_add_f32 v[18:19], v[18:19], 0 op_sel_hi:[1,0]
	v_pk_add_f32 v[16:17], v[16:17], 0 op_sel_hi:[1,0]
	v_pk_add_f32 v[14:15], v[14:15], 0 op_sel_hi:[1,0]
	v_pk_add_f32 v[12:13], v[12:13], 0 op_sel_hi:[1,0]
	v_pk_add_f32 v[10:11], v[10:11], 0 op_sel_hi:[1,0]
	v_pk_add_f32 v[8:9], v[8:9], 0 op_sel_hi:[1,0]
	v_pk_add_f32 v[6:7], v[6:7], 0 op_sel_hi:[1,0]
	v_pk_add_f32 v[4:5], v[4:5], 0 op_sel_hi:[1,0]
	v_pk_add_f32 v[2:3], v[2:3], 0 op_sel_hi:[1,0]
	v_pk_add_f32 v[0:1], v[0:1], 0 op_sel_hi:[1,0]
	s_waitcnt vmcnt(0)
	v_pk_fma_f32 v[126:127], v[126:127], v[186:187], v[190:191]
	v_pk_fma_f32 v[124:125], v[124:125], v[184:185], v[188:189]
	global_store_dwordx4 v[146:147], v[124:127], off
	global_load_dwordx4 v[188:191], v[164:165], off
	global_load_dwordx4 v[192:195], v[166:167], off
	global_load_dwordx4 v[196:199], v[168:169], off
	global_load_dwordx4 v[200:203], v[170:171], off
	global_load_dwordx4 v[204:207], v[174:175], off
	global_load_dwordx4 v[208:211], v[178:179], off
	global_load_dwordx4 v[212:215], v[182:183], off
	global_load_dwordx4 v[216:219], v[144:145], off offset:64
	global_load_dwordx4 v[220:223], v[146:147], off offset:64
	global_load_dwordx4 v[224:227], v[164:165], off offset:64
	global_load_dwordx4 v[228:231], v[166:167], off offset:64
	global_load_dwordx4 v[232:235], v[168:169], off offset:64
	s_waitcnt vmcnt(11)
	v_pk_fma_f32 v[122:123], v[122:123], v[186:187], v[190:191]
	v_pk_fma_f32 v[120:121], v[120:121], v[184:185], v[188:189]
	global_store_dwordx4 v[164:165], v[120:123], off
	global_load_dwordx4 v[188:191], v[162:163], off offset:64
	s_waitcnt vmcnt(12)
	v_pk_fma_f32 v[118:119], v[118:119], v[186:187], v[194:195]
	v_pk_fma_f32 v[116:117], v[116:117], v[184:185], v[192:193]
	global_store_dwordx4 v[166:167], v[116:119], off
	global_load_dwordx4 v[192:195], v[172:173], off offset:64
	s_waitcnt vmcnt(13)
	v_pk_fma_f32 v[114:115], v[114:115], v[186:187], v[198:199]
	v_pk_fma_f32 v[112:113], v[112:113], v[184:185], v[196:197]
	global_store_dwordx4 v[168:169], v[112:115], off
	global_load_dwordx4 v[196:199], v[176:177], off offset:64
	s_waitcnt vmcnt(14)
	v_pk_fma_f32 v[110:111], v[110:111], v[186:187], v[202:203]
	v_pk_fma_f32 v[108:109], v[108:109], v[184:185], v[200:201]
	global_store_dwordx4 v[170:171], v[108:111], off
	global_load_dwordx4 v[200:203], v[180:181], off offset:64
	s_waitcnt vmcnt(15)
	v_pk_fma_f32 v[106:107], v[106:107], v[186:187], v[206:207]
	v_pk_fma_f32 v[104:105], v[104:105], v[184:185], v[204:205]
	global_store_dwordx4 v[174:175], v[104:107], off
	global_load_dwordx4 v[204:207], v[144:145], off offset:512
	s_waitcnt vmcnt(16)
	v_pk_fma_f32 v[102:103], v[102:103], v[186:187], v[210:211]
	v_pk_fma_f32 v[100:101], v[100:101], v[184:185], v[208:209]
	global_store_dwordx4 v[178:179], v[100:103], off
	global_load_dwordx4 v[208:211], v[146:147], off offset:512
	s_waitcnt vmcnt(17)
	v_pk_fma_f32 v[98:99], v[98:99], v[186:187], v[214:215]
	v_pk_fma_f32 v[96:97], v[96:97], v[184:185], v[212:213]
	global_store_dwordx4 v[182:183], v[96:99], off
	global_load_dwordx4 v[184:187], v[164:165], off offset:512
	s_waitcnt vmcnt(17)
	v_pk_fma_f32 v[94:95], v[94:95], v[218:219], v[222:223]
	v_pk_fma_f32 v[92:93], v[92:93], v[216:217], v[220:221]
	global_store_dwordx4 v[146:147], v[92:95], off offset:64
	global_load_dwordx4 v[212:215], v[166:167], off offset:512
	global_load_dwordx4 v[220:223], v[168:169], off offset:512
	s_waitcnt vmcnt(19)
	v_pk_fma_f32 v[90:91], v[90:91], v[218:219], v[226:227]
	v_pk_fma_f32 v[88:89], v[88:89], v[216:217], v[224:225]
	global_store_dwordx4 v[164:165], v[88:91], off offset:64
	global_load_dwordx4 v[224:227], v[162:163], off offset:512
	s_waitcnt vmcnt(20)
	v_pk_fma_f32 v[86:87], v[86:87], v[218:219], v[230:231]
	v_pk_fma_f32 v[84:85], v[84:85], v[216:217], v[228:229]
	global_store_dwordx4 v[166:167], v[84:87], off offset:64
	global_load_dwordx4 v[228:231], v[172:173], off offset:512
	s_waitcnt vmcnt(21)
	v_pk_fma_f32 v[82:83], v[82:83], v[218:219], v[234:235]
	v_pk_fma_f32 v[80:81], v[80:81], v[216:217], v[232:233]
	global_store_dwordx4 v[168:169], v[80:83], off offset:64
	global_load_dwordx4 v[232:235], v[176:177], off offset:512
	s_waitcnt vmcnt(21)
	v_pk_fma_f32 v[74:75], v[74:75], v[218:219], v[190:191]
	v_pk_fma_f32 v[72:73], v[72:73], v[216:217], v[188:189]
	global_store_dwordx4 v[162:163], v[72:75], off offset:64
	global_load_dwordx4 v[188:191], v[180:181], off offset:512
	s_waitcnt vmcnt(21)
	v_pk_fma_f32 v[66:67], v[66:67], v[218:219], v[194:195]
	v_pk_fma_f32 v[64:65], v[64:65], v[216:217], v[192:193]
	global_store_dwordx4 v[172:173], v[64:67], off offset:64
	global_load_dwordx4 v[192:195], v[144:145], off offset:576
	s_waitcnt vmcnt(21)
	v_pk_fma_f32 v[58:59], v[58:59], v[218:219], v[198:199]
	v_pk_fma_f32 v[56:57], v[56:57], v[216:217], v[196:197]
	global_store_dwordx4 v[176:177], v[56:59], off offset:64
	global_load_dwordx4 v[196:199], v[146:147], off offset:576
	v_pk_add_f32 v[64:65], v[78:79], 0 op_sel_hi:[1,0]
	v_pk_add_f32 v[66:67], v[76:77], 0 op_sel_hi:[1,0]
	s_waitcnt vmcnt(21)
	v_pk_fma_f32 v[46:47], v[46:47], v[218:219], v[202:203]
	v_pk_fma_f32 v[44:45], v[44:45], v[216:217], v[200:201]
	global_store_dwordx4 v[180:181], v[44:47], off offset:64
	global_load_dwordx4 v[200:203], v[164:165], off offset:576
	s_waitcnt vmcnt(19)
	v_pk_fma_f32 v[58:59], v[64:65], v[206:207], v[210:211]
	v_pk_fma_f32 v[56:57], v[66:67], v[204:205], v[208:209]
	global_store_dwordx4 v[146:147], v[56:59], off offset:512
	global_load_dwordx4 v[208:211], v[166:167], off offset:576
	global_load_dwordx4 v[216:219], v[168:169], off offset:576
	v_pk_add_f32 v[64:65], v[70:71], 0 op_sel_hi:[1,0]
	v_pk_add_f32 v[66:67], v[68:69], 0 op_sel_hi:[1,0]
	s_waitcnt vmcnt(20)
	v_pk_fma_f32 v[58:59], v[64:65], v[206:207], v[186:187]
	v_pk_fma_f32 v[56:57], v[66:67], v[204:205], v[184:185]
	global_store_dwordx4 v[164:165], v[56:59], off offset:512
	global_load_dwordx4 v[184:187], v[162:163], off offset:576
	s_waitcnt vmcnt(20)
	v_pk_fma_f32 v[58:59], v[62:63], v[206:207], v[214:215]
	v_pk_fma_f32 v[56:57], v[60:61], v[204:205], v[212:213]
	global_store_dwordx4 v[166:167], v[56:59], off offset:512
	global_load_dwordx4 v[212:215], v[172:173], off offset:576
	s_waitcnt vmcnt(21)
	v_pk_fma_f32 v[54:55], v[54:55], v[206:207], v[222:223]
	v_pk_fma_f32 v[52:53], v[52:53], v[204:205], v[220:221]
	global_store_dwordx4 v[168:169], v[52:55], off offset:512
	global_load_dwordx4 v[220:223], v[176:177], off offset:576
	s_waitcnt vmcnt(21)
	v_pk_fma_f32 v[34:35], v[34:35], v[206:207], v[226:227]
	v_pk_fma_f32 v[32:33], v[32:33], v[204:205], v[224:225]
	global_store_dwordx4 v[162:163], v[32:35], off offset:512
	global_load_dwordx4 v[224:227], v[180:181], off offset:576
	s_waitcnt vmcnt(21)
	v_pk_fma_f32 v[26:27], v[26:27], v[206:207], v[230:231]
	v_pk_fma_f32 v[24:25], v[24:25], v[204:205], v[228:229]
	global_store_dwordx4 v[172:173], v[24:27], off offset:512
	s_waitcnt vmcnt(20)
	v_pk_fma_f32 v[22:23], v[22:23], v[206:207], v[234:235]
	v_pk_fma_f32 v[20:21], v[20:21], v[204:205], v[232:233]
	global_store_dwordx4 v[176:177], v[20:23], off offset:512
	v_pk_add_f32 v[24:25], v[50:51], 0 op_sel_hi:[1,0]
	v_pk_add_f32 v[26:27], v[48:49], 0 op_sel_hi:[1,0]
	s_waitcnt vmcnt(19)
	v_pk_fma_f32 v[18:19], v[18:19], v[206:207], v[190:191]
	v_pk_fma_f32 v[16:17], v[16:17], v[204:205], v[188:189]
	global_store_dwordx4 v[180:181], v[16:19], off offset:512
	s_waitcnt vmcnt(16)
	v_pk_fma_f32 v[22:23], v[24:25], v[194:195], v[198:199]
	v_pk_fma_f32 v[20:21], v[26:27], v[192:193], v[196:197]
	global_store_dwordx4 v[146:147], v[20:23], off offset:576
	v_pk_add_f32 v[24:25], v[42:43], 0 op_sel_hi:[1,0]
	v_pk_add_f32 v[26:27], v[40:41], 0 op_sel_hi:[1,0]
	s_waitcnt vmcnt(15)
	v_pk_fma_f32 v[22:23], v[24:25], v[194:195], v[202:203]
	v_pk_fma_f32 v[20:21], v[26:27], v[192:193], v[200:201]
	global_store_dwordx4 v[164:165], v[20:23], off offset:576
	v_pk_add_f32 v[24:25], v[38:39], 0 op_sel_hi:[1,0]
	v_pk_add_f32 v[26:27], v[36:37], 0 op_sel_hi:[1,0]
	s_waitcnt vmcnt(14)
	v_pk_fma_f32 v[22:23], v[24:25], v[194:195], v[210:211]
	v_pk_fma_f32 v[20:21], v[26:27], v[192:193], v[208:209]
	global_store_dwordx4 v[166:167], v[20:23], off offset:576
	v_pk_add_f32 v[24:25], v[30:31], 0 op_sel_hi:[1,0]
	v_pk_add_f32 v[26:27], v[28:29], 0 op_sel_hi:[1,0]
	s_waitcnt vmcnt(14)
	v_pk_fma_f32 v[22:23], v[24:25], v[194:195], v[218:219]
	v_pk_fma_f32 v[20:21], v[26:27], v[192:193], v[216:217]
	global_store_dwordx4 v[168:169], v[20:23], off offset:576
	s_waitcnt vmcnt(13)
	v_pk_fma_f32 v[14:15], v[14:15], v[194:195], v[186:187]
	v_pk_fma_f32 v[12:13], v[12:13], v[192:193], v[184:185]
	global_store_dwordx4 v[162:163], v[12:15], off offset:576
	s_waitcnt vmcnt(12)
	v_pk_fma_f32 v[10:11], v[10:11], v[194:195], v[214:215]
	v_pk_fma_f32 v[8:9], v[8:9], v[192:193], v[212:213]
	global_store_dwordx4 v[172:173], v[8:11], off offset:576
	s_waitcnt vmcnt(11)
	v_pk_fma_f32 v[6:7], v[6:7], v[194:195], v[222:223]
	v_pk_fma_f32 v[4:5], v[4:5], v[192:193], v[220:221]
	global_store_dwordx4 v[176:177], v[4:7], off offset:576
	s_waitcnt vmcnt(10)
	v_pk_fma_f32 v[2:3], v[2:3], v[194:195], v[226:227]
	v_pk_fma_f32 v[0:1], v[0:1], v[192:193], v[224:225]
	global_store_dwordx4 v[180:181], v[0:3], off offset:576
	s_cbranch_vccz .LBB0_2070
	s_waitcnt vmcnt(0)
	s_cmpk_gt_u32 s1, 0xff
	s_cbranch_scc1 .LBB0_2085
	s_barrier

.LBB0_2097:
	ds_read_b128 v[144:147], v139
	ds_read_b128 v[148:151], v139 offset:1024
	ds_read_b128 v[152:155], v139 offset:2048
	ds_read_b128 v[156:159], v139 offset:3072
	s_add_u32 s20, s18, 0x100
	s_addc_u32 s21, s19, 0
	s_cmp_eq_u32 s61, 4
	s_cselect_b32 s25, s17, s21
	s_cselect_b32 s24, s16, s20
	s_cselect_b32 s23, s11, s60
	s_cselect_b32 s22, s10, s47
	s_mov_b32 m0, s35
	v_lshl_add_u64 v[192:193], s[18:19], 0, v[132:133]
	ds_read_b128 v[160:163], v140
	ds_read_b128 v[164:167], v140 offset:1024
	ds_read_b128 v[168:171], v140 offset:2048
	ds_read_b128 v[172:175], v140 offset:3072
	ds_read_b128 v[176:179], v140 offset:4096
	ds_read_b128 v[180:183], v140 offset:5120
	ds_read_b128 v[184:187], v140 offset:6144
	ds_read_b128 v[188:191], v140 offset:7168
	global_load_lds_dwordx4 v[192:193], off
	v_lshl_add_u64 v[192:193], s[18:19], 0, v[134:135]
	s_mov_b32 m0, s36
	s_nop 0
	global_load_lds_dwordx4 v[192:193], off
	s_waitcnt lgkmcnt(8)
	s_barrier
	s_waitcnt lgkmcnt(0)
	s_waitcnt lgkmcnt(0)
	v_mfma_f32_16x16x32_bf16 v[124:127], v[144:147], v[160:163], v[124:127]
	v_mfma_f32_16x16x32_bf16 v[120:123], v[152:155], v[160:163], v[120:123]
	v_mfma_f32_16x16x32_bf16 v[116:119], v[144:147], v[168:171], v[116:119]
	v_mfma_f32_16x16x32_bf16 v[112:115], v[152:155], v[168:171], v[112:115]
	v_mfma_f32_16x16x32_bf16 v[100:103], v[144:147], v[176:179], v[100:103]
	v_mfma_f32_16x16x32_bf16 v[96:99], v[152:155], v[176:179], v[96:99]
	v_mfma_f32_16x16x32_bf16 v[84:87], v[144:147], v[184:187], v[84:87]
	v_mfma_f32_16x16x32_bf16 v[80:83], v[152:155], v[184:187], v[80:83]
	v_mfma_f32_16x16x32_bf16 v[124:127], v[148:151], v[164:167], v[124:127]
	v_mfma_f32_16x16x32_bf16 v[120:123], v[156:159], v[164:167], v[120:123]
	v_mfma_f32_16x16x32_bf16 v[116:119], v[148:151], v[172:175], v[116:119]
	v_mfma_f32_16x16x32_bf16 v[112:115], v[156:159], v[172:175], v[112:115]
	v_mfma_f32_16x16x32_bf16 v[100:103], v[148:151], v[180:183], v[100:103]
	v_mfma_f32_16x16x32_bf16 v[96:99], v[156:159], v[180:183], v[96:99]
	v_mfma_f32_16x16x32_bf16 v[84:87], v[148:151], v[188:191], v[84:87]
	v_mfma_f32_16x16x32_bf16 v[80:83], v[156:159], v[188:191], v[80:83]
	s_barrier
	s_mov_b32 m0, s37
	v_lshl_add_u64 v[208:209], s[22:23], 0, v[130:131]
	ds_read_b128 v[192:195], v141
	ds_read_b128 v[196:199], v141 offset:1024
	ds_read_b128 v[200:203], v141 offset:2048
	ds_read_b128 v[204:207], v141 offset:3072
	global_load_lds_dwordx4 v[208:209], off
	v_lshl_add_u64 v[210:211], s[22:23], 0, v[128:129]
	s_mov_b32 m0, s38
	s_nop 0
	global_load_lds_dwordx4 v[210:211], off
	s_barrier
	s_waitcnt lgkmcnt(0)
	s_waitcnt lgkmcnt(0)
	v_mfma_f32_16x16x32_bf16 v[108:111], v[192:195], v[160:163], v[108:111]
	v_mfma_f32_16x16x32_bf16 v[104:107], v[200:203], v[160:163], v[104:107]
	v_mfma_f32_16x16x32_bf16 v[92:95], v[192:195], v[168:171], v[92:95]
	v_mfma_f32_16x16x32_bf16 v[88:91], v[200:203], v[168:171], v[88:91]
	v_mfma_f32_16x16x32_bf16 v[76:79], v[192:195], v[176:179], v[76:79]
	v_mfma_f32_16x16x32_bf16 v[72:75], v[200:203], v[176:179], v[72:75]
	v_mfma_f32_16x16x32_bf16 v[68:71], v[192:195], v[184:187], v[68:71]
	v_mfma_f32_16x16x32_bf16 v[64:67], v[200:203], v[184:187], v[64:67]
	v_mfma_f32_16x16x32_bf16 v[108:111], v[196:199], v[164:167], v[108:111]
	v_mfma_f32_16x16x32_bf16 v[104:107], v[204:207], v[164:167], v[104:107]
	v_mfma_f32_16x16x32_bf16 v[92:95], v[196:199], v[172:175], v[92:95]
	v_mfma_f32_16x16x32_bf16 v[88:91], v[204:207], v[172:175], v[88:91]
	v_mfma_f32_16x16x32_bf16 v[76:79], v[196:199], v[180:183], v[76:79]
	v_mfma_f32_16x16x32_bf16 v[72:75], v[204:207], v[180:183], v[72:75]
	v_mfma_f32_16x16x32_bf16 v[68:71], v[196:199], v[188:191], v[68:71]
	v_mfma_f32_16x16x32_bf16 v[64:67], v[204:207], v[188:191], v[64:67]
	s_mov_b32 m0, s3
	v_lshl_add_u64 v[212:213], s[24:25], 0, v[130:131]
	s_barrier
	ds_read_b128 v[160:163], v140 offset:16384
	ds_read_b128 v[164:167], v140 offset:17408
	ds_read_b128 v[168:171], v140 offset:18432
	ds_read_b128 v[172:175], v140 offset:19456
	ds_read_b128 v[176:179], v140 offset:20480
	ds_read_b128 v[180:183], v140 offset:21504
	ds_read_b128 v[184:187], v140 offset:22528
	ds_read_b128 v[188:191], v140 offset:23552
	global_load_lds_dwordx4 v[212:213], off
	v_lshl_add_u64 v[214:215], s[24:25], 0, v[128:129]
	s_mov_b32 m0, s4
	s_nop 0
	global_load_lds_dwordx4 v[214:215], off
	s_barrier
	s_waitcnt lgkmcnt(0)
	s_waitcnt lgkmcnt(0)
	v_mfma_f32_16x16x32_bf16 v[60:63], v[144:147], v[160:163], v[60:63]
	v_mfma_f32_16x16x32_bf16 v[56:59], v[152:155], v[160:163], v[56:59]
	v_mfma_f32_16x16x32_bf16 v[52:55], v[144:147], v[168:171], v[52:55]
	v_mfma_f32_16x16x32_bf16 v[48:51], v[152:155], v[168:171], v[48:51]
	v_mfma_f32_16x16x32_bf16 v[36:39], v[144:147], v[176:179], v[36:39]
	v_mfma_f32_16x16x32_bf16 v[32:35], v[152:155], v[176:179], v[32:35]
	v_mfma_f32_16x16x32_bf16 v[20:23], v[144:147], v[184:187], v[20:23]
	v_mfma_f32_16x16x32_bf16 v[16:19], v[152:155], v[184:187], v[16:19]
	v_mfma_f32_16x16x32_bf16 v[60:63], v[148:151], v[164:167], v[60:63]
	v_mfma_f32_16x16x32_bf16 v[56:59], v[156:159], v[164:167], v[56:59]
	v_mfma_f32_16x16x32_bf16 v[52:55], v[148:151], v[172:175], v[52:55]
	v_mfma_f32_16x16x32_bf16 v[48:51], v[156:159], v[172:175], v[48:51]
	v_mfma_f32_16x16x32_bf16 v[36:39], v[148:151], v[180:183], v[36:39]
	v_mfma_f32_16x16x32_bf16 v[32:35], v[156:159], v[180:183], v[32:35]
	v_mfma_f32_16x16x32_bf16 v[20:23], v[148:151], v[188:191], v[20:23]
	v_mfma_f32_16x16x32_bf16 v[16:19], v[156:159], v[188:191], v[16:19]
	s_barrier
	s_add_u32 s18, s22, 0x160000
	s_addc_u32 s19, s23, 0
	s_mov_b32 m0, s39
	v_lshl_add_u64 v[144:145], s[18:19], 0, v[130:131]
	global_load_lds_dwordx4 v[144:145], off
	v_lshl_add_u64 v[144:145], s[18:19], 0, v[128:129]
	s_mov_b32 m0, s40
	s_nop 0
	global_load_lds_dwordx4 v[144:145], off
	s_waitcnt vmcnt(6)
	s_barrier
	v_mfma_f32_16x16x32_bf16 v[44:47], v[192:195], v[160:163], v[44:47]
	v_mfma_f32_16x16x32_bf16 v[40:43], v[200:203], v[160:163], v[40:43]
	v_mfma_f32_16x16x32_bf16 v[28:31], v[192:195], v[168:171], v[28:31]
	v_mfma_f32_16x16x32_bf16 v[24:27], v[200:203], v[168:171], v[24:27]
	v_mfma_f32_16x16x32_bf16 v[12:15], v[192:195], v[176:179], v[12:15]
	v_mfma_f32_16x16x32_bf16 v[8:11], v[200:203], v[176:179], v[8:11]
	v_mfma_f32_16x16x32_bf16 v[4:7], v[192:195], v[184:187], v[4:7]
	v_mfma_f32_16x16x32_bf16 v[0:3], v[200:203], v[184:187], v[0:3]
	v_mfma_f32_16x16x32_bf16 v[44:47], v[196:199], v[164:167], v[44:47]
	v_mfma_f32_16x16x32_bf16 v[40:43], v[204:207], v[164:167], v[40:43]
	v_mfma_f32_16x16x32_bf16 v[28:31], v[196:199], v[172:175], v[28:31]
	v_mfma_f32_16x16x32_bf16 v[24:27], v[204:207], v[172:175], v[24:27]
	v_mfma_f32_16x16x32_bf16 v[12:15], v[196:199], v[180:183], v[12:15]
	v_mfma_f32_16x16x32_bf16 v[8:11], v[204:207], v[180:183], v[8:11]
	v_mfma_f32_16x16x32_bf16 v[4:7], v[196:199], v[188:191], v[4:7]
	v_mfma_f32_16x16x32_bf16 v[0:3], v[204:207], v[188:191], v[0:3]
	s_barrier
	ds_read_b128 v[144:147], v142
	ds_read_b128 v[148:151], v142 offset:1024
	ds_read_b128 v[152:155], v142 offset:2048
	ds_read_b128 v[156:159], v142 offset:3072
	s_add_u32 s18, s24, 0x160000
	s_addc_u32 s19, s25, 0
	s_mov_b32 m0, s5
	v_lshl_add_u64 v[192:193], s[18:19], 0, v[130:131]
	ds_read_b128 v[160:163], v140 offset:32768
	ds_read_b128 v[164:167], v140 offset:33792
	ds_read_b128 v[168:171], v140 offset:34816
	ds_read_b128 v[172:175], v140 offset:35840
	ds_read_b128 v[176:179], v140 offset:36864
	ds_read_b128 v[180:183], v140 offset:37888
	ds_read_b128 v[184:187], v140 offset:38912
	ds_read_b128 v[188:191], v140 offset:39936
	global_load_lds_dwordx4 v[192:193], off
	v_lshl_add_u64 v[192:193], s[18:19], 0, v[128:129]
	s_mov_b32 m0, s26
	s_nop 0
	global_load_lds_dwordx4 v[192:193], off
	s_waitcnt lgkmcnt(8)
	s_barrier
	s_waitcnt lgkmcnt(0)
	s_waitcnt lgkmcnt(0)
	v_mfma_f32_16x16x32_bf16 v[124:127], v[144:147], v[160:163], v[124:127]
	v_mfma_f32_16x16x32_bf16 v[120:123], v[152:155], v[160:163], v[120:123]
	v_mfma_f32_16x16x32_bf16 v[116:119], v[144:147], v[168:171], v[116:119]
	v_mfma_f32_16x16x32_bf16 v[112:115], v[152:155], v[168:171], v[112:115]
	v_mfma_f32_16x16x32_bf16 v[100:103], v[144:147], v[176:179], v[100:103]
	v_mfma_f32_16x16x32_bf16 v[96:99], v[152:155], v[176:179], v[96:99]
	v_mfma_f32_16x16x32_bf16 v[84:87], v[144:147], v[184:187], v[84:87]
	v_mfma_f32_16x16x32_bf16 v[80:83], v[152:155], v[184:187], v[80:83]
	v_mfma_f32_16x16x32_bf16 v[124:127], v[148:151], v[164:167], v[124:127]
	v_mfma_f32_16x16x32_bf16 v[120:123], v[156:159], v[164:167], v[120:123]
	v_mfma_f32_16x16x32_bf16 v[116:119], v[148:151], v[172:175], v[116:119]
	v_mfma_f32_16x16x32_bf16 v[112:115], v[156:159], v[172:175], v[112:115]
	v_mfma_f32_16x16x32_bf16 v[100:103], v[148:151], v[180:183], v[100:103]
	v_mfma_f32_16x16x32_bf16 v[96:99], v[156:159], v[180:183], v[96:99]
	v_mfma_f32_16x16x32_bf16 v[84:87], v[148:151], v[188:191], v[84:87]
	v_mfma_f32_16x16x32_bf16 v[80:83], v[156:159], v[188:191], v[80:83]
	s_barrier
	s_add_i32 s24, 0, 0x1c000
	s_add_i32 s18, s41, s2
	v_add_u32_e32 v143, s24, v137
	v_lshl_add_u64 v[208:209], v[208:209], 0, s[12:13]
	s_mov_b32 m0, s18
	ds_read_b128 v[192:195], v143
	ds_read_b128 v[196:199], v143 offset:1024
	ds_read_b128 v[200:203], v143 offset:2048
	ds_read_b128 v[204:207], v143 offset:3072
	global_load_lds_dwordx4 v[208:209], off
	v_lshl_add_u64 v[208:209], v[210:211], 0, s[12:13]
	s_add_i32 m0, s18, 0x2000
	s_nop 0
	global_load_lds_dwordx4 v[208:209], off
	s_barrier
	s_waitcnt lgkmcnt(0)
	s_waitcnt lgkmcnt(0)
	v_mfma_f32_16x16x32_bf16 v[108:111], v[192:195], v[160:163], v[108:111]
	v_mfma_f32_16x16x32_bf16 v[104:107], v[200:203], v[160:163], v[104:107]
	v_mfma_f32_16x16x32_bf16 v[92:95], v[192:195], v[168:171], v[92:95]
	v_mfma_f32_16x16x32_bf16 v[88:91], v[200:203], v[168:171], v[88:91]
	v_mfma_f32_16x16x32_bf16 v[76:79], v[192:195], v[176:179], v[76:79]
	v_mfma_f32_16x16x32_bf16 v[72:75], v[200:203], v[176:179], v[72:75]
	v_mfma_f32_16x16x32_bf16 v[68:71], v[192:195], v[184:187], v[68:71]
	v_mfma_f32_16x16x32_bf16 v[64:67], v[200:203], v[184:187], v[64:67]
	v_mfma_f32_16x16x32_bf16 v[108:111], v[196:199], v[164:167], v[108:111]
	v_mfma_f32_16x16x32_bf16 v[104:107], v[204:207], v[164:167], v[104:107]
	v_mfma_f32_16x16x32_bf16 v[92:95], v[196:199], v[172:175], v[92:95]
	v_mfma_f32_16x16x32_bf16 v[88:91], v[204:207], v[172:175], v[88:91]
	v_mfma_f32_16x16x32_bf16 v[76:79], v[196:199], v[180:183], v[76:79]
	v_mfma_f32_16x16x32_bf16 v[72:75], v[204:207], v[180:183], v[72:75]
	v_mfma_f32_16x16x32_bf16 v[68:71], v[196:199], v[188:191], v[68:71]
	v_mfma_f32_16x16x32_bf16 v[64:67], v[204:207], v[188:191], v[64:67]
	s_mov_b32 m0, s31
	v_lshl_add_u64 v[208:209], v[212:213], 0, s[12:13]
	s_barrier
	ds_read_b128 v[160:163], v140 offset:49152
	ds_read_b128 v[164:167], v140 offset:50176
	ds_read_b128 v[168:171], v140 offset:51200
	ds_read_b128 v[172:175], v140 offset:52224
	ds_read_b128 v[176:179], v140 offset:53248
	ds_read_b128 v[180:183], v140 offset:54272
	ds_read_b128 v[184:187], v140 offset:55296
	ds_read_b128 v[188:191], v140 offset:56320
	global_load_lds_dwordx4 v[208:209], off
	v_lshl_add_u64 v[208:209], v[214:215], 0, s[12:13]
	s_mov_b32 m0, s34
	s_nop 0
	global_load_lds_dwordx4 v[208:209], off
	s_barrier
	s_waitcnt lgkmcnt(0)
	s_waitcnt lgkmcnt(0)
	v_mfma_f32_16x16x32_bf16 v[60:63], v[144:147], v[160:163], v[60:63]
	v_mfma_f32_16x16x32_bf16 v[56:59], v[152:155], v[160:163], v[56:59]
	v_mfma_f32_16x16x32_bf16 v[52:55], v[144:147], v[168:171], v[52:55]
	v_mfma_f32_16x16x32_bf16 v[48:51], v[152:155], v[168:171], v[48:51]
	v_mfma_f32_16x16x32_bf16 v[36:39], v[144:147], v[176:179], v[36:39]
	v_mfma_f32_16x16x32_bf16 v[32:35], v[152:155], v[176:179], v[32:35]
	v_mfma_f32_16x16x32_bf16 v[20:23], v[144:147], v[184:187], v[20:23]
	v_mfma_f32_16x16x32_bf16 v[16:19], v[152:155], v[184:187], v[16:19]
	v_mfma_f32_16x16x32_bf16 v[60:63], v[148:151], v[164:167], v[60:63]
	v_mfma_f32_16x16x32_bf16 v[56:59], v[156:159], v[164:167], v[56:59]
	v_mfma_f32_16x16x32_bf16 v[52:55], v[148:151], v[172:175], v[52:55]
	v_mfma_f32_16x16x32_bf16 v[48:51], v[156:159], v[172:175], v[48:51]
	v_mfma_f32_16x16x32_bf16 v[36:39], v[148:151], v[180:183], v[36:39]
	v_mfma_f32_16x16x32_bf16 v[32:35], v[156:159], v[180:183], v[32:35]
	v_mfma_f32_16x16x32_bf16 v[20:23], v[148:151], v[188:191], v[20:23]
	v_mfma_f32_16x16x32_bf16 v[16:19], v[156:159], v[188:191], v[16:19]
	s_barrier
	s_add_u32 s18, s22, 0x160080
	s_addc_u32 s19, s23, 0
	s_add_i32 s22, s24, s2
	v_lshl_add_u64 v[144:145], s[18:19], 0, v[130:131]
	s_mov_b32 m0, s22
	s_nop 0
	global_load_lds_dwordx4 v[144:145], off
	v_lshl_add_u64 v[144:145], s[18:19], 0, v[128:129]
	s_add_i32 m0, s22, 0x2000
	s_nop 0
	global_load_lds_dwordx4 v[144:145], off
	s_waitcnt vmcnt(6)
	s_barrier
	v_mfma_f32_16x16x32_bf16 v[44:47], v[192:195], v[160:163], v[44:47]
	v_mfma_f32_16x16x32_bf16 v[40:43], v[200:203], v[160:163], v[40:43]
	v_mfma_f32_16x16x32_bf16 v[28:31], v[192:195], v[168:171], v[28:31]
	v_mfma_f32_16x16x32_bf16 v[24:27], v[200:203], v[168:171], v[24:27]
	v_mfma_f32_16x16x32_bf16 v[12:15], v[192:195], v[176:179], v[12:15]
	v_mfma_f32_16x16x32_bf16 v[8:11], v[200:203], v[176:179], v[8:11]
	v_mfma_f32_16x16x32_bf16 v[4:7], v[192:195], v[184:187], v[4:7]
	v_mfma_f32_16x16x32_bf16 v[0:3], v[200:203], v[184:187], v[0:3]
	v_mfma_f32_16x16x32_bf16 v[44:47], v[196:199], v[164:167], v[44:47]
	v_mfma_f32_16x16x32_bf16 v[40:43], v[204:207], v[164:167], v[40:43]
	v_mfma_f32_16x16x32_bf16 v[28:31], v[196:199], v[172:175], v[28:31]
	v_mfma_f32_16x16x32_bf16 v[24:27], v[204:207], v[172:175], v[24:27]
	v_mfma_f32_16x16x32_bf16 v[12:15], v[196:199], v[180:183], v[12:15]
	v_mfma_f32_16x16x32_bf16 v[8:11], v[204:207], v[180:183], v[8:11]
	v_mfma_f32_16x16x32_bf16 v[4:7], v[196:199], v[188:191], v[4:7]
	v_mfma_f32_16x16x32_bf16 v[0:3], v[204:207], v[188:191], v[0:3]
	s_add_i32 s61, s61, 2
	s_add_u32 s47, s47, 0x100
	s_addc_u32 s60, s60, 0
	s_cmp_gt_u32 s61, 5
	s_mov_b64 s[18:19], s[20:21]
	s_barrier
	s_cbranch_scc0 .LBB0_2097
	s_ashr_i32 s18, s30, 1
	s_and_b32 s18, s18, 0xfffffe00
	s_lshl_b32 s19, s29, 8
	s_add_i32 s19, s19, s18
	v_add_u32_e32 v146, s19, v136
	v_lshl_or_b32 v144, s28, 8, v138
	v_ashrrev_i32_e32 v147, 31, v146
	v_readlane_b32 s52, v240, 22
	v_ashrrev_i32_e32 v145, 31, v144
	v_lshlrev_b64 v[148:149], 13, v[146:147]
	v_readlane_b32 s66, v240, 36
	v_readlane_b32 s67, v240, 37
	v_lshlrev_b64 v[144:145], 2, v[144:145]
	s_mov_b64 s[18:19], 0x100000
	v_lshl_add_u64 v[148:149], s[66:67], 0, v[148:149]
	v_lshl_add_u64 v[148:149], v[148:149], 0, v[144:145]
	global_store_dwordx4 v[148:149], v[124:127], off
	global_store_dwordx4 v[148:149], v[120:123], off offset:64
	global_store_dwordx4 v[148:149], v[108:111], off offset:512
	global_store_dwordx4 v[148:149], v[104:107], off offset:576
	v_readlane_b32 s53, v240, 23
	v_readlane_b32 s56, v240, 26
	v_or_b32_e32 v104, 16, v146
	v_ashrrev_i32_e32 v105, 31, v104
	v_lshlrev_b64 v[104:105], 13, v[104:105]
	v_lshl_add_u64 v[104:105], s[66:67], 0, v[104:105]
	v_lshl_add_u64 v[104:105], v[104:105], 0, v[144:145]
	global_store_dwordx4 v[104:105], v[116:119], off
	global_store_dwordx4 v[104:105], v[112:115], off offset:64
	global_store_dwordx4 v[104:105], v[92:95], off offset:512
	global_store_dwordx4 v[104:105], v[88:91], off offset:576
	v_readlane_b32 s57, v240, 27
	v_readlane_b32 s60, v240, 30
	v_or_b32_e32 v88, 32, v146
	v_ashrrev_i32_e32 v89, 31, v88
	v_lshlrev_b64 v[88:89], 13, v[88:89]
	v_lshl_add_u64 v[88:89], s[66:67], 0, v[88:89]
	v_lshl_add_u64 v[88:89], v[88:89], 0, v[144:145]
	global_store_dwordx4 v[88:89], v[100:103], off
	global_store_dwordx4 v[88:89], v[96:99], off offset:64
	global_store_dwordx4 v[88:89], v[76:79], off offset:512
	global_store_dwordx4 v[88:89], v[72:75], off offset:576
	v_readlane_b32 s61, v240, 31
	v_readlane_b32 s62, v240, 32
	v_or_b32_e32 v72, 48, v146
	v_ashrrev_i32_e32 v73, 31, v72
	v_lshlrev_b64 v[72:73], 13, v[72:73]
	v_lshl_add_u64 v[72:73], s[66:67], 0, v[72:73]
	v_lshl_add_u64 v[72:73], v[72:73], 0, v[144:145]
	global_store_dwordx4 v[72:73], v[84:87], off
	global_store_dwordx4 v[72:73], v[80:83], off offset:64
	global_store_dwordx4 v[72:73], v[68:71], off offset:512
	global_store_dwordx4 v[72:73], v[64:67], off offset:576
	v_readlane_b32 s63, v240, 33
	s_mov_b32 s30, s43
	v_lshl_add_u64 v[64:65], v[148:149], 0, s[18:19]
	s_mov_b32 s18, 0x100000
	v_add_co_u32_e32 v66, vcc, s18, v148
	s_mov_b64 s[18:19], 0x120000
	s_nop 0
	v_addc_co_u32_e32 v67, vcc, 0, v149, vcc
	global_store_dwordx4 v[66:67], v[60:63], off
	global_store_dwordx4 v[64:65], v[56:59], off offset:64
	global_store_dwordx4 v[64:65], v[44:47], off offset:512
	global_store_dwordx4 v[64:65], v[40:43], off offset:576
	s_mov_b32 s28, s42
	s_mov_b32 s29, s46
	v_lshl_add_u64 v[40:41], v[148:149], 0, s[18:19]
	s_mov_b32 s18, 0x120000
	v_add_co_u32_e32 v42, vcc, s18, v148
	s_mov_b64 s[18:19], 0x140000
	s_nop 0
	v_addc_co_u32_e32 v43, vcc, 0, v149, vcc
	global_store_dwordx4 v[42:43], v[52:55], off
	global_store_dwordx4 v[40:41], v[48:51], off offset:64
	global_store_dwordx4 v[40:41], v[28:31], off offset:512
	global_store_dwordx4 v[40:41], v[24:27], off offset:576
	s_mov_b64 s[20:21], s[10:11]
	v_readlane_b32 s54, v240, 24
	v_lshl_add_u64 v[24:25], v[148:149], 0, s[18:19]
	s_mov_b32 s18, 0x140000
	v_add_co_u32_e32 v26, vcc, s18, v148
	s_mov_b64 s[18:19], 0x160000
	s_nop 0
	v_addc_co_u32_e32 v27, vcc, 0, v149, vcc
	global_store_dwordx4 v[26:27], v[36:39], off
	global_store_dwordx4 v[24:25], v[32:35], off offset:64
	global_store_dwordx4 v[24:25], v[12:15], off offset:512
	global_store_dwordx4 v[24:25], v[8:11], off offset:576
	v_readlane_b32 s55, v240, 25
	v_readlane_b32 s58, v240, 28
	v_add_co_u32_e32 v10, vcc, 0x160000, v148
	v_lshl_add_u64 v[8:9], v[148:149], 0, s[18:19]
	s_nop 0
	v_addc_co_u32_e32 v11, vcc, 0, v149, vcc
	s_and_b64 vcc, exec, s[14:15]
	s_mov_b64 s[18:19], s[16:17]
	v_readlane_b32 s59, v240, 29
	v_readlane_b32 s64, v240, 34
	v_readlane_b32 s65, v240, 35
	global_store_dwordx4 v[10:11], v[20:23], off
	global_store_dwordx4 v[8:9], v[16:19], off offset:64
	global_store_dwordx4 v[8:9], v[4:7], off offset:512
	global_store_dwordx4 v[8:9], v[0:3], off offset:576
	s_cbranch_vccz .LBB0_2090
	s_waitcnt vmcnt(0)
	s_cmpk_gt_u32 s1, 0xff
	s_cbranch_scc1 .LBB0_2101
	s_barrier

.LBB0_2281:
	ds_read_b128 v[140:143], v157
	ds_read_b128 v[144:147], v157 offset:1024
	ds_read_b128 v[148:151], v157 offset:2048
	ds_read_b128 v[160:163], v157 offset:3072
	s_add_u32 s30, s28, 0x100
	s_addc_u32 s31, s29, 0
	s_cmp_eq_u32 s69, 28
	s_cselect_b32 s37, s19, s31
	s_cselect_b32 s36, s65, s30
	s_cselect_b32 s35, s17, s68
	s_cselect_b32 s34, s66, s67
	v_lshl_add_u64 v[152:153], s[28:29], 0, v[132:133]
	s_add_i32 m0, s4, 0xc000
	ds_read_b128 v[164:167], v158
	ds_read_b128 v[168:171], v158 offset:1024
	ds_read_b128 v[172:175], v158 offset:2048
	ds_read_b128 v[176:179], v158 offset:3072
	ds_read_b128 v[180:183], v158 offset:4096
	ds_read_b128 v[184:187], v158 offset:5120
	ds_read_b128 v[188:191], v158 offset:6144
	ds_read_b128 v[192:195], v158 offset:7168
	global_load_lds_dwordx4 v[152:153], off
	v_lshl_add_u64 v[152:153], s[28:29], 0, v[134:135]
	s_add_i32 m0, s4, 0xe000
	s_nop 0
	global_load_lds_dwordx4 v[152:153], off
	s_waitcnt lgkmcnt(8)
	s_barrier
	s_waitcnt lgkmcnt(0)
	s_waitcnt lgkmcnt(0)
	v_mfma_f32_16x16x32_bf16 v[124:127], v[140:143], v[164:167], v[124:127]
	v_mfma_f32_16x16x32_bf16 v[120:123], v[148:151], v[164:167], v[120:123]
	v_mfma_f32_16x16x32_bf16 v[116:119], v[140:143], v[172:175], v[116:119]
	v_mfma_f32_16x16x32_bf16 v[108:111], v[148:151], v[172:175], v[108:111]
	v_mfma_f32_16x16x32_bf16 v[100:103], v[140:143], v[180:183], v[100:103]
	v_mfma_f32_16x16x32_bf16 v[92:95], v[148:151], v[180:183], v[92:95]
	v_mfma_f32_16x16x32_bf16 v[84:87], v[140:143], v[188:191], v[84:87]
	v_mfma_f32_16x16x32_bf16 v[76:79], v[148:151], v[188:191], v[76:79]
	v_mfma_f32_16x16x32_bf16 v[124:127], v[144:147], v[168:171], v[124:127]
	v_mfma_f32_16x16x32_bf16 v[120:123], v[160:163], v[168:171], v[120:123]
	v_mfma_f32_16x16x32_bf16 v[116:119], v[144:147], v[176:179], v[116:119]
	v_mfma_f32_16x16x32_bf16 v[108:111], v[160:163], v[176:179], v[108:111]
	v_mfma_f32_16x16x32_bf16 v[100:103], v[144:147], v[184:187], v[100:103]
	v_mfma_f32_16x16x32_bf16 v[92:95], v[160:163], v[184:187], v[92:95]
	v_mfma_f32_16x16x32_bf16 v[84:87], v[144:147], v[192:195], v[84:87]
	v_mfma_f32_16x16x32_bf16 v[76:79], v[160:163], v[192:195], v[76:79]
	s_barrier
	s_add_i32 s28, s47, s3
	v_lshl_add_u64 v[152:153], s[34:35], 0, v[128:129]
	s_mov_b32 m0, s28
	ds_read_b128 v[196:199], v159
	ds_read_b128 v[200:203], v159 offset:1024
	ds_read_b128 v[204:207], v159 offset:2048
	ds_read_b128 v[208:211], v159 offset:3072
	global_load_lds_dwordx4 v[152:153], off
	v_lshl_add_u64 v[212:213], s[34:35], 0, v[130:131]
	s_add_i32 m0, s28, 0x2000
	s_nop 0
	global_load_lds_dwordx4 v[212:213], off
	s_barrier
	s_waitcnt lgkmcnt(0)
	s_waitcnt lgkmcnt(0)
	v_mfma_f32_16x16x32_bf16 v[112:115], v[196:199], v[164:167], v[112:115]
	v_mfma_f32_16x16x32_bf16 v[104:107], v[204:207], v[164:167], v[104:107]
	v_mfma_f32_16x16x32_bf16 v[96:99], v[196:199], v[172:175], v[96:99]
	v_mfma_f32_16x16x32_bf16 v[88:91], v[204:207], v[172:175], v[88:91]
	v_mfma_f32_16x16x32_bf16 v[80:83], v[196:199], v[180:183], v[80:83]
	v_mfma_f32_16x16x32_bf16 v[72:75], v[204:207], v[180:183], v[72:75]
	v_mfma_f32_16x16x32_bf16 v[68:71], v[196:199], v[188:191], v[68:71]
	v_mfma_f32_16x16x32_bf16 v[64:67], v[204:207], v[188:191], v[64:67]
	v_mfma_f32_16x16x32_bf16 v[112:115], v[200:203], v[168:171], v[112:115]
	v_mfma_f32_16x16x32_bf16 v[104:107], v[208:211], v[168:171], v[104:107]
	v_mfma_f32_16x16x32_bf16 v[96:99], v[200:203], v[176:179], v[96:99]
	v_mfma_f32_16x16x32_bf16 v[88:91], v[208:211], v[176:179], v[88:91]
	v_mfma_f32_16x16x32_bf16 v[80:83], v[200:203], v[184:187], v[80:83]
	v_mfma_f32_16x16x32_bf16 v[72:75], v[208:211], v[184:187], v[72:75]
	v_mfma_f32_16x16x32_bf16 v[68:71], v[200:203], v[192:195], v[68:71]
	v_mfma_f32_16x16x32_bf16 v[64:67], v[208:211], v[192:195], v[64:67]
	s_mov_b32 m0, s4
	v_lshl_add_u64 v[214:215], s[36:37], 0, v[128:129]
	s_barrier
	ds_read_b128 v[164:167], v158 offset:16384
	ds_read_b128 v[168:171], v158 offset:17408
	ds_read_b128 v[172:175], v158 offset:18432
	ds_read_b128 v[176:179], v158 offset:19456
	ds_read_b128 v[180:183], v158 offset:20480
	ds_read_b128 v[184:187], v158 offset:21504
	ds_read_b128 v[188:191], v158 offset:22528
	ds_read_b128 v[192:195], v158 offset:23552
	global_load_lds_dwordx4 v[214:215], off
	v_lshl_add_u64 v[216:217], s[36:37], 0, v[130:131]
	s_mov_b32 m0, s5
	s_nop 0
	global_load_lds_dwordx4 v[216:217], off
	s_barrier
	s_waitcnt lgkmcnt(0)
	s_waitcnt lgkmcnt(0)
	v_mfma_f32_16x16x32_bf16 v[60:63], v[140:143], v[164:167], v[60:63]
	v_mfma_f32_16x16x32_bf16 v[56:59], v[148:151], v[164:167], v[56:59]
	v_mfma_f32_16x16x32_bf16 v[52:55], v[140:143], v[172:175], v[52:55]
	v_mfma_f32_16x16x32_bf16 v[48:51], v[148:151], v[172:175], v[48:51]
	v_mfma_f32_16x16x32_bf16 v[40:43], v[140:143], v[180:183], v[40:43]
	v_mfma_f32_16x16x32_bf16 v[32:35], v[148:151], v[180:183], v[32:35]
	v_mfma_f32_16x16x32_bf16 v[24:27], v[140:143], v[188:191], v[24:27]
	v_mfma_f32_16x16x32_bf16 v[16:19], v[148:151], v[188:191], v[16:19]
	v_mfma_f32_16x16x32_bf16 v[60:63], v[144:147], v[168:171], v[60:63]
	v_mfma_f32_16x16x32_bf16 v[56:59], v[160:163], v[168:171], v[56:59]
	v_mfma_f32_16x16x32_bf16 v[52:55], v[144:147], v[176:179], v[52:55]
	v_mfma_f32_16x16x32_bf16 v[48:51], v[160:163], v[176:179], v[48:51]
	v_mfma_f32_16x16x32_bf16 v[40:43], v[144:147], v[184:187], v[40:43]
	v_mfma_f32_16x16x32_bf16 v[32:35], v[160:163], v[184:187], v[32:35]
	v_mfma_f32_16x16x32_bf16 v[24:27], v[144:147], v[192:195], v[24:27]
	v_mfma_f32_16x16x32_bf16 v[16:19], v[160:163], v[192:195], v[16:19]
	s_barrier
	s_add_u32 s28, s34, 0x80000
	s_addc_u32 s29, s35, 0
	s_add_i32 s70, s62, s3
	v_lshl_add_u64 v[140:141], s[28:29], 0, v[128:129]
	s_mov_b32 m0, s70
	s_nop 0
	global_load_lds_dwordx4 v[140:141], off
	v_lshl_add_u64 v[140:141], s[28:29], 0, v[130:131]
	s_add_i32 m0, s70, 0x2000
	s_nop 0
	global_load_lds_dwordx4 v[140:141], off
	s_waitcnt vmcnt(6)
	s_barrier
	v_mfma_f32_16x16x32_bf16 v[44:47], v[196:199], v[164:167], v[44:47]
	v_mfma_f32_16x16x32_bf16 v[36:39], v[204:207], v[164:167], v[36:39]
	v_mfma_f32_16x16x32_bf16 v[28:31], v[196:199], v[172:175], v[28:31]
	v_mfma_f32_16x16x32_bf16 v[20:23], v[204:207], v[172:175], v[20:23]
	v_mfma_f32_16x16x32_bf16 v[12:15], v[196:199], v[180:183], v[12:15]
	v_mfma_f32_16x16x32_bf16 v[8:11], v[204:207], v[180:183], v[8:11]
	v_mfma_f32_16x16x32_bf16 v[4:7], v[196:199], v[188:191], v[4:7]
	v_mfma_f32_16x16x32_bf16 v[0:3], v[204:207], v[188:191], v[0:3]
	v_mfma_f32_16x16x32_bf16 v[44:47], v[200:203], v[168:171], v[44:47]
	v_mfma_f32_16x16x32_bf16 v[36:39], v[208:211], v[168:171], v[36:39]
	v_mfma_f32_16x16x32_bf16 v[28:31], v[200:203], v[176:179], v[28:31]
	v_mfma_f32_16x16x32_bf16 v[20:23], v[208:211], v[176:179], v[20:23]
	v_mfma_f32_16x16x32_bf16 v[12:15], v[200:203], v[184:187], v[12:15]
	v_mfma_f32_16x16x32_bf16 v[8:11], v[208:211], v[184:187], v[8:11]
	v_mfma_f32_16x16x32_bf16 v[4:7], v[200:203], v[192:195], v[4:7]
	v_mfma_f32_16x16x32_bf16 v[0:3], v[208:211], v[192:195], v[0:3]
	s_add_i32 s70, 0, 0x18000
	v_add_u32_e32 v160, s70, v155
	s_barrier
	ds_read_b128 v[140:143], v160
	ds_read_b128 v[144:147], v160 offset:1024
	ds_read_b128 v[148:151], v160 offset:2048
	ds_read_b128 v[160:163], v160 offset:3072
	s_add_u32 s28, s36, 0x80000
	s_addc_u32 s29, s37, 0
	s_mov_b32 m0, s38
	v_lshl_add_u64 v[196:197], s[28:29], 0, v[128:129]
	ds_read_b128 v[164:167], v158 offset:32768
	ds_read_b128 v[168:171], v158 offset:33792
	ds_read_b128 v[172:175], v158 offset:34816
	ds_read_b128 v[176:179], v158 offset:35840
	ds_read_b128 v[180:183], v158 offset:36864
	ds_read_b128 v[184:187], v158 offset:37888
	ds_read_b128 v[188:191], v158 offset:38912
	ds_read_b128 v[192:195], v158 offset:39936
	global_load_lds_dwordx4 v[196:197], off
	v_lshl_add_u64 v[196:197], s[28:29], 0, v[130:131]
	s_mov_b32 m0, s39
	s_nop 0
	global_load_lds_dwordx4 v[196:197], off
	s_waitcnt lgkmcnt(8)
	s_barrier
	s_waitcnt lgkmcnt(0)
	s_waitcnt lgkmcnt(0)
	v_mfma_f32_16x16x32_bf16 v[124:127], v[140:143], v[164:167], v[124:127]
	v_mfma_f32_16x16x32_bf16 v[120:123], v[148:151], v[164:167], v[120:123]
	v_mfma_f32_16x16x32_bf16 v[116:119], v[140:143], v[172:175], v[116:119]
	v_mfma_f32_16x16x32_bf16 v[108:111], v[148:151], v[172:175], v[108:111]
	v_mfma_f32_16x16x32_bf16 v[100:103], v[140:143], v[180:183], v[100:103]
	v_mfma_f32_16x16x32_bf16 v[92:95], v[148:151], v[180:183], v[92:95]
	v_mfma_f32_16x16x32_bf16 v[84:87], v[140:143], v[188:191], v[84:87]
	v_mfma_f32_16x16x32_bf16 v[76:79], v[148:151], v[188:191], v[76:79]
	v_mfma_f32_16x16x32_bf16 v[124:127], v[144:147], v[168:171], v[124:127]
	v_mfma_f32_16x16x32_bf16 v[120:123], v[160:163], v[168:171], v[120:123]
	v_mfma_f32_16x16x32_bf16 v[116:119], v[144:147], v[176:179], v[116:119]
	v_mfma_f32_16x16x32_bf16 v[108:111], v[160:163], v[176:179], v[108:111]
	v_mfma_f32_16x16x32_bf16 v[100:103], v[144:147], v[184:187], v[100:103]
	v_mfma_f32_16x16x32_bf16 v[92:95], v[160:163], v[184:187], v[92:95]
	v_mfma_f32_16x16x32_bf16 v[84:87], v[144:147], v[192:195], v[84:87]
	v_mfma_f32_16x16x32_bf16 v[76:79], v[160:163], v[192:195], v[76:79]
	s_barrier
	s_add_i32 s36, 0, 0x1c000
	s_add_i32 s28, s70, s3
	v_add_u32_e32 v208, s36, v155
	v_lshl_add_u64 v[152:153], v[152:153], 0, s[12:13]
	s_mov_b32 m0, s28
	ds_read_b128 v[196:199], v208
	ds_read_b128 v[200:203], v208 offset:1024
	ds_read_b128 v[204:207], v208 offset:2048
	ds_read_b128 v[208:211], v208 offset:3072
	global_load_lds_dwordx4 v[152:153], off
	v_lshl_add_u64 v[152:153], v[212:213], 0, s[12:13]
	s_add_i32 m0, s28, 0x2000
	s_nop 0
	global_load_lds_dwordx4 v[152:153], off
	s_barrier
	s_waitcnt lgkmcnt(0)
	s_waitcnt lgkmcnt(0)
	v_mfma_f32_16x16x32_bf16 v[112:115], v[196:199], v[164:167], v[112:115]
	v_mfma_f32_16x16x32_bf16 v[104:107], v[204:207], v[164:167], v[104:107]
	v_mfma_f32_16x16x32_bf16 v[96:99], v[196:199], v[172:175], v[96:99]
	v_mfma_f32_16x16x32_bf16 v[88:91], v[204:207], v[172:175], v[88:91]
	v_mfma_f32_16x16x32_bf16 v[80:83], v[196:199], v[180:183], v[80:83]
	v_mfma_f32_16x16x32_bf16 v[72:75], v[204:207], v[180:183], v[72:75]
	v_mfma_f32_16x16x32_bf16 v[68:71], v[196:199], v[188:191], v[68:71]
	v_mfma_f32_16x16x32_bf16 v[64:67], v[204:207], v[188:191], v[64:67]
	v_mfma_f32_16x16x32_bf16 v[112:115], v[200:203], v[168:171], v[112:115]
	v_mfma_f32_16x16x32_bf16 v[104:107], v[208:211], v[168:171], v[104:107]
	v_mfma_f32_16x16x32_bf16 v[96:99], v[200:203], v[176:179], v[96:99]
	v_mfma_f32_16x16x32_bf16 v[88:91], v[208:211], v[176:179], v[88:91]
	v_mfma_f32_16x16x32_bf16 v[80:83], v[200:203], v[184:187], v[80:83]
	v_mfma_f32_16x16x32_bf16 v[72:75], v[208:211], v[184:187], v[72:75]
	v_mfma_f32_16x16x32_bf16 v[68:71], v[200:203], v[192:195], v[68:71]
	v_mfma_f32_16x16x32_bf16 v[64:67], v[208:211], v[192:195], v[64:67]
	s_mov_b32 m0, s42
	v_lshl_add_u64 v[152:153], v[214:215], 0, s[12:13]
	s_barrier
	ds_read_b128 v[164:167], v158 offset:49152
	ds_read_b128 v[168:171], v158 offset:50176
	ds_read_b128 v[172:175], v158 offset:51200
	ds_read_b128 v[176:179], v158 offset:52224
	ds_read_b128 v[180:183], v158 offset:53248
	ds_read_b128 v[184:187], v158 offset:54272
	ds_read_b128 v[188:191], v158 offset:55296
	ds_read_b128 v[192:195], v158 offset:56320
	global_load_lds_dwordx4 v[152:153], off
	v_lshl_add_u64 v[152:153], v[216:217], 0, s[12:13]
	s_mov_b32 m0, s43
	s_nop 0
	global_load_lds_dwordx4 v[152:153], off
	s_barrier
	s_waitcnt lgkmcnt(0)
	s_waitcnt lgkmcnt(0)
	v_mfma_f32_16x16x32_bf16 v[60:63], v[140:143], v[164:167], v[60:63]
	v_mfma_f32_16x16x32_bf16 v[56:59], v[148:151], v[164:167], v[56:59]
	v_mfma_f32_16x16x32_bf16 v[52:55], v[140:143], v[172:175], v[52:55]
	v_mfma_f32_16x16x32_bf16 v[48:51], v[148:151], v[172:175], v[48:51]
	v_mfma_f32_16x16x32_bf16 v[40:43], v[140:143], v[180:183], v[40:43]
	v_mfma_f32_16x16x32_bf16 v[32:35], v[148:151], v[180:183], v[32:35]
	v_mfma_f32_16x16x32_bf16 v[24:27], v[140:143], v[188:191], v[24:27]
	v_mfma_f32_16x16x32_bf16 v[16:19], v[148:151], v[188:191], v[16:19]
	v_mfma_f32_16x16x32_bf16 v[60:63], v[144:147], v[168:171], v[60:63]
	v_mfma_f32_16x16x32_bf16 v[56:59], v[160:163], v[168:171], v[56:59]
	v_mfma_f32_16x16x32_bf16 v[52:55], v[144:147], v[176:179], v[52:55]
	v_mfma_f32_16x16x32_bf16 v[48:51], v[160:163], v[176:179], v[48:51]
	v_mfma_f32_16x16x32_bf16 v[40:43], v[144:147], v[184:187], v[40:43]
	v_mfma_f32_16x16x32_bf16 v[32:35], v[160:163], v[184:187], v[32:35]
	v_mfma_f32_16x16x32_bf16 v[24:27], v[144:147], v[192:195], v[24:27]
	v_mfma_f32_16x16x32_bf16 v[16:19], v[160:163], v[192:195], v[16:19]
	s_barrier
	s_add_u32 s28, s34, 0x80080
	s_addc_u32 s29, s35, 0
	s_add_i32 s34, s36, s3
	v_lshl_add_u64 v[140:141], s[28:29], 0, v[128:129]
	s_mov_b32 m0, s34
	s_nop 0
	global_load_lds_dwordx4 v[140:141], off
	v_lshl_add_u64 v[140:141], s[28:29], 0, v[130:131]
	s_add_i32 m0, s34, 0x2000
	s_nop 0
	global_load_lds_dwordx4 v[140:141], off
	s_waitcnt vmcnt(6)
	s_barrier
	v_mfma_f32_16x16x32_bf16 v[44:47], v[196:199], v[164:167], v[44:47]
	v_mfma_f32_16x16x32_bf16 v[36:39], v[204:207], v[164:167], v[36:39]
	v_mfma_f32_16x16x32_bf16 v[28:31], v[196:199], v[172:175], v[28:31]
	v_mfma_f32_16x16x32_bf16 v[20:23], v[204:207], v[172:175], v[20:23]
	v_mfma_f32_16x16x32_bf16 v[12:15], v[196:199], v[180:183], v[12:15]
	v_mfma_f32_16x16x32_bf16 v[8:11], v[204:207], v[180:183], v[8:11]
	v_mfma_f32_16x16x32_bf16 v[4:7], v[196:199], v[188:191], v[4:7]
	v_mfma_f32_16x16x32_bf16 v[0:3], v[204:207], v[188:191], v[0:3]
	v_mfma_f32_16x16x32_bf16 v[44:47], v[200:203], v[168:171], v[44:47]
	v_mfma_f32_16x16x32_bf16 v[36:39], v[208:211], v[168:171], v[36:39]
	v_mfma_f32_16x16x32_bf16 v[28:31], v[200:203], v[176:179], v[28:31]
	v_mfma_f32_16x16x32_bf16 v[20:23], v[208:211], v[176:179], v[20:23]
	v_mfma_f32_16x16x32_bf16 v[12:15], v[200:203], v[184:187], v[12:15]
	v_mfma_f32_16x16x32_bf16 v[8:11], v[208:211], v[184:187], v[8:11]
	v_mfma_f32_16x16x32_bf16 v[4:7], v[200:203], v[192:195], v[4:7]
	v_mfma_f32_16x16x32_bf16 v[0:3], v[208:211], v[192:195], v[0:3]
	s_add_i32 s69, s69, 2
	s_add_u32 s67, s67, 0x100
	s_addc_u32 s68, s68, 0
	s_cmp_gt_u32 s69, 29
	s_mov_b64 s[28:29], s[30:31]
	s_barrier
	s_cbranch_scc0 .LBB0_2281
	v_lshl_add_u32 v148, s26, 8, v154
	v_lshl_or_b32 v146, s27, 8, v156
	s_cmp_eq_u32 s27, 48
	v_ashrrev_i32_e32 v149, 31, v148
	s_mov_b64 s[26:27], -1
	v_or_b32_e32 v144, 16, v148
	v_or_b32_e32 v142, 32, v148
	v_or_b32_e32 v140, 48, v148
	s_cbranch_scc1 .LBB0_2284
	v_readlane_b32 s64, v240, 22
	v_readlane_b32 s72, v240, 30
	v_readlane_b32 s73, v240, 31
	v_ashrrev_i32_e32 v147, 31, v146
	v_lshlrev_b64 v[152:153], 1, v[146:147]
	v_mov_b64_e32 v[150:151], s[72:73]
	v_mad_i64_i32 v[160:161], s[26:27], v148, s41, v[150:151]
	v_pk_add_f32 v[162:163], v[126:127], 0 op_sel_hi:[1,0]
	v_pk_add_f32 v[164:165], v[124:125], 0 op_sel_hi:[1,0]
	v_lshl_add_u64 v[160:161], v[160:161], 0, v[152:153]
	v_cvt_pk_bf16_f32 v164, v164, v165
	v_cvt_pk_bf16_f32 v165, v162, v163
	global_store_dwordx2 v[160:161], v[164:165], off
	v_pk_add_f32 v[162:163], v[122:123], 0 op_sel_hi:[1,0]
	v_pk_add_f32 v[164:165], v[120:121], 0 op_sel_hi:[1,0]
	v_add_u32_e32 v141, 0x80, v148
	v_cvt_pk_bf16_f32 v164, v164, v165
	v_cvt_pk_bf16_f32 v165, v162, v163
	global_store_dwordx2 v[160:161], v[164:165], off offset:32
	v_pk_add_f32 v[162:163], v[114:115], 0 op_sel_hi:[1,0]
	v_pk_add_f32 v[164:165], v[112:113], 0 op_sel_hi:[1,0]
	v_readlane_b32 s65, v240, 23
	v_cvt_pk_bf16_f32 v164, v164, v165
	v_cvt_pk_bf16_f32 v165, v162, v163
	global_store_dwordx2 v[160:161], v[164:165], off offset:256
	v_pk_add_f32 v[162:163], v[106:107], 0 op_sel_hi:[1,0]
	v_pk_add_f32 v[164:165], v[104:105], 0 op_sel_hi:[1,0]
	v_readlane_b32 s66, v240, 24
	v_cvt_pk_bf16_f32 v164, v164, v165
	v_cvt_pk_bf16_f32 v165, v162, v163
	global_store_dwordx2 v[160:161], v[164:165], off offset:288
	v_mad_i64_i32 v[160:161], s[26:27], v144, s41, v[150:151]
	v_pk_add_f32 v[162:163], v[118:119], 0 op_sel_hi:[1,0]
	v_pk_add_f32 v[164:165], v[116:117], 0 op_sel_hi:[1,0]
	v_lshl_add_u64 v[160:161], v[160:161], 0, v[152:153]
	v_cvt_pk_bf16_f32 v164, v164, v165
	v_cvt_pk_bf16_f32 v165, v162, v163
	global_store_dwordx2 v[160:161], v[164:165], off
	v_pk_add_f32 v[162:163], v[110:111], 0 op_sel_hi:[1,0]
	v_pk_add_f32 v[164:165], v[108:109], 0 op_sel_hi:[1,0]
	v_readlane_b32 s67, v240, 25
	v_cvt_pk_bf16_f32 v164, v164, v165
	v_cvt_pk_bf16_f32 v165, v162, v163
	global_store_dwordx2 v[160:161], v[164:165], off offset:32
	v_pk_add_f32 v[162:163], v[98:99], 0 op_sel_hi:[1,0]
	v_pk_add_f32 v[164:165], v[96:97], 0 op_sel_hi:[1,0]
	v_readlane_b32 s68, v240, 26
	v_cvt_pk_bf16_f32 v164, v164, v165
	v_cvt_pk_bf16_f32 v165, v162, v163
	global_store_dwordx2 v[160:161], v[164:165], off offset:256
	v_pk_add_f32 v[162:163], v[90:91], 0 op_sel_hi:[1,0]
	v_pk_add_f32 v[164:165], v[88:89], 0 op_sel_hi:[1,0]
	v_readlane_b32 s69, v240, 27
	v_cvt_pk_bf16_f32 v164, v164, v165
	v_cvt_pk_bf16_f32 v165, v162, v163
	global_store_dwordx2 v[160:161], v[164:165], off offset:288
	v_mad_i64_i32 v[160:161], s[26:27], v142, s41, v[150:151]
	v_pk_add_f32 v[162:163], v[102:103], 0 op_sel_hi:[1,0]
	v_pk_add_f32 v[164:165], v[100:101], 0 op_sel_hi:[1,0]
	v_lshl_add_u64 v[160:161], v[160:161], 0, v[152:153]
	v_cvt_pk_bf16_f32 v164, v164, v165
	v_cvt_pk_bf16_f32 v165, v162, v163
	global_store_dwordx2 v[160:161], v[164:165], off
	v_pk_add_f32 v[162:163], v[94:95], 0 op_sel_hi:[1,0]
	v_pk_add_f32 v[164:165], v[92:93], 0 op_sel_hi:[1,0]
	v_readlane_b32 s70, v240, 28
	v_cvt_pk_bf16_f32 v164, v164, v165
	v_cvt_pk_bf16_f32 v165, v162, v163
	global_store_dwordx2 v[160:161], v[164:165], off offset:32
	v_pk_add_f32 v[162:163], v[82:83], 0 op_sel_hi:[1,0]
	v_pk_add_f32 v[164:165], v[80:81], 0 op_sel_hi:[1,0]
	v_readlane_b32 s71, v240, 29
	v_cvt_pk_bf16_f32 v164, v164, v165
	v_cvt_pk_bf16_f32 v165, v162, v163
	global_store_dwordx2 v[160:161], v[164:165], off offset:256
	v_pk_add_f32 v[162:163], v[74:75], 0 op_sel_hi:[1,0]
	v_pk_add_f32 v[164:165], v[72:73], 0 op_sel_hi:[1,0]
	v_readlane_b32 s74, v240, 32
	v_cvt_pk_bf16_f32 v164, v164, v165
	v_cvt_pk_bf16_f32 v165, v162, v163
	global_store_dwordx2 v[160:161], v[164:165], off offset:288
	v_mad_i64_i32 v[160:161], s[26:27], v140, s41, v[150:151]
	v_pk_add_f32 v[162:163], v[86:87], 0 op_sel_hi:[1,0]
	v_pk_add_f32 v[164:165], v[84:85], 0 op_sel_hi:[1,0]
	v_lshl_add_u64 v[160:161], v[160:161], 0, v[152:153]
	v_cvt_pk_bf16_f32 v164, v164, v165
	v_cvt_pk_bf16_f32 v165, v162, v163
	global_store_dwordx2 v[160:161], v[164:165], off
	v_pk_add_f32 v[162:163], v[78:79], 0 op_sel_hi:[1,0]
	v_pk_add_f32 v[164:165], v[76:77], 0 op_sel_hi:[1,0]
	v_readlane_b32 s75, v240, 33
	v_cvt_pk_bf16_f32 v164, v164, v165
	v_cvt_pk_bf16_f32 v165, v162, v163
	global_store_dwordx2 v[160:161], v[164:165], off offset:32
	v_pk_add_f32 v[162:163], v[70:71], 0 op_sel_hi:[1,0]
	v_pk_add_f32 v[164:165], v[68:69], 0 op_sel_hi:[1,0]
	v_readlane_b32 s76, v240, 34
	v_cvt_pk_bf16_f32 v164, v164, v165
	v_cvt_pk_bf16_f32 v165, v162, v163
	global_store_dwordx2 v[160:161], v[164:165], off offset:256
	v_pk_add_f32 v[162:163], v[66:67], 0 op_sel_hi:[1,0]
	v_pk_add_f32 v[164:165], v[64:65], 0 op_sel_hi:[1,0]
	v_readlane_b32 s77, v240, 35
	v_cvt_pk_bf16_f32 v164, v164, v165
	v_cvt_pk_bf16_f32 v165, v162, v163
	global_store_dwordx2 v[160:161], v[164:165], off offset:288
	v_mad_i64_i32 v[160:161], s[26:27], v141, s41, v[150:151]
	v_pk_add_f32 v[162:163], v[62:63], 0 op_sel_hi:[1,0]
	v_pk_add_f32 v[164:165], v[60:61], 0 op_sel_hi:[1,0]
	v_lshl_add_u64 v[160:161], v[160:161], 0, v[152:153]
	v_cvt_pk_bf16_f32 v164, v164, v165
	v_cvt_pk_bf16_f32 v165, v162, v163
	global_store_dwordx2 v[160:161], v[164:165], off
	v_pk_add_f32 v[162:163], v[58:59], 0 op_sel_hi:[1,0]
	v_pk_add_f32 v[164:165], v[56:57], 0 op_sel_hi:[1,0]
	v_add_u32_e32 v141, 0x90, v148
	v_cvt_pk_bf16_f32 v164, v164, v165
	v_cvt_pk_bf16_f32 v165, v162, v163
	global_store_dwordx2 v[160:161], v[164:165], off offset:32
	v_pk_add_f32 v[162:163], v[46:47], 0 op_sel_hi:[1,0]
	v_pk_add_f32 v[164:165], v[44:45], 0 op_sel_hi:[1,0]
	v_readlane_b32 s78, v240, 36
	v_cvt_pk_bf16_f32 v164, v164, v165
	v_cvt_pk_bf16_f32 v165, v162, v163
	global_store_dwordx2 v[160:161], v[164:165], off offset:256
	v_pk_add_f32 v[162:163], v[38:39], 0 op_sel_hi:[1,0]
	v_pk_add_f32 v[164:165], v[36:37], 0 op_sel_hi:[1,0]
	v_readlane_b32 s79, v240, 37
	v_cvt_pk_bf16_f32 v164, v164, v165
	v_cvt_pk_bf16_f32 v165, v162, v163
	global_store_dwordx2 v[160:161], v[164:165], off offset:288
	v_mad_i64_i32 v[160:161], s[26:27], v141, s41, v[150:151]
	v_pk_add_f32 v[162:163], v[54:55], 0 op_sel_hi:[1,0]
	v_pk_add_f32 v[164:165], v[52:53], 0 op_sel_hi:[1,0]
	v_lshl_add_u64 v[160:161], v[160:161], 0, v[152:153]
	v_cvt_pk_bf16_f32 v164, v164, v165
	v_cvt_pk_bf16_f32 v165, v162, v163
	global_store_dwordx2 v[160:161], v[164:165], off
	v_pk_add_f32 v[162:163], v[50:51], 0 op_sel_hi:[1,0]
	v_pk_add_f32 v[164:165], v[48:49], 0 op_sel_hi:[1,0]
	v_add_u32_e32 v141, 0xa0, v148
	v_cvt_pk_bf16_f32 v164, v164, v165
	v_cvt_pk_bf16_f32 v165, v162, v163
	global_store_dwordx2 v[160:161], v[164:165], off offset:32
	v_pk_add_f32 v[162:163], v[30:31], 0 op_sel_hi:[1,0]
	v_pk_add_f32 v[164:165], v[28:29], 0 op_sel_hi:[1,0]
	s_nop 0
	v_cvt_pk_bf16_f32 v164, v164, v165
	v_cvt_pk_bf16_f32 v165, v162, v163
	global_store_dwordx2 v[160:161], v[164:165], off offset:256
	v_pk_add_f32 v[162:163], v[22:23], 0 op_sel_hi:[1,0]
	v_pk_add_f32 v[164:165], v[20:21], 0 op_sel_hi:[1,0]
	s_nop 0
	v_cvt_pk_bf16_f32 v164, v164, v165
	v_cvt_pk_bf16_f32 v165, v162, v163
	global_store_dwordx2 v[160:161], v[164:165], off offset:288
	v_mad_i64_i32 v[160:161], s[26:27], v141, s41, v[150:151]
	v_pk_add_f32 v[162:163], v[42:43], 0 op_sel_hi:[1,0]
	v_pk_add_f32 v[164:165], v[40:41], 0 op_sel_hi:[1,0]
	v_lshl_add_u64 v[160:161], v[160:161], 0, v[152:153]
	v_cvt_pk_bf16_f32 v164, v164, v165
	v_cvt_pk_bf16_f32 v165, v162, v163
	global_store_dwordx2 v[160:161], v[164:165], off
	v_pk_add_f32 v[162:163], v[34:35], 0 op_sel_hi:[1,0]
	v_pk_add_f32 v[164:165], v[32:33], 0 op_sel_hi:[1,0]
	v_add_u32_e32 v141, 0xb0, v148
	v_cvt_pk_bf16_f32 v164, v164, v165
	v_cvt_pk_bf16_f32 v165, v162, v163
	global_store_dwordx2 v[160:161], v[164:165], off offset:32
	v_pk_add_f32 v[162:163], v[14:15], 0 op_sel_hi:[1,0]
	v_pk_add_f32 v[164:165], v[12:13], 0 op_sel_hi:[1,0]
	v_mad_i64_i32 v[150:151], s[26:27], v141, s41, v[150:151]
	v_cvt_pk_bf16_f32 v164, v164, v165
	v_cvt_pk_bf16_f32 v165, v162, v163
	global_store_dwordx2 v[160:161], v[164:165], off offset:256
	v_pk_add_f32 v[162:163], v[10:11], 0 op_sel_hi:[1,0]
	v_pk_add_f32 v[164:165], v[8:9], 0 op_sel_hi:[1,0]
	v_lshl_add_u64 v[150:151], v[150:151], 0, v[152:153]
	v_cvt_pk_bf16_f32 v164, v164, v165
	v_cvt_pk_bf16_f32 v165, v162, v163
	global_store_dwordx2 v[160:161], v[164:165], off offset:288
	v_pk_add_f32 v[152:153], v[26:27], 0 op_sel_hi:[1,0]
	v_pk_add_f32 v[160:161], v[24:25], 0 op_sel_hi:[1,0]
	s_mov_b64 s[26:27], 0
	v_cvt_pk_bf16_f32 v160, v160, v161
	v_cvt_pk_bf16_f32 v161, v152, v153
	global_store_dwordx2 v[150:151], v[160:161], off
	v_pk_add_f32 v[152:153], v[18:19], 0 op_sel_hi:[1,0]
	v_pk_add_f32 v[160:161], v[16:17], 0 op_sel_hi:[1,0]
	s_nop 0
	v_cvt_pk_bf16_f32 v160, v160, v161
	v_cvt_pk_bf16_f32 v161, v152, v153
	global_store_dwordx2 v[150:151], v[160:161], off offset:32
	v_pk_add_f32 v[152:153], v[6:7], 0 op_sel_hi:[1,0]
	v_pk_add_f32 v[160:161], v[4:5], 0 op_sel_hi:[1,0]
	s_nop 0
	v_cvt_pk_bf16_f32 v160, v160, v161
	v_cvt_pk_bf16_f32 v161, v152, v153
	global_store_dwordx2 v[150:151], v[160:161], off offset:256
	v_pk_add_f32 v[152:153], v[2:3], 0 op_sel_hi:[1,0]
	v_pk_add_f32 v[160:161], v[0:1], 0 op_sel_hi:[1,0]
	s_nop 0
	v_cvt_pk_bf16_f32 v160, v160, v161
	v_cvt_pk_bf16_f32 v161, v152, v153
	global_store_dwordx2 v[150:151], v[160:161], off offset:288

.LBB0_2676:
	ds_read_b128 v[128:131], v151
	ds_read_b128 v[144:147], v151 offset:1024
	ds_read_b128 v[154:157], v151 offset:2048
	ds_read_b128 v[158:161], v151 offset:3072
	s_add_u32 s28, s26, 0x100
	s_addc_u32 s29, s27, 0
	s_cmp_eq_u32 s62, 60
	s_cselect_b32 s35, s17, s29
	s_cselect_b32 s34, s52, s28
	s_cselect_b32 s31, s15, s57
	s_cselect_b32 s30, s53, s56
	v_lshl_add_u64 v[194:195], s[26:27], 0, v[136:137]
	s_add_i32 m0, s4, 0xc000
	ds_read_b128 v[162:165], v152
	ds_read_b128 v[166:169], v152 offset:1024
	ds_read_b128 v[170:173], v152 offset:2048
	ds_read_b128 v[174:177], v152 offset:3072
	ds_read_b128 v[178:181], v152 offset:4096
	ds_read_b128 v[182:185], v152 offset:5120
	ds_read_b128 v[186:189], v152 offset:6144
	ds_read_b128 v[190:193], v152 offset:7168
	global_load_lds_dwordx4 v[194:195], off
	v_lshl_add_u64 v[194:195], s[26:27], 0, v[138:139]
	s_add_i32 m0, s4, 0xe000
	s_nop 0
	global_load_lds_dwordx4 v[194:195], off
	s_waitcnt lgkmcnt(8)
	s_barrier
	s_waitcnt lgkmcnt(0)
	s_waitcnt lgkmcnt(0)
	v_mfma_f32_16x16x32_bf16 v[124:127], v[128:131], v[162:165], v[124:127]
	v_mfma_f32_16x16x32_bf16 v[92:95], v[154:157], v[162:165], v[92:95]
	v_mfma_f32_16x16x32_bf16 v[120:123], v[128:131], v[170:173], v[120:123]
	v_mfma_f32_16x16x32_bf16 v[88:91], v[154:157], v[170:173], v[88:91]
	v_mfma_f32_16x16x32_bf16 v[116:119], v[128:131], v[178:181], v[116:119]
	v_mfma_f32_16x16x32_bf16 v[84:87], v[154:157], v[178:181], v[84:87]
	v_mfma_f32_16x16x32_bf16 v[112:115], v[128:131], v[186:189], v[112:115]
	v_mfma_f32_16x16x32_bf16 v[80:83], v[154:157], v[186:189], v[80:83]
	v_mfma_f32_16x16x32_bf16 v[124:127], v[144:147], v[166:169], v[124:127]
	v_mfma_f32_16x16x32_bf16 v[92:95], v[158:161], v[166:169], v[92:95]
	v_mfma_f32_16x16x32_bf16 v[120:123], v[144:147], v[174:177], v[120:123]
	v_mfma_f32_16x16x32_bf16 v[88:91], v[158:161], v[174:177], v[88:91]
	v_mfma_f32_16x16x32_bf16 v[116:119], v[144:147], v[182:185], v[116:119]
	v_mfma_f32_16x16x32_bf16 v[84:87], v[158:161], v[182:185], v[84:87]
	v_mfma_f32_16x16x32_bf16 v[112:115], v[144:147], v[190:193], v[112:115]
	v_mfma_f32_16x16x32_bf16 v[80:83], v[158:161], v[190:193], v[80:83]
	s_barrier
	s_add_i32 s26, s43, s3
	v_lshl_add_u64 v[210:211], s[30:31], 0, v[132:133]
	s_mov_b32 m0, s26
	ds_read_b128 v[194:197], v153
	ds_read_b128 v[198:201], v153 offset:1024
	ds_read_b128 v[202:205], v153 offset:2048
	ds_read_b128 v[206:209], v153 offset:3072
	global_load_lds_dwordx4 v[210:211], off
	v_lshl_add_u64 v[212:213], s[30:31], 0, v[134:135]
	s_add_i32 m0, s26, 0x2000
	s_nop 0
	global_load_lds_dwordx4 v[212:213], off
	s_barrier
	s_waitcnt lgkmcnt(0)
	s_waitcnt lgkmcnt(0)
	v_mfma_f32_16x16x32_bf16 v[76:79], v[194:197], v[162:165], v[76:79]
	v_mfma_f32_16x16x32_bf16 v[48:51], v[202:205], v[162:165], v[48:51]
	v_mfma_f32_16x16x32_bf16 v[68:71], v[194:197], v[170:173], v[68:71]
	v_mfma_f32_16x16x32_bf16 v[40:43], v[202:205], v[170:173], v[40:43]
	v_mfma_f32_16x16x32_bf16 v[60:63], v[194:197], v[178:181], v[60:63]
	v_mfma_f32_16x16x32_bf16 v[36:39], v[202:205], v[178:181], v[36:39]
	v_mfma_f32_16x16x32_bf16 v[52:55], v[194:197], v[186:189], v[52:55]
	v_mfma_f32_16x16x32_bf16 v[28:31], v[202:205], v[186:189], v[28:31]
	v_mfma_f32_16x16x32_bf16 v[76:79], v[198:201], v[166:169], v[76:79]
	v_mfma_f32_16x16x32_bf16 v[48:51], v[206:209], v[166:169], v[48:51]
	v_mfma_f32_16x16x32_bf16 v[68:71], v[198:201], v[174:177], v[68:71]
	v_mfma_f32_16x16x32_bf16 v[40:43], v[206:209], v[174:177], v[40:43]
	v_mfma_f32_16x16x32_bf16 v[60:63], v[198:201], v[182:185], v[60:63]
	v_mfma_f32_16x16x32_bf16 v[36:39], v[206:209], v[182:185], v[36:39]
	v_mfma_f32_16x16x32_bf16 v[52:55], v[198:201], v[190:193], v[52:55]
	v_mfma_f32_16x16x32_bf16 v[28:31], v[206:209], v[190:193], v[28:31]
	s_mov_b32 m0, s4
	v_lshl_add_u64 v[214:215], s[34:35], 0, v[132:133]
	s_barrier
	ds_read_b128 v[162:165], v152 offset:16384
	ds_read_b128 v[166:169], v152 offset:17408
	ds_read_b128 v[170:173], v152 offset:18432
	ds_read_b128 v[174:177], v152 offset:19456
	ds_read_b128 v[178:181], v152 offset:20480
	ds_read_b128 v[182:185], v152 offset:21504
	ds_read_b128 v[186:189], v152 offset:22528
	ds_read_b128 v[190:193], v152 offset:23552
	global_load_lds_dwordx4 v[214:215], off
	v_lshl_add_u64 v[216:217], s[34:35], 0, v[134:135]
	s_mov_b32 m0, s5
	s_nop 0
	global_load_lds_dwordx4 v[216:217], off
	s_barrier
	s_waitcnt lgkmcnt(0)
	s_waitcnt lgkmcnt(0)
	v_mfma_f32_16x16x32_bf16 v[108:111], v[128:131], v[162:165], v[108:111]
	v_mfma_f32_16x16x32_bf16 v[72:75], v[154:157], v[162:165], v[72:75]
	v_mfma_f32_16x16x32_bf16 v[104:107], v[128:131], v[170:173], v[104:107]
	v_mfma_f32_16x16x32_bf16 v[64:67], v[154:157], v[170:173], v[64:67]
	v_mfma_f32_16x16x32_bf16 v[100:103], v[128:131], v[178:181], v[100:103]
	v_mfma_f32_16x16x32_bf16 v[56:59], v[154:157], v[178:181], v[56:59]
	v_mfma_f32_16x16x32_bf16 v[96:99], v[128:131], v[186:189], v[96:99]
	v_mfma_f32_16x16x32_bf16 v[44:47], v[154:157], v[186:189], v[44:47]
	v_mfma_f32_16x16x32_bf16 v[108:111], v[144:147], v[166:169], v[108:111]
	v_mfma_f32_16x16x32_bf16 v[72:75], v[158:161], v[166:169], v[72:75]
	v_mfma_f32_16x16x32_bf16 v[104:107], v[144:147], v[174:177], v[104:107]
	v_mfma_f32_16x16x32_bf16 v[64:67], v[158:161], v[174:177], v[64:67]
	v_mfma_f32_16x16x32_bf16 v[100:103], v[144:147], v[182:185], v[100:103]
	v_mfma_f32_16x16x32_bf16 v[56:59], v[158:161], v[182:185], v[56:59]
	v_mfma_f32_16x16x32_bf16 v[96:99], v[144:147], v[190:193], v[96:99]
	v_mfma_f32_16x16x32_bf16 v[44:47], v[158:161], v[190:193], v[44:47]
	s_barrier
	s_add_u32 s26, s30, 0x100000
	s_addc_u32 s27, s31, 0
	s_add_i32 s63, s46, s3
	v_lshl_add_u64 v[128:129], s[26:27], 0, v[132:133]
	s_mov_b32 m0, s63
	s_nop 0
	global_load_lds_dwordx4 v[128:129], off
	v_lshl_add_u64 v[128:129], s[26:27], 0, v[134:135]
	s_add_i32 m0, s63, 0x2000
	s_nop 0
	global_load_lds_dwordx4 v[128:129], off
	s_waitcnt vmcnt(6)
	s_barrier
	v_mfma_f32_16x16x32_bf16 v[32:35], v[194:197], v[162:165], v[32:35]
	v_mfma_f32_16x16x32_bf16 v[12:15], v[202:205], v[162:165], v[12:15]
	v_mfma_f32_16x16x32_bf16 v[24:27], v[194:197], v[170:173], v[24:27]
	v_mfma_f32_16x16x32_bf16 v[8:11], v[202:205], v[170:173], v[8:11]
	v_mfma_f32_16x16x32_bf16 v[20:23], v[194:197], v[178:181], v[20:23]
	v_mfma_f32_16x16x32_bf16 v[4:7], v[202:205], v[178:181], v[4:7]
	v_mfma_f32_16x16x32_bf16 v[16:19], v[194:197], v[186:189], v[16:19]
	v_mfma_f32_16x16x32_bf16 v[0:3], v[202:205], v[186:189], v[0:3]
	v_mfma_f32_16x16x32_bf16 v[32:35], v[198:201], v[166:169], v[32:35]
	v_mfma_f32_16x16x32_bf16 v[12:15], v[206:209], v[166:169], v[12:15]
	v_mfma_f32_16x16x32_bf16 v[24:27], v[198:201], v[174:177], v[24:27]
	v_mfma_f32_16x16x32_bf16 v[8:11], v[206:209], v[174:177], v[8:11]
	v_mfma_f32_16x16x32_bf16 v[20:23], v[198:201], v[182:185], v[20:23]
	v_mfma_f32_16x16x32_bf16 v[4:7], v[206:209], v[182:185], v[4:7]
	v_mfma_f32_16x16x32_bf16 v[16:19], v[198:201], v[190:193], v[16:19]
	v_mfma_f32_16x16x32_bf16 v[0:3], v[206:209], v[190:193], v[0:3]
	s_add_i32 s63, 0, 0x18000
	v_add_u32_e32 v158, s63, v149
	s_barrier
	ds_read_b128 v[128:131], v158
	ds_read_b128 v[144:147], v158 offset:1024
	ds_read_b128 v[154:157], v158 offset:2048
	ds_read_b128 v[158:161], v158 offset:3072
	s_add_u32 s26, s34, 0x100000
	s_addc_u32 s27, s35, 0
	s_mov_b32 m0, s23
	v_lshl_add_u64 v[194:195], s[26:27], 0, v[132:133]
	ds_read_b128 v[162:165], v152 offset:32768
	ds_read_b128 v[166:169], v152 offset:33792
	ds_read_b128 v[170:173], v152 offset:34816
	ds_read_b128 v[174:177], v152 offset:35840
	ds_read_b128 v[178:181], v152 offset:36864
	ds_read_b128 v[182:185], v152 offset:37888
	ds_read_b128 v[186:189], v152 offset:38912
	ds_read_b128 v[190:193], v152 offset:39936
	global_load_lds_dwordx4 v[194:195], off
	v_lshl_add_u64 v[194:195], s[26:27], 0, v[134:135]
	s_mov_b32 m0, s36
	s_nop 0
	global_load_lds_dwordx4 v[194:195], off
	s_waitcnt lgkmcnt(8)
	s_barrier
	s_waitcnt lgkmcnt(0)
	s_waitcnt lgkmcnt(0)
	v_mfma_f32_16x16x32_bf16 v[124:127], v[128:131], v[162:165], v[124:127]
	v_mfma_f32_16x16x32_bf16 v[92:95], v[154:157], v[162:165], v[92:95]
	v_mfma_f32_16x16x32_bf16 v[120:123], v[128:131], v[170:173], v[120:123]
	v_mfma_f32_16x16x32_bf16 v[88:91], v[154:157], v[170:173], v[88:91]
	v_mfma_f32_16x16x32_bf16 v[116:119], v[128:131], v[178:181], v[116:119]
	v_mfma_f32_16x16x32_bf16 v[84:87], v[154:157], v[178:181], v[84:87]
	v_mfma_f32_16x16x32_bf16 v[112:115], v[128:131], v[186:189], v[112:115]
	v_mfma_f32_16x16x32_bf16 v[80:83], v[154:157], v[186:189], v[80:83]
	v_mfma_f32_16x16x32_bf16 v[124:127], v[144:147], v[166:169], v[124:127]
	v_mfma_f32_16x16x32_bf16 v[92:95], v[158:161], v[166:169], v[92:95]
	v_mfma_f32_16x16x32_bf16 v[120:123], v[144:147], v[174:177], v[120:123]
	v_mfma_f32_16x16x32_bf16 v[88:91], v[158:161], v[174:177], v[88:91]
	v_mfma_f32_16x16x32_bf16 v[116:119], v[144:147], v[182:185], v[116:119]
	v_mfma_f32_16x16x32_bf16 v[84:87], v[158:161], v[182:185], v[84:87]
	v_mfma_f32_16x16x32_bf16 v[112:115], v[144:147], v[190:193], v[112:115]
	v_mfma_f32_16x16x32_bf16 v[80:83], v[158:161], v[190:193], v[80:83]
	s_barrier
	s_add_i32 s34, 0, 0x1c000
	s_add_i32 s26, s63, s3
	v_add_u32_e32 v206, s34, v149
	v_lshl_add_u64 v[210:211], v[210:211], 0, s[12:13]
	s_mov_b32 m0, s26
	ds_read_b128 v[194:197], v206
	ds_read_b128 v[198:201], v206 offset:1024
	ds_read_b128 v[202:205], v206 offset:2048
	ds_read_b128 v[206:209], v206 offset:3072
	global_load_lds_dwordx4 v[210:211], off
	v_lshl_add_u64 v[210:211], v[212:213], 0, s[12:13]
	s_add_i32 m0, s26, 0x2000
	s_nop 0
	global_load_lds_dwordx4 v[210:211], off
	s_barrier
	s_waitcnt lgkmcnt(0)
	s_waitcnt lgkmcnt(0)
	v_mfma_f32_16x16x32_bf16 v[76:79], v[194:197], v[162:165], v[76:79]
	v_mfma_f32_16x16x32_bf16 v[48:51], v[202:205], v[162:165], v[48:51]
	v_mfma_f32_16x16x32_bf16 v[68:71], v[194:197], v[170:173], v[68:71]
	v_mfma_f32_16x16x32_bf16 v[40:43], v[202:205], v[170:173], v[40:43]
	v_mfma_f32_16x16x32_bf16 v[60:63], v[194:197], v[178:181], v[60:63]
	v_mfma_f32_16x16x32_bf16 v[36:39], v[202:205], v[178:181], v[36:39]
	v_mfma_f32_16x16x32_bf16 v[52:55], v[194:197], v[186:189], v[52:55]
	v_mfma_f32_16x16x32_bf16 v[28:31], v[202:205], v[186:189], v[28:31]
	v_mfma_f32_16x16x32_bf16 v[76:79], v[198:201], v[166:169], v[76:79]
	v_mfma_f32_16x16x32_bf16 v[48:51], v[206:209], v[166:169], v[48:51]
	v_mfma_f32_16x16x32_bf16 v[68:71], v[198:201], v[174:177], v[68:71]
	v_mfma_f32_16x16x32_bf16 v[40:43], v[206:209], v[174:177], v[40:43]
	v_mfma_f32_16x16x32_bf16 v[60:63], v[198:201], v[182:185], v[60:63]
	v_mfma_f32_16x16x32_bf16 v[36:39], v[206:209], v[182:185], v[36:39]
	v_mfma_f32_16x16x32_bf16 v[52:55], v[198:201], v[190:193], v[52:55]
	v_mfma_f32_16x16x32_bf16 v[28:31], v[206:209], v[190:193], v[28:31]
	s_mov_b32 m0, s38
	v_lshl_add_u64 v[210:211], v[214:215], 0, s[12:13]
	s_barrier
	ds_read_b128 v[162:165], v152 offset:49152
	ds_read_b128 v[166:169], v152 offset:50176
	ds_read_b128 v[170:173], v152 offset:51200
	ds_read_b128 v[174:177], v152 offset:52224
	ds_read_b128 v[178:181], v152 offset:53248
	ds_read_b128 v[182:185], v152 offset:54272
	ds_read_b128 v[186:189], v152 offset:55296
	ds_read_b128 v[190:193], v152 offset:56320
	global_load_lds_dwordx4 v[210:211], off
	v_lshl_add_u64 v[210:211], v[216:217], 0, s[12:13]
	s_mov_b32 m0, s39
	s_nop 0
	global_load_lds_dwordx4 v[210:211], off
	s_barrier
	s_waitcnt lgkmcnt(0)
	s_waitcnt lgkmcnt(0)
	v_mfma_f32_16x16x32_bf16 v[108:111], v[128:131], v[162:165], v[108:111]
	v_mfma_f32_16x16x32_bf16 v[72:75], v[154:157], v[162:165], v[72:75]
	v_mfma_f32_16x16x32_bf16 v[104:107], v[128:131], v[170:173], v[104:107]
	v_mfma_f32_16x16x32_bf16 v[64:67], v[154:157], v[170:173], v[64:67]
	v_mfma_f32_16x16x32_bf16 v[100:103], v[128:131], v[178:181], v[100:103]
	v_mfma_f32_16x16x32_bf16 v[56:59], v[154:157], v[178:181], v[56:59]
	v_mfma_f32_16x16x32_bf16 v[96:99], v[128:131], v[186:189], v[96:99]
	v_mfma_f32_16x16x32_bf16 v[44:47], v[154:157], v[186:189], v[44:47]
	v_mfma_f32_16x16x32_bf16 v[108:111], v[144:147], v[166:169], v[108:111]
	v_mfma_f32_16x16x32_bf16 v[72:75], v[158:161], v[166:169], v[72:75]
	v_mfma_f32_16x16x32_bf16 v[104:107], v[144:147], v[174:177], v[104:107]
	v_mfma_f32_16x16x32_bf16 v[64:67], v[158:161], v[174:177], v[64:67]
	v_mfma_f32_16x16x32_bf16 v[100:103], v[144:147], v[182:185], v[100:103]
	v_mfma_f32_16x16x32_bf16 v[56:59], v[158:161], v[182:185], v[56:59]
	v_mfma_f32_16x16x32_bf16 v[96:99], v[144:147], v[190:193], v[96:99]
	v_mfma_f32_16x16x32_bf16 v[44:47], v[158:161], v[190:193], v[44:47]
	s_barrier
	s_add_u32 s26, s30, 0x100080
	s_addc_u32 s27, s31, 0
	s_add_i32 s30, s34, s3
	v_lshl_add_u64 v[128:129], s[26:27], 0, v[132:133]
	s_mov_b32 m0, s30
	s_nop 0
	global_load_lds_dwordx4 v[128:129], off
	v_lshl_add_u64 v[128:129], s[26:27], 0, v[134:135]
	s_add_i32 m0, s30, 0x2000
	s_nop 0
	global_load_lds_dwordx4 v[128:129], off
	s_waitcnt vmcnt(6)
	s_barrier
	v_mfma_f32_16x16x32_bf16 v[32:35], v[194:197], v[162:165], v[32:35]
	v_mfma_f32_16x16x32_bf16 v[12:15], v[202:205], v[162:165], v[12:15]
	v_mfma_f32_16x16x32_bf16 v[24:27], v[194:197], v[170:173], v[24:27]
	v_mfma_f32_16x16x32_bf16 v[8:11], v[202:205], v[170:173], v[8:11]
	v_mfma_f32_16x16x32_bf16 v[20:23], v[194:197], v[178:181], v[20:23]
	v_mfma_f32_16x16x32_bf16 v[4:7], v[202:205], v[178:181], v[4:7]
	v_mfma_f32_16x16x32_bf16 v[16:19], v[194:197], v[186:189], v[16:19]
	v_mfma_f32_16x16x32_bf16 v[0:3], v[202:205], v[186:189], v[0:3]
	v_mfma_f32_16x16x32_bf16 v[32:35], v[198:201], v[166:169], v[32:35]
	v_mfma_f32_16x16x32_bf16 v[12:15], v[206:209], v[166:169], v[12:15]
	v_mfma_f32_16x16x32_bf16 v[24:27], v[198:201], v[174:177], v[24:27]
	v_mfma_f32_16x16x32_bf16 v[8:11], v[206:209], v[174:177], v[8:11]
	v_mfma_f32_16x16x32_bf16 v[20:23], v[198:201], v[182:185], v[20:23]
	v_mfma_f32_16x16x32_bf16 v[4:7], v[206:209], v[182:185], v[4:7]
	v_mfma_f32_16x16x32_bf16 v[16:19], v[198:201], v[190:193], v[16:19]
	v_mfma_f32_16x16x32_bf16 v[0:3], v[206:209], v[190:193], v[0:3]
	s_add_i32 s62, s62, 2
	s_add_u32 s56, s56, 0x100
	s_addc_u32 s57, s57, 0
	s_cmp_gt_u32 s62, 61
	s_mov_b64 s[26:27], s[28:29]
	s_barrier
	s_cbranch_scc0 .LBB0_2676
	s_cmp_lt_u32 s22, 32
	s_movk_i32 s15, 0x3000
	s_cselect_b32 s15, s15, 0x6000
	s_cmp_gt_i32 s22, 15
	v_lshl_add_u32 v158, s22, 8, v148
	s_cselect_b32 s15, s15, 0
	v_readlane_b32 s48, v240, 22
	v_lshl_or_b32 v128, s47, 8, v150
	s_lshl_b32 s15, s15, 2
	v_ashrrev_i32_e32 v159, 31, v158
	v_readlane_b32 s49, v240, 23
	v_readlane_b32 s50, v240, 24
	v_readlane_b32 s51, v240, 25
	v_readlane_b32 s52, v240, 26
	v_readlane_b32 s53, v240, 27
	s_add_u32 s26, s41, s15
	v_ashrrev_i32_e32 v129, 31, v128
	v_lshlrev_b64 v[146:147], 13, v[158:159]
	v_readlane_b32 s54, v240, 28
	v_readlane_b32 s55, v240, 29
	s_mov_b64 s[44:45], s[48:49]
	s_mov_b64 s[48:49], s[52:53]
	s_addc_u32 s27, s42, 0
	v_lshlrev_b64 v[160:161], 2, v[128:129]
	v_lshl_add_u64 v[146:147], s[48:49], 0, v[146:147]
	v_lshl_add_u64 v[144:145], s[26:27], 0, v[160:161]
	v_lshl_add_u64 v[146:147], v[146:147], 0, v[160:161]
	s_mov_b32 s15, 0x100000
	s_mov_b64 s[26:27], 0x100000
	v_readlane_b32 s58, v240, 32
	v_readlane_b32 s59, v240, 33
	v_readlane_b32 s62, v240, 36
	v_readlane_b32 s63, v240, 37
	s_mov_b32 s47, s14
	s_mov_b32 s22, s16
	s_mov_b64 s[28:29], s[20:21]
	v_readlane_b32 s56, v240, 30
	v_readlane_b32 s57, v240, 31
	v_readlane_b32 s60, v240, 34
	v_readlane_b32 s61, v240, 35
	s_mov_b64 s[50:51], s[54:55]
	v_or_b32_e32 v162, 16, v158
	v_ashrrev_i32_e32 v163, 31, v162
	v_lshlrev_b64 v[164:165], 13, v[162:163]
	v_lshl_add_u64 v[162:163], s[48:49], 0, v[164:165]
	v_lshl_add_u64 v[164:165], v[162:163], 0, v[160:161]
	v_or_b32_e32 v162, 32, v158
	v_ashrrev_i32_e32 v163, 31, v162
	v_lshlrev_b64 v[166:167], 13, v[162:163]
	v_lshl_add_u64 v[162:163], s[48:49], 0, v[166:167]
	v_lshl_add_u64 v[166:167], v[162:163], 0, v[160:161]
	v_or_b32_e32 v162, 48, v158
	v_ashrrev_i32_e32 v163, 31, v162
	v_lshlrev_b64 v[168:169], 13, v[162:163]
	v_lshl_add_u64 v[162:163], s[48:49], 0, v[168:169]
	v_lshl_add_u64 v[168:169], v[162:163], 0, v[160:161]
	v_add_co_u32_e32 v162, vcc, s15, v146
	s_mov_b32 s15, 0x120000
	s_nop 0
	v_addc_co_u32_e32 v163, vcc, 0, v147, vcc
	v_lshl_add_u64 v[170:171], v[146:147], 0, s[26:27]
	s_mov_b64 s[26:27], 0x120000
	v_add_co_u32_e32 v172, vcc, s15, v146
	s_mov_b32 s15, 0x140000
	s_nop 0
	v_addc_co_u32_e32 v173, vcc, 0, v147, vcc
	v_lshl_add_u64 v[174:175], v[146:147], 0, s[26:27]
	s_mov_b64 s[26:27], 0x140000
	v_add_co_u32_e32 v176, vcc, s15, v146
	s_mov_b32 s15, 0x160000
	s_nop 0
	v_addc_co_u32_e32 v177, vcc, 0, v147, vcc
	v_lshl_add_u64 v[178:179], v[146:147], 0, s[26:27]
	s_mov_b64 s[26:27], 0x160000
	v_add_co_u32_e32 v180, vcc, s15, v146
	v_lshl_add_u64 v[182:183], v[146:147], 0, s[26:27]
	s_nop 0
	v_addc_co_u32_e32 v181, vcc, 0, v147, vcc
	s_and_b64 vcc, exec, s[10:11]
	s_mov_b64 s[26:27], s[18:19]
	global_load_dwordx4 v[184:187], v[144:145], off
	global_load_dwordx4 v[188:191], v[146:147], off
	v_pk_add_f32 v[126:127], v[126:127], 0 op_sel_hi:[1,0]
	v_pk_add_f32 v[124:125], v[124:125], 0 op_sel_hi:[1,0]
	v_pk_add_f32 v[122:123], v[122:123], 0 op_sel_hi:[1,0]
	v_pk_add_f32 v[120:121], v[120:121], 0 op_sel_hi:[1,0]
	v_pk_add_f32 v[118:119], v[118:119], 0 op_sel_hi:[1,0]
	v_pk_add_f32 v[116:117], v[116:117], 0 op_sel_hi:[1,0]
	v_pk_add_f32 v[114:115], v[114:115], 0 op_sel_hi:[1,0]
	v_pk_add_f32 v[112:113], v[112:113], 0 op_sel_hi:[1,0]
	v_pk_add_f32 v[110:111], v[110:111], 0 op_sel_hi:[1,0]
	v_pk_add_f32 v[108:109], v[108:109], 0 op_sel_hi:[1,0]
	v_pk_add_f32 v[106:107], v[106:107], 0 op_sel_hi:[1,0]
	v_pk_add_f32 v[104:105], v[104:105], 0 op_sel_hi:[1,0]
	v_pk_add_f32 v[102:103], v[102:103], 0 op_sel_hi:[1,0]
	v_pk_add_f32 v[100:101], v[100:101], 0 op_sel_hi:[1,0]
	v_pk_add_f32 v[98:99], v[98:99], 0 op_sel_hi:[1,0]
	v_pk_add_f32 v[96:97], v[96:97], 0 op_sel_hi:[1,0]
	v_pk_add_f32 v[94:95], v[94:95], 0 op_sel_hi:[1,0]
	v_pk_add_f32 v[92:93], v[92:93], 0 op_sel_hi:[1,0]
	v_pk_add_f32 v[90:91], v[90:91], 0 op_sel_hi:[1,0]
	v_pk_add_f32 v[88:89], v[88:89], 0 op_sel_hi:[1,0]
	v_pk_add_f32 v[86:87], v[86:87], 0 op_sel_hi:[1,0]
	v_pk_add_f32 v[84:85], v[84:85], 0 op_sel_hi:[1,0]
	v_pk_add_f32 v[82:83], v[82:83], 0 op_sel_hi:[1,0]
	v_pk_add_f32 v[80:81], v[80:81], 0 op_sel_hi:[1,0]
	v_pk_add_f32 v[74:75], v[74:75], 0 op_sel_hi:[1,0]
	v_pk_add_f32 v[72:73], v[72:73], 0 op_sel_hi:[1,0]
	v_pk_add_f32 v[66:67], v[66:67], 0 op_sel_hi:[1,0]
	v_pk_add_f32 v[64:65], v[64:65], 0 op_sel_hi:[1,0]
	v_pk_add_f32 v[58:59], v[58:59], 0 op_sel_hi:[1,0]
	v_pk_add_f32 v[56:57], v[56:57], 0 op_sel_hi:[1,0]
	v_pk_add_f32 v[46:47], v[46:47], 0 op_sel_hi:[1,0]
	v_pk_add_f32 v[44:45], v[44:45], 0 op_sel_hi:[1,0]
	v_pk_add_f32 v[62:63], v[62:63], 0 op_sel_hi:[1,0]
	v_pk_add_f32 v[60:61], v[60:61], 0 op_sel_hi:[1,0]
	v_pk_add_f32 v[54:55], v[54:55], 0 op_sel_hi:[1,0]
	v_pk_add_f32 v[52:53], v[52:53], 0 op_sel_hi:[1,0]
	v_pk_add_f32 v[34:35], v[34:35], 0 op_sel_hi:[1,0]
	v_pk_add_f32 v[32:33], v[32:33], 0 op_sel_hi:[1,0]
	v_pk_add_f32 v[26:27], v[26:27], 0 op_sel_hi:[1,0]
	v_pk_add_f32 v[24:25], v[24:25], 0 op_sel_hi:[1,0]
	v_pk_add_f32 v[22:23], v[22:23], 0 op_sel_hi:[1,0]
	v_pk_add_f32 v[20:21], v[20:21], 0 op_sel_hi:[1,0]
	v_pk_add_f32 v[18:19], v[18:19], 0 op_sel_hi:[1,0]
	v_pk_add_f32 v[16:17], v[16:17], 0 op_sel_hi:[1,0]
	v_pk_add_f32 v[14:15], v[14:15], 0 op_sel_hi:[1,0]
	v_pk_add_f32 v[12:13], v[12:13], 0 op_sel_hi:[1,0]
	v_pk_add_f32 v[10:11], v[10:11], 0 op_sel_hi:[1,0]
	v_pk_add_f32 v[8:9], v[8:9], 0 op_sel_hi:[1,0]
	v_pk_add_f32 v[6:7], v[6:7], 0 op_sel_hi:[1,0]
	v_pk_add_f32 v[4:5], v[4:5], 0 op_sel_hi:[1,0]
	v_pk_add_f32 v[2:3], v[2:3], 0 op_sel_hi:[1,0]
	v_pk_add_f32 v[0:1], v[0:1], 0 op_sel_hi:[1,0]
	s_waitcnt vmcnt(0)
	v_pk_fma_f32 v[126:127], v[126:127], v[186:187], v[190:191]
	v_pk_fma_f32 v[124:125], v[124:125], v[184:185], v[188:189]
	global_store_dwordx4 v[146:147], v[124:127], off
	global_load_dwordx4 v[188:191], v[164:165], off
	global_load_dwordx4 v[192:195], v[166:167], off
	global_load_dwordx4 v[196:199], v[168:169], off
	global_load_dwordx4 v[200:203], v[162:163], off
	global_load_dwordx4 v[204:207], v[172:173], off
	global_load_dwordx4 v[208:211], v[176:177], off
	global_load_dwordx4 v[212:215], v[180:181], off
	global_load_dwordx4 v[216:219], v[144:145], off offset:64
	global_load_dwordx4 v[220:223], v[146:147], off offset:64
	global_load_dwordx4 v[224:227], v[164:165], off offset:64
	global_load_dwordx4 v[228:231], v[166:167], off offset:64
	global_load_dwordx4 v[232:235], v[168:169], off offset:64
	s_waitcnt vmcnt(11)
	v_pk_fma_f32 v[122:123], v[122:123], v[186:187], v[190:191]
	v_pk_fma_f32 v[120:121], v[120:121], v[184:185], v[188:189]
	global_store_dwordx4 v[164:165], v[120:123], off
	global_load_dwordx4 v[188:191], v[170:171], off offset:64
	s_waitcnt vmcnt(12)
	v_pk_fma_f32 v[118:119], v[118:119], v[186:187], v[194:195]
	v_pk_fma_f32 v[116:117], v[116:117], v[184:185], v[192:193]
	global_store_dwordx4 v[166:167], v[116:119], off
	global_load_dwordx4 v[192:195], v[174:175], off offset:64
	s_waitcnt vmcnt(13)
	v_pk_fma_f32 v[114:115], v[114:115], v[186:187], v[198:199]
	v_pk_fma_f32 v[112:113], v[112:113], v[184:185], v[196:197]
	global_store_dwordx4 v[168:169], v[112:115], off
	global_load_dwordx4 v[196:199], v[178:179], off offset:64
	s_waitcnt vmcnt(14)
	v_pk_fma_f32 v[110:111], v[110:111], v[186:187], v[202:203]
	v_pk_fma_f32 v[108:109], v[108:109], v[184:185], v[200:201]
	global_store_dwordx4 v[162:163], v[108:111], off
	global_load_dwordx4 v[200:203], v[182:183], off offset:64
	s_waitcnt vmcnt(15)
	v_pk_fma_f32 v[106:107], v[106:107], v[186:187], v[206:207]
	v_pk_fma_f32 v[104:105], v[104:105], v[184:185], v[204:205]
	global_store_dwordx4 v[172:173], v[104:107], off
	global_load_dwordx4 v[204:207], v[144:145], off offset:512
	s_waitcnt vmcnt(16)
	v_pk_fma_f32 v[102:103], v[102:103], v[186:187], v[210:211]
	v_pk_fma_f32 v[100:101], v[100:101], v[184:185], v[208:209]
	global_store_dwordx4 v[176:177], v[100:103], off
	global_load_dwordx4 v[208:211], v[146:147], off offset:512
	s_waitcnt vmcnt(17)
	v_pk_fma_f32 v[98:99], v[98:99], v[186:187], v[214:215]
	v_pk_fma_f32 v[96:97], v[96:97], v[184:185], v[212:213]
	global_store_dwordx4 v[180:181], v[96:99], off
	global_load_dwordx4 v[184:187], v[164:165], off offset:512
	s_waitcnt vmcnt(17)
	v_pk_fma_f32 v[94:95], v[94:95], v[218:219], v[222:223]
	v_pk_fma_f32 v[92:93], v[92:93], v[216:217], v[220:221]
	global_store_dwordx4 v[146:147], v[92:95], off offset:64
	global_load_dwordx4 v[212:215], v[166:167], off offset:512
	global_load_dwordx4 v[220:223], v[168:169], off offset:512
	s_waitcnt vmcnt(19)
	v_pk_fma_f32 v[90:91], v[90:91], v[218:219], v[226:227]
	v_pk_fma_f32 v[88:89], v[88:89], v[216:217], v[224:225]
	global_store_dwordx4 v[164:165], v[88:91], off offset:64
	global_load_dwordx4 v[224:227], v[170:171], off offset:512
	s_waitcnt vmcnt(20)
	v_pk_fma_f32 v[86:87], v[86:87], v[218:219], v[230:231]
	v_pk_fma_f32 v[84:85], v[84:85], v[216:217], v[228:229]
	global_store_dwordx4 v[166:167], v[84:87], off offset:64
	global_load_dwordx4 v[228:231], v[174:175], off offset:512
	s_waitcnt vmcnt(21)
	v_pk_fma_f32 v[82:83], v[82:83], v[218:219], v[234:235]
	v_pk_fma_f32 v[80:81], v[80:81], v[216:217], v[232:233]
	global_store_dwordx4 v[168:169], v[80:83], off offset:64
	global_load_dwordx4 v[232:235], v[178:179], off offset:512
	s_waitcnt vmcnt(21)
	v_pk_fma_f32 v[74:75], v[74:75], v[218:219], v[190:191]
	v_pk_fma_f32 v[72:73], v[72:73], v[216:217], v[188:189]
	global_store_dwordx4 v[170:171], v[72:75], off offset:64
	global_load_dwordx4 v[188:191], v[182:183], off offset:512
	s_waitcnt vmcnt(21)
	v_pk_fma_f32 v[66:67], v[66:67], v[218:219], v[194:195]
	v_pk_fma_f32 v[64:65], v[64:65], v[216:217], v[192:193]
	global_store_dwordx4 v[174:175], v[64:67], off offset:64
	global_load_dwordx4 v[192:195], v[144:145], off offset:576
	s_waitcnt vmcnt(21)
	v_pk_fma_f32 v[58:59], v[58:59], v[218:219], v[198:199]
	v_pk_fma_f32 v[56:57], v[56:57], v[216:217], v[196:197]
	global_store_dwordx4 v[178:179], v[56:59], off offset:64
	global_load_dwordx4 v[196:199], v[146:147], off offset:576
	v_pk_add_f32 v[64:65], v[78:79], 0 op_sel_hi:[1,0]
	v_pk_add_f32 v[66:67], v[76:77], 0 op_sel_hi:[1,0]
	s_waitcnt vmcnt(21)
	v_pk_fma_f32 v[46:47], v[46:47], v[218:219], v[202:203]
	v_pk_fma_f32 v[44:45], v[44:45], v[216:217], v[200:201]
	global_store_dwordx4 v[182:183], v[44:47], off offset:64
	global_load_dwordx4 v[200:203], v[164:165], off offset:576
	s_waitcnt vmcnt(19)
	v_pk_fma_f32 v[58:59], v[64:65], v[206:207], v[210:211]
	v_pk_fma_f32 v[56:57], v[66:67], v[204:205], v[208:209]
	global_store_dwordx4 v[146:147], v[56:59], off offset:512
	global_load_dwordx4 v[208:211], v[166:167], off offset:576
	global_load_dwordx4 v[216:219], v[168:169], off offset:576
	v_pk_add_f32 v[64:65], v[70:71], 0 op_sel_hi:[1,0]
	v_pk_add_f32 v[66:67], v[68:69], 0 op_sel_hi:[1,0]
	s_waitcnt vmcnt(20)
	v_pk_fma_f32 v[58:59], v[64:65], v[206:207], v[186:187]
	v_pk_fma_f32 v[56:57], v[66:67], v[204:205], v[184:185]
	global_store_dwordx4 v[164:165], v[56:59], off offset:512
	global_load_dwordx4 v[184:187], v[170:171], off offset:576
	s_waitcnt vmcnt(20)
	v_pk_fma_f32 v[58:59], v[62:63], v[206:207], v[214:215]
	v_pk_fma_f32 v[56:57], v[60:61], v[204:205], v[212:213]
	global_store_dwordx4 v[166:167], v[56:59], off offset:512
	global_load_dwordx4 v[212:215], v[174:175], off offset:576
	s_waitcnt vmcnt(21)
	v_pk_fma_f32 v[54:55], v[54:55], v[206:207], v[222:223]
	v_pk_fma_f32 v[52:53], v[52:53], v[204:205], v[220:221]
	global_store_dwordx4 v[168:169], v[52:55], off offset:512
	global_load_dwordx4 v[220:223], v[178:179], off offset:576
	s_waitcnt vmcnt(21)
	v_pk_fma_f32 v[34:35], v[34:35], v[206:207], v[226:227]
	v_pk_fma_f32 v[32:33], v[32:33], v[204:205], v[224:225]
	global_store_dwordx4 v[170:171], v[32:35], off offset:512
	global_load_dwordx4 v[224:227], v[182:183], off offset:576
	s_waitcnt vmcnt(21)
	v_pk_fma_f32 v[26:27], v[26:27], v[206:207], v[230:231]
	v_pk_fma_f32 v[24:25], v[24:25], v[204:205], v[228:229]
	global_store_dwordx4 v[174:175], v[24:27], off offset:512
	s_waitcnt vmcnt(20)
	v_pk_fma_f32 v[22:23], v[22:23], v[206:207], v[234:235]
	v_pk_fma_f32 v[20:21], v[20:21], v[204:205], v[232:233]
	global_store_dwordx4 v[178:179], v[20:23], off offset:512
	v_pk_add_f32 v[24:25], v[50:51], 0 op_sel_hi:[1,0]
	v_pk_add_f32 v[26:27], v[48:49], 0 op_sel_hi:[1,0]
	s_waitcnt vmcnt(19)
	v_pk_fma_f32 v[18:19], v[18:19], v[206:207], v[190:191]
	v_pk_fma_f32 v[16:17], v[16:17], v[204:205], v[188:189]
	global_store_dwordx4 v[182:183], v[16:19], off offset:512
	s_waitcnt vmcnt(16)
	v_pk_fma_f32 v[22:23], v[24:25], v[194:195], v[198:199]
	v_pk_fma_f32 v[20:21], v[26:27], v[192:193], v[196:197]
	global_store_dwordx4 v[146:147], v[20:23], off offset:576
	v_pk_add_f32 v[24:25], v[42:43], 0 op_sel_hi:[1,0]
	v_pk_add_f32 v[26:27], v[40:41], 0 op_sel_hi:[1,0]
	s_waitcnt vmcnt(15)
	v_pk_fma_f32 v[22:23], v[24:25], v[194:195], v[202:203]
	v_pk_fma_f32 v[20:21], v[26:27], v[192:193], v[200:201]
	global_store_dwordx4 v[164:165], v[20:23], off offset:576
	v_pk_add_f32 v[24:25], v[38:39], 0 op_sel_hi:[1,0]
	v_pk_add_f32 v[26:27], v[36:37], 0 op_sel_hi:[1,0]
	s_waitcnt vmcnt(14)
	v_pk_fma_f32 v[22:23], v[24:25], v[194:195], v[210:211]
	v_pk_fma_f32 v[20:21], v[26:27], v[192:193], v[208:209]
	global_store_dwordx4 v[166:167], v[20:23], off offset:576
	v_pk_add_f32 v[24:25], v[30:31], 0 op_sel_hi:[1,0]
	v_pk_add_f32 v[26:27], v[28:29], 0 op_sel_hi:[1,0]
	s_waitcnt vmcnt(14)
	v_pk_fma_f32 v[22:23], v[24:25], v[194:195], v[218:219]
	v_pk_fma_f32 v[20:21], v[26:27], v[192:193], v[216:217]
	global_store_dwordx4 v[168:169], v[20:23], off offset:576
	s_waitcnt vmcnt(13)
	v_pk_fma_f32 v[14:15], v[14:15], v[194:195], v[186:187]
	v_pk_fma_f32 v[12:13], v[12:13], v[192:193], v[184:185]
	global_store_dwordx4 v[170:171], v[12:15], off offset:576
	s_waitcnt vmcnt(12)
	v_pk_fma_f32 v[10:11], v[10:11], v[194:195], v[214:215]
	v_pk_fma_f32 v[8:9], v[8:9], v[192:193], v[212:213]
	global_store_dwordx4 v[174:175], v[8:11], off offset:576
	s_waitcnt vmcnt(11)
	v_pk_fma_f32 v[6:7], v[6:7], v[194:195], v[222:223]
	v_pk_fma_f32 v[4:5], v[4:5], v[192:193], v[220:221]
	global_store_dwordx4 v[178:179], v[4:7], off offset:576
	s_waitcnt vmcnt(10)
	v_pk_fma_f32 v[2:3], v[2:3], v[194:195], v[226:227]
	v_pk_fma_f32 v[0:1], v[0:1], v[192:193], v[224:225]
	global_store_dwordx4 v[182:183], v[0:3], off offset:576
	s_cbranch_vccz .LBB0_2669
	s_waitcnt vmcnt(0)
	s_mov_b64 s[54:55], s[58:59]
	s_mov_b64 s[58:59], s[62:63]
	s_cmpk_gt_u32 s1, 0xff
	s_cbranch_scc1 .LBB0_2680
	s_barrier

.LBB0_2688:
	ds_read_b128 v[142:145], v139
	ds_read_b128 v[146:149], v139 offset:1024
	ds_read_b128 v[150:153], v139 offset:2048
	ds_read_b128 v[154:157], v139 offset:3072
	s_add_u32 s30, s28, 0x100
	s_addc_u32 s31, s29, 0
	s_cmp_eq_u32 s62, 4
	s_cselect_b32 s37, s19, s31
	s_cselect_b32 s36, s52, s30
	s_cselect_b32 s35, s17, s57
	s_cselect_b32 s34, s53, s56
	v_lshl_add_u64 v[190:191], s[28:29], 0, v[132:133]
	s_add_i32 m0, s5, 0xc000
	ds_read_b128 v[158:161], v140
	ds_read_b128 v[162:165], v140 offset:1024
	ds_read_b128 v[166:169], v140 offset:2048
	ds_read_b128 v[170:173], v140 offset:3072
	ds_read_b128 v[174:177], v140 offset:4096
	ds_read_b128 v[178:181], v140 offset:5120
	ds_read_b128 v[182:185], v140 offset:6144
	ds_read_b128 v[186:189], v140 offset:7168
	global_load_lds_dwordx4 v[190:191], off
	v_lshl_add_u64 v[190:191], s[28:29], 0, v[134:135]
	s_add_i32 m0, s5, 0xe000
	s_nop 0
	global_load_lds_dwordx4 v[190:191], off
	s_waitcnt lgkmcnt(8)
	s_barrier
	s_waitcnt lgkmcnt(0)
	s_waitcnt lgkmcnt(0)
	v_mfma_f32_16x16x32_bf16 v[124:127], v[142:145], v[158:161], v[124:127]
	v_mfma_f32_16x16x32_bf16 v[120:123], v[150:153], v[158:161], v[120:123]
	v_mfma_f32_16x16x32_bf16 v[116:119], v[142:145], v[166:169], v[116:119]
	v_mfma_f32_16x16x32_bf16 v[112:115], v[150:153], v[166:169], v[112:115]
	v_mfma_f32_16x16x32_bf16 v[100:103], v[142:145], v[174:177], v[100:103]
	v_mfma_f32_16x16x32_bf16 v[96:99], v[150:153], v[174:177], v[96:99]
	v_mfma_f32_16x16x32_bf16 v[84:87], v[142:145], v[182:185], v[84:87]
	v_mfma_f32_16x16x32_bf16 v[80:83], v[150:153], v[182:185], v[80:83]
	v_mfma_f32_16x16x32_bf16 v[124:127], v[146:149], v[162:165], v[124:127]
	v_mfma_f32_16x16x32_bf16 v[120:123], v[154:157], v[162:165], v[120:123]
	v_mfma_f32_16x16x32_bf16 v[116:119], v[146:149], v[170:173], v[116:119]
	v_mfma_f32_16x16x32_bf16 v[112:115], v[154:157], v[170:173], v[112:115]
	v_mfma_f32_16x16x32_bf16 v[100:103], v[146:149], v[178:181], v[100:103]
	v_mfma_f32_16x16x32_bf16 v[96:99], v[154:157], v[178:181], v[96:99]
	v_mfma_f32_16x16x32_bf16 v[84:87], v[146:149], v[186:189], v[84:87]
	v_mfma_f32_16x16x32_bf16 v[80:83], v[154:157], v[186:189], v[80:83]
	s_barrier
	s_add_i32 s28, s43, s4
	v_lshl_add_u64 v[206:207], s[34:35], 0, v[130:131]
	s_mov_b32 m0, s28
	ds_read_b128 v[190:193], v141
	ds_read_b128 v[194:197], v141 offset:1024
	ds_read_b128 v[198:201], v141 offset:2048
	ds_read_b128 v[202:205], v141 offset:3072
	global_load_lds_dwordx4 v[206:207], off
	v_lshl_add_u64 v[208:209], s[34:35], 0, v[128:129]
	s_add_i32 m0, s28, 0x2000
	s_nop 0
	global_load_lds_dwordx4 v[208:209], off
	s_barrier
	s_waitcnt lgkmcnt(0)
	s_waitcnt lgkmcnt(0)
	v_mfma_f32_16x16x32_bf16 v[108:111], v[190:193], v[158:161], v[108:111]
	v_mfma_f32_16x16x32_bf16 v[104:107], v[198:201], v[158:161], v[104:107]
	v_mfma_f32_16x16x32_bf16 v[92:95], v[190:193], v[166:169], v[92:95]
	v_mfma_f32_16x16x32_bf16 v[88:91], v[198:201], v[166:169], v[88:91]
	v_mfma_f32_16x16x32_bf16 v[76:79], v[190:193], v[174:177], v[76:79]
	v_mfma_f32_16x16x32_bf16 v[72:75], v[198:201], v[174:177], v[72:75]
	v_mfma_f32_16x16x32_bf16 v[68:71], v[190:193], v[182:185], v[68:71]
	v_mfma_f32_16x16x32_bf16 v[64:67], v[198:201], v[182:185], v[64:67]
	v_mfma_f32_16x16x32_bf16 v[108:111], v[194:197], v[162:165], v[108:111]
	v_mfma_f32_16x16x32_bf16 v[104:107], v[202:205], v[162:165], v[104:107]
	v_mfma_f32_16x16x32_bf16 v[92:95], v[194:197], v[170:173], v[92:95]
	v_mfma_f32_16x16x32_bf16 v[88:91], v[202:205], v[170:173], v[88:91]
	v_mfma_f32_16x16x32_bf16 v[76:79], v[194:197], v[178:181], v[76:79]
	v_mfma_f32_16x16x32_bf16 v[72:75], v[202:205], v[178:181], v[72:75]
	v_mfma_f32_16x16x32_bf16 v[68:71], v[194:197], v[186:189], v[68:71]
	v_mfma_f32_16x16x32_bf16 v[64:67], v[202:205], v[186:189], v[64:67]
	s_mov_b32 m0, s5
	v_lshl_add_u64 v[210:211], s[36:37], 0, v[130:131]
	s_barrier
	ds_read_b128 v[158:161], v140 offset:16384
	ds_read_b128 v[162:165], v140 offset:17408
	ds_read_b128 v[166:169], v140 offset:18432
	ds_read_b128 v[170:173], v140 offset:19456
	ds_read_b128 v[174:177], v140 offset:20480
	ds_read_b128 v[178:181], v140 offset:21504
	ds_read_b128 v[182:185], v140 offset:22528
	ds_read_b128 v[186:189], v140 offset:23552
	global_load_lds_dwordx4 v[210:211], off
	v_lshl_add_u64 v[212:213], s[36:37], 0, v[128:129]
	s_mov_b32 m0, s11
	s_nop 0
	global_load_lds_dwordx4 v[212:213], off
	s_barrier
	s_waitcnt lgkmcnt(0)
	s_waitcnt lgkmcnt(0)
	v_mfma_f32_16x16x32_bf16 v[60:63], v[142:145], v[158:161], v[60:63]
	v_mfma_f32_16x16x32_bf16 v[56:59], v[150:153], v[158:161], v[56:59]
	v_mfma_f32_16x16x32_bf16 v[52:55], v[142:145], v[166:169], v[52:55]
	v_mfma_f32_16x16x32_bf16 v[48:51], v[150:153], v[166:169], v[48:51]
	v_mfma_f32_16x16x32_bf16 v[36:39], v[142:145], v[174:177], v[36:39]
	v_mfma_f32_16x16x32_bf16 v[32:35], v[150:153], v[174:177], v[32:35]
	v_mfma_f32_16x16x32_bf16 v[20:23], v[142:145], v[182:185], v[20:23]
	v_mfma_f32_16x16x32_bf16 v[16:19], v[150:153], v[182:185], v[16:19]
	v_mfma_f32_16x16x32_bf16 v[60:63], v[146:149], v[162:165], v[60:63]
	v_mfma_f32_16x16x32_bf16 v[56:59], v[154:157], v[162:165], v[56:59]
	v_mfma_f32_16x16x32_bf16 v[52:55], v[146:149], v[170:173], v[52:55]
	v_mfma_f32_16x16x32_bf16 v[48:51], v[154:157], v[170:173], v[48:51]
	v_mfma_f32_16x16x32_bf16 v[36:39], v[146:149], v[178:181], v[36:39]
	v_mfma_f32_16x16x32_bf16 v[32:35], v[154:157], v[178:181], v[32:35]
	v_mfma_f32_16x16x32_bf16 v[20:23], v[146:149], v[186:189], v[20:23]
	v_mfma_f32_16x16x32_bf16 v[16:19], v[154:157], v[186:189], v[16:19]
	s_barrier
	s_add_u32 s28, s34, 0x100000
	s_addc_u32 s29, s35, 0
	s_add_i32 s63, s46, s4
	v_lshl_add_u64 v[142:143], s[28:29], 0, v[130:131]
	s_mov_b32 m0, s63
	s_nop 0
	global_load_lds_dwordx4 v[142:143], off
	v_lshl_add_u64 v[142:143], s[28:29], 0, v[128:129]
	s_add_i32 m0, s63, 0x2000
	s_nop 0
	global_load_lds_dwordx4 v[142:143], off
	s_waitcnt vmcnt(6)
	s_barrier
	v_mfma_f32_16x16x32_bf16 v[44:47], v[190:193], v[158:161], v[44:47]
	v_mfma_f32_16x16x32_bf16 v[40:43], v[198:201], v[158:161], v[40:43]
	v_mfma_f32_16x16x32_bf16 v[28:31], v[190:193], v[166:169], v[28:31]
	v_mfma_f32_16x16x32_bf16 v[24:27], v[198:201], v[166:169], v[24:27]
	v_mfma_f32_16x16x32_bf16 v[12:15], v[190:193], v[174:177], v[12:15]
	v_mfma_f32_16x16x32_bf16 v[8:11], v[198:201], v[174:177], v[8:11]
	v_mfma_f32_16x16x32_bf16 v[4:7], v[190:193], v[182:185], v[4:7]
	v_mfma_f32_16x16x32_bf16 v[0:3], v[198:201], v[182:185], v[0:3]
	v_mfma_f32_16x16x32_bf16 v[44:47], v[194:197], v[162:165], v[44:47]
	v_mfma_f32_16x16x32_bf16 v[40:43], v[202:205], v[162:165], v[40:43]
	v_mfma_f32_16x16x32_bf16 v[28:31], v[194:197], v[170:173], v[28:31]
	v_mfma_f32_16x16x32_bf16 v[24:27], v[202:205], v[170:173], v[24:27]
	v_mfma_f32_16x16x32_bf16 v[12:15], v[194:197], v[178:181], v[12:15]
	v_mfma_f32_16x16x32_bf16 v[8:11], v[202:205], v[178:181], v[8:11]
	v_mfma_f32_16x16x32_bf16 v[4:7], v[194:197], v[186:189], v[4:7]
	v_mfma_f32_16x16x32_bf16 v[0:3], v[202:205], v[186:189], v[0:3]
	s_add_i32 s63, 0, 0x18000
	v_add_u32_e32 v154, s63, v137
	s_barrier
	ds_read_b128 v[142:145], v154
	ds_read_b128 v[146:149], v154 offset:1024
	ds_read_b128 v[150:153], v154 offset:2048
	ds_read_b128 v[154:157], v154 offset:3072
	s_add_u32 s28, s36, 0x100000
	s_addc_u32 s29, s37, 0
	s_mov_b32 m0, s13
	v_lshl_add_u64 v[190:191], s[28:29], 0, v[130:131]
	ds_read_b128 v[158:161], v140 offset:32768
	ds_read_b128 v[162:165], v140 offset:33792
	ds_read_b128 v[166:169], v140 offset:34816
	ds_read_b128 v[170:173], v140 offset:35840
	ds_read_b128 v[174:177], v140 offset:36864
	ds_read_b128 v[178:181], v140 offset:37888
	ds_read_b128 v[182:185], v140 offset:38912
	ds_read_b128 v[186:189], v140 offset:39936
	global_load_lds_dwordx4 v[190:191], off
	v_lshl_add_u64 v[190:191], s[28:29], 0, v[128:129]
	s_mov_b32 m0, s38
	s_nop 0
	global_load_lds_dwordx4 v[190:191], off
	s_waitcnt lgkmcnt(8)
	s_barrier
	s_waitcnt lgkmcnt(0)
	s_waitcnt lgkmcnt(0)
	v_mfma_f32_16x16x32_bf16 v[124:127], v[142:145], v[158:161], v[124:127]
	v_mfma_f32_16x16x32_bf16 v[120:123], v[150:153], v[158:161], v[120:123]
	v_mfma_f32_16x16x32_bf16 v[116:119], v[142:145], v[166:169], v[116:119]
	v_mfma_f32_16x16x32_bf16 v[112:115], v[150:153], v[166:169], v[112:115]
	v_mfma_f32_16x16x32_bf16 v[100:103], v[142:145], v[174:177], v[100:103]
	v_mfma_f32_16x16x32_bf16 v[96:99], v[150:153], v[174:177], v[96:99]
	v_mfma_f32_16x16x32_bf16 v[84:87], v[142:145], v[182:185], v[84:87]
	v_mfma_f32_16x16x32_bf16 v[80:83], v[150:153], v[182:185], v[80:83]
	v_mfma_f32_16x16x32_bf16 v[124:127], v[146:149], v[162:165], v[124:127]
	v_mfma_f32_16x16x32_bf16 v[120:123], v[154:157], v[162:165], v[120:123]
	v_mfma_f32_16x16x32_bf16 v[116:119], v[146:149], v[170:173], v[116:119]
	v_mfma_f32_16x16x32_bf16 v[112:115], v[154:157], v[170:173], v[112:115]
	v_mfma_f32_16x16x32_bf16 v[100:103], v[146:149], v[178:181], v[100:103]
	v_mfma_f32_16x16x32_bf16 v[96:99], v[154:157], v[178:181], v[96:99]
	v_mfma_f32_16x16x32_bf16 v[84:87], v[146:149], v[186:189], v[84:87]
	v_mfma_f32_16x16x32_bf16 v[80:83], v[154:157], v[186:189], v[80:83]
	s_barrier
	s_add_i32 s36, 0, 0x1c000
	s_add_i32 s28, s63, s4
	v_add_u32_e32 v202, s36, v137
	v_lshl_add_u64 v[206:207], v[206:207], 0, s[14:15]
	s_mov_b32 m0, s28
	ds_read_b128 v[190:193], v202
	ds_read_b128 v[194:197], v202 offset:1024
	ds_read_b128 v[198:201], v202 offset:2048
	ds_read_b128 v[202:205], v202 offset:3072
	global_load_lds_dwordx4 v[206:207], off
	v_lshl_add_u64 v[206:207], v[208:209], 0, s[14:15]
	s_add_i32 m0, s28, 0x2000
	s_nop 0
	global_load_lds_dwordx4 v[206:207], off
	s_barrier
	s_waitcnt lgkmcnt(0)
	s_waitcnt lgkmcnt(0)
	v_mfma_f32_16x16x32_bf16 v[108:111], v[190:193], v[158:161], v[108:111]
	v_mfma_f32_16x16x32_bf16 v[104:107], v[198:201], v[158:161], v[104:107]
	v_mfma_f32_16x16x32_bf16 v[92:95], v[190:193], v[166:169], v[92:95]
	v_mfma_f32_16x16x32_bf16 v[88:91], v[198:201], v[166:169], v[88:91]
	v_mfma_f32_16x16x32_bf16 v[76:79], v[190:193], v[174:177], v[76:79]
	v_mfma_f32_16x16x32_bf16 v[72:75], v[198:201], v[174:177], v[72:75]
	v_mfma_f32_16x16x32_bf16 v[68:71], v[190:193], v[182:185], v[68:71]
	v_mfma_f32_16x16x32_bf16 v[64:67], v[198:201], v[182:185], v[64:67]
	v_mfma_f32_16x16x32_bf16 v[108:111], v[194:197], v[162:165], v[108:111]
	v_mfma_f32_16x16x32_bf16 v[104:107], v[202:205], v[162:165], v[104:107]
	v_mfma_f32_16x16x32_bf16 v[92:95], v[194:197], v[170:173], v[92:95]
	v_mfma_f32_16x16x32_bf16 v[88:91], v[202:205], v[170:173], v[88:91]
	v_mfma_f32_16x16x32_bf16 v[76:79], v[194:197], v[178:181], v[76:79]
	v_mfma_f32_16x16x32_bf16 v[72:75], v[202:205], v[178:181], v[72:75]
	v_mfma_f32_16x16x32_bf16 v[68:71], v[194:197], v[186:189], v[68:71]
	v_mfma_f32_16x16x32_bf16 v[64:67], v[202:205], v[186:189], v[64:67]
	s_mov_b32 m0, s41
	v_lshl_add_u64 v[206:207], v[210:211], 0, s[14:15]
	s_barrier
	ds_read_b128 v[158:161], v140 offset:49152
	ds_read_b128 v[162:165], v140 offset:50176
	ds_read_b128 v[166:169], v140 offset:51200
	ds_read_b128 v[170:173], v140 offset:52224
	ds_read_b128 v[174:177], v140 offset:53248
	ds_read_b128 v[178:181], v140 offset:54272
	ds_read_b128 v[182:185], v140 offset:55296
	ds_read_b128 v[186:189], v140 offset:56320
	global_load_lds_dwordx4 v[206:207], off
	v_lshl_add_u64 v[206:207], v[212:213], 0, s[14:15]
	s_mov_b32 m0, s42
	s_nop 0
	global_load_lds_dwordx4 v[206:207], off
	s_barrier
	s_waitcnt lgkmcnt(0)
	s_waitcnt lgkmcnt(0)
	v_mfma_f32_16x16x32_bf16 v[60:63], v[142:145], v[158:161], v[60:63]
	v_mfma_f32_16x16x32_bf16 v[56:59], v[150:153], v[158:161], v[56:59]
	v_mfma_f32_16x16x32_bf16 v[52:55], v[142:145], v[166:169], v[52:55]
	v_mfma_f32_16x16x32_bf16 v[48:51], v[150:153], v[166:169], v[48:51]
	v_mfma_f32_16x16x32_bf16 v[36:39], v[142:145], v[174:177], v[36:39]
	v_mfma_f32_16x16x32_bf16 v[32:35], v[150:153], v[174:177], v[32:35]
	v_mfma_f32_16x16x32_bf16 v[20:23], v[142:145], v[182:185], v[20:23]
	v_mfma_f32_16x16x32_bf16 v[16:19], v[150:153], v[182:185], v[16:19]
	v_mfma_f32_16x16x32_bf16 v[60:63], v[146:149], v[162:165], v[60:63]
	v_mfma_f32_16x16x32_bf16 v[56:59], v[154:157], v[162:165], v[56:59]
	v_mfma_f32_16x16x32_bf16 v[52:55], v[146:149], v[170:173], v[52:55]
	v_mfma_f32_16x16x32_bf16 v[48:51], v[154:157], v[170:173], v[48:51]
	v_mfma_f32_16x16x32_bf16 v[36:39], v[146:149], v[178:181], v[36:39]
	v_mfma_f32_16x16x32_bf16 v[32:35], v[154:157], v[178:181], v[32:35]
	v_mfma_f32_16x16x32_bf16 v[20:23], v[146:149], v[186:189], v[20:23]
	v_mfma_f32_16x16x32_bf16 v[16:19], v[154:157], v[186:189], v[16:19]
	s_barrier
	s_add_u32 s28, s34, 0x100080
	s_addc_u32 s29, s35, 0
	s_add_i32 s34, s36, s4
	v_lshl_add_u64 v[142:143], s[28:29], 0, v[130:131]
	s_mov_b32 m0, s34
	s_nop 0
	global_load_lds_dwordx4 v[142:143], off
	v_lshl_add_u64 v[142:143], s[28:29], 0, v[128:129]
	s_add_i32 m0, s34, 0x2000
	s_nop 0
	global_load_lds_dwordx4 v[142:143], off
	s_waitcnt vmcnt(6)
	s_barrier
	v_mfma_f32_16x16x32_bf16 v[44:47], v[190:193], v[158:161], v[44:47]
	v_mfma_f32_16x16x32_bf16 v[40:43], v[198:201], v[158:161], v[40:43]
	v_mfma_f32_16x16x32_bf16 v[28:31], v[190:193], v[166:169], v[28:31]
	v_mfma_f32_16x16x32_bf16 v[24:27], v[198:201], v[166:169], v[24:27]
	v_mfma_f32_16x16x32_bf16 v[12:15], v[190:193], v[174:177], v[12:15]
	v_mfma_f32_16x16x32_bf16 v[8:11], v[198:201], v[174:177], v[8:11]
	v_mfma_f32_16x16x32_bf16 v[4:7], v[190:193], v[182:185], v[4:7]
	v_mfma_f32_16x16x32_bf16 v[0:3], v[198:201], v[182:185], v[0:3]
	v_mfma_f32_16x16x32_bf16 v[44:47], v[194:197], v[162:165], v[44:47]
	v_mfma_f32_16x16x32_bf16 v[40:43], v[202:205], v[162:165], v[40:43]
	v_mfma_f32_16x16x32_bf16 v[28:31], v[194:197], v[170:173], v[28:31]
	v_mfma_f32_16x16x32_bf16 v[24:27], v[202:205], v[170:173], v[24:27]
	v_mfma_f32_16x16x32_bf16 v[12:15], v[194:197], v[178:181], v[12:15]
	v_mfma_f32_16x16x32_bf16 v[8:11], v[202:205], v[178:181], v[8:11]
	v_mfma_f32_16x16x32_bf16 v[4:7], v[194:197], v[186:189], v[4:7]
	v_mfma_f32_16x16x32_bf16 v[0:3], v[202:205], v[186:189], v[0:3]
	s_add_i32 s62, s62, 2
	s_add_u32 s56, s56, 0x100
	s_addc_u32 s57, s57, 0
	s_cmp_gt_u32 s62, 5
	s_mov_b64 s[28:29], s[30:31]
	s_barrier
	s_cbranch_scc0 .LBB0_2688
	s_ashr_i32 s17, s40, 1
	s_and_b32 s17, s17, 0xfffffe00
	s_lshl_b32 s12, s12, 8
	s_add_i32 s12, s12, s17
	v_readlane_b32 s48, v240, 22
	v_add_u32_e32 v144, s12, v136
	v_readlane_b32 s49, v240, 23
	v_readlane_b32 s50, v240, 24
	v_readlane_b32 s51, v240, 25
	v_readlane_b32 s52, v240, 26
	v_readlane_b32 s53, v240, 27
	v_lshl_or_b32 v142, s10, 8, v138
	v_ashrrev_i32_e32 v145, 31, v144
	v_readlane_b32 s54, v240, 28
	v_readlane_b32 s55, v240, 29
	v_readlane_b32 s58, v240, 32
	v_readlane_b32 s59, v240, 33
	v_readlane_b32 s62, v240, 36
	v_readlane_b32 s63, v240, 37
	s_mov_b64 s[44:45], s[48:49]
	s_mov_b64 s[48:49], s[52:53]
	v_ashrrev_i32_e32 v143, 31, v142
	v_lshlrev_b64 v[146:147], 13, v[144:145]
	s_mov_b64 s[50:51], s[54:55]
	s_mov_b64 s[54:55], s[58:59]
	s_mov_b64 s[58:59], s[62:63]
	v_lshl_add_u64 v[146:147], s[58:59], 0, v[146:147]
	v_lshlrev_b64 v[142:143], 2, v[142:143]
	v_lshl_add_u64 v[146:147], v[146:147], 0, v[142:143]
	global_store_dwordx4 v[146:147], v[124:127], off
	global_store_dwordx4 v[146:147], v[120:123], off offset:64
	global_store_dwordx4 v[146:147], v[108:111], off offset:512
	global_store_dwordx4 v[146:147], v[104:107], off offset:576
	s_mov_b32 s10, 0x100000
	s_mov_b64 s[28:29], 0x100000
	v_or_b32_e32 v104, 16, v144
	v_ashrrev_i32_e32 v105, 31, v104
	v_lshlrev_b64 v[104:105], 13, v[104:105]
	v_lshl_add_u64 v[104:105], s[58:59], 0, v[104:105]
	v_lshl_add_u64 v[104:105], v[104:105], 0, v[142:143]
	global_store_dwordx4 v[104:105], v[116:119], off
	global_store_dwordx4 v[104:105], v[112:115], off offset:64
	global_store_dwordx4 v[104:105], v[92:95], off offset:512
	global_store_dwordx4 v[104:105], v[88:91], off offset:576
	s_mov_b32 s40, s47
	s_mov_b32 s12, s18
	v_or_b32_e32 v88, 32, v144
	v_ashrrev_i32_e32 v89, 31, v88
	v_lshlrev_b64 v[88:89], 13, v[88:89]
	v_lshl_add_u64 v[88:89], s[58:59], 0, v[88:89]
	v_lshl_add_u64 v[88:89], v[88:89], 0, v[142:143]
	global_store_dwordx4 v[88:89], v[100:103], off
	global_store_dwordx4 v[88:89], v[96:99], off offset:64
	global_store_dwordx4 v[88:89], v[76:79], off offset:512
	global_store_dwordx4 v[88:89], v[72:75], off offset:576
	s_mov_b64 s[30:31], s[26:27]
	v_readlane_b32 s56, v240, 30
	v_or_b32_e32 v72, 48, v144
	v_ashrrev_i32_e32 v73, 31, v72
	v_lshlrev_b64 v[72:73], 13, v[72:73]
	v_lshl_add_u64 v[72:73], s[58:59], 0, v[72:73]
	v_lshl_add_u64 v[72:73], v[72:73], 0, v[142:143]
	global_store_dwordx4 v[72:73], v[84:87], off
	global_store_dwordx4 v[72:73], v[80:83], off offset:64
	global_store_dwordx4 v[72:73], v[68:71], off offset:512
	global_store_dwordx4 v[72:73], v[64:67], off offset:576
	v_readlane_b32 s57, v240, 31
	v_readlane_b32 s60, v240, 34
	v_add_co_u32_e32 v66, vcc, s10, v146
	s_mov_b32 s10, 0x120000
	s_nop 0
	v_addc_co_u32_e32 v67, vcc, 0, v147, vcc
	v_lshl_add_u64 v[64:65], v[146:147], 0, s[28:29]
	global_store_dwordx4 v[66:67], v[60:63], off
	global_store_dwordx4 v[64:65], v[56:59], off offset:64
	global_store_dwordx4 v[64:65], v[44:47], off offset:512
	global_store_dwordx4 v[64:65], v[40:43], off offset:576
	s_mov_b64 s[28:29], 0x120000
	v_readlane_b32 s61, v240, 35
	v_add_co_u32_e32 v42, vcc, s10, v146
	s_mov_b32 s10, 0x140000
	s_nop 0
	v_addc_co_u32_e32 v43, vcc, 0, v147, vcc
	v_lshl_add_u64 v[40:41], v[146:147], 0, s[28:29]
	global_store_dwordx4 v[42:43], v[52:55], off
	global_store_dwordx4 v[40:41], v[48:51], off offset:64
	global_store_dwordx4 v[40:41], v[28:31], off offset:512
	global_store_dwordx4 v[40:41], v[24:27], off offset:576
	s_mov_b64 s[28:29], 0x140000
	s_nop 0
	v_add_co_u32_e32 v26, vcc, s10, v146
	v_lshl_add_u64 v[24:25], v[146:147], 0, s[28:29]
	s_nop 0
	v_addc_co_u32_e32 v27, vcc, 0, v147, vcc
	global_store_dwordx4 v[26:27], v[36:39], off
	global_store_dwordx4 v[24:25], v[32:35], off offset:64
	global_store_dwordx4 v[24:25], v[12:15], off offset:512
	global_store_dwordx4 v[24:25], v[8:11], off offset:576
	s_mov_b64 s[28:29], 0x160000
	s_mov_b32 s10, s16
	v_add_co_u32_e32 v10, vcc, 0x160000, v146
	v_lshl_add_u64 v[8:9], v[146:147], 0, s[28:29]
	s_nop 0
	v_addc_co_u32_e32 v11, vcc, 0, v147, vcc
	s_and_b64 vcc, exec, s[20:21]
	s_mov_b64 s[28:29], s[22:23]
	global_store_dwordx4 v[10:11], v[20:23], off
	global_store_dwordx4 v[8:9], v[16:19], off offset:64
	global_store_dwordx4 v[8:9], v[4:7], off offset:512
	global_store_dwordx4 v[8:9], v[0:3], off offset:576
	s_cbranch_vccz .LBB0_2685
	s_waitcnt vmcnt(0)
	s_cmpk_gt_u32 s1, 0xff
	s_cbranch_scc1 .LBB0_2692
	s_barrier

.LBB0_2812:
	ds_read_b128 v[148:151], v144
	ds_read_b128 v[152:155], v144 offset:1024
	ds_read_b128 v[156:159], v144 offset:2048
	ds_read_b128 v[160:163], v144 offset:3072
	s_add_u32 s26, s22, 0x100
	s_addc_u32 s27, s23, 0
	s_cmp_eq_u32 s57, 28
	s_cselect_b32 s31, s15, s27
	s_cselect_b32 s30, s47, s26
	s_cselect_b32 s29, s13, s56
	s_cselect_b32 s28, s52, s53
	v_lshl_add_u64 v[196:197], s[22:23], 0, v[134:135]
	s_add_i32 m0, s5, 0xc000
	ds_read_b128 v[164:167], v145
	ds_read_b128 v[168:171], v145 offset:1024
	ds_read_b128 v[172:175], v145 offset:2048
	ds_read_b128 v[176:179], v145 offset:3072
	ds_read_b128 v[180:183], v145 offset:4096
	ds_read_b128 v[184:187], v145 offset:5120
	ds_read_b128 v[188:191], v145 offset:6144
	ds_read_b128 v[192:195], v145 offset:7168
	global_load_lds_dwordx4 v[196:197], off
	v_lshl_add_u64 v[196:197], s[22:23], 0, v[136:137]
	s_add_i32 m0, s5, 0xe000
	s_nop 0
	global_load_lds_dwordx4 v[196:197], off
	s_waitcnt lgkmcnt(8)
	s_barrier
	s_waitcnt lgkmcnt(0)
	s_waitcnt lgkmcnt(0)
	v_mfma_f32_16x16x32_bf16 v[124:127], v[148:151], v[164:167], v[124:127]
	v_mfma_f32_16x16x32_bf16 v[120:123], v[156:159], v[164:167], v[120:123]
	v_mfma_f32_16x16x32_bf16 v[108:111], v[148:151], v[172:175], v[108:111]
	v_mfma_f32_16x16x32_bf16 v[104:107], v[156:159], v[172:175], v[104:107]
	v_mfma_f32_16x16x32_bf16 v[92:95], v[148:151], v[180:183], v[92:95]
	v_mfma_f32_16x16x32_bf16 v[88:91], v[156:159], v[180:183], v[88:91]
	v_mfma_f32_16x16x32_bf16 v[76:79], v[148:151], v[188:191], v[76:79]
	v_mfma_f32_16x16x32_bf16 v[72:75], v[156:159], v[188:191], v[72:75]
	v_mfma_f32_16x16x32_bf16 v[124:127], v[152:155], v[168:171], v[124:127]
	v_mfma_f32_16x16x32_bf16 v[120:123], v[160:163], v[168:171], v[120:123]
	v_mfma_f32_16x16x32_bf16 v[108:111], v[152:155], v[176:179], v[108:111]
	v_mfma_f32_16x16x32_bf16 v[104:107], v[160:163], v[176:179], v[104:107]
	v_mfma_f32_16x16x32_bf16 v[92:95], v[152:155], v[184:187], v[92:95]
	v_mfma_f32_16x16x32_bf16 v[88:91], v[160:163], v[184:187], v[88:91]
	v_mfma_f32_16x16x32_bf16 v[76:79], v[152:155], v[192:195], v[76:79]
	v_mfma_f32_16x16x32_bf16 v[72:75], v[160:163], v[192:195], v[72:75]
	s_barrier
	s_add_i32 s22, s42, s2
	v_lshl_add_u64 v[212:213], s[28:29], 0, v[130:131]
	s_mov_b32 m0, s22
	ds_read_b128 v[196:199], v146
	ds_read_b128 v[200:203], v146 offset:1024
	ds_read_b128 v[204:207], v146 offset:2048
	ds_read_b128 v[208:211], v146 offset:3072
	global_load_lds_dwordx4 v[212:213], off
	v_lshl_add_u64 v[214:215], s[28:29], 0, v[128:129]
	s_add_i32 m0, s22, 0x2000
	s_nop 0
	global_load_lds_dwordx4 v[214:215], off
	s_barrier
	s_waitcnt lgkmcnt(0)
	s_waitcnt lgkmcnt(0)
	v_mfma_f32_16x16x32_bf16 v[116:119], v[196:199], v[164:167], v[116:119]
	v_mfma_f32_16x16x32_bf16 v[112:115], v[204:207], v[164:167], v[112:115]
	v_mfma_f32_16x16x32_bf16 v[100:103], v[196:199], v[172:175], v[100:103]
	v_mfma_f32_16x16x32_bf16 v[96:99], v[204:207], v[172:175], v[96:99]
	v_mfma_f32_16x16x32_bf16 v[84:87], v[196:199], v[180:183], v[84:87]
	v_mfma_f32_16x16x32_bf16 v[80:83], v[204:207], v[180:183], v[80:83]
	v_mfma_f32_16x16x32_bf16 v[68:71], v[196:199], v[188:191], v[68:71]
	v_mfma_f32_16x16x32_bf16 v[64:67], v[204:207], v[188:191], v[64:67]
	v_mfma_f32_16x16x32_bf16 v[116:119], v[200:203], v[168:171], v[116:119]
	v_mfma_f32_16x16x32_bf16 v[112:115], v[208:211], v[168:171], v[112:115]
	v_mfma_f32_16x16x32_bf16 v[100:103], v[200:203], v[176:179], v[100:103]
	v_mfma_f32_16x16x32_bf16 v[96:99], v[208:211], v[176:179], v[96:99]
	v_mfma_f32_16x16x32_bf16 v[84:87], v[200:203], v[184:187], v[84:87]
	v_mfma_f32_16x16x32_bf16 v[80:83], v[208:211], v[184:187], v[80:83]
	v_mfma_f32_16x16x32_bf16 v[68:71], v[200:203], v[192:195], v[68:71]
	v_mfma_f32_16x16x32_bf16 v[64:67], v[208:211], v[192:195], v[64:67]
	s_mov_b32 m0, s5
	v_lshl_add_u64 v[216:217], s[30:31], 0, v[130:131]
	s_barrier
	ds_read_b128 v[164:167], v145 offset:16384
	ds_read_b128 v[168:171], v145 offset:17408
	ds_read_b128 v[172:175], v145 offset:18432
	ds_read_b128 v[176:179], v145 offset:19456
	ds_read_b128 v[180:183], v145 offset:20480
	ds_read_b128 v[184:187], v145 offset:21504
	ds_read_b128 v[188:191], v145 offset:22528
	ds_read_b128 v[192:195], v145 offset:23552
	global_load_lds_dwordx4 v[216:217], off
	v_lshl_add_u64 v[218:219], s[30:31], 0, v[128:129]
	s_mov_b32 m0, s34
	s_nop 0
	global_load_lds_dwordx4 v[218:219], off
	s_barrier
	s_waitcnt lgkmcnt(0)
	s_waitcnt lgkmcnt(0)
	v_mfma_f32_16x16x32_bf16 v[60:63], v[148:151], v[164:167], v[60:63]
	v_mfma_f32_16x16x32_bf16 v[56:59], v[156:159], v[164:167], v[56:59]
	v_mfma_f32_16x16x32_bf16 v[44:47], v[148:151], v[172:175], v[44:47]
	v_mfma_f32_16x16x32_bf16 v[40:43], v[156:159], v[172:175], v[40:43]
	v_mfma_f32_16x16x32_bf16 v[28:31], v[148:151], v[180:183], v[28:31]
	v_mfma_f32_16x16x32_bf16 v[24:27], v[156:159], v[180:183], v[24:27]
	v_mfma_f32_16x16x32_bf16 v[12:15], v[148:151], v[188:191], v[12:15]
	v_mfma_f32_16x16x32_bf16 v[8:11], v[156:159], v[188:191], v[8:11]
	v_mfma_f32_16x16x32_bf16 v[60:63], v[152:155], v[168:171], v[60:63]
	v_mfma_f32_16x16x32_bf16 v[56:59], v[160:163], v[168:171], v[56:59]
	v_mfma_f32_16x16x32_bf16 v[44:47], v[152:155], v[176:179], v[44:47]
	v_mfma_f32_16x16x32_bf16 v[40:43], v[160:163], v[176:179], v[40:43]
	v_mfma_f32_16x16x32_bf16 v[28:31], v[152:155], v[184:187], v[28:31]
	v_mfma_f32_16x16x32_bf16 v[24:27], v[160:163], v[184:187], v[24:27]
	v_mfma_f32_16x16x32_bf16 v[12:15], v[152:155], v[192:195], v[12:15]
	v_mfma_f32_16x16x32_bf16 v[8:11], v[160:163], v[192:195], v[8:11]
	s_barrier
	s_add_u32 s22, s28, 0x80000
	s_addc_u32 s23, s29, 0
	s_add_i32 s60, s43, s2
	v_lshl_add_u64 v[148:149], s[22:23], 0, v[130:131]
	s_mov_b32 m0, s60
	s_nop 0
	global_load_lds_dwordx4 v[148:149], off
	v_lshl_add_u64 v[148:149], s[22:23], 0, v[128:129]
	s_add_i32 m0, s60, 0x2000
	s_nop 0
	global_load_lds_dwordx4 v[148:149], off
	s_waitcnt vmcnt(6)
	s_barrier
	v_mfma_f32_16x16x32_bf16 v[52:55], v[196:199], v[164:167], v[52:55]
	v_mfma_f32_16x16x32_bf16 v[48:51], v[204:207], v[164:167], v[48:51]
	v_mfma_f32_16x16x32_bf16 v[36:39], v[196:199], v[172:175], v[36:39]
	v_mfma_f32_16x16x32_bf16 v[32:35], v[204:207], v[172:175], v[32:35]
	v_mfma_f32_16x16x32_bf16 v[20:23], v[196:199], v[180:183], v[20:23]
	v_mfma_f32_16x16x32_bf16 v[16:19], v[204:207], v[180:183], v[16:19]
	v_mfma_f32_16x16x32_bf16 v[4:7], v[196:199], v[188:191], v[4:7]
	v_mfma_f32_16x16x32_bf16 v[0:3], v[204:207], v[188:191], v[0:3]
	v_mfma_f32_16x16x32_bf16 v[52:55], v[200:203], v[168:171], v[52:55]
	v_mfma_f32_16x16x32_bf16 v[48:51], v[208:211], v[168:171], v[48:51]
	v_mfma_f32_16x16x32_bf16 v[36:39], v[200:203], v[176:179], v[36:39]
	v_mfma_f32_16x16x32_bf16 v[32:35], v[208:211], v[176:179], v[32:35]
	v_mfma_f32_16x16x32_bf16 v[20:23], v[200:203], v[184:187], v[20:23]
	v_mfma_f32_16x16x32_bf16 v[16:19], v[208:211], v[184:187], v[16:19]
	v_mfma_f32_16x16x32_bf16 v[4:7], v[200:203], v[192:195], v[4:7]
	v_mfma_f32_16x16x32_bf16 v[0:3], v[208:211], v[192:195], v[0:3]
	s_add_i32 s60, 0, 0x18000
	v_add_u32_e32 v147, s60, v143
	s_barrier
	ds_read_b128 v[148:151], v147
	ds_read_b128 v[152:155], v147 offset:1024
	ds_read_b128 v[156:159], v147 offset:2048
	ds_read_b128 v[160:163], v147 offset:3072
	s_add_u32 s22, s30, 0x80000
	s_addc_u32 s23, s31, 0
	s_mov_b32 m0, s35
	v_lshl_add_u64 v[196:197], s[22:23], 0, v[130:131]
	ds_read_b128 v[164:167], v145 offset:32768
	ds_read_b128 v[168:171], v145 offset:33792
	ds_read_b128 v[172:175], v145 offset:34816
	ds_read_b128 v[176:179], v145 offset:35840
	ds_read_b128 v[180:183], v145 offset:36864
	ds_read_b128 v[184:187], v145 offset:37888
	ds_read_b128 v[188:191], v145 offset:38912
	ds_read_b128 v[192:195], v145 offset:39936
	global_load_lds_dwordx4 v[196:197], off
	v_lshl_add_u64 v[196:197], s[22:23], 0, v[128:129]
	s_mov_b32 m0, s36
	s_nop 0
	global_load_lds_dwordx4 v[196:197], off
	s_waitcnt lgkmcnt(8)
	s_barrier
	s_waitcnt lgkmcnt(0)
	s_waitcnt lgkmcnt(0)
	v_mfma_f32_16x16x32_bf16 v[124:127], v[148:151], v[164:167], v[124:127]
	v_mfma_f32_16x16x32_bf16 v[120:123], v[156:159], v[164:167], v[120:123]
	v_mfma_f32_16x16x32_bf16 v[108:111], v[148:151], v[172:175], v[108:111]
	v_mfma_f32_16x16x32_bf16 v[104:107], v[156:159], v[172:175], v[104:107]
	v_mfma_f32_16x16x32_bf16 v[92:95], v[148:151], v[180:183], v[92:95]
	v_mfma_f32_16x16x32_bf16 v[88:91], v[156:159], v[180:183], v[88:91]
	v_mfma_f32_16x16x32_bf16 v[76:79], v[148:151], v[188:191], v[76:79]
	v_mfma_f32_16x16x32_bf16 v[72:75], v[156:159], v[188:191], v[72:75]
	v_mfma_f32_16x16x32_bf16 v[124:127], v[152:155], v[168:171], v[124:127]
	v_mfma_f32_16x16x32_bf16 v[120:123], v[160:163], v[168:171], v[120:123]
	v_mfma_f32_16x16x32_bf16 v[108:111], v[152:155], v[176:179], v[108:111]
	v_mfma_f32_16x16x32_bf16 v[104:107], v[160:163], v[176:179], v[104:107]
	v_mfma_f32_16x16x32_bf16 v[92:95], v[152:155], v[184:187], v[92:95]
	v_mfma_f32_16x16x32_bf16 v[88:91], v[160:163], v[184:187], v[88:91]
	v_mfma_f32_16x16x32_bf16 v[76:79], v[152:155], v[192:195], v[76:79]
	v_mfma_f32_16x16x32_bf16 v[72:75], v[160:163], v[192:195], v[72:75]
	s_barrier
	s_add_i32 s30, 0, 0x1c000
	s_add_i32 s22, s60, s2
	v_add_u32_e32 v147, s30, v143
	v_lshl_add_u64 v[212:213], v[212:213], 0, s[10:11]
	s_mov_b32 m0, s22
	ds_read_b128 v[196:199], v147
	ds_read_b128 v[200:203], v147 offset:1024
	ds_read_b128 v[204:207], v147 offset:2048
	ds_read_b128 v[208:211], v147 offset:3072
	global_load_lds_dwordx4 v[212:213], off
	v_lshl_add_u64 v[212:213], v[214:215], 0, s[10:11]
	s_add_i32 m0, s22, 0x2000
	s_nop 0
	global_load_lds_dwordx4 v[212:213], off
	s_barrier
	s_waitcnt lgkmcnt(0)
	s_waitcnt lgkmcnt(0)
	v_mfma_f32_16x16x32_bf16 v[116:119], v[196:199], v[164:167], v[116:119]
	v_mfma_f32_16x16x32_bf16 v[112:115], v[204:207], v[164:167], v[112:115]
	v_mfma_f32_16x16x32_bf16 v[100:103], v[196:199], v[172:175], v[100:103]
	v_mfma_f32_16x16x32_bf16 v[96:99], v[204:207], v[172:175], v[96:99]
	v_mfma_f32_16x16x32_bf16 v[84:87], v[196:199], v[180:183], v[84:87]
	v_mfma_f32_16x16x32_bf16 v[80:83], v[204:207], v[180:183], v[80:83]
	v_mfma_f32_16x16x32_bf16 v[68:71], v[196:199], v[188:191], v[68:71]
	v_mfma_f32_16x16x32_bf16 v[64:67], v[204:207], v[188:191], v[64:67]
	v_mfma_f32_16x16x32_bf16 v[116:119], v[200:203], v[168:171], v[116:119]
	v_mfma_f32_16x16x32_bf16 v[112:115], v[208:211], v[168:171], v[112:115]
	v_mfma_f32_16x16x32_bf16 v[100:103], v[200:203], v[176:179], v[100:103]
	v_mfma_f32_16x16x32_bf16 v[96:99], v[208:211], v[176:179], v[96:99]
	v_mfma_f32_16x16x32_bf16 v[84:87], v[200:203], v[184:187], v[84:87]
	v_mfma_f32_16x16x32_bf16 v[80:83], v[208:211], v[184:187], v[80:83]
	v_mfma_f32_16x16x32_bf16 v[68:71], v[200:203], v[192:195], v[68:71]
	v_mfma_f32_16x16x32_bf16 v[64:67], v[208:211], v[192:195], v[64:67]
	s_mov_b32 m0, s38
	v_lshl_add_u64 v[212:213], v[216:217], 0, s[10:11]
	s_barrier
	ds_read_b128 v[164:167], v145 offset:49152
	ds_read_b128 v[168:171], v145 offset:50176
	ds_read_b128 v[172:175], v145 offset:51200
	ds_read_b128 v[176:179], v145 offset:52224
	ds_read_b128 v[180:183], v145 offset:53248
	ds_read_b128 v[184:187], v145 offset:54272
	ds_read_b128 v[188:191], v145 offset:55296
	ds_read_b128 v[192:195], v145 offset:56320
	global_load_lds_dwordx4 v[212:213], off
	v_lshl_add_u64 v[212:213], v[218:219], 0, s[10:11]
	s_mov_b32 m0, s39
	s_nop 0
	global_load_lds_dwordx4 v[212:213], off
	s_barrier
	s_waitcnt lgkmcnt(0)
	s_waitcnt lgkmcnt(0)
	v_mfma_f32_16x16x32_bf16 v[60:63], v[148:151], v[164:167], v[60:63]
	v_mfma_f32_16x16x32_bf16 v[56:59], v[156:159], v[164:167], v[56:59]
	v_mfma_f32_16x16x32_bf16 v[44:47], v[148:151], v[172:175], v[44:47]
	v_mfma_f32_16x16x32_bf16 v[40:43], v[156:159], v[172:175], v[40:43]
	v_mfma_f32_16x16x32_bf16 v[28:31], v[148:151], v[180:183], v[28:31]
	v_mfma_f32_16x16x32_bf16 v[24:27], v[156:159], v[180:183], v[24:27]
	v_mfma_f32_16x16x32_bf16 v[12:15], v[148:151], v[188:191], v[12:15]
	v_mfma_f32_16x16x32_bf16 v[8:11], v[156:159], v[188:191], v[8:11]
	v_mfma_f32_16x16x32_bf16 v[60:63], v[152:155], v[168:171], v[60:63]
	v_mfma_f32_16x16x32_bf16 v[56:59], v[160:163], v[168:171], v[56:59]
	v_mfma_f32_16x16x32_bf16 v[44:47], v[152:155], v[176:179], v[44:47]
	v_mfma_f32_16x16x32_bf16 v[40:43], v[160:163], v[176:179], v[40:43]
	v_mfma_f32_16x16x32_bf16 v[28:31], v[152:155], v[184:187], v[28:31]
	v_mfma_f32_16x16x32_bf16 v[24:27], v[160:163], v[184:187], v[24:27]
	v_mfma_f32_16x16x32_bf16 v[12:15], v[152:155], v[192:195], v[12:15]
	v_mfma_f32_16x16x32_bf16 v[8:11], v[160:163], v[192:195], v[8:11]
	s_barrier
	s_add_u32 s22, s28, 0x80080
	s_addc_u32 s23, s29, 0
	s_add_i32 s28, s30, s2
	v_lshl_add_u64 v[148:149], s[22:23], 0, v[130:131]
	s_mov_b32 m0, s28
	s_nop 0
	global_load_lds_dwordx4 v[148:149], off
	v_lshl_add_u64 v[148:149], s[22:23], 0, v[128:129]
	s_add_i32 m0, s28, 0x2000
	s_nop 0
	global_load_lds_dwordx4 v[148:149], off
	s_waitcnt vmcnt(6)
	s_barrier
	v_mfma_f32_16x16x32_bf16 v[52:55], v[196:199], v[164:167], v[52:55]
	v_mfma_f32_16x16x32_bf16 v[48:51], v[204:207], v[164:167], v[48:51]
	v_mfma_f32_16x16x32_bf16 v[36:39], v[196:199], v[172:175], v[36:39]
	v_mfma_f32_16x16x32_bf16 v[32:35], v[204:207], v[172:175], v[32:35]
	v_mfma_f32_16x16x32_bf16 v[20:23], v[196:199], v[180:183], v[20:23]
	v_mfma_f32_16x16x32_bf16 v[16:19], v[204:207], v[180:183], v[16:19]
	v_mfma_f32_16x16x32_bf16 v[4:7], v[196:199], v[188:191], v[4:7]
	v_mfma_f32_16x16x32_bf16 v[0:3], v[204:207], v[188:191], v[0:3]
	v_mfma_f32_16x16x32_bf16 v[52:55], v[200:203], v[168:171], v[52:55]
	v_mfma_f32_16x16x32_bf16 v[48:51], v[208:211], v[168:171], v[48:51]
	v_mfma_f32_16x16x32_bf16 v[36:39], v[200:203], v[176:179], v[36:39]
	v_mfma_f32_16x16x32_bf16 v[32:35], v[208:211], v[176:179], v[32:35]
	v_mfma_f32_16x16x32_bf16 v[20:23], v[200:203], v[184:187], v[20:23]
	v_mfma_f32_16x16x32_bf16 v[16:19], v[208:211], v[184:187], v[16:19]
	v_mfma_f32_16x16x32_bf16 v[4:7], v[200:203], v[192:195], v[4:7]
	v_mfma_f32_16x16x32_bf16 v[0:3], v[208:211], v[192:195], v[0:3]
	s_add_i32 s57, s57, 2
	s_add_u32 s53, s53, 0x100
	s_addc_u32 s56, s56, 0
	s_cmp_gt_u32 s57, 29
	s_mov_b64 s[22:23], s[26:27]
	s_barrier
	s_cbranch_scc0 .LBB0_2812
	v_mul_f32_e32 v150, 0xbfb8aa3b, v124
	v_mul_f32_e32 v151, 0xbfb8aa3b, v125
	v_exp_f32_e32 v150, v150
	v_exp_f32_e32 v151, v151
	s_lshl_b32 s13, s21, 7
	v_lshl_add_u32 v147, s20, 8, v142
	v_add_f32_e32 v150, 1.0, v150
	v_add_f32_e32 v151, 1.0, v151
	v_rcp_f32_e32 v150, v150
	v_rcp_f32_e32 v151, v151
	s_or_b32 s20, s13, s40
	s_ashr_i32 s21, s20, 31
	v_mad_i64_i32 v[148:149], s[22:23], v147, s46, v[132:133]
	v_pk_mul_f32 v[124:125], v[124:125], v[150:151]
	s_lshl_b64 s[20:21], s[20:21], 1
	v_pk_mul_f32 v[120:121], v[120:121], v[124:125]
	s_and_b64 vcc, exec, s[8:9]
	v_cvt_pk_bf16_f32 v120, v120, v121
	v_mul_f32_e32 v121, 0xbfb8aa3b, v126
	v_exp_f32_e32 v121, v121
	s_mov_b64 s[26:27], s[18:19]
	v_add_f32_e32 v121, 1.0, v121
	v_rcp_f32_e32 v124, v121
	v_mul_f32_e32 v121, 0xbfb8aa3b, v127
	v_exp_f32_e32 v121, v121
	s_nop 0
	v_add_f32_e32 v121, 1.0, v121
	v_rcp_f32_e32 v125, v121
	s_nop 0
	v_pk_mul_f32 v[124:125], v[126:127], v[124:125]
	s_nop 0
	v_pk_mul_f32 v[122:123], v[122:123], v[124:125]
	s_nop 0
	v_cvt_pk_bf16_f32 v121, v122, v123
	v_lshl_add_u64 v[122:123], v[148:149], 0, s[20:21]
	global_store_dwordx2 v[122:123], v[120:121], off
	v_mul_f32_e32 v120, 0xbfb8aa3b, v116
	v_mul_f32_e32 v121, 0xbfb8aa3b, v117
	v_exp_f32_e32 v120, v120
	v_exp_f32_e32 v121, v121
	v_add_f32_e32 v120, 1.0, v120
	v_add_f32_e32 v121, 1.0, v121
	v_rcp_f32_e32 v120, v120
	v_rcp_f32_e32 v121, v121
	s_nop 0
	v_pk_mul_f32 v[116:117], v[116:117], v[120:121]
	s_nop 0
	v_pk_mul_f32 v[112:113], v[112:113], v[116:117]
	s_nop 0
	v_cvt_pk_bf16_f32 v112, v112, v113
	v_mul_f32_e32 v113, 0xbfb8aa3b, v118
	v_exp_f32_e32 v113, v113
	s_nop 0
	v_add_f32_e32 v113, 1.0, v113
	v_rcp_f32_e32 v116, v113
	v_mul_f32_e32 v113, 0xbfb8aa3b, v119
	v_exp_f32_e32 v113, v113
	s_nop 0
	v_add_f32_e32 v113, 1.0, v113
	v_rcp_f32_e32 v117, v113
	s_nop 0
	v_pk_mul_f32 v[116:117], v[118:119], v[116:117]
	s_nop 0
	v_pk_mul_f32 v[114:115], v[114:115], v[116:117]
	s_nop 0
	v_cvt_pk_bf16_f32 v113, v114, v115
	v_mul_f32_e32 v114, 0xbfb8aa3b, v108
	v_mul_f32_e32 v115, 0xbfb8aa3b, v109
	v_exp_f32_e32 v114, v114
	v_exp_f32_e32 v115, v115
	global_store_dwordx2 v[122:123], v[112:113], off offset:128
	v_or_b32_e32 v112, 16, v147
	v_add_f32_e32 v114, 1.0, v114
	v_add_f32_e32 v115, 1.0, v115
	v_rcp_f32_e32 v114, v114
	v_rcp_f32_e32 v115, v115
	v_mad_i64_i32 v[112:113], s[22:23], v112, s46, v[132:133]
	v_pk_mul_f32 v[108:109], v[108:109], v[114:115]
	s_nop 0
	v_pk_mul_f32 v[104:105], v[104:105], v[108:109]
	s_nop 0
	v_cvt_pk_bf16_f32 v104, v104, v105
	v_mul_f32_e32 v105, 0xbfb8aa3b, v110
	v_exp_f32_e32 v105, v105
	s_nop 0
	v_add_f32_e32 v105, 1.0, v105
	v_rcp_f32_e32 v108, v105
	v_mul_f32_e32 v105, 0xbfb8aa3b, v111
	v_exp_f32_e32 v105, v105
	s_nop 0
	v_add_f32_e32 v105, 1.0, v105
	v_rcp_f32_e32 v109, v105
	s_nop 0
	v_pk_mul_f32 v[108:109], v[110:111], v[108:109]
	s_nop 0
	v_pk_mul_f32 v[106:107], v[106:107], v[108:109]
	s_nop 0
	v_cvt_pk_bf16_f32 v105, v106, v107
	v_lshl_add_u64 v[106:107], v[112:113], 0, s[20:21]
	global_store_dwordx2 v[106:107], v[104:105], off
	v_mul_f32_e32 v104, 0xbfb8aa3b, v100
	v_mul_f32_e32 v105, 0xbfb8aa3b, v101
	v_exp_f32_e32 v104, v104
	v_exp_f32_e32 v105, v105
	v_add_f32_e32 v104, 1.0, v104
	v_add_f32_e32 v105, 1.0, v105
	v_rcp_f32_e32 v104, v104
	v_rcp_f32_e32 v105, v105
	s_nop 0
	v_pk_mul_f32 v[100:101], v[100:101], v[104:105]
	s_nop 0
	v_pk_mul_f32 v[96:97], v[96:97], v[100:101]
	s_nop 0
	v_cvt_pk_bf16_f32 v96, v96, v97
	v_mul_f32_e32 v97, 0xbfb8aa3b, v102
	v_exp_f32_e32 v97, v97
	s_nop 0
	v_add_f32_e32 v97, 1.0, v97
	v_rcp_f32_e32 v100, v97
	v_mul_f32_e32 v97, 0xbfb8aa3b, v103
	v_exp_f32_e32 v97, v97
	s_nop 0
	v_add_f32_e32 v97, 1.0, v97
	v_rcp_f32_e32 v101, v97
	s_nop 0
	v_pk_mul_f32 v[100:101], v[102:103], v[100:101]
	s_nop 0
	v_pk_mul_f32 v[98:99], v[98:99], v[100:101]
	s_nop 0
	v_cvt_pk_bf16_f32 v97, v98, v99
	v_mul_f32_e32 v98, 0xbfb8aa3b, v92
	v_mul_f32_e32 v99, 0xbfb8aa3b, v93
	v_exp_f32_e32 v98, v98
	v_exp_f32_e32 v99, v99
	global_store_dwordx2 v[106:107], v[96:97], off offset:128
	v_or_b32_e32 v96, 32, v147
	v_add_f32_e32 v98, 1.0, v98
	v_add_f32_e32 v99, 1.0, v99
	v_rcp_f32_e32 v98, v98
	v_rcp_f32_e32 v99, v99
	v_mad_i64_i32 v[96:97], s[22:23], v96, s46, v[132:133]
	v_pk_mul_f32 v[92:93], v[92:93], v[98:99]
	s_nop 0
	v_pk_mul_f32 v[88:89], v[88:89], v[92:93]
	s_nop 0
	v_cvt_pk_bf16_f32 v88, v88, v89
	v_mul_f32_e32 v89, 0xbfb8aa3b, v94
	v_exp_f32_e32 v89, v89
	s_nop 0
	v_add_f32_e32 v89, 1.0, v89
	v_rcp_f32_e32 v92, v89
	v_mul_f32_e32 v89, 0xbfb8aa3b, v95
	v_exp_f32_e32 v89, v89
	s_nop 0
	v_add_f32_e32 v89, 1.0, v89
	v_rcp_f32_e32 v93, v89
	s_nop 0
	v_pk_mul_f32 v[92:93], v[94:95], v[92:93]
	s_nop 0
	v_pk_mul_f32 v[90:91], v[90:91], v[92:93]
	s_nop 0
	v_cvt_pk_bf16_f32 v89, v90, v91
	v_lshl_add_u64 v[90:91], v[96:97], 0, s[20:21]
	global_store_dwordx2 v[90:91], v[88:89], off
	v_mul_f32_e32 v88, 0xbfb8aa3b, v84
	v_mul_f32_e32 v89, 0xbfb8aa3b, v85
	v_exp_f32_e32 v88, v88
	v_exp_f32_e32 v89, v89
	v_add_f32_e32 v88, 1.0, v88
	v_add_f32_e32 v89, 1.0, v89
	v_rcp_f32_e32 v88, v88
	v_rcp_f32_e32 v89, v89
	s_nop 0
	v_pk_mul_f32 v[84:85], v[84:85], v[88:89]
	s_nop 0
	v_pk_mul_f32 v[80:81], v[80:81], v[84:85]
	s_nop 0
	v_cvt_pk_bf16_f32 v80, v80, v81
	v_mul_f32_e32 v81, 0xbfb8aa3b, v86
	v_exp_f32_e32 v81, v81
	s_nop 0
	v_add_f32_e32 v81, 1.0, v81
	v_rcp_f32_e32 v84, v81
	v_mul_f32_e32 v81, 0xbfb8aa3b, v87
	v_exp_f32_e32 v81, v81
	s_nop 0
	v_add_f32_e32 v81, 1.0, v81
	v_rcp_f32_e32 v85, v81
	s_nop 0
	v_pk_mul_f32 v[84:85], v[86:87], v[84:85]
	s_nop 0
	v_pk_mul_f32 v[82:83], v[82:83], v[84:85]
	s_nop 0
	v_cvt_pk_bf16_f32 v81, v82, v83
	v_mul_f32_e32 v82, 0xbfb8aa3b, v76
	v_mul_f32_e32 v83, 0xbfb8aa3b, v77
	v_exp_f32_e32 v82, v82
	v_exp_f32_e32 v83, v83
	global_store_dwordx2 v[90:91], v[80:81], off offset:128
	v_or_b32_e32 v80, 48, v147
	v_add_f32_e32 v82, 1.0, v82
	v_add_f32_e32 v83, 1.0, v83
	v_rcp_f32_e32 v82, v82
	v_rcp_f32_e32 v83, v83
	v_mad_i64_i32 v[80:81], s[22:23], v80, s46, v[132:133]
	v_pk_mul_f32 v[76:77], v[76:77], v[82:83]
	s_nop 0
	v_pk_mul_f32 v[72:73], v[72:73], v[76:77]
	s_nop 0
	v_cvt_pk_bf16_f32 v72, v72, v73
	v_mul_f32_e32 v73, 0xbfb8aa3b, v78
	v_exp_f32_e32 v73, v73
	s_nop 0
	v_add_f32_e32 v73, 1.0, v73
	v_rcp_f32_e32 v76, v73
	v_mul_f32_e32 v73, 0xbfb8aa3b, v79
	v_exp_f32_e32 v73, v73
	s_nop 0
	v_add_f32_e32 v73, 1.0, v73
	v_rcp_f32_e32 v77, v73
	s_nop 0
	v_pk_mul_f32 v[76:77], v[78:79], v[76:77]
	s_nop 0
	v_pk_mul_f32 v[74:75], v[74:75], v[76:77]
	s_nop 0
	v_cvt_pk_bf16_f32 v73, v74, v75
	v_lshl_add_u64 v[74:75], v[80:81], 0, s[20:21]
	global_store_dwordx2 v[74:75], v[72:73], off
	v_mul_f32_e32 v72, 0xbfb8aa3b, v68
	v_mul_f32_e32 v73, 0xbfb8aa3b, v69
	v_exp_f32_e32 v72, v72
	v_exp_f32_e32 v73, v73
	v_add_f32_e32 v72, 1.0, v72
	v_add_f32_e32 v73, 1.0, v73
	v_rcp_f32_e32 v72, v72
	v_rcp_f32_e32 v73, v73
	s_nop 0
	v_pk_mul_f32 v[68:69], v[68:69], v[72:73]
	s_nop 0
	v_pk_mul_f32 v[64:65], v[64:65], v[68:69]
	s_nop 0
	v_cvt_pk_bf16_f32 v64, v64, v65
	v_mul_f32_e32 v65, 0xbfb8aa3b, v70
	v_exp_f32_e32 v65, v65
	s_nop 0
	v_add_f32_e32 v65, 1.0, v65
	v_rcp_f32_e32 v68, v65
	v_mul_f32_e32 v65, 0xbfb8aa3b, v71
	v_exp_f32_e32 v65, v65
	s_nop 0
	v_add_f32_e32 v65, 1.0, v65
	v_rcp_f32_e32 v69, v65
	s_nop 0
	v_pk_mul_f32 v[68:69], v[70:71], v[68:69]
	s_nop 0
	v_pk_mul_f32 v[66:67], v[66:67], v[68:69]
	s_nop 0
	v_cvt_pk_bf16_f32 v65, v66, v67
	v_mul_f32_e32 v66, 0xbfb8aa3b, v60
	v_mul_f32_e32 v67, 0xbfb8aa3b, v61
	v_exp_f32_e32 v66, v66
	v_exp_f32_e32 v67, v67
	global_store_dwordx2 v[74:75], v[64:65], off offset:128
	v_add_u32_e32 v64, 0x80, v147
	v_add_f32_e32 v66, 1.0, v66
	v_add_f32_e32 v67, 1.0, v67
	v_rcp_f32_e32 v66, v66
	v_rcp_f32_e32 v67, v67
	v_mad_i64_i32 v[64:65], s[22:23], v64, s46, v[132:133]
	v_pk_mul_f32 v[60:61], v[60:61], v[66:67]
	s_nop 0
	v_pk_mul_f32 v[56:57], v[56:57], v[60:61]
	s_nop 0
	v_cvt_pk_bf16_f32 v56, v56, v57
	v_mul_f32_e32 v57, 0xbfb8aa3b, v62
	v_exp_f32_e32 v57, v57
	s_nop 0
	v_add_f32_e32 v57, 1.0, v57
	v_rcp_f32_e32 v60, v57
	v_mul_f32_e32 v57, 0xbfb8aa3b, v63
	v_exp_f32_e32 v57, v57
	s_nop 0
	v_add_f32_e32 v57, 1.0, v57
	v_rcp_f32_e32 v61, v57
	s_nop 0
	v_pk_mul_f32 v[60:61], v[62:63], v[60:61]
	s_nop 0
	v_pk_mul_f32 v[58:59], v[58:59], v[60:61]
	s_nop 0
	v_cvt_pk_bf16_f32 v57, v58, v59
	v_lshl_add_u64 v[58:59], v[64:65], 0, s[20:21]
	global_store_dwordx2 v[58:59], v[56:57], off
	v_mul_f32_e32 v56, 0xbfb8aa3b, v52
	v_mul_f32_e32 v57, 0xbfb8aa3b, v53
	v_exp_f32_e32 v56, v56
	v_exp_f32_e32 v57, v57
	v_add_f32_e32 v56, 1.0, v56
	v_add_f32_e32 v57, 1.0, v57
	v_rcp_f32_e32 v56, v56
	v_rcp_f32_e32 v57, v57
	s_nop 0
	v_pk_mul_f32 v[52:53], v[52:53], v[56:57]
	s_nop 0
	v_pk_mul_f32 v[48:49], v[48:49], v[52:53]
	s_nop 0
	v_cvt_pk_bf16_f32 v48, v48, v49
	v_mul_f32_e32 v49, 0xbfb8aa3b, v54
	v_exp_f32_e32 v49, v49
	s_nop 0
	v_add_f32_e32 v49, 1.0, v49
	v_rcp_f32_e32 v52, v49
	v_mul_f32_e32 v49, 0xbfb8aa3b, v55
	v_exp_f32_e32 v49, v49
	s_nop 0
	v_add_f32_e32 v49, 1.0, v49
	v_rcp_f32_e32 v53, v49
	s_nop 0
	v_pk_mul_f32 v[52:53], v[54:55], v[52:53]
	s_nop 0
	v_pk_mul_f32 v[50:51], v[50:51], v[52:53]
	s_nop 0
	v_cvt_pk_bf16_f32 v49, v50, v51
	v_mul_f32_e32 v50, 0xbfb8aa3b, v44
	v_mul_f32_e32 v51, 0xbfb8aa3b, v45
	v_exp_f32_e32 v50, v50
	v_exp_f32_e32 v51, v51
	global_store_dwordx2 v[58:59], v[48:49], off offset:128
	v_add_u32_e32 v48, 0x90, v147
	v_add_f32_e32 v50, 1.0, v50
	v_add_f32_e32 v51, 1.0, v51
	v_rcp_f32_e32 v50, v50
	v_rcp_f32_e32 v51, v51
	v_mad_i64_i32 v[48:49], s[22:23], v48, s46, v[132:133]
	v_pk_mul_f32 v[44:45], v[44:45], v[50:51]
	s_nop 0
	v_pk_mul_f32 v[40:41], v[40:41], v[44:45]
	s_nop 0
	v_cvt_pk_bf16_f32 v40, v40, v41
	v_mul_f32_e32 v41, 0xbfb8aa3b, v46
	v_exp_f32_e32 v41, v41
	s_nop 0
	v_add_f32_e32 v41, 1.0, v41
	v_rcp_f32_e32 v44, v41
	v_mul_f32_e32 v41, 0xbfb8aa3b, v47
	v_exp_f32_e32 v41, v41
	s_nop 0
	v_add_f32_e32 v41, 1.0, v41
	v_rcp_f32_e32 v45, v41
	s_nop 0
	v_pk_mul_f32 v[44:45], v[46:47], v[44:45]
	s_nop 0
	v_pk_mul_f32 v[42:43], v[42:43], v[44:45]
	s_nop 0
	v_cvt_pk_bf16_f32 v41, v42, v43
	v_lshl_add_u64 v[42:43], v[48:49], 0, s[20:21]
	global_store_dwordx2 v[42:43], v[40:41], off
	v_mul_f32_e32 v40, 0xbfb8aa3b, v36
	v_mul_f32_e32 v41, 0xbfb8aa3b, v37
	v_exp_f32_e32 v40, v40
	v_exp_f32_e32 v41, v41
	v_add_f32_e32 v40, 1.0, v40
	v_add_f32_e32 v41, 1.0, v41
	v_rcp_f32_e32 v40, v40
	v_rcp_f32_e32 v41, v41
	s_nop 0
	v_pk_mul_f32 v[36:37], v[36:37], v[40:41]
	s_nop 0
	v_pk_mul_f32 v[32:33], v[32:33], v[36:37]
	s_nop 0
	v_cvt_pk_bf16_f32 v32, v32, v33
	v_mul_f32_e32 v33, 0xbfb8aa3b, v38
	v_exp_f32_e32 v33, v33
	s_nop 0
	v_add_f32_e32 v33, 1.0, v33
	v_rcp_f32_e32 v36, v33
	v_mul_f32_e32 v33, 0xbfb8aa3b, v39
	v_exp_f32_e32 v33, v33
	s_nop 0
	v_add_f32_e32 v33, 1.0, v33
	v_rcp_f32_e32 v37, v33
	s_nop 0
	v_pk_mul_f32 v[36:37], v[38:39], v[36:37]
	s_nop 0
	v_pk_mul_f32 v[34:35], v[34:35], v[36:37]
	s_nop 0
	v_cvt_pk_bf16_f32 v33, v34, v35
	v_mul_f32_e32 v34, 0xbfb8aa3b, v28
	v_mul_f32_e32 v35, 0xbfb8aa3b, v29
	v_exp_f32_e32 v34, v34
	v_exp_f32_e32 v35, v35
	global_store_dwordx2 v[42:43], v[32:33], off offset:128
	v_add_u32_e32 v32, 0xa0, v147
	v_add_f32_e32 v34, 1.0, v34
	v_add_f32_e32 v35, 1.0, v35
	v_rcp_f32_e32 v34, v34
	v_rcp_f32_e32 v35, v35
	v_mad_i64_i32 v[32:33], s[22:23], v32, s46, v[132:133]
	v_pk_mul_f32 v[28:29], v[28:29], v[34:35]
	s_nop 0
	v_pk_mul_f32 v[24:25], v[24:25], v[28:29]
	s_nop 0
	v_cvt_pk_bf16_f32 v24, v24, v25
	v_mul_f32_e32 v25, 0xbfb8aa3b, v30
	v_exp_f32_e32 v25, v25
	s_nop 0
	v_add_f32_e32 v25, 1.0, v25
	v_rcp_f32_e32 v28, v25
	v_mul_f32_e32 v25, 0xbfb8aa3b, v31
	v_exp_f32_e32 v25, v25
	s_nop 0
	v_add_f32_e32 v25, 1.0, v25
	v_rcp_f32_e32 v29, v25
	s_nop 0
	v_pk_mul_f32 v[28:29], v[30:31], v[28:29]
	s_nop 0
	v_pk_mul_f32 v[26:27], v[26:27], v[28:29]
	s_nop 0
	v_cvt_pk_bf16_f32 v25, v26, v27
	v_lshl_add_u64 v[26:27], v[32:33], 0, s[20:21]
	global_store_dwordx2 v[26:27], v[24:25], off
	v_mul_f32_e32 v24, 0xbfb8aa3b, v20
	v_mul_f32_e32 v25, 0xbfb8aa3b, v21
	v_exp_f32_e32 v24, v24
	v_exp_f32_e32 v25, v25
	v_add_f32_e32 v24, 1.0, v24
	v_add_f32_e32 v25, 1.0, v25
	v_rcp_f32_e32 v24, v24
	v_rcp_f32_e32 v25, v25
	s_nop 0
	v_pk_mul_f32 v[20:21], v[20:21], v[24:25]
	s_nop 0
	v_pk_mul_f32 v[16:17], v[16:17], v[20:21]
	s_nop 0
	v_cvt_pk_bf16_f32 v16, v16, v17
	v_mul_f32_e32 v17, 0xbfb8aa3b, v22
	v_exp_f32_e32 v17, v17
	s_nop 0
	v_add_f32_e32 v17, 1.0, v17
	v_rcp_f32_e32 v20, v17
	v_mul_f32_e32 v17, 0xbfb8aa3b, v23
	v_exp_f32_e32 v17, v17
	s_nop 0
	v_add_f32_e32 v17, 1.0, v17
	v_rcp_f32_e32 v21, v17
	s_nop 0
	v_pk_mul_f32 v[20:21], v[22:23], v[20:21]
	s_nop 0
	v_pk_mul_f32 v[18:19], v[18:19], v[20:21]
	s_nop 0
	v_cvt_pk_bf16_f32 v17, v18, v19
	v_mul_f32_e32 v18, 0xbfb8aa3b, v12
	v_mul_f32_e32 v19, 0xbfb8aa3b, v13
	v_exp_f32_e32 v18, v18
	v_exp_f32_e32 v19, v19
	global_store_dwordx2 v[26:27], v[16:17], off offset:128
	v_add_u32_e32 v16, 0xb0, v147
	v_add_f32_e32 v18, 1.0, v18
	v_add_f32_e32 v19, 1.0, v19
	v_rcp_f32_e32 v18, v18
	v_rcp_f32_e32 v19, v19
	v_mad_i64_i32 v[16:17], s[22:23], v16, s46, v[132:133]
	s_mov_b64 s[22:23], s[16:17]
	v_pk_mul_f32 v[12:13], v[12:13], v[18:19]
	s_nop 0
	v_pk_mul_f32 v[8:9], v[8:9], v[12:13]
	s_nop 0
	v_cvt_pk_bf16_f32 v8, v8, v9
	v_mul_f32_e32 v9, 0xbfb8aa3b, v14
	v_exp_f32_e32 v9, v9
	s_nop 0
	v_add_f32_e32 v9, 1.0, v9
	v_rcp_f32_e32 v12, v9
	v_mul_f32_e32 v9, 0xbfb8aa3b, v15
	v_exp_f32_e32 v9, v9
	s_nop 0
	v_add_f32_e32 v9, 1.0, v9
	v_rcp_f32_e32 v13, v9
	s_nop 0
	v_pk_mul_f32 v[12:13], v[14:15], v[12:13]
	s_nop 0
	v_pk_mul_f32 v[10:11], v[10:11], v[12:13]
	s_nop 0
	v_cvt_pk_bf16_f32 v9, v10, v11
	v_lshl_add_u64 v[10:11], v[16:17], 0, s[20:21]
	global_store_dwordx2 v[10:11], v[8:9], off
	v_mul_f32_e32 v8, 0xbfb8aa3b, v4
	v_mul_f32_e32 v9, 0xbfb8aa3b, v5
	v_exp_f32_e32 v8, v8
	v_exp_f32_e32 v9, v9
	s_mov_b32 s21, s12
	s_mov_b32 s20, s14
	v_add_f32_e32 v8, 1.0, v8
	v_add_f32_e32 v9, 1.0, v9
	v_rcp_f32_e32 v8, v8
	v_rcp_f32_e32 v9, v9
	s_nop 0
	v_pk_mul_f32 v[4:5], v[4:5], v[8:9]
	s_nop 0
	v_pk_mul_f32 v[0:1], v[0:1], v[4:5]
	s_nop 0
	v_cvt_pk_bf16_f32 v0, v0, v1
	v_mul_f32_e32 v1, 0xbfb8aa3b, v6
	v_exp_f32_e32 v1, v1
	s_nop 0
	v_add_f32_e32 v1, 1.0, v1
	v_rcp_f32_e32 v4, v1
	v_mul_f32_e32 v1, 0xbfb8aa3b, v7
	v_exp_f32_e32 v1, v1
	s_nop 0
	v_add_f32_e32 v1, 1.0, v1
	v_rcp_f32_e32 v5, v1
	s_nop 0
	v_pk_mul_f32 v[4:5], v[6:7], v[4:5]
	s_nop 0
	v_pk_mul_f32 v[2:3], v[2:3], v[4:5]
	s_nop 0
	v_cvt_pk_bf16_f32 v1, v2, v3
	global_store_dwordx2 v[10:11], v[0:1], off offset:128
	s_cbranch_vccz .LBB0_2809
	s_waitcnt vmcnt(0)
	s_cmpk_gt_u32 s1, 0xff
	s_cbranch_scc1 .LBB0_2816
	s_barrier

.LBB0_2911:
	ds_read_b128 v[128:131], v151
	ds_read_b128 v[144:147], v151 offset:1024
	ds_read_b128 v[154:157], v151 offset:2048
	ds_read_b128 v[158:161], v151 offset:3072
	s_add_u32 s18, s16, 0x100
	s_addc_u32 s19, s17, 0
	s_cmpk_eq_i32 s46, 0x54
	s_cselect_b32 s23, s11, s19
	s_cselect_b32 s22, s10, s18
	s_cselect_b32 s21, s13, s43
	s_cselect_b32 s20, s12, s42
	v_lshl_add_u64 v[194:195], s[16:17], 0, v[136:137]
	s_add_i32 m0, s4, 0xc000
	ds_read_b128 v[162:165], v152
	ds_read_b128 v[166:169], v152 offset:1024
	ds_read_b128 v[170:173], v152 offset:2048
	ds_read_b128 v[174:177], v152 offset:3072
	ds_read_b128 v[178:181], v152 offset:4096
	ds_read_b128 v[182:185], v152 offset:5120
	ds_read_b128 v[186:189], v152 offset:6144
	ds_read_b128 v[190:193], v152 offset:7168
	global_load_lds_dwordx4 v[194:195], off
	v_lshl_add_u64 v[194:195], s[16:17], 0, v[138:139]
	s_add_i32 m0, s4, 0xe000
	s_nop 0
	global_load_lds_dwordx4 v[194:195], off
	s_waitcnt lgkmcnt(8)
	s_barrier
	s_waitcnt lgkmcnt(0)
	s_waitcnt lgkmcnt(0)
	v_mfma_f32_16x16x32_bf16 v[124:127], v[128:131], v[162:165], v[124:127]
	v_mfma_f32_16x16x32_bf16 v[92:95], v[154:157], v[162:165], v[92:95]
	v_mfma_f32_16x16x32_bf16 v[120:123], v[128:131], v[170:173], v[120:123]
	v_mfma_f32_16x16x32_bf16 v[88:91], v[154:157], v[170:173], v[88:91]
	v_mfma_f32_16x16x32_bf16 v[116:119], v[128:131], v[178:181], v[116:119]
	v_mfma_f32_16x16x32_bf16 v[84:87], v[154:157], v[178:181], v[84:87]
	v_mfma_f32_16x16x32_bf16 v[112:115], v[128:131], v[186:189], v[112:115]
	v_mfma_f32_16x16x32_bf16 v[80:83], v[154:157], v[186:189], v[80:83]
	v_mfma_f32_16x16x32_bf16 v[124:127], v[144:147], v[166:169], v[124:127]
	v_mfma_f32_16x16x32_bf16 v[92:95], v[158:161], v[166:169], v[92:95]
	v_mfma_f32_16x16x32_bf16 v[120:123], v[144:147], v[174:177], v[120:123]
	v_mfma_f32_16x16x32_bf16 v[88:91], v[158:161], v[174:177], v[88:91]
	v_mfma_f32_16x16x32_bf16 v[116:119], v[144:147], v[182:185], v[116:119]
	v_mfma_f32_16x16x32_bf16 v[84:87], v[158:161], v[182:185], v[84:87]
	v_mfma_f32_16x16x32_bf16 v[112:115], v[144:147], v[190:193], v[112:115]
	v_mfma_f32_16x16x32_bf16 v[80:83], v[158:161], v[190:193], v[80:83]
	s_barrier
	s_add_i32 s16, s36, s3
	v_lshl_add_u64 v[210:211], s[20:21], 0, v[132:133]
	s_mov_b32 m0, s16
	ds_read_b128 v[194:197], v153
	ds_read_b128 v[198:201], v153 offset:1024
	ds_read_b128 v[202:205], v153 offset:2048
	ds_read_b128 v[206:209], v153 offset:3072
	global_load_lds_dwordx4 v[210:211], off
	v_lshl_add_u64 v[212:213], s[20:21], 0, v[134:135]
	s_add_i32 m0, s16, 0x2000
	s_nop 0
	global_load_lds_dwordx4 v[212:213], off
	s_barrier
	s_waitcnt lgkmcnt(0)
	s_waitcnt lgkmcnt(0)
	v_mfma_f32_16x16x32_bf16 v[76:79], v[194:197], v[162:165], v[76:79]
	v_mfma_f32_16x16x32_bf16 v[48:51], v[202:205], v[162:165], v[48:51]
	v_mfma_f32_16x16x32_bf16 v[68:71], v[194:197], v[170:173], v[68:71]
	v_mfma_f32_16x16x32_bf16 v[40:43], v[202:205], v[170:173], v[40:43]
	v_mfma_f32_16x16x32_bf16 v[60:63], v[194:197], v[178:181], v[60:63]
	v_mfma_f32_16x16x32_bf16 v[36:39], v[202:205], v[178:181], v[36:39]
	v_mfma_f32_16x16x32_bf16 v[52:55], v[194:197], v[186:189], v[52:55]
	v_mfma_f32_16x16x32_bf16 v[28:31], v[202:205], v[186:189], v[28:31]
	v_mfma_f32_16x16x32_bf16 v[76:79], v[198:201], v[166:169], v[76:79]
	v_mfma_f32_16x16x32_bf16 v[48:51], v[206:209], v[166:169], v[48:51]
	v_mfma_f32_16x16x32_bf16 v[68:71], v[198:201], v[174:177], v[68:71]
	v_mfma_f32_16x16x32_bf16 v[40:43], v[206:209], v[174:177], v[40:43]
	v_mfma_f32_16x16x32_bf16 v[60:63], v[198:201], v[182:185], v[60:63]
	v_mfma_f32_16x16x32_bf16 v[36:39], v[206:209], v[182:185], v[36:39]
	v_mfma_f32_16x16x32_bf16 v[52:55], v[198:201], v[190:193], v[52:55]
	v_mfma_f32_16x16x32_bf16 v[28:31], v[206:209], v[190:193], v[28:31]
	s_mov_b32 m0, s4
	v_lshl_add_u64 v[214:215], s[22:23], 0, v[132:133]
	s_barrier
	ds_read_b128 v[162:165], v152 offset:16384
	ds_read_b128 v[166:169], v152 offset:17408
	ds_read_b128 v[170:173], v152 offset:18432
	ds_read_b128 v[174:177], v152 offset:19456
	ds_read_b128 v[178:181], v152 offset:20480
	ds_read_b128 v[182:185], v152 offset:21504
	ds_read_b128 v[186:189], v152 offset:22528
	ds_read_b128 v[190:193], v152 offset:23552
	global_load_lds_dwordx4 v[214:215], off
	v_lshl_add_u64 v[216:217], s[22:23], 0, v[134:135]
	s_mov_b32 m0, s5
	s_nop 0
	global_load_lds_dwordx4 v[216:217], off
	s_barrier
	s_waitcnt lgkmcnt(0)
	s_waitcnt lgkmcnt(0)
	v_mfma_f32_16x16x32_bf16 v[108:111], v[128:131], v[162:165], v[108:111]
	v_mfma_f32_16x16x32_bf16 v[72:75], v[154:157], v[162:165], v[72:75]
	v_mfma_f32_16x16x32_bf16 v[104:107], v[128:131], v[170:173], v[104:107]
	v_mfma_f32_16x16x32_bf16 v[64:67], v[154:157], v[170:173], v[64:67]
	v_mfma_f32_16x16x32_bf16 v[100:103], v[128:131], v[178:181], v[100:103]
	v_mfma_f32_16x16x32_bf16 v[56:59], v[154:157], v[178:181], v[56:59]
	v_mfma_f32_16x16x32_bf16 v[96:99], v[128:131], v[186:189], v[96:99]
	v_mfma_f32_16x16x32_bf16 v[44:47], v[154:157], v[186:189], v[44:47]
	v_mfma_f32_16x16x32_bf16 v[108:111], v[144:147], v[166:169], v[108:111]
	v_mfma_f32_16x16x32_bf16 v[72:75], v[158:161], v[166:169], v[72:75]
	v_mfma_f32_16x16x32_bf16 v[104:107], v[144:147], v[174:177], v[104:107]
	v_mfma_f32_16x16x32_bf16 v[64:67], v[158:161], v[174:177], v[64:67]
	v_mfma_f32_16x16x32_bf16 v[100:103], v[144:147], v[182:185], v[100:103]
	v_mfma_f32_16x16x32_bf16 v[56:59], v[158:161], v[182:185], v[56:59]
	v_mfma_f32_16x16x32_bf16 v[96:99], v[144:147], v[190:193], v[96:99]
	v_mfma_f32_16x16x32_bf16 v[44:47], v[158:161], v[190:193], v[44:47]
	s_barrier
	s_add_u32 s16, s20, 0x160000
	s_addc_u32 s17, s21, 0
	s_add_i32 s47, s37, s3
	v_lshl_add_u64 v[128:129], s[16:17], 0, v[132:133]
	s_mov_b32 m0, s47
	s_nop 0
	global_load_lds_dwordx4 v[128:129], off
	v_lshl_add_u64 v[128:129], s[16:17], 0, v[134:135]
	s_add_i32 m0, s47, 0x2000
	s_nop 0
	global_load_lds_dwordx4 v[128:129], off
	s_waitcnt vmcnt(6)
	s_barrier
	v_mfma_f32_16x16x32_bf16 v[32:35], v[194:197], v[162:165], v[32:35]
	v_mfma_f32_16x16x32_bf16 v[12:15], v[202:205], v[162:165], v[12:15]
	v_mfma_f32_16x16x32_bf16 v[24:27], v[194:197], v[170:173], v[24:27]
	v_mfma_f32_16x16x32_bf16 v[8:11], v[202:205], v[170:173], v[8:11]
	v_mfma_f32_16x16x32_bf16 v[20:23], v[194:197], v[178:181], v[20:23]
	v_mfma_f32_16x16x32_bf16 v[4:7], v[202:205], v[178:181], v[4:7]
	v_mfma_f32_16x16x32_bf16 v[16:19], v[194:197], v[186:189], v[16:19]
	v_mfma_f32_16x16x32_bf16 v[0:3], v[202:205], v[186:189], v[0:3]
	v_mfma_f32_16x16x32_bf16 v[32:35], v[198:201], v[166:169], v[32:35]
	v_mfma_f32_16x16x32_bf16 v[12:15], v[206:209], v[166:169], v[12:15]
	v_mfma_f32_16x16x32_bf16 v[24:27], v[198:201], v[174:177], v[24:27]
	v_mfma_f32_16x16x32_bf16 v[8:11], v[206:209], v[174:177], v[8:11]
	v_mfma_f32_16x16x32_bf16 v[20:23], v[198:201], v[182:185], v[20:23]
	v_mfma_f32_16x16x32_bf16 v[4:7], v[206:209], v[182:185], v[4:7]
	v_mfma_f32_16x16x32_bf16 v[16:19], v[198:201], v[190:193], v[16:19]
	v_mfma_f32_16x16x32_bf16 v[0:3], v[206:209], v[190:193], v[0:3]
	s_add_i32 s47, 0, 0x18000
	v_add_u32_e32 v158, s47, v149
	s_barrier
	ds_read_b128 v[128:131], v158
	ds_read_b128 v[144:147], v158 offset:1024
	ds_read_b128 v[154:157], v158 offset:2048
	ds_read_b128 v[158:161], v158 offset:3072
	s_add_u32 s16, s22, 0x160000
	s_addc_u32 s17, s23, 0
	s_mov_b32 m0, s26
	v_lshl_add_u64 v[194:195], s[16:17], 0, v[132:133]
	ds_read_b128 v[162:165], v152 offset:32768
	ds_read_b128 v[166:169], v152 offset:33792
	ds_read_b128 v[170:173], v152 offset:34816
	ds_read_b128 v[174:177], v152 offset:35840
	ds_read_b128 v[178:181], v152 offset:36864
	ds_read_b128 v[182:185], v152 offset:37888
	ds_read_b128 v[186:189], v152 offset:38912
	ds_read_b128 v[190:193], v152 offset:39936
	global_load_lds_dwordx4 v[194:195], off
	v_lshl_add_u64 v[194:195], s[16:17], 0, v[134:135]
	s_mov_b32 m0, s27
	s_nop 0
	global_load_lds_dwordx4 v[194:195], off
	s_waitcnt lgkmcnt(8)
	s_barrier
	s_waitcnt lgkmcnt(0)
	s_waitcnt lgkmcnt(0)
	v_mfma_f32_16x16x32_bf16 v[124:127], v[128:131], v[162:165], v[124:127]
	v_mfma_f32_16x16x32_bf16 v[92:95], v[154:157], v[162:165], v[92:95]
	v_mfma_f32_16x16x32_bf16 v[120:123], v[128:131], v[170:173], v[120:123]
	v_mfma_f32_16x16x32_bf16 v[88:91], v[154:157], v[170:173], v[88:91]
	v_mfma_f32_16x16x32_bf16 v[116:119], v[128:131], v[178:181], v[116:119]
	v_mfma_f32_16x16x32_bf16 v[84:87], v[154:157], v[178:181], v[84:87]
	v_mfma_f32_16x16x32_bf16 v[112:115], v[128:131], v[186:189], v[112:115]
	v_mfma_f32_16x16x32_bf16 v[80:83], v[154:157], v[186:189], v[80:83]
	v_mfma_f32_16x16x32_bf16 v[124:127], v[144:147], v[166:169], v[124:127]
	v_mfma_f32_16x16x32_bf16 v[92:95], v[158:161], v[166:169], v[92:95]
	v_mfma_f32_16x16x32_bf16 v[120:123], v[144:147], v[174:177], v[120:123]
	v_mfma_f32_16x16x32_bf16 v[88:91], v[158:161], v[174:177], v[88:91]
	v_mfma_f32_16x16x32_bf16 v[116:119], v[144:147], v[182:185], v[116:119]
	v_mfma_f32_16x16x32_bf16 v[84:87], v[158:161], v[182:185], v[84:87]
	v_mfma_f32_16x16x32_bf16 v[112:115], v[144:147], v[190:193], v[112:115]
	v_mfma_f32_16x16x32_bf16 v[80:83], v[158:161], v[190:193], v[80:83]
	s_barrier
	s_add_i32 s22, 0, 0x1c000
	s_add_i32 s16, s47, s3
	v_add_u32_e32 v206, s22, v149
	v_lshl_add_u64 v[210:211], v[210:211], 0, s[14:15]
	s_mov_b32 m0, s16
	ds_read_b128 v[194:197], v206
	ds_read_b128 v[198:201], v206 offset:1024
	ds_read_b128 v[202:205], v206 offset:2048
	ds_read_b128 v[206:209], v206 offset:3072
	global_load_lds_dwordx4 v[210:211], off
	v_lshl_add_u64 v[210:211], v[212:213], 0, s[14:15]
	s_add_i32 m0, s16, 0x2000
	s_nop 0
	global_load_lds_dwordx4 v[210:211], off
	s_barrier
	s_waitcnt lgkmcnt(0)
	s_waitcnt lgkmcnt(0)
	v_mfma_f32_16x16x32_bf16 v[76:79], v[194:197], v[162:165], v[76:79]
	v_mfma_f32_16x16x32_bf16 v[48:51], v[202:205], v[162:165], v[48:51]
	v_mfma_f32_16x16x32_bf16 v[68:71], v[194:197], v[170:173], v[68:71]
	v_mfma_f32_16x16x32_bf16 v[40:43], v[202:205], v[170:173], v[40:43]
	v_mfma_f32_16x16x32_bf16 v[60:63], v[194:197], v[178:181], v[60:63]
	v_mfma_f32_16x16x32_bf16 v[36:39], v[202:205], v[178:181], v[36:39]
	v_mfma_f32_16x16x32_bf16 v[52:55], v[194:197], v[186:189], v[52:55]
	v_mfma_f32_16x16x32_bf16 v[28:31], v[202:205], v[186:189], v[28:31]
	v_mfma_f32_16x16x32_bf16 v[76:79], v[198:201], v[166:169], v[76:79]
	v_mfma_f32_16x16x32_bf16 v[48:51], v[206:209], v[166:169], v[48:51]
	v_mfma_f32_16x16x32_bf16 v[68:71], v[198:201], v[174:177], v[68:71]
	v_mfma_f32_16x16x32_bf16 v[40:43], v[206:209], v[174:177], v[40:43]
	v_mfma_f32_16x16x32_bf16 v[60:63], v[198:201], v[182:185], v[60:63]
	v_mfma_f32_16x16x32_bf16 v[36:39], v[206:209], v[182:185], v[36:39]
	v_mfma_f32_16x16x32_bf16 v[52:55], v[198:201], v[190:193], v[52:55]
	v_mfma_f32_16x16x32_bf16 v[28:31], v[206:209], v[190:193], v[28:31]
	s_mov_b32 m0, s29
	v_lshl_add_u64 v[210:211], v[214:215], 0, s[14:15]
	s_barrier
	ds_read_b128 v[162:165], v152 offset:49152
	ds_read_b128 v[166:169], v152 offset:50176
	ds_read_b128 v[170:173], v152 offset:51200
	ds_read_b128 v[174:177], v152 offset:52224
	ds_read_b128 v[178:181], v152 offset:53248
	ds_read_b128 v[182:185], v152 offset:54272
	ds_read_b128 v[186:189], v152 offset:55296
	ds_read_b128 v[190:193], v152 offset:56320
	global_load_lds_dwordx4 v[210:211], off
	v_lshl_add_u64 v[210:211], v[216:217], 0, s[14:15]
	s_mov_b32 m0, s30
	s_nop 0
	global_load_lds_dwordx4 v[210:211], off
	s_barrier
	s_waitcnt lgkmcnt(0)
	s_waitcnt lgkmcnt(0)
	v_mfma_f32_16x16x32_bf16 v[108:111], v[128:131], v[162:165], v[108:111]
	v_mfma_f32_16x16x32_bf16 v[72:75], v[154:157], v[162:165], v[72:75]
	v_mfma_f32_16x16x32_bf16 v[104:107], v[128:131], v[170:173], v[104:107]
	v_mfma_f32_16x16x32_bf16 v[64:67], v[154:157], v[170:173], v[64:67]
	v_mfma_f32_16x16x32_bf16 v[100:103], v[128:131], v[178:181], v[100:103]
	v_mfma_f32_16x16x32_bf16 v[56:59], v[154:157], v[178:181], v[56:59]
	v_mfma_f32_16x16x32_bf16 v[96:99], v[128:131], v[186:189], v[96:99]
	v_mfma_f32_16x16x32_bf16 v[44:47], v[154:157], v[186:189], v[44:47]
	v_mfma_f32_16x16x32_bf16 v[108:111], v[144:147], v[166:169], v[108:111]
	v_mfma_f32_16x16x32_bf16 v[72:75], v[158:161], v[166:169], v[72:75]
	v_mfma_f32_16x16x32_bf16 v[104:107], v[144:147], v[174:177], v[104:107]
	v_mfma_f32_16x16x32_bf16 v[64:67], v[158:161], v[174:177], v[64:67]
	v_mfma_f32_16x16x32_bf16 v[100:103], v[144:147], v[182:185], v[100:103]
	v_mfma_f32_16x16x32_bf16 v[56:59], v[158:161], v[182:185], v[56:59]
	v_mfma_f32_16x16x32_bf16 v[96:99], v[144:147], v[190:193], v[96:99]
	v_mfma_f32_16x16x32_bf16 v[44:47], v[158:161], v[190:193], v[44:47]
	s_barrier
	s_add_u32 s16, s20, 0x160080
	s_addc_u32 s17, s21, 0
	s_add_i32 s20, s22, s3
	v_lshl_add_u64 v[128:129], s[16:17], 0, v[132:133]
	s_mov_b32 m0, s20
	s_nop 0
	global_load_lds_dwordx4 v[128:129], off
	v_lshl_add_u64 v[128:129], s[16:17], 0, v[134:135]
	s_add_i32 m0, s20, 0x2000
	s_nop 0
	global_load_lds_dwordx4 v[128:129], off
	s_waitcnt vmcnt(6)
	s_barrier
	v_mfma_f32_16x16x32_bf16 v[32:35], v[194:197], v[162:165], v[32:35]
	v_mfma_f32_16x16x32_bf16 v[12:15], v[202:205], v[162:165], v[12:15]
	v_mfma_f32_16x16x32_bf16 v[24:27], v[194:197], v[170:173], v[24:27]
	v_mfma_f32_16x16x32_bf16 v[8:11], v[202:205], v[170:173], v[8:11]
	v_mfma_f32_16x16x32_bf16 v[20:23], v[194:197], v[178:181], v[20:23]
	v_mfma_f32_16x16x32_bf16 v[4:7], v[202:205], v[178:181], v[4:7]
	v_mfma_f32_16x16x32_bf16 v[16:19], v[194:197], v[186:189], v[16:19]
	v_mfma_f32_16x16x32_bf16 v[0:3], v[202:205], v[186:189], v[0:3]
	v_mfma_f32_16x16x32_bf16 v[32:35], v[198:201], v[166:169], v[32:35]
	v_mfma_f32_16x16x32_bf16 v[12:15], v[206:209], v[166:169], v[12:15]
	v_mfma_f32_16x16x32_bf16 v[24:27], v[198:201], v[174:177], v[24:27]
	v_mfma_f32_16x16x32_bf16 v[8:11], v[206:209], v[174:177], v[8:11]
	v_mfma_f32_16x16x32_bf16 v[20:23], v[198:201], v[182:185], v[20:23]
	v_mfma_f32_16x16x32_bf16 v[4:7], v[206:209], v[182:185], v[4:7]
	v_mfma_f32_16x16x32_bf16 v[16:19], v[198:201], v[190:193], v[16:19]
	v_mfma_f32_16x16x32_bf16 v[0:3], v[206:209], v[190:193], v[0:3]
	s_add_i32 s46, s46, 2
	s_add_u32 s42, s42, 0x100
	s_addc_u32 s43, s43, 0
	s_cmpk_gt_u32 s46, 0x55
	s_mov_b64 s[16:17], s[18:19]
	s_barrier
	s_cbranch_scc0 .LBB0_2911
	s_cmp_lt_u32 s40, 32
	s_movk_i32 s16, 0x3000
	s_cselect_b32 s16, s16, 0x6000
	s_cmp_gt_i32 s40, 15
	v_lshl_add_u32 v158, s40, 8, v148
	s_cselect_b32 s16, s16, 0
	v_lshl_or_b32 v128, s41, 8, v150
	s_lshl_b32 s16, s16, 2
	v_ashrrev_i32_e32 v159, 31, v158
	s_add_u32 s16, s34, s16
	v_ashrrev_i32_e32 v129, 31, v128
	v_lshlrev_b64 v[146:147], 13, v[158:159]
	s_addc_u32 s17, s35, 0
	v_lshlrev_b64 v[160:161], 2, v[128:129]
	v_lshl_add_u64 v[146:147], s[48:49], 0, v[146:147]
	v_lshl_add_u64 v[144:145], s[16:17], 0, v[160:161]
	v_lshl_add_u64 v[146:147], v[146:147], 0, v[160:161]
	s_mov_b64 s[16:17], 0x100000
	s_mov_b32 s41, s38
	s_mov_b32 s40, s39
	s_mov_b64 s[18:19], s[12:13]
	v_or_b32_e32 v162, 16, v158
	v_ashrrev_i32_e32 v163, 31, v162
	v_lshlrev_b64 v[164:165], 13, v[162:163]
	v_lshl_add_u64 v[162:163], s[48:49], 0, v[164:165]
	v_lshl_add_u64 v[164:165], v[162:163], 0, v[160:161]
	v_or_b32_e32 v162, 32, v158
	v_ashrrev_i32_e32 v163, 31, v162
	v_lshlrev_b64 v[166:167], 13, v[162:163]
	v_lshl_add_u64 v[162:163], s[48:49], 0, v[166:167]
	v_lshl_add_u64 v[166:167], v[162:163], 0, v[160:161]
	v_or_b32_e32 v162, 48, v158
	v_ashrrev_i32_e32 v163, 31, v162
	v_lshlrev_b64 v[168:169], 13, v[162:163]
	v_lshl_add_u64 v[162:163], s[48:49], 0, v[168:169]
	v_lshl_add_u64 v[168:169], v[162:163], 0, v[160:161]
	v_lshl_add_u64 v[162:163], v[146:147], 0, s[16:17]
	s_mov_b32 s16, 0x100000
	v_add_co_u32_e32 v170, vcc, s16, v146
	s_mov_b64 s[16:17], 0x120000
	s_nop 0
	v_addc_co_u32_e32 v171, vcc, 0, v147, vcc
	v_lshl_add_u64 v[172:173], v[146:147], 0, s[16:17]
	s_mov_b32 s16, 0x120000
	v_add_co_u32_e32 v174, vcc, s16, v146
	s_mov_b64 s[16:17], 0x140000
	s_nop 0
	v_addc_co_u32_e32 v175, vcc, 0, v147, vcc
	v_lshl_add_u64 v[176:177], v[146:147], 0, s[16:17]
	s_mov_b32 s16, 0x140000
	v_add_co_u32_e32 v178, vcc, s16, v146
	s_mov_b64 s[16:17], 0x160000
	s_nop 0
	v_addc_co_u32_e32 v179, vcc, 0, v147, vcc
	v_lshl_add_u64 v[180:181], v[146:147], 0, s[16:17]
	s_mov_b32 s16, 0x160000
	v_add_co_u32_e32 v182, vcc, s16, v146
	s_mov_b64 s[16:17], s[10:11]
	s_nop 0
	v_addc_co_u32_e32 v183, vcc, 0, v147, vcc
	s_and_b64 vcc, exec, s[8:9]
	global_load_dwordx4 v[184:187], v[144:145], off
	global_load_dwordx4 v[188:191], v[146:147], off
	v_pk_add_f32 v[126:127], v[126:127], 0 op_sel_hi:[1,0]
	v_pk_add_f32 v[124:125], v[124:125], 0 op_sel_hi:[1,0]
	v_pk_add_f32 v[122:123], v[122:123], 0 op_sel_hi:[1,0]
	v_pk_add_f32 v[120:121], v[120:121], 0 op_sel_hi:[1,0]
	v_pk_add_f32 v[118:119], v[118:119], 0 op_sel_hi:[1,0]
	v_pk_add_f32 v[116:117], v[116:117], 0 op_sel_hi:[1,0]
	v_pk_add_f32 v[114:115], v[114:115], 0 op_sel_hi:[1,0]
	v_pk_add_f32 v[112:113], v[112:113], 0 op_sel_hi:[1,0]
	v_pk_add_f32 v[110:111], v[110:111], 0 op_sel_hi:[1,0]
	v_pk_add_f32 v[108:109], v[108:109], 0 op_sel_hi:[1,0]
	v_pk_add_f32 v[106:107], v[106:107], 0 op_sel_hi:[1,0]
	v_pk_add_f32 v[104:105], v[104:105], 0 op_sel_hi:[1,0]
	v_pk_add_f32 v[102:103], v[102:103], 0 op_sel_hi:[1,0]
	v_pk_add_f32 v[100:101], v[100:101], 0 op_sel_hi:[1,0]
	v_pk_add_f32 v[98:99], v[98:99], 0 op_sel_hi:[1,0]
	v_pk_add_f32 v[96:97], v[96:97], 0 op_sel_hi:[1,0]
	v_pk_add_f32 v[94:95], v[94:95], 0 op_sel_hi:[1,0]
	v_pk_add_f32 v[92:93], v[92:93], 0 op_sel_hi:[1,0]
	v_pk_add_f32 v[90:91], v[90:91], 0 op_sel_hi:[1,0]
	v_pk_add_f32 v[88:89], v[88:89], 0 op_sel_hi:[1,0]
	v_pk_add_f32 v[86:87], v[86:87], 0 op_sel_hi:[1,0]
	v_pk_add_f32 v[84:85], v[84:85], 0 op_sel_hi:[1,0]
	v_pk_add_f32 v[82:83], v[82:83], 0 op_sel_hi:[1,0]
	v_pk_add_f32 v[80:81], v[80:81], 0 op_sel_hi:[1,0]
	v_pk_add_f32 v[74:75], v[74:75], 0 op_sel_hi:[1,0]
	v_pk_add_f32 v[72:73], v[72:73], 0 op_sel_hi:[1,0]
	v_pk_add_f32 v[66:67], v[66:67], 0 op_sel_hi:[1,0]
	v_pk_add_f32 v[64:65], v[64:65], 0 op_sel_hi:[1,0]
	v_pk_add_f32 v[58:59], v[58:59], 0 op_sel_hi:[1,0]
	v_pk_add_f32 v[56:57], v[56:57], 0 op_sel_hi:[1,0]
	v_pk_add_f32 v[46:47], v[46:47], 0 op_sel_hi:[1,0]
	v_pk_add_f32 v[44:45], v[44:45], 0 op_sel_hi:[1,0]
	v_pk_add_f32 v[62:63], v[62:63], 0 op_sel_hi:[1,0]
	v_pk_add_f32 v[60:61], v[60:61], 0 op_sel_hi:[1,0]
	v_pk_add_f32 v[54:55], v[54:55], 0 op_sel_hi:[1,0]
	v_pk_add_f32 v[52:53], v[52:53], 0 op_sel_hi:[1,0]
	v_pk_add_f32 v[34:35], v[34:35], 0 op_sel_hi:[1,0]
	v_pk_add_f32 v[32:33], v[32:33], 0 op_sel_hi:[1,0]
	v_pk_add_f32 v[26:27], v[26:27], 0 op_sel_hi:[1,0]
	v_pk_add_f32 v[24:25], v[24:25], 0 op_sel_hi:[1,0]
	v_pk_add_f32 v[22:23], v[22:23], 0 op_sel_hi:[1,0]
	v_pk_add_f32 v[20:21], v[20:21], 0 op_sel_hi:[1,0]
	v_pk_add_f32 v[18:19], v[18:19], 0 op_sel_hi:[1,0]
	v_pk_add_f32 v[16:17], v[16:17], 0 op_sel_hi:[1,0]
	v_pk_add_f32 v[14:15], v[14:15], 0 op_sel_hi:[1,0]
	v_pk_add_f32 v[12:13], v[12:13], 0 op_sel_hi:[1,0]
	v_pk_add_f32 v[10:11], v[10:11], 0 op_sel_hi:[1,0]
	v_pk_add_f32 v[8:9], v[8:9], 0 op_sel_hi:[1,0]
	v_pk_add_f32 v[6:7], v[6:7], 0 op_sel_hi:[1,0]
	v_pk_add_f32 v[4:5], v[4:5], 0 op_sel_hi:[1,0]
	v_pk_add_f32 v[2:3], v[2:3], 0 op_sel_hi:[1,0]
	v_pk_add_f32 v[0:1], v[0:1], 0 op_sel_hi:[1,0]
	s_waitcnt vmcnt(0)
	v_pk_fma_f32 v[126:127], v[126:127], v[186:187], v[190:191]
	v_pk_fma_f32 v[124:125], v[124:125], v[184:185], v[188:189]
	global_store_dwordx4 v[146:147], v[124:127], off
	global_load_dwordx4 v[188:191], v[164:165], off
	global_load_dwordx4 v[192:195], v[166:167], off
	global_load_dwordx4 v[196:199], v[168:169], off
	global_load_dwordx4 v[200:203], v[170:171], off
	global_load_dwordx4 v[204:207], v[174:175], off
	global_load_dwordx4 v[208:211], v[178:179], off
	global_load_dwordx4 v[212:215], v[182:183], off
	global_load_dwordx4 v[216:219], v[144:145], off offset:64
	global_load_dwordx4 v[220:223], v[146:147], off offset:64
	global_load_dwordx4 v[224:227], v[164:165], off offset:64
	global_load_dwordx4 v[228:231], v[166:167], off offset:64
	global_load_dwordx4 v[232:235], v[168:169], off offset:64
	s_waitcnt vmcnt(11)
	v_pk_fma_f32 v[122:123], v[122:123], v[186:187], v[190:191]
	v_pk_fma_f32 v[120:121], v[120:121], v[184:185], v[188:189]
	global_store_dwordx4 v[164:165], v[120:123], off
	global_load_dwordx4 v[188:191], v[162:163], off offset:64
	s_waitcnt vmcnt(12)
	v_pk_fma_f32 v[118:119], v[118:119], v[186:187], v[194:195]
	v_pk_fma_f32 v[116:117], v[116:117], v[184:185], v[192:193]
	global_store_dwordx4 v[166:167], v[116:119], off
	global_load_dwordx4 v[192:195], v[172:173], off offset:64
	s_waitcnt vmcnt(13)
	v_pk_fma_f32 v[114:115], v[114:115], v[186:187], v[198:199]
	v_pk_fma_f32 v[112:113], v[112:113], v[184:185], v[196:197]
	global_store_dwordx4 v[168:169], v[112:115], off
	global_load_dwordx4 v[196:199], v[176:177], off offset:64
	s_waitcnt vmcnt(14)
	v_pk_fma_f32 v[110:111], v[110:111], v[186:187], v[202:203]
	v_pk_fma_f32 v[108:109], v[108:109], v[184:185], v[200:201]
	global_store_dwordx4 v[170:171], v[108:111], off
	global_load_dwordx4 v[200:203], v[180:181], off offset:64
	s_waitcnt vmcnt(15)
	v_pk_fma_f32 v[106:107], v[106:107], v[186:187], v[206:207]
	v_pk_fma_f32 v[104:105], v[104:105], v[184:185], v[204:205]
	global_store_dwordx4 v[174:175], v[104:107], off
	global_load_dwordx4 v[204:207], v[144:145], off offset:512
	s_waitcnt vmcnt(16)
	v_pk_fma_f32 v[102:103], v[102:103], v[186:187], v[210:211]
	v_pk_fma_f32 v[100:101], v[100:101], v[184:185], v[208:209]
	global_store_dwordx4 v[178:179], v[100:103], off
	global_load_dwordx4 v[208:211], v[146:147], off offset:512
	s_waitcnt vmcnt(17)
	v_pk_fma_f32 v[98:99], v[98:99], v[186:187], v[214:215]
	v_pk_fma_f32 v[96:97], v[96:97], v[184:185], v[212:213]
	global_store_dwordx4 v[182:183], v[96:99], off
	global_load_dwordx4 v[184:187], v[164:165], off offset:512
	s_waitcnt vmcnt(17)
	v_pk_fma_f32 v[94:95], v[94:95], v[218:219], v[222:223]
	v_pk_fma_f32 v[92:93], v[92:93], v[216:217], v[220:221]
	global_store_dwordx4 v[146:147], v[92:95], off offset:64
	global_load_dwordx4 v[212:215], v[166:167], off offset:512
	global_load_dwordx4 v[220:223], v[168:169], off offset:512
	s_waitcnt vmcnt(19)
	v_pk_fma_f32 v[90:91], v[90:91], v[218:219], v[226:227]
	v_pk_fma_f32 v[88:89], v[88:89], v[216:217], v[224:225]
	global_store_dwordx4 v[164:165], v[88:91], off offset:64
	global_load_dwordx4 v[224:227], v[162:163], off offset:512
	s_waitcnt vmcnt(20)
	v_pk_fma_f32 v[86:87], v[86:87], v[218:219], v[230:231]
	v_pk_fma_f32 v[84:85], v[84:85], v[216:217], v[228:229]
	global_store_dwordx4 v[166:167], v[84:87], off offset:64
	global_load_dwordx4 v[228:231], v[172:173], off offset:512
	s_waitcnt vmcnt(21)
	v_pk_fma_f32 v[82:83], v[82:83], v[218:219], v[234:235]
	v_pk_fma_f32 v[80:81], v[80:81], v[216:217], v[232:233]
	global_store_dwordx4 v[168:169], v[80:83], off offset:64
	global_load_dwordx4 v[232:235], v[176:177], off offset:512
	s_waitcnt vmcnt(21)
	v_pk_fma_f32 v[74:75], v[74:75], v[218:219], v[190:191]
	v_pk_fma_f32 v[72:73], v[72:73], v[216:217], v[188:189]
	global_store_dwordx4 v[162:163], v[72:75], off offset:64
	global_load_dwordx4 v[188:191], v[180:181], off offset:512
	s_waitcnt vmcnt(21)
	v_pk_fma_f32 v[66:67], v[66:67], v[218:219], v[194:195]
	v_pk_fma_f32 v[64:65], v[64:65], v[216:217], v[192:193]
	global_store_dwordx4 v[172:173], v[64:67], off offset:64
	global_load_dwordx4 v[192:195], v[144:145], off offset:576
	s_waitcnt vmcnt(21)
	v_pk_fma_f32 v[58:59], v[58:59], v[218:219], v[198:199]
	v_pk_fma_f32 v[56:57], v[56:57], v[216:217], v[196:197]
	global_store_dwordx4 v[176:177], v[56:59], off offset:64
	global_load_dwordx4 v[196:199], v[146:147], off offset:576
	v_pk_add_f32 v[64:65], v[78:79], 0 op_sel_hi:[1,0]
	v_pk_add_f32 v[66:67], v[76:77], 0 op_sel_hi:[1,0]
	s_waitcnt vmcnt(21)
	v_pk_fma_f32 v[46:47], v[46:47], v[218:219], v[202:203]
	v_pk_fma_f32 v[44:45], v[44:45], v[216:217], v[200:201]
	global_store_dwordx4 v[180:181], v[44:47], off offset:64
	global_load_dwordx4 v[200:203], v[164:165], off offset:576
	s_waitcnt vmcnt(19)
	v_pk_fma_f32 v[58:59], v[64:65], v[206:207], v[210:211]
	v_pk_fma_f32 v[56:57], v[66:67], v[204:205], v[208:209]
	global_store_dwordx4 v[146:147], v[56:59], off offset:512
	global_load_dwordx4 v[208:211], v[166:167], off offset:576
	global_load_dwordx4 v[216:219], v[168:169], off offset:576
	v_pk_add_f32 v[64:65], v[70:71], 0 op_sel_hi:[1,0]
	v_pk_add_f32 v[66:67], v[68:69], 0 op_sel_hi:[1,0]
	s_waitcnt vmcnt(20)
	v_pk_fma_f32 v[58:59], v[64:65], v[206:207], v[186:187]
	v_pk_fma_f32 v[56:57], v[66:67], v[204:205], v[184:185]
	global_store_dwordx4 v[164:165], v[56:59], off offset:512
	global_load_dwordx4 v[184:187], v[162:163], off offset:576
	s_waitcnt vmcnt(20)
	v_pk_fma_f32 v[58:59], v[62:63], v[206:207], v[214:215]
	v_pk_fma_f32 v[56:57], v[60:61], v[204:205], v[212:213]
	global_store_dwordx4 v[166:167], v[56:59], off offset:512
	global_load_dwordx4 v[212:215], v[172:173], off offset:576
	s_waitcnt vmcnt(21)
	v_pk_fma_f32 v[54:55], v[54:55], v[206:207], v[222:223]
	v_pk_fma_f32 v[52:53], v[52:53], v[204:205], v[220:221]
	global_store_dwordx4 v[168:169], v[52:55], off offset:512
	global_load_dwordx4 v[220:223], v[176:177], off offset:576
	s_waitcnt vmcnt(21)
	v_pk_fma_f32 v[34:35], v[34:35], v[206:207], v[226:227]
	v_pk_fma_f32 v[32:33], v[32:33], v[204:205], v[224:225]
	global_store_dwordx4 v[162:163], v[32:35], off offset:512
	global_load_dwordx4 v[224:227], v[180:181], off offset:576
	s_waitcnt vmcnt(21)
	v_pk_fma_f32 v[26:27], v[26:27], v[206:207], v[230:231]
	v_pk_fma_f32 v[24:25], v[24:25], v[204:205], v[228:229]
	global_store_dwordx4 v[172:173], v[24:27], off offset:512
	s_waitcnt vmcnt(20)
	v_pk_fma_f32 v[22:23], v[22:23], v[206:207], v[234:235]
	v_pk_fma_f32 v[20:21], v[20:21], v[204:205], v[232:233]
	global_store_dwordx4 v[176:177], v[20:23], off offset:512
	v_pk_add_f32 v[24:25], v[50:51], 0 op_sel_hi:[1,0]
	v_pk_add_f32 v[26:27], v[48:49], 0 op_sel_hi:[1,0]
	s_waitcnt vmcnt(19)
	v_pk_fma_f32 v[18:19], v[18:19], v[206:207], v[190:191]
	v_pk_fma_f32 v[16:17], v[16:17], v[204:205], v[188:189]
	global_store_dwordx4 v[180:181], v[16:19], off offset:512
	s_waitcnt vmcnt(16)
	v_pk_fma_f32 v[22:23], v[24:25], v[194:195], v[198:199]
	v_pk_fma_f32 v[20:21], v[26:27], v[192:193], v[196:197]
	global_store_dwordx4 v[146:147], v[20:23], off offset:576
	v_pk_add_f32 v[24:25], v[42:43], 0 op_sel_hi:[1,0]
	v_pk_add_f32 v[26:27], v[40:41], 0 op_sel_hi:[1,0]
	s_waitcnt vmcnt(15)
	v_pk_fma_f32 v[22:23], v[24:25], v[194:195], v[202:203]
	v_pk_fma_f32 v[20:21], v[26:27], v[192:193], v[200:201]
	global_store_dwordx4 v[164:165], v[20:23], off offset:576
	v_pk_add_f32 v[24:25], v[38:39], 0 op_sel_hi:[1,0]
	v_pk_add_f32 v[26:27], v[36:37], 0 op_sel_hi:[1,0]
	s_waitcnt vmcnt(14)
	v_pk_fma_f32 v[22:23], v[24:25], v[194:195], v[210:211]
	v_pk_fma_f32 v[20:21], v[26:27], v[192:193], v[208:209]
	global_store_dwordx4 v[166:167], v[20:23], off offset:576
	v_pk_add_f32 v[24:25], v[30:31], 0 op_sel_hi:[1,0]
	v_pk_add_f32 v[26:27], v[28:29], 0 op_sel_hi:[1,0]
	s_waitcnt vmcnt(14)
	v_pk_fma_f32 v[22:23], v[24:25], v[194:195], v[218:219]
	v_pk_fma_f32 v[20:21], v[26:27], v[192:193], v[216:217]
	global_store_dwordx4 v[168:169], v[20:23], off offset:576
	s_waitcnt vmcnt(13)
	v_pk_fma_f32 v[14:15], v[14:15], v[194:195], v[186:187]
	v_pk_fma_f32 v[12:13], v[12:13], v[192:193], v[184:185]
	global_store_dwordx4 v[162:163], v[12:15], off offset:576
	s_waitcnt vmcnt(12)
	v_pk_fma_f32 v[10:11], v[10:11], v[194:195], v[214:215]
	v_pk_fma_f32 v[8:9], v[8:9], v[192:193], v[212:213]
	global_store_dwordx4 v[172:173], v[8:11], off offset:576
	s_waitcnt vmcnt(11)
	v_pk_fma_f32 v[6:7], v[6:7], v[194:195], v[222:223]
	v_pk_fma_f32 v[4:5], v[4:5], v[192:193], v[220:221]
	global_store_dwordx4 v[176:177], v[4:7], off offset:576
	s_waitcnt vmcnt(10)
	v_pk_fma_f32 v[2:3], v[2:3], v[194:195], v[226:227]
	v_pk_fma_f32 v[0:1], v[0:1], v[192:193], v[224:225]
	global_store_dwordx4 v[180:181], v[0:3], off offset:576
	s_cbranch_vccz .LBB0_2900
	s_waitcnt vmcnt(0)
	s_cmpk_gt_u32 s1, 0xff
	s_cbranch_scc1 .LBB0_2915
	s_barrier

.LBB0_2927:
	ds_read_b128 v[144:147], v139
	ds_read_b128 v[148:151], v139 offset:1024
	ds_read_b128 v[152:155], v139 offset:2048
	ds_read_b128 v[156:159], v139 offset:3072
	s_add_u32 s16, s14, 0x100
	s_addc_u32 s17, s15, 0
	s_cmp_eq_u32 s47, 4
	s_cselect_b32 s21, s13, s17
	s_cselect_b32 s20, s12, s16
	s_cselect_b32 s19, s7, s46
	s_cselect_b32 s18, s6, s43
	s_mov_b32 m0, s31
	v_lshl_add_u64 v[192:193], s[14:15], 0, v[132:133]
	ds_read_b128 v[160:163], v140
	ds_read_b128 v[164:167], v140 offset:1024
	ds_read_b128 v[168:171], v140 offset:2048
	ds_read_b128 v[172:175], v140 offset:3072
	ds_read_b128 v[176:179], v140 offset:4096
	ds_read_b128 v[180:183], v140 offset:5120
	ds_read_b128 v[184:187], v140 offset:6144
	ds_read_b128 v[188:191], v140 offset:7168
	global_load_lds_dwordx4 v[192:193], off
	v_lshl_add_u64 v[192:193], s[14:15], 0, v[134:135]
	s_mov_b32 m0, s34
	s_nop 0
	global_load_lds_dwordx4 v[192:193], off
	s_waitcnt lgkmcnt(8)
	s_barrier
	s_waitcnt lgkmcnt(0)
	s_waitcnt lgkmcnt(0)
	v_mfma_f32_16x16x32_bf16 v[124:127], v[144:147], v[160:163], v[124:127]
	v_mfma_f32_16x16x32_bf16 v[120:123], v[152:155], v[160:163], v[120:123]
	v_mfma_f32_16x16x32_bf16 v[116:119], v[144:147], v[168:171], v[116:119]
	v_mfma_f32_16x16x32_bf16 v[112:115], v[152:155], v[168:171], v[112:115]
	v_mfma_f32_16x16x32_bf16 v[100:103], v[144:147], v[176:179], v[100:103]
	v_mfma_f32_16x16x32_bf16 v[96:99], v[152:155], v[176:179], v[96:99]
	v_mfma_f32_16x16x32_bf16 v[84:87], v[144:147], v[184:187], v[84:87]
	v_mfma_f32_16x16x32_bf16 v[80:83], v[152:155], v[184:187], v[80:83]
	v_mfma_f32_16x16x32_bf16 v[124:127], v[148:151], v[164:167], v[124:127]
	v_mfma_f32_16x16x32_bf16 v[120:123], v[156:159], v[164:167], v[120:123]
	v_mfma_f32_16x16x32_bf16 v[116:119], v[148:151], v[172:175], v[116:119]
	v_mfma_f32_16x16x32_bf16 v[112:115], v[156:159], v[172:175], v[112:115]
	v_mfma_f32_16x16x32_bf16 v[100:103], v[148:151], v[180:183], v[100:103]
	v_mfma_f32_16x16x32_bf16 v[96:99], v[156:159], v[180:183], v[96:99]
	v_mfma_f32_16x16x32_bf16 v[84:87], v[148:151], v[188:191], v[84:87]
	v_mfma_f32_16x16x32_bf16 v[80:83], v[156:159], v[188:191], v[80:83]
	s_barrier
	s_mov_b32 m0, s35
	v_lshl_add_u64 v[208:209], s[18:19], 0, v[130:131]
	ds_read_b128 v[192:195], v141
	ds_read_b128 v[196:199], v141 offset:1024
	ds_read_b128 v[200:203], v141 offset:2048
	ds_read_b128 v[204:207], v141 offset:3072
	global_load_lds_dwordx4 v[208:209], off
	v_lshl_add_u64 v[210:211], s[18:19], 0, v[128:129]
	s_mov_b32 m0, s36
	s_nop 0
	global_load_lds_dwordx4 v[210:211], off
	s_barrier
	s_waitcnt lgkmcnt(0)
	s_waitcnt lgkmcnt(0)
	v_mfma_f32_16x16x32_bf16 v[108:111], v[192:195], v[160:163], v[108:111]
	v_mfma_f32_16x16x32_bf16 v[104:107], v[200:203], v[160:163], v[104:107]
	v_mfma_f32_16x16x32_bf16 v[92:95], v[192:195], v[168:171], v[92:95]
	v_mfma_f32_16x16x32_bf16 v[88:91], v[200:203], v[168:171], v[88:91]
	v_mfma_f32_16x16x32_bf16 v[76:79], v[192:195], v[176:179], v[76:79]
	v_mfma_f32_16x16x32_bf16 v[72:75], v[200:203], v[176:179], v[72:75]
	v_mfma_f32_16x16x32_bf16 v[68:71], v[192:195], v[184:187], v[68:71]
	v_mfma_f32_16x16x32_bf16 v[64:67], v[200:203], v[184:187], v[64:67]
	v_mfma_f32_16x16x32_bf16 v[108:111], v[196:199], v[164:167], v[108:111]
	v_mfma_f32_16x16x32_bf16 v[104:107], v[204:207], v[164:167], v[104:107]
	v_mfma_f32_16x16x32_bf16 v[92:95], v[196:199], v[172:175], v[92:95]
	v_mfma_f32_16x16x32_bf16 v[88:91], v[204:207], v[172:175], v[88:91]
	v_mfma_f32_16x16x32_bf16 v[76:79], v[196:199], v[180:183], v[76:79]
	v_mfma_f32_16x16x32_bf16 v[72:75], v[204:207], v[180:183], v[72:75]
	v_mfma_f32_16x16x32_bf16 v[68:71], v[196:199], v[188:191], v[68:71]
	v_mfma_f32_16x16x32_bf16 v[64:67], v[204:207], v[188:191], v[64:67]
	s_mov_b32 m0, s3
	v_lshl_add_u64 v[212:213], s[20:21], 0, v[130:131]
	s_barrier
	ds_read_b128 v[160:163], v140 offset:16384
	ds_read_b128 v[164:167], v140 offset:17408
	ds_read_b128 v[168:171], v140 offset:18432
	ds_read_b128 v[172:175], v140 offset:19456
	ds_read_b128 v[176:179], v140 offset:20480
	ds_read_b128 v[180:183], v140 offset:21504
	ds_read_b128 v[184:187], v140 offset:22528
	ds_read_b128 v[188:191], v140 offset:23552
	global_load_lds_dwordx4 v[212:213], off
	v_lshl_add_u64 v[214:215], s[20:21], 0, v[128:129]
	s_mov_b32 m0, s4
	s_nop 0
	global_load_lds_dwordx4 v[214:215], off
	s_barrier
	s_waitcnt lgkmcnt(0)
	s_waitcnt lgkmcnt(0)
	v_mfma_f32_16x16x32_bf16 v[60:63], v[144:147], v[160:163], v[60:63]
	v_mfma_f32_16x16x32_bf16 v[56:59], v[152:155], v[160:163], v[56:59]
	v_mfma_f32_16x16x32_bf16 v[52:55], v[144:147], v[168:171], v[52:55]
	v_mfma_f32_16x16x32_bf16 v[48:51], v[152:155], v[168:171], v[48:51]
	v_mfma_f32_16x16x32_bf16 v[36:39], v[144:147], v[176:179], v[36:39]
	v_mfma_f32_16x16x32_bf16 v[32:35], v[152:155], v[176:179], v[32:35]
	v_mfma_f32_16x16x32_bf16 v[20:23], v[144:147], v[184:187], v[20:23]
	v_mfma_f32_16x16x32_bf16 v[16:19], v[152:155], v[184:187], v[16:19]
	v_mfma_f32_16x16x32_bf16 v[60:63], v[148:151], v[164:167], v[60:63]
	v_mfma_f32_16x16x32_bf16 v[56:59], v[156:159], v[164:167], v[56:59]
	v_mfma_f32_16x16x32_bf16 v[52:55], v[148:151], v[172:175], v[52:55]
	v_mfma_f32_16x16x32_bf16 v[48:51], v[156:159], v[172:175], v[48:51]
	v_mfma_f32_16x16x32_bf16 v[36:39], v[148:151], v[180:183], v[36:39]
	v_mfma_f32_16x16x32_bf16 v[32:35], v[156:159], v[180:183], v[32:35]
	v_mfma_f32_16x16x32_bf16 v[20:23], v[148:151], v[188:191], v[20:23]
	v_mfma_f32_16x16x32_bf16 v[16:19], v[156:159], v[188:191], v[16:19]
	s_barrier
	s_add_u32 s14, s18, 0x160000
	s_addc_u32 s15, s19, 0
	s_mov_b32 m0, s37
	v_lshl_add_u64 v[144:145], s[14:15], 0, v[130:131]
	global_load_lds_dwordx4 v[144:145], off
	v_lshl_add_u64 v[144:145], s[14:15], 0, v[128:129]
	s_mov_b32 m0, s38
	s_nop 0
	global_load_lds_dwordx4 v[144:145], off
	s_waitcnt vmcnt(6)
	s_barrier
	v_mfma_f32_16x16x32_bf16 v[44:47], v[192:195], v[160:163], v[44:47]
	v_mfma_f32_16x16x32_bf16 v[40:43], v[200:203], v[160:163], v[40:43]
	v_mfma_f32_16x16x32_bf16 v[28:31], v[192:195], v[168:171], v[28:31]
	v_mfma_f32_16x16x32_bf16 v[24:27], v[200:203], v[168:171], v[24:27]
	v_mfma_f32_16x16x32_bf16 v[12:15], v[192:195], v[176:179], v[12:15]
	v_mfma_f32_16x16x32_bf16 v[8:11], v[200:203], v[176:179], v[8:11]
	v_mfma_f32_16x16x32_bf16 v[4:7], v[192:195], v[184:187], v[4:7]
	v_mfma_f32_16x16x32_bf16 v[0:3], v[200:203], v[184:187], v[0:3]
	v_mfma_f32_16x16x32_bf16 v[44:47], v[196:199], v[164:167], v[44:47]
	v_mfma_f32_16x16x32_bf16 v[40:43], v[204:207], v[164:167], v[40:43]
	v_mfma_f32_16x16x32_bf16 v[28:31], v[196:199], v[172:175], v[28:31]
	v_mfma_f32_16x16x32_bf16 v[24:27], v[204:207], v[172:175], v[24:27]
	v_mfma_f32_16x16x32_bf16 v[12:15], v[196:199], v[180:183], v[12:15]
	v_mfma_f32_16x16x32_bf16 v[8:11], v[204:207], v[180:183], v[8:11]
	v_mfma_f32_16x16x32_bf16 v[4:7], v[196:199], v[188:191], v[4:7]
	v_mfma_f32_16x16x32_bf16 v[0:3], v[204:207], v[188:191], v[0:3]
	s_barrier
	ds_read_b128 v[144:147], v142
	ds_read_b128 v[148:151], v142 offset:1024
	ds_read_b128 v[152:155], v142 offset:2048
	ds_read_b128 v[156:159], v142 offset:3072
	s_add_u32 s14, s20, 0x160000
	s_addc_u32 s15, s21, 0
	s_mov_b32 m0, s5
	v_lshl_add_u64 v[192:193], s[14:15], 0, v[130:131]
	ds_read_b128 v[160:163], v140 offset:32768
	ds_read_b128 v[164:167], v140 offset:33792
	ds_read_b128 v[168:171], v140 offset:34816
	ds_read_b128 v[172:175], v140 offset:35840
	ds_read_b128 v[176:179], v140 offset:36864
	ds_read_b128 v[180:183], v140 offset:37888
	ds_read_b128 v[184:187], v140 offset:38912
	ds_read_b128 v[188:191], v140 offset:39936
	global_load_lds_dwordx4 v[192:193], off
	v_lshl_add_u64 v[192:193], s[14:15], 0, v[128:129]
	s_mov_b32 m0, s22
	s_nop 0
	global_load_lds_dwordx4 v[192:193], off
	s_waitcnt lgkmcnt(8)
	s_barrier
	s_waitcnt lgkmcnt(0)
	s_waitcnt lgkmcnt(0)
	v_mfma_f32_16x16x32_bf16 v[124:127], v[144:147], v[160:163], v[124:127]
	v_mfma_f32_16x16x32_bf16 v[120:123], v[152:155], v[160:163], v[120:123]
	v_mfma_f32_16x16x32_bf16 v[116:119], v[144:147], v[168:171], v[116:119]
	v_mfma_f32_16x16x32_bf16 v[112:115], v[152:155], v[168:171], v[112:115]
	v_mfma_f32_16x16x32_bf16 v[100:103], v[144:147], v[176:179], v[100:103]
	v_mfma_f32_16x16x32_bf16 v[96:99], v[152:155], v[176:179], v[96:99]
	v_mfma_f32_16x16x32_bf16 v[84:87], v[144:147], v[184:187], v[84:87]
	v_mfma_f32_16x16x32_bf16 v[80:83], v[152:155], v[184:187], v[80:83]
	v_mfma_f32_16x16x32_bf16 v[124:127], v[148:151], v[164:167], v[124:127]
	v_mfma_f32_16x16x32_bf16 v[120:123], v[156:159], v[164:167], v[120:123]
	v_mfma_f32_16x16x32_bf16 v[116:119], v[148:151], v[172:175], v[116:119]
	v_mfma_f32_16x16x32_bf16 v[112:115], v[156:159], v[172:175], v[112:115]
	v_mfma_f32_16x16x32_bf16 v[100:103], v[148:151], v[180:183], v[100:103]
	v_mfma_f32_16x16x32_bf16 v[96:99], v[156:159], v[180:183], v[96:99]
	v_mfma_f32_16x16x32_bf16 v[84:87], v[148:151], v[188:191], v[84:87]
	v_mfma_f32_16x16x32_bf16 v[80:83], v[156:159], v[188:191], v[80:83]
	s_barrier
	s_add_i32 s20, 0, 0x1c000
	s_add_i32 s14, s39, s2
	v_add_u32_e32 v143, s20, v137
	v_lshl_add_u64 v[208:209], v[208:209], 0, s[8:9]
	s_mov_b32 m0, s14
	ds_read_b128 v[192:195], v143
	ds_read_b128 v[196:199], v143 offset:1024
	ds_read_b128 v[200:203], v143 offset:2048
	ds_read_b128 v[204:207], v143 offset:3072
	global_load_lds_dwordx4 v[208:209], off
	v_lshl_add_u64 v[208:209], v[210:211], 0, s[8:9]
	s_add_i32 m0, s14, 0x2000
	s_nop 0
	global_load_lds_dwordx4 v[208:209], off
	s_barrier
	s_waitcnt lgkmcnt(0)
	s_waitcnt lgkmcnt(0)
	v_mfma_f32_16x16x32_bf16 v[108:111], v[192:195], v[160:163], v[108:111]
	v_mfma_f32_16x16x32_bf16 v[104:107], v[200:203], v[160:163], v[104:107]
	v_mfma_f32_16x16x32_bf16 v[92:95], v[192:195], v[168:171], v[92:95]
	v_mfma_f32_16x16x32_bf16 v[88:91], v[200:203], v[168:171], v[88:91]
	v_mfma_f32_16x16x32_bf16 v[76:79], v[192:195], v[176:179], v[76:79]
	v_mfma_f32_16x16x32_bf16 v[72:75], v[200:203], v[176:179], v[72:75]
	v_mfma_f32_16x16x32_bf16 v[68:71], v[192:195], v[184:187], v[68:71]
	v_mfma_f32_16x16x32_bf16 v[64:67], v[200:203], v[184:187], v[64:67]
	v_mfma_f32_16x16x32_bf16 v[108:111], v[196:199], v[164:167], v[108:111]
	v_mfma_f32_16x16x32_bf16 v[104:107], v[204:207], v[164:167], v[104:107]
	v_mfma_f32_16x16x32_bf16 v[92:95], v[196:199], v[172:175], v[92:95]
	v_mfma_f32_16x16x32_bf16 v[88:91], v[204:207], v[172:175], v[88:91]
	v_mfma_f32_16x16x32_bf16 v[76:79], v[196:199], v[180:183], v[76:79]
	v_mfma_f32_16x16x32_bf16 v[72:75], v[204:207], v[180:183], v[72:75]
	v_mfma_f32_16x16x32_bf16 v[68:71], v[196:199], v[188:191], v[68:71]
	v_mfma_f32_16x16x32_bf16 v[64:67], v[204:207], v[188:191], v[64:67]
	s_mov_b32 m0, s29
	v_lshl_add_u64 v[208:209], v[212:213], 0, s[8:9]
	s_barrier
	ds_read_b128 v[160:163], v140 offset:49152
	ds_read_b128 v[164:167], v140 offset:50176
	ds_read_b128 v[168:171], v140 offset:51200
	ds_read_b128 v[172:175], v140 offset:52224
	ds_read_b128 v[176:179], v140 offset:53248
	ds_read_b128 v[180:183], v140 offset:54272
	ds_read_b128 v[184:187], v140 offset:55296
	ds_read_b128 v[188:191], v140 offset:56320
	global_load_lds_dwordx4 v[208:209], off
	v_lshl_add_u64 v[208:209], v[214:215], 0, s[8:9]
	s_mov_b32 m0, s30
	s_nop 0
	global_load_lds_dwordx4 v[208:209], off
	s_barrier
	s_waitcnt lgkmcnt(0)
	s_waitcnt lgkmcnt(0)
	v_mfma_f32_16x16x32_bf16 v[60:63], v[144:147], v[160:163], v[60:63]
	v_mfma_f32_16x16x32_bf16 v[56:59], v[152:155], v[160:163], v[56:59]
	v_mfma_f32_16x16x32_bf16 v[52:55], v[144:147], v[168:171], v[52:55]
	v_mfma_f32_16x16x32_bf16 v[48:51], v[152:155], v[168:171], v[48:51]
	v_mfma_f32_16x16x32_bf16 v[36:39], v[144:147], v[176:179], v[36:39]
	v_mfma_f32_16x16x32_bf16 v[32:35], v[152:155], v[176:179], v[32:35]
	v_mfma_f32_16x16x32_bf16 v[20:23], v[144:147], v[184:187], v[20:23]
	v_mfma_f32_16x16x32_bf16 v[16:19], v[152:155], v[184:187], v[16:19]
	v_mfma_f32_16x16x32_bf16 v[60:63], v[148:151], v[164:167], v[60:63]
	v_mfma_f32_16x16x32_bf16 v[56:59], v[156:159], v[164:167], v[56:59]
	v_mfma_f32_16x16x32_bf16 v[52:55], v[148:151], v[172:175], v[52:55]
	v_mfma_f32_16x16x32_bf16 v[48:51], v[156:159], v[172:175], v[48:51]
	v_mfma_f32_16x16x32_bf16 v[36:39], v[148:151], v[180:183], v[36:39]
	v_mfma_f32_16x16x32_bf16 v[32:35], v[156:159], v[180:183], v[32:35]
	v_mfma_f32_16x16x32_bf16 v[20:23], v[148:151], v[188:191], v[20:23]
	v_mfma_f32_16x16x32_bf16 v[16:19], v[156:159], v[188:191], v[16:19]
	s_barrier
	s_add_u32 s14, s18, 0x160080
	s_addc_u32 s15, s19, 0
	s_add_i32 s18, s20, s2
	v_lshl_add_u64 v[144:145], s[14:15], 0, v[130:131]
	s_mov_b32 m0, s18
	s_nop 0
	global_load_lds_dwordx4 v[144:145], off
	v_lshl_add_u64 v[144:145], s[14:15], 0, v[128:129]
	s_add_i32 m0, s18, 0x2000
	s_nop 0
	global_load_lds_dwordx4 v[144:145], off
	s_waitcnt vmcnt(6)
	s_barrier
	v_mfma_f32_16x16x32_bf16 v[44:47], v[192:195], v[160:163], v[44:47]
	v_mfma_f32_16x16x32_bf16 v[40:43], v[200:203], v[160:163], v[40:43]
	v_mfma_f32_16x16x32_bf16 v[28:31], v[192:195], v[168:171], v[28:31]
	v_mfma_f32_16x16x32_bf16 v[24:27], v[200:203], v[168:171], v[24:27]
	v_mfma_f32_16x16x32_bf16 v[12:15], v[192:195], v[176:179], v[12:15]
	v_mfma_f32_16x16x32_bf16 v[8:11], v[200:203], v[176:179], v[8:11]
	v_mfma_f32_16x16x32_bf16 v[4:7], v[192:195], v[184:187], v[4:7]
	v_mfma_f32_16x16x32_bf16 v[0:3], v[200:203], v[184:187], v[0:3]
	v_mfma_f32_16x16x32_bf16 v[44:47], v[196:199], v[164:167], v[44:47]
	v_mfma_f32_16x16x32_bf16 v[40:43], v[204:207], v[164:167], v[40:43]
	v_mfma_f32_16x16x32_bf16 v[28:31], v[196:199], v[172:175], v[28:31]
	v_mfma_f32_16x16x32_bf16 v[24:27], v[204:207], v[172:175], v[24:27]
	v_mfma_f32_16x16x32_bf16 v[12:15], v[196:199], v[180:183], v[12:15]
	v_mfma_f32_16x16x32_bf16 v[8:11], v[204:207], v[180:183], v[8:11]
	v_mfma_f32_16x16x32_bf16 v[4:7], v[196:199], v[188:191], v[4:7]
	v_mfma_f32_16x16x32_bf16 v[0:3], v[204:207], v[188:191], v[0:3]
	s_add_i32 s47, s47, 2
	s_add_u32 s43, s43, 0x100
	s_addc_u32 s46, s46, 0
	s_cmp_gt_u32 s47, 5
	s_mov_b64 s[14:15], s[16:17]
	s_barrier
	s_cbranch_scc0 .LBB0_2927
	s_ashr_i32 s14, s28, 1
	s_and_b32 s14, s14, 0xfffffe00
	s_lshl_b32 s15, s27, 8
	s_add_i32 s15, s15, s14
	v_add_u32_e32 v146, s15, v136
	v_lshl_or_b32 v144, s26, 8, v138
	v_ashrrev_i32_e32 v147, 31, v146
	v_ashrrev_i32_e32 v145, 31, v144
	v_lshlrev_b64 v[148:149], 13, v[146:147]
	v_lshl_add_u64 v[148:149], s[58:59], 0, v[148:149]
	v_lshlrev_b64 v[144:145], 2, v[144:145]
	v_lshl_add_u64 v[148:149], v[148:149], 0, v[144:145]
	global_store_dwordx4 v[148:149], v[124:127], off
	global_store_dwordx4 v[148:149], v[120:123], off offset:64
	global_store_dwordx4 v[148:149], v[108:111], off offset:512
	global_store_dwordx4 v[148:149], v[104:107], off offset:576
	s_mov_b64 s[14:15], 0x100000
	s_mov_b32 s28, s41
	v_or_b32_e32 v104, 16, v146
	v_ashrrev_i32_e32 v105, 31, v104
	v_lshlrev_b64 v[104:105], 13, v[104:105]
	v_lshl_add_u64 v[104:105], s[58:59], 0, v[104:105]
	v_lshl_add_u64 v[104:105], v[104:105], 0, v[144:145]
	global_store_dwordx4 v[104:105], v[116:119], off
	global_store_dwordx4 v[104:105], v[112:115], off offset:64
	global_store_dwordx4 v[104:105], v[92:95], off offset:512
	global_store_dwordx4 v[104:105], v[88:91], off offset:576
	s_mov_b32 s26, s40
	s_mov_b32 s27, s42
	v_or_b32_e32 v88, 32, v146
	v_ashrrev_i32_e32 v89, 31, v88
	v_lshlrev_b64 v[88:89], 13, v[88:89]
	v_lshl_add_u64 v[88:89], s[58:59], 0, v[88:89]
	v_lshl_add_u64 v[88:89], v[88:89], 0, v[144:145]
	global_store_dwordx4 v[88:89], v[100:103], off
	global_store_dwordx4 v[88:89], v[96:99], off offset:64
	global_store_dwordx4 v[88:89], v[76:79], off offset:512
	global_store_dwordx4 v[88:89], v[72:75], off offset:576
	s_mov_b64 s[16:17], s[6:7]
	s_nop 0
	v_or_b32_e32 v72, 48, v146
	v_ashrrev_i32_e32 v73, 31, v72
	v_lshlrev_b64 v[72:73], 13, v[72:73]
	v_lshl_add_u64 v[72:73], s[58:59], 0, v[72:73]
	v_lshl_add_u64 v[72:73], v[72:73], 0, v[144:145]
	global_store_dwordx4 v[72:73], v[84:87], off
	global_store_dwordx4 v[72:73], v[80:83], off offset:64
	global_store_dwordx4 v[72:73], v[68:71], off offset:512
	global_store_dwordx4 v[72:73], v[64:67], off offset:576
	s_nop 1
	v_lshl_add_u64 v[64:65], v[148:149], 0, s[14:15]
	s_mov_b32 s14, 0x100000
	v_add_co_u32_e32 v66, vcc, s14, v148
	s_mov_b64 s[14:15], 0x120000
	s_nop 0
	v_addc_co_u32_e32 v67, vcc, 0, v149, vcc
	global_store_dwordx4 v[66:67], v[60:63], off
	global_store_dwordx4 v[64:65], v[56:59], off offset:64
	global_store_dwordx4 v[64:65], v[44:47], off offset:512
	global_store_dwordx4 v[64:65], v[40:43], off offset:576
	s_nop 1
	v_lshl_add_u64 v[40:41], v[148:149], 0, s[14:15]
	s_mov_b32 s14, 0x120000
	v_add_co_u32_e32 v42, vcc, s14, v148
	s_mov_b64 s[14:15], 0x140000
	s_nop 0
	v_addc_co_u32_e32 v43, vcc, 0, v149, vcc
	global_store_dwordx4 v[42:43], v[52:55], off
	global_store_dwordx4 v[40:41], v[48:51], off offset:64
	global_store_dwordx4 v[40:41], v[28:31], off offset:512
	global_store_dwordx4 v[40:41], v[24:27], off offset:576
	s_nop 1
	v_lshl_add_u64 v[24:25], v[148:149], 0, s[14:15]
	s_mov_b32 s14, 0x140000
	v_add_co_u32_e32 v26, vcc, s14, v148
	s_mov_b64 s[14:15], 0x160000
	s_nop 0
	v_addc_co_u32_e32 v27, vcc, 0, v149, vcc
	global_store_dwordx4 v[26:27], v[36:39], off
	global_store_dwordx4 v[24:25], v[32:35], off offset:64
	global_store_dwordx4 v[24:25], v[12:15], off offset:512
	global_store_dwordx4 v[24:25], v[8:11], off offset:576
	s_nop 1
	v_add_co_u32_e32 v10, vcc, 0x160000, v148
	v_lshl_add_u64 v[8:9], v[148:149], 0, s[14:15]
	s_nop 0
	v_addc_co_u32_e32 v11, vcc, 0, v149, vcc
	s_and_b64 vcc, exec, s[10:11]
	s_mov_b64 s[14:15], s[12:13]
	global_store_dwordx4 v[10:11], v[20:23], off
	global_store_dwordx4 v[8:9], v[16:19], off offset:64
	global_store_dwordx4 v[8:9], v[4:7], off offset:512
	global_store_dwordx4 v[8:9], v[0:3], off offset:576
	s_cbranch_vccz .LBB0_2920
	s_waitcnt vmcnt(0)
	s_cmpk_gt_u32 s1, 0xff
	s_cbranch_scc1 .LBB0_2931
	s_barrier

.LBB0_3276:
	ds_read_b128 v[128:131], v183
	ds_read_b128 v[132:135], v183 offset:1024
	ds_read_b128 v[136:139], v183 offset:2048
	ds_read_b128 v[140:143], v183 offset:3072
	s_add_u32 s36, s34, 0x100
	s_addc_u32 s37, s35, 0
	s_cmp_eq_u32 s64, 28
	s_cselect_b32 s41, s23, s37
	s_cselect_b32 s40, s60, s36
	s_cselect_b32 s39, s21, s63
	s_cselect_b32 s38, s61, s62
	v_lshl_add_u64 v[194:195], s[34:35], 0, v[160:161]
	s_add_i32 m0, s5, 0xc000
	ds_read_b128 v[144:147], v184
	ds_read_b128 v[148:151], v184 offset:1024
	ds_read_b128 v[152:155], v184 offset:2048
	ds_read_b128 v[168:171], v184 offset:3072
	ds_read_b128 v[172:175], v184 offset:4096
	ds_read_b128 v[176:179], v184 offset:5120
	ds_read_b128 v[186:189], v184 offset:6144
	ds_read_b128 v[190:193], v184 offset:7168
	global_load_lds_dwordx4 v[194:195], off
	v_lshl_add_u64 v[194:195], s[34:35], 0, v[162:163]
	s_add_i32 m0, s5, 0xe000
	s_nop 0
	global_load_lds_dwordx4 v[194:195], off
	s_waitcnt lgkmcnt(8)
	s_barrier
	s_waitcnt lgkmcnt(0)
	s_waitcnt lgkmcnt(0)
	v_mfma_f32_16x16x32_bf16 v[124:127], v[128:131], v[144:147], v[124:127]
	v_mfma_f32_16x16x32_bf16 v[120:123], v[136:139], v[144:147], v[120:123]
	v_mfma_f32_16x16x32_bf16 v[116:119], v[128:131], v[152:155], v[116:119]
	v_mfma_f32_16x16x32_bf16 v[112:115], v[136:139], v[152:155], v[112:115]
	v_mfma_f32_16x16x32_bf16 v[104:107], v[128:131], v[172:175], v[104:107]
	v_mfma_f32_16x16x32_bf16 v[108:111], v[136:139], v[172:175], v[108:111]
	v_mfma_f32_16x16x32_bf16 v[96:99], v[128:131], v[186:189], v[96:99]
	v_mfma_f32_16x16x32_bf16 v[100:103], v[136:139], v[186:189], v[100:103]
	v_mfma_f32_16x16x32_bf16 v[124:127], v[132:135], v[148:151], v[124:127]
	v_mfma_f32_16x16x32_bf16 v[120:123], v[140:143], v[148:151], v[120:123]
	v_mfma_f32_16x16x32_bf16 v[116:119], v[132:135], v[168:171], v[116:119]
	v_mfma_f32_16x16x32_bf16 v[112:115], v[140:143], v[168:171], v[112:115]
	v_mfma_f32_16x16x32_bf16 v[104:107], v[132:135], v[176:179], v[104:107]
	v_mfma_f32_16x16x32_bf16 v[108:111], v[140:143], v[176:179], v[108:111]
	v_mfma_f32_16x16x32_bf16 v[96:99], v[132:135], v[190:193], v[96:99]
	v_mfma_f32_16x16x32_bf16 v[100:103], v[140:143], v[190:193], v[100:103]
	s_barrier
	s_add_i32 s34, s54, s4
	v_lshl_add_u64 v[210:211], s[38:39], 0, v[156:157]
	s_mov_b32 m0, s34
	ds_read_b128 v[194:197], v185
	ds_read_b128 v[198:201], v185 offset:1024
	ds_read_b128 v[202:205], v185 offset:2048
	ds_read_b128 v[206:209], v185 offset:3072
	global_load_lds_dwordx4 v[210:211], off
	v_lshl_add_u64 v[212:213], s[38:39], 0, v[158:159]
	s_add_i32 m0, s34, 0x2000
	s_nop 0
	global_load_lds_dwordx4 v[212:213], off
	s_barrier
	s_waitcnt lgkmcnt(0)
	s_waitcnt lgkmcnt(0)
	v_mfma_f32_16x16x32_bf16 v[56:59], v[194:197], v[144:147], v[56:59]
	v_mfma_f32_16x16x32_bf16 v[60:63], v[202:205], v[144:147], v[60:63]
	v_mfma_f32_16x16x32_bf16 v[48:51], v[194:197], v[152:155], v[48:51]
	v_mfma_f32_16x16x32_bf16 v[52:55], v[202:205], v[152:155], v[52:55]
	v_mfma_f32_16x16x32_bf16 v[40:43], v[194:197], v[172:175], v[40:43]
	v_mfma_f32_16x16x32_bf16 v[44:47], v[202:205], v[172:175], v[44:47]
	v_mfma_f32_16x16x32_bf16 v[32:35], v[194:197], v[186:189], v[32:35]
	v_mfma_f32_16x16x32_bf16 v[36:39], v[202:205], v[186:189], v[36:39]
	v_mfma_f32_16x16x32_bf16 v[56:59], v[198:201], v[148:151], v[56:59]
	v_mfma_f32_16x16x32_bf16 v[60:63], v[206:209], v[148:151], v[60:63]
	v_mfma_f32_16x16x32_bf16 v[48:51], v[198:201], v[168:171], v[48:51]
	v_mfma_f32_16x16x32_bf16 v[52:55], v[206:209], v[168:171], v[52:55]
	v_mfma_f32_16x16x32_bf16 v[40:43], v[198:201], v[176:179], v[40:43]
	v_mfma_f32_16x16x32_bf16 v[44:47], v[206:209], v[176:179], v[44:47]
	v_mfma_f32_16x16x32_bf16 v[32:35], v[198:201], v[190:193], v[32:35]
	v_mfma_f32_16x16x32_bf16 v[36:39], v[206:209], v[190:193], v[36:39]
	s_mov_b32 m0, s5
	v_lshl_add_u64 v[214:215], s[40:41], 0, v[156:157]
	s_barrier
	ds_read_b128 v[144:147], v184 offset:16384
	ds_read_b128 v[148:151], v184 offset:17408
	ds_read_b128 v[152:155], v184 offset:18432
	ds_read_b128 v[168:171], v184 offset:19456
	ds_read_b128 v[172:175], v184 offset:20480
	ds_read_b128 v[176:179], v184 offset:21504
	ds_read_b128 v[186:189], v184 offset:22528
	ds_read_b128 v[190:193], v184 offset:23552
	global_load_lds_dwordx4 v[214:215], off
	v_lshl_add_u64 v[216:217], s[40:41], 0, v[158:159]
	s_mov_b32 m0, s31
	s_nop 0
	global_load_lds_dwordx4 v[216:217], off
	s_barrier
	s_waitcnt lgkmcnt(0)
	s_waitcnt lgkmcnt(0)
	v_mfma_f32_16x16x32_bf16 v[88:91], v[128:131], v[144:147], v[88:91]
	v_mfma_f32_16x16x32_bf16 v[92:95], v[136:139], v[144:147], v[92:95]
	v_mfma_f32_16x16x32_bf16 v[80:83], v[128:131], v[152:155], v[80:83]
	v_mfma_f32_16x16x32_bf16 v[84:87], v[136:139], v[152:155], v[84:87]
	v_mfma_f32_16x16x32_bf16 v[72:75], v[128:131], v[172:175], v[72:75]
	v_mfma_f32_16x16x32_bf16 v[76:79], v[136:139], v[172:175], v[76:79]
	v_mfma_f32_16x16x32_bf16 v[64:67], v[128:131], v[186:189], v[64:67]
	v_mfma_f32_16x16x32_bf16 v[68:71], v[136:139], v[186:189], v[68:71]
	v_mfma_f32_16x16x32_bf16 v[88:91], v[132:135], v[148:151], v[88:91]
	v_mfma_f32_16x16x32_bf16 v[92:95], v[140:143], v[148:151], v[92:95]
	v_mfma_f32_16x16x32_bf16 v[80:83], v[132:135], v[168:171], v[80:83]
	v_mfma_f32_16x16x32_bf16 v[84:87], v[140:143], v[168:171], v[84:87]
	v_mfma_f32_16x16x32_bf16 v[72:75], v[132:135], v[176:179], v[72:75]
	v_mfma_f32_16x16x32_bf16 v[76:79], v[140:143], v[176:179], v[76:79]
	v_mfma_f32_16x16x32_bf16 v[64:67], v[132:135], v[190:193], v[64:67]
	v_mfma_f32_16x16x32_bf16 v[68:71], v[140:143], v[190:193], v[68:71]
	s_barrier
	s_add_u32 s34, s38, 0x80000
	s_addc_u32 s35, s39, 0
	s_add_i32 s65, s55, s4
	v_lshl_add_u64 v[128:129], s[34:35], 0, v[156:157]
	s_mov_b32 m0, s65
	s_nop 0
	global_load_lds_dwordx4 v[128:129], off
	v_lshl_add_u64 v[128:129], s[34:35], 0, v[158:159]
	s_add_i32 m0, s65, 0x2000
	s_nop 0
	global_load_lds_dwordx4 v[128:129], off
	s_waitcnt vmcnt(6)
	s_barrier
	v_mfma_f32_16x16x32_bf16 v[24:27], v[194:197], v[144:147], v[24:27]
	v_mfma_f32_16x16x32_bf16 v[28:31], v[202:205], v[144:147], v[28:31]
	v_mfma_f32_16x16x32_bf16 v[16:19], v[194:197], v[152:155], v[16:19]
	v_mfma_f32_16x16x32_bf16 v[20:23], v[202:205], v[152:155], v[20:23]
	v_mfma_f32_16x16x32_bf16 v[8:11], v[194:197], v[172:175], v[8:11]
	v_mfma_f32_16x16x32_bf16 v[12:15], v[202:205], v[172:175], v[12:15]
	v_mfma_f32_16x16x32_bf16 v[0:3], v[194:197], v[186:189], v[0:3]
	v_mfma_f32_16x16x32_bf16 v[4:7], v[202:205], v[186:189], v[4:7]
	v_mfma_f32_16x16x32_bf16 v[24:27], v[198:201], v[148:151], v[24:27]
	v_mfma_f32_16x16x32_bf16 v[28:31], v[206:209], v[148:151], v[28:31]
	v_mfma_f32_16x16x32_bf16 v[16:19], v[198:201], v[168:171], v[16:19]
	v_mfma_f32_16x16x32_bf16 v[20:23], v[206:209], v[168:171], v[20:23]
	v_mfma_f32_16x16x32_bf16 v[8:11], v[198:201], v[176:179], v[8:11]
	v_mfma_f32_16x16x32_bf16 v[12:15], v[206:209], v[176:179], v[12:15]
	v_mfma_f32_16x16x32_bf16 v[0:3], v[198:201], v[190:193], v[0:3]
	v_mfma_f32_16x16x32_bf16 v[4:7], v[206:209], v[190:193], v[4:7]
	s_add_i32 s65, 0, 0x18000
	v_add_u32_e32 v140, s65, v181
	s_barrier
	ds_read_b128 v[128:131], v140
	ds_read_b128 v[132:135], v140 offset:1024
	ds_read_b128 v[136:139], v140 offset:2048
	ds_read_b128 v[140:143], v140 offset:3072
	s_add_u32 s34, s40, 0x80000
	s_addc_u32 s35, s41, 0
	s_mov_b32 m0, s42
	v_lshl_add_u64 v[194:195], s[34:35], 0, v[156:157]
	ds_read_b128 v[144:147], v184 offset:32768
	ds_read_b128 v[148:151], v184 offset:33792
	ds_read_b128 v[152:155], v184 offset:34816
	ds_read_b128 v[168:171], v184 offset:35840
	ds_read_b128 v[172:175], v184 offset:36864
	ds_read_b128 v[176:179], v184 offset:37888
	ds_read_b128 v[186:189], v184 offset:38912
	ds_read_b128 v[190:193], v184 offset:39936
	global_load_lds_dwordx4 v[194:195], off
	v_lshl_add_u64 v[194:195], s[34:35], 0, v[158:159]
	s_mov_b32 m0, s43
	s_nop 0
	global_load_lds_dwordx4 v[194:195], off
	s_waitcnt lgkmcnt(8)
	s_barrier
	s_waitcnt lgkmcnt(0)
	s_waitcnt lgkmcnt(0)
	v_mfma_f32_16x16x32_bf16 v[124:127], v[128:131], v[144:147], v[124:127]
	v_mfma_f32_16x16x32_bf16 v[120:123], v[136:139], v[144:147], v[120:123]
	v_mfma_f32_16x16x32_bf16 v[116:119], v[128:131], v[152:155], v[116:119]
	v_mfma_f32_16x16x32_bf16 v[112:115], v[136:139], v[152:155], v[112:115]
	v_mfma_f32_16x16x32_bf16 v[104:107], v[128:131], v[172:175], v[104:107]
	v_mfma_f32_16x16x32_bf16 v[108:111], v[136:139], v[172:175], v[108:111]
	v_mfma_f32_16x16x32_bf16 v[96:99], v[128:131], v[186:189], v[96:99]
	v_mfma_f32_16x16x32_bf16 v[100:103], v[136:139], v[186:189], v[100:103]
	v_mfma_f32_16x16x32_bf16 v[124:127], v[132:135], v[148:151], v[124:127]
	v_mfma_f32_16x16x32_bf16 v[120:123], v[140:143], v[148:151], v[120:123]
	v_mfma_f32_16x16x32_bf16 v[116:119], v[132:135], v[168:171], v[116:119]
	v_mfma_f32_16x16x32_bf16 v[112:115], v[140:143], v[168:171], v[112:115]
	v_mfma_f32_16x16x32_bf16 v[104:107], v[132:135], v[176:179], v[104:107]
	v_mfma_f32_16x16x32_bf16 v[108:111], v[140:143], v[176:179], v[108:111]
	v_mfma_f32_16x16x32_bf16 v[96:99], v[132:135], v[190:193], v[96:99]
	v_mfma_f32_16x16x32_bf16 v[100:103], v[140:143], v[190:193], v[100:103]
	s_barrier
	s_add_i32 s40, 0, 0x1c000
	s_add_i32 s34, s65, s4
	v_add_u32_e32 v206, s40, v181
	v_lshl_add_u64 v[210:211], v[210:211], 0, s[10:11]
	s_mov_b32 m0, s34
	ds_read_b128 v[194:197], v206
	ds_read_b128 v[198:201], v206 offset:1024
	ds_read_b128 v[202:205], v206 offset:2048
	ds_read_b128 v[206:209], v206 offset:3072
	global_load_lds_dwordx4 v[210:211], off
	v_lshl_add_u64 v[210:211], v[212:213], 0, s[10:11]
	s_add_i32 m0, s34, 0x2000
	s_nop 0
	global_load_lds_dwordx4 v[210:211], off
	s_barrier
	s_waitcnt lgkmcnt(0)
	s_waitcnt lgkmcnt(0)
	v_mfma_f32_16x16x32_bf16 v[56:59], v[194:197], v[144:147], v[56:59]
	v_mfma_f32_16x16x32_bf16 v[60:63], v[202:205], v[144:147], v[60:63]
	v_mfma_f32_16x16x32_bf16 v[48:51], v[194:197], v[152:155], v[48:51]
	v_mfma_f32_16x16x32_bf16 v[52:55], v[202:205], v[152:155], v[52:55]
	v_mfma_f32_16x16x32_bf16 v[40:43], v[194:197], v[172:175], v[40:43]
	v_mfma_f32_16x16x32_bf16 v[44:47], v[202:205], v[172:175], v[44:47]
	v_mfma_f32_16x16x32_bf16 v[32:35], v[194:197], v[186:189], v[32:35]
	v_mfma_f32_16x16x32_bf16 v[36:39], v[202:205], v[186:189], v[36:39]
	v_mfma_f32_16x16x32_bf16 v[56:59], v[198:201], v[148:151], v[56:59]
	v_mfma_f32_16x16x32_bf16 v[60:63], v[206:209], v[148:151], v[60:63]
	v_mfma_f32_16x16x32_bf16 v[48:51], v[198:201], v[168:171], v[48:51]
	v_mfma_f32_16x16x32_bf16 v[52:55], v[206:209], v[168:171], v[52:55]
	v_mfma_f32_16x16x32_bf16 v[40:43], v[198:201], v[176:179], v[40:43]
	v_mfma_f32_16x16x32_bf16 v[44:47], v[206:209], v[176:179], v[44:47]
	v_mfma_f32_16x16x32_bf16 v[32:35], v[198:201], v[190:193], v[32:35]
	v_mfma_f32_16x16x32_bf16 v[36:39], v[206:209], v[190:193], v[36:39]
	s_mov_b32 m0, s47
	v_lshl_add_u64 v[210:211], v[214:215], 0, s[10:11]
	s_barrier
	ds_read_b128 v[144:147], v184 offset:49152
	ds_read_b128 v[148:151], v184 offset:50176
	ds_read_b128 v[152:155], v184 offset:51200
	ds_read_b128 v[168:171], v184 offset:52224
	ds_read_b128 v[172:175], v184 offset:53248
	ds_read_b128 v[176:179], v184 offset:54272
	ds_read_b128 v[186:189], v184 offset:55296
	ds_read_b128 v[190:193], v184 offset:56320
	global_load_lds_dwordx4 v[210:211], off
	v_lshl_add_u64 v[210:211], v[216:217], 0, s[10:11]
	s_mov_b32 m0, s50
	s_nop 0
	global_load_lds_dwordx4 v[210:211], off
	s_barrier
	s_waitcnt lgkmcnt(0)
	s_waitcnt lgkmcnt(0)
	v_mfma_f32_16x16x32_bf16 v[88:91], v[128:131], v[144:147], v[88:91]
	v_mfma_f32_16x16x32_bf16 v[92:95], v[136:139], v[144:147], v[92:95]
	v_mfma_f32_16x16x32_bf16 v[80:83], v[128:131], v[152:155], v[80:83]
	v_mfma_f32_16x16x32_bf16 v[84:87], v[136:139], v[152:155], v[84:87]
	v_mfma_f32_16x16x32_bf16 v[72:75], v[128:131], v[172:175], v[72:75]
	v_mfma_f32_16x16x32_bf16 v[76:79], v[136:139], v[172:175], v[76:79]
	v_mfma_f32_16x16x32_bf16 v[64:67], v[128:131], v[186:189], v[64:67]
	v_mfma_f32_16x16x32_bf16 v[68:71], v[136:139], v[186:189], v[68:71]
	v_mfma_f32_16x16x32_bf16 v[88:91], v[132:135], v[148:151], v[88:91]
	v_mfma_f32_16x16x32_bf16 v[92:95], v[140:143], v[148:151], v[92:95]
	v_mfma_f32_16x16x32_bf16 v[80:83], v[132:135], v[168:171], v[80:83]
	v_mfma_f32_16x16x32_bf16 v[84:87], v[140:143], v[168:171], v[84:87]
	v_mfma_f32_16x16x32_bf16 v[72:75], v[132:135], v[176:179], v[72:75]
	v_mfma_f32_16x16x32_bf16 v[76:79], v[140:143], v[176:179], v[76:79]
	v_mfma_f32_16x16x32_bf16 v[64:67], v[132:135], v[190:193], v[64:67]
	v_mfma_f32_16x16x32_bf16 v[68:71], v[140:143], v[190:193], v[68:71]
	s_barrier
	s_add_u32 s34, s38, 0x80080
	s_addc_u32 s35, s39, 0
	s_add_i32 s38, s40, s4
	v_lshl_add_u64 v[128:129], s[34:35], 0, v[156:157]
	s_mov_b32 m0, s38
	s_nop 0
	global_load_lds_dwordx4 v[128:129], off
	v_lshl_add_u64 v[128:129], s[34:35], 0, v[158:159]
	s_add_i32 m0, s38, 0x2000
	s_nop 0
	global_load_lds_dwordx4 v[128:129], off
	s_waitcnt vmcnt(6)
	s_barrier
	v_mfma_f32_16x16x32_bf16 v[24:27], v[194:197], v[144:147], v[24:27]
	v_mfma_f32_16x16x32_bf16 v[28:31], v[202:205], v[144:147], v[28:31]
	v_mfma_f32_16x16x32_bf16 v[16:19], v[194:197], v[152:155], v[16:19]
	v_mfma_f32_16x16x32_bf16 v[20:23], v[202:205], v[152:155], v[20:23]
	v_mfma_f32_16x16x32_bf16 v[8:11], v[194:197], v[172:175], v[8:11]
	v_mfma_f32_16x16x32_bf16 v[12:15], v[202:205], v[172:175], v[12:15]
	v_mfma_f32_16x16x32_bf16 v[0:3], v[194:197], v[186:189], v[0:3]
	v_mfma_f32_16x16x32_bf16 v[4:7], v[202:205], v[186:189], v[4:7]
	v_mfma_f32_16x16x32_bf16 v[24:27], v[198:201], v[148:151], v[24:27]
	v_mfma_f32_16x16x32_bf16 v[28:31], v[206:209], v[148:151], v[28:31]
	v_mfma_f32_16x16x32_bf16 v[16:19], v[198:201], v[168:171], v[16:19]
	v_mfma_f32_16x16x32_bf16 v[20:23], v[206:209], v[168:171], v[20:23]
	v_mfma_f32_16x16x32_bf16 v[8:11], v[198:201], v[176:179], v[8:11]
	v_mfma_f32_16x16x32_bf16 v[12:15], v[206:209], v[176:179], v[12:15]
	v_mfma_f32_16x16x32_bf16 v[0:3], v[198:201], v[190:193], v[0:3]
	v_mfma_f32_16x16x32_bf16 v[4:7], v[206:209], v[190:193], v[4:7]
	s_add_i32 s64, s64, 2
	s_add_u32 s62, s62, 0x100
	s_addc_u32 s63, s63, 0
	s_cmp_gt_u32 s64, 29
	s_mov_b64 s[34:35], s[36:37]
	s_barrier
	s_cbranch_scc0 .LBB0_3276
	v_lshl_or_b32 v168, s59, 7, v182
	v_ashrrev_i32_e32 v169, 31, v168
	v_lshlrev_b64 v[140:141], 2, v[168:169]
	v_lshl_add_u64 v[128:129], s[12:13], 0, v[140:141]
	global_load_dwordx4 v[132:135], v[128:129], off
	v_lshl_add_u64 v[128:129], s[8:9], 0, v[140:141]
	s_cmp_lt_u32 s30, 32
	s_movk_i32 s21, 0x3000
	global_load_dwordx4 v[128:131], v[128:129], off
	s_cselect_b32 s21, s21, 0x6000
	s_cmp_gt_i32 s30, 15
	s_cselect_b32 s21, s21, 0
	s_lshl_b32 s21, s21, 2
	s_add_u32 s34, s52, s21
	s_addc_u32 s35, s53, 0
	v_lshl_add_u64 v[170:171], s[34:35], 0, v[140:141]
	v_lshl_add_u32 v142, s30, 8, v180
	global_load_dwordx4 v[136:139], v[170:171], off
	v_or_b32_e32 v144, 16, v142
	v_readlane_b32 s60, v240, 22
	v_ashrrev_i32_e32 v143, 31, v142
	v_ashrrev_i32_e32 v145, 31, v144
	v_readlane_b32 s64, v240, 26
	v_readlane_b32 s65, v240, 27
	v_lshlrev_b64 v[146:147], 13, v[142:143]
	s_mov_b64 s[40:41], s[64:65]
	v_lshlrev_b64 v[144:145], 13, v[144:145]
	v_lshl_add_u64 v[146:147], s[40:41], 0, v[146:147]
	v_lshl_add_u64 v[144:145], s[40:41], 0, v[144:145]
	v_lshl_add_u64 v[174:175], v[146:147], 0, v[140:141]
	v_lshl_add_u64 v[172:173], v[144:145], 0, v[140:141]
	global_load_dwordx4 v[148:151], v[174:175], off
	global_load_dwordx4 v[152:155], v[172:173], off
	v_or_b32_e32 v144, 32, v142
	v_or_b32_e32 v142, 48, v142
	v_ashrrev_i32_e32 v145, 31, v144
	v_ashrrev_i32_e32 v143, 31, v142
	v_lshlrev_b64 v[144:145], 13, v[144:145]
	v_lshlrev_b64 v[142:143], 13, v[142:143]
	v_lshl_add_u64 v[144:145], s[40:41], 0, v[144:145]
	v_lshl_add_u64 v[142:143], s[40:41], 0, v[142:143]
	v_lshl_add_u64 v[178:179], v[144:145], 0, v[140:141]
	v_lshl_add_u64 v[176:177], v[142:143], 0, v[140:141]
	global_load_dwordx4 v[140:143], v[174:175], off offset:256
	global_load_dwordx4 v[186:189], v[178:179], off
	global_load_dwordx4 v[190:193], v[176:177], off
	global_load_dwordx4 v[144:147], v[172:173], off offset:256
	s_mov_b32 s21, 0x100000
	s_mov_b64 s[34:35], 0x100000
	s_mov_b32 s59, s20
	s_mov_b32 s30, s22
	s_mov_b64 s[36:37], s[28:29]
	v_readlane_b32 s61, v240, 23
	v_readlane_b32 s62, v240, 24
	v_readlane_b32 s63, v240, 25
	v_readlane_b32 s66, v240, 28
	v_readlane_b32 s67, v240, 29
	v_readlane_b32 s68, v240, 30
	v_readlane_b32 s69, v240, 31
	v_readlane_b32 s70, v240, 32
	v_readlane_b32 s71, v240, 33
	v_readlane_b32 s72, v240, 34
	v_readlane_b32 s73, v240, 35
	v_readlane_b32 s74, v240, 36
	v_readlane_b32 s75, v240, 37
	s_waitcnt vmcnt(0)
	v_add_f32_e32 v169, v120, v132
	v_add_f32_e32 v194, v121, v133
	v_add_f32_e32 v195, v122, v134
	v_add_f32_e32 v196, v123, v135
	v_pk_add_f32 v[120:121], v[126:127], v[130:131]
	v_pk_add_f32 v[122:123], v[124:125], v[128:129]
	v_add_f32_e32 v124, v112, v132
	v_add_f32_e32 v125, v113, v133
	v_add_f32_e32 v126, v114, v134
	v_add_f32_e32 v127, v115, v135
	v_pk_add_f32 v[112:113], v[118:119], v[130:131]
	v_pk_add_f32 v[114:115], v[116:117], v[128:129]
	v_mul_f32_e32 v116, 0xbfb8aa3b, v169
	v_mul_f32_e32 v117, 0xbfb8aa3b, v194
	v_mul_f32_e32 v118, 0xbfb8aa3b, v195
	v_mul_f32_e32 v119, 0xbfb8aa3b, v196
	v_mul_f32_e32 v124, 0xbfb8aa3b, v124
	v_mul_f32_e32 v125, 0xbfb8aa3b, v125
	v_mul_f32_e32 v126, 0xbfb8aa3b, v126
	v_mul_f32_e32 v127, 0xbfb8aa3b, v127
	v_exp_f32_e32 v169, v116
	v_exp_f32_e32 v194, v117
	v_exp_f32_e32 v195, v118
	v_exp_f32_e32 v196, v119
	v_exp_f32_e32 v124, v124
	v_exp_f32_e32 v125, v125
	v_exp_f32_e32 v126, v126
	v_exp_f32_e32 v127, v127
	v_add_f32_e32 v108, v108, v132
	v_mul_f32_e32 v108, 0xbfb8aa3b, v108
	v_pk_mul_f32 v[116:117], v[138:139], v[120:121]
	v_pk_mul_f32 v[118:119], v[136:137], v[122:123]
	v_pk_mul_f32 v[120:121], v[138:139], v[112:113]
	v_pk_mul_f32 v[122:123], v[136:137], v[114:115]
	v_add_f32_e32 v112, 1.0, v169
	v_add_f32_e32 v113, 1.0, v194
	v_add_f32_e32 v114, 1.0, v195
	v_add_f32_e32 v115, 1.0, v196
	v_add_f32_e32 v124, 1.0, v124
	v_add_f32_e32 v125, 1.0, v125
	v_add_f32_e32 v126, 1.0, v126
	v_add_f32_e32 v127, 1.0, v127
	v_rcp_f32_e32 v112, v112
	v_rcp_f32_e32 v113, v113
	v_rcp_f32_e32 v114, v114
	v_rcp_f32_e32 v115, v115
	v_rcp_f32_e32 v124, v124
	v_rcp_f32_e32 v126, v126
	v_rcp_f32_e32 v127, v127
	v_rcp_f32_e32 v125, v125
	v_exp_f32_e32 v108, v108
	v_add_f32_e32 v109, v109, v133
	v_mul_f32_e32 v109, 0xbfb8aa3b, v109
	v_exp_f32_e32 v109, v109
	v_pk_fma_f32 v[114:115], v[116:117], v[114:115], v[150:151]
	v_pk_fma_f32 v[112:113], v[118:119], v[112:113], v[148:149]
	v_pk_fma_f32 v[118:119], v[120:121], v[126:127], v[154:155]
	v_pk_fma_f32 v[116:117], v[122:123], v[124:125], v[152:153]
	v_add_f32_e32 v108, 1.0, v108
	global_store_dwordx4 v[174:175], v[112:115], off
	global_store_dwordx4 v[172:173], v[116:119], off
	v_add_f32_e32 v100, v100, v132
	v_rcp_f32_e32 v112, v108
	v_add_f32_e32 v108, v110, v134
	v_add_co_u32_e32 v116, vcc, s21, v174
	v_mul_f32_e32 v108, 0xbfb8aa3b, v108
	s_nop 0
	v_addc_co_u32_e32 v117, vcc, 0, v175, vcc
	v_add_f32_e32 v113, 1.0, v109
	v_exp_f32_e32 v114, v108
	v_add_f32_e32 v115, v111, v135
	global_load_dwordx4 v[108:111], v[116:117], off
	v_mul_f32_e32 v115, 0xbfb8aa3b, v115
	v_exp_f32_e32 v115, v115
	v_add_f32_e32 v114, 1.0, v114
	v_mul_f32_e32 v100, 0xbfb8aa3b, v100
	v_rcp_f32_e32 v113, v113
	v_add_f32_e32 v115, 1.0, v115
	v_rcp_f32_e32 v114, v114
	v_rcp_f32_e32 v115, v115
	v_exp_f32_e32 v100, v100
	v_pk_add_f32 v[106:107], v[106:107], v[130:131]
	v_pk_add_f32 v[104:105], v[104:105], v[128:129]
	v_pk_mul_f32 v[118:119], v[138:139], v[106:107]
	v_pk_mul_f32 v[120:121], v[136:137], v[104:105]
	v_pk_fma_f32 v[114:115], v[118:119], v[114:115], v[188:189]
	v_pk_fma_f32 v[112:113], v[120:121], v[112:113], v[186:187]
	v_add_f32_e32 v100, 1.0, v100
	global_store_dwordx4 v[178:179], v[112:115], off
	v_add_f32_e32 v101, v101, v133
	v_mul_f32_e32 v101, 0xbfb8aa3b, v101
	v_rcp_f32_e32 v112, v100
	v_add_f32_e32 v100, v102, v134
	v_mul_f32_e32 v100, 0xbfb8aa3b, v100
	v_exp_f32_e32 v114, v100
	v_add_f32_e32 v100, v103, v135
	v_mul_f32_e32 v115, 0xbfb8aa3b, v100
	v_exp_f32_e32 v101, v101
	v_exp_f32_e32 v115, v115
	v_add_f32_e32 v114, 1.0, v114
	v_rcp_f32_e32 v114, v114
	v_add_f32_e32 v113, 1.0, v101
	v_add_f32_e32 v115, 1.0, v115
	v_rcp_f32_e32 v113, v113
	v_rcp_f32_e32 v115, v115
	v_pk_add_f32 v[98:99], v[98:99], v[130:131]
	v_pk_add_f32 v[96:97], v[96:97], v[128:129]
	v_pk_mul_f32 v[120:121], v[138:139], v[98:99]
	v_pk_mul_f32 v[122:123], v[136:137], v[96:97]
	v_add_f32_e32 v92, v92, v132
	v_pk_fma_f32 v[114:115], v[120:121], v[114:115], v[192:193]
	v_pk_fma_f32 v[112:113], v[122:123], v[112:113], v[190:191]
	v_mul_f32_e32 v92, 0xbfb8aa3b, v92
	global_store_dwordx4 v[176:177], v[112:115], off
	v_add_co_u32_e32 v118, vcc, s56, v174
	s_nop 0
	v_exp_f32_e32 v112, v92
	v_add_f32_e32 v92, v93, v133
	v_mul_f32_e32 v92, 0xbfb8aa3b, v92
	v_addc_co_u32_e32 v119, vcc, 0, v175, vcc
	v_exp_f32_e32 v113, v92
	v_add_f32_e32 v94, v94, v134
	v_add_f32_e32 v95, v95, v135
	global_load_dwordx4 v[100:103], v[118:119], off
	v_mul_f32_e32 v94, 0xbfb8aa3b, v94
	v_mul_f32_e32 v95, 0xbfb8aa3b, v95
	v_add_co_u32_e32 v122, vcc, s57, v174
	v_exp_f32_e32 v94, v94
	v_exp_f32_e32 v95, v95
	v_add_f32_e32 v112, 1.0, v112
	v_addc_co_u32_e32 v123, vcc, 0, v175, vcc
	v_rcp_f32_e32 v120, v112
	v_add_f32_e32 v121, 1.0, v113
	global_load_dwordx4 v[112:115], v[122:123], off
	v_add_f32_e32 v94, 1.0, v94
	v_add_f32_e32 v95, 1.0, v95
	v_rcp_f32_e32 v94, v94
	v_rcp_f32_e32 v95, v95
	v_rcp_f32_e32 v121, v121
	v_pk_add_f32 v[90:91], v[90:91], v[130:131]
	v_pk_add_f32 v[88:89], v[88:89], v[128:129]
	v_pk_mul_f32 v[124:125], v[138:139], v[90:91]
	v_pk_mul_f32 v[126:127], v[136:137], v[88:89]
	v_add_f32_e32 v84, v84, v132
	v_mul_f32_e32 v84, 0xbfb8aa3b, v84
	v_add_f32_e32 v86, v86, v134
	v_add_f32_e32 v87, v87, v135
	v_mul_f32_e32 v86, 0xbfb8aa3b, v86
	s_waitcnt vmcnt(0)
	v_pk_fma_f32 v[110:111], v[124:125], v[94:95], v[110:111]
	v_add_co_u32_e32 v94, vcc, s58, v174
	v_pk_fma_f32 v[108:109], v[126:127], v[120:121], v[108:109]
	s_nop 0
	v_addc_co_u32_e32 v95, vcc, 0, v175, vcc
	global_store_dwordx4 v[116:117], v[108:111], off
	global_load_dwordx4 v[108:111], v[94:95], off
	v_exp_f32_e32 v116, v84
	v_add_f32_e32 v84, v85, v133
	v_mul_f32_e32 v87, 0xbfb8aa3b, v87
	v_mul_f32_e32 v84, 0xbfb8aa3b, v84
	v_exp_f32_e32 v86, v86
	v_exp_f32_e32 v87, v87
	v_exp_f32_e32 v117, v84
	v_add_f32_e32 v78, v78, v134
	v_add_f32_e32 v79, v79, v135
	v_mul_f32_e32 v78, 0xbfb8aa3b, v78
	v_mul_f32_e32 v79, 0xbfb8aa3b, v79
	v_exp_f32_e32 v78, v78
	v_exp_f32_e32 v79, v79
	v_add_f32_e32 v86, 1.0, v86
	v_add_f32_e32 v87, 1.0, v87
	v_add_f32_e32 v116, 1.0, v116
	v_add_f32_e32 v117, 1.0, v117
	v_rcp_f32_e32 v86, v86
	v_rcp_f32_e32 v87, v87
	v_rcp_f32_e32 v116, v116
	v_rcp_f32_e32 v117, v117
	v_pk_add_f32 v[82:83], v[82:83], v[130:131]
	v_add_f32_e32 v76, v76, v132
	v_add_f32_e32 v78, 1.0, v78
	v_add_f32_e32 v79, 1.0, v79
	v_pk_add_f32 v[80:81], v[80:81], v[128:129]
	v_pk_mul_f32 v[120:121], v[138:139], v[82:83]
	v_mul_f32_e32 v76, 0xbfb8aa3b, v76
	v_rcp_f32_e32 v78, v78
	v_rcp_f32_e32 v79, v79
	v_pk_mul_f32 v[124:125], v[136:137], v[80:81]
	v_pk_add_f32 v[74:75], v[74:75], v[130:131]
	v_add_f32_e32 v68, v68, v132
	v_add_f32_e32 v70, v70, v134
	v_add_f32_e32 v71, v71, v135
	v_mul_f32_e32 v68, 0xbfb8aa3b, v68
	v_mul_f32_e32 v70, 0xbfb8aa3b, v70
	v_mul_f32_e32 v71, 0xbfb8aa3b, v71
	v_exp_f32_e32 v70, v70
	v_exp_f32_e32 v71, v71
	v_pk_add_f32 v[72:73], v[72:73], v[128:129]
	v_pk_add_f32 v[66:67], v[66:67], v[130:131]
	v_add_f32_e32 v70, 1.0, v70
	v_add_f32_e32 v71, 1.0, v71
	v_rcp_f32_e32 v70, v70
	v_pk_fma_f32 v[102:103], v[120:121], v[86:87], v[102:103]
	v_exp_f32_e32 v86, v76
	v_add_f32_e32 v76, v77, v133
	v_pk_fma_f32 v[100:101], v[124:125], v[116:117], v[100:101]
	v_mul_f32_e32 v76, 0xbfb8aa3b, v76
	global_store_dwordx4 v[118:119], v[100:103], off
	v_exp_f32_e32 v87, v76
	v_add_f32_e32 v86, 1.0, v86
	v_pk_mul_f32 v[100:101], v[138:139], v[74:75]
	v_rcp_f32_e32 v86, v86
	v_add_f32_e32 v87, 1.0, v87
	v_rcp_f32_e32 v87, v87
	v_pk_fma_f32 v[102:103], v[100:101], v[78:79], v[114:115]
	v_exp_f32_e32 v78, v68
	v_add_f32_e32 v68, v69, v133
	v_mul_f32_e32 v68, 0xbfb8aa3b, v68
	v_exp_f32_e32 v79, v68
	v_rcp_f32_e32 v71, v71
	v_add_f32_e32 v78, 1.0, v78
	v_pk_mul_f32 v[116:117], v[136:137], v[72:73]
	v_add_f32_e32 v79, 1.0, v79
	v_rcp_f32_e32 v78, v78
	v_rcp_f32_e32 v79, v79
	v_pk_fma_f32 v[100:101], v[116:117], v[86:87], v[112:113]
	v_pk_mul_f32 v[86:87], v[138:139], v[66:67]
	global_store_dwordx4 v[122:123], v[100:103], off
	v_pk_add_f32 v[64:65], v[64:65], v[128:129]
	v_lshl_add_u64 v[92:93], v[174:175], 0, s[34:35]
	v_pk_mul_f32 v[100:101], v[136:137], v[64:65]
	v_lshl_add_u64 v[84:85], v[174:175], 0, s[14:15]
	v_lshl_add_u64 v[76:77], v[174:175], 0, s[16:17]
	v_lshl_add_u64 v[68:69], v[174:175], 0, s[18:19]
	global_load_dwordx4 v[104:107], v[178:179], off offset:256
	global_load_dwordx4 v[96:99], v[176:177], off offset:256
	s_waitcnt vmcnt(0)
	v_pk_fma_f32 v[102:103], v[86:87], v[70:71], v[110:111]
	v_or_b32_e32 v70, 64, v168
	v_ashrrev_i32_e32 v71, 31, v70
	v_pk_fma_f32 v[100:101], v[100:101], v[78:79], v[108:109]
	v_lshlrev_b64 v[70:71], 2, v[70:71]
	global_store_dwordx4 v[94:95], v[100:103], off
	v_lshl_add_u64 v[78:79], s[12:13], 0, v[70:71]
	global_load_dwordx4 v[100:103], v[78:79], off
	v_lshl_add_u64 v[70:71], s[8:9], 0, v[70:71]
	global_load_dwordx4 v[88:91], v[92:93], off offset:256
	global_load_dwordx4 v[80:83], v[84:85], off offset:256
	global_load_dwordx4 v[72:75], v[76:77], off offset:256
	global_load_dwordx4 v[64:67], v[68:69], off offset:256
	global_load_dwordx4 v[108:111], v[70:71], off
	global_load_dwordx4 v[112:115], v[170:171], off offset:256
	s_and_b64 vcc, exec, s[6:7]
	s_mov_b64 s[34:35], s[26:27]
	s_waitcnt vmcnt(0)
	v_add_f32_e32 v60, v60, v100
	v_add_f32_e32 v61, v61, v101
	v_add_f32_e32 v62, v62, v102
	v_add_f32_e32 v63, v63, v103
	v_add_f32_e32 v52, v52, v100
	v_add_f32_e32 v53, v53, v101
	v_add_f32_e32 v54, v54, v102
	v_add_f32_e32 v55, v55, v103
	v_add_f32_e32 v44, v44, v100
	v_add_f32_e32 v45, v45, v101
	v_add_f32_e32 v46, v46, v102
	v_add_f32_e32 v47, v47, v103
	v_add_f32_e32 v36, v36, v100
	v_add_f32_e32 v37, v37, v101
	v_add_f32_e32 v38, v38, v102
	v_add_f32_e32 v39, v39, v103
	v_add_f32_e32 v28, v28, v100
	v_add_f32_e32 v29, v29, v101
	v_add_f32_e32 v30, v30, v102
	v_add_f32_e32 v31, v31, v103
	v_add_f32_e32 v20, v20, v100
	v_add_f32_e32 v21, v21, v101
	v_add_f32_e32 v22, v22, v102
	v_add_f32_e32 v23, v23, v103
	v_add_f32_e32 v12, v12, v100
	v_add_f32_e32 v13, v13, v101
	v_add_f32_e32 v14, v14, v102
	v_add_f32_e32 v15, v15, v103
	v_add_f32_e32 v4, v4, v100
	v_add_f32_e32 v5, v5, v101
	v_add_f32_e32 v6, v6, v102
	v_add_f32_e32 v7, v7, v103
	v_mul_f32_e32 v60, 0xbfb8aa3b, v60
	v_mul_f32_e32 v61, 0xbfb8aa3b, v61
	v_mul_f32_e32 v62, 0xbfb8aa3b, v62
	v_mul_f32_e32 v63, 0xbfb8aa3b, v63
	v_mul_f32_e32 v52, 0xbfb8aa3b, v52
	v_mul_f32_e32 v53, 0xbfb8aa3b, v53
	v_mul_f32_e32 v54, 0xbfb8aa3b, v54
	v_mul_f32_e32 v55, 0xbfb8aa3b, v55
	v_mul_f32_e32 v44, 0xbfb8aa3b, v44
	v_mul_f32_e32 v45, 0xbfb8aa3b, v45
	v_mul_f32_e32 v46, 0xbfb8aa3b, v46
	v_mul_f32_e32 v47, 0xbfb8aa3b, v47
	v_mul_f32_e32 v36, 0xbfb8aa3b, v36
	v_mul_f32_e32 v37, 0xbfb8aa3b, v37
	v_mul_f32_e32 v38, 0xbfb8aa3b, v38
	v_mul_f32_e32 v39, 0xbfb8aa3b, v39
	v_mul_f32_e32 v28, 0xbfb8aa3b, v28
	v_mul_f32_e32 v29, 0xbfb8aa3b, v29
	v_mul_f32_e32 v30, 0xbfb8aa3b, v30
	v_mul_f32_e32 v31, 0xbfb8aa3b, v31
	v_mul_f32_e32 v20, 0xbfb8aa3b, v20
	v_mul_f32_e32 v21, 0xbfb8aa3b, v21
	v_mul_f32_e32 v22, 0xbfb8aa3b, v22
	v_mul_f32_e32 v23, 0xbfb8aa3b, v23
	v_mul_f32_e32 v12, 0xbfb8aa3b, v12
	v_mul_f32_e32 v13, 0xbfb8aa3b, v13
	v_mul_f32_e32 v14, 0xbfb8aa3b, v14
	v_mul_f32_e32 v15, 0xbfb8aa3b, v15
	v_mul_f32_e32 v4, 0xbfb8aa3b, v4
	v_mul_f32_e32 v5, 0xbfb8aa3b, v5
	v_mul_f32_e32 v6, 0xbfb8aa3b, v6
	v_mul_f32_e32 v7, 0xbfb8aa3b, v7
	v_exp_f32_e32 v60, v60
	v_exp_f32_e32 v61, v61
	v_exp_f32_e32 v62, v62
	v_exp_f32_e32 v63, v63
	v_exp_f32_e32 v52, v52
	v_exp_f32_e32 v53, v53
	v_exp_f32_e32 v54, v54
	v_exp_f32_e32 v55, v55
	v_exp_f32_e32 v44, v44
	v_exp_f32_e32 v45, v45
	v_exp_f32_e32 v46, v46
	v_exp_f32_e32 v47, v47
	v_exp_f32_e32 v36, v36
	v_exp_f32_e32 v37, v37
	v_exp_f32_e32 v38, v38
	v_exp_f32_e32 v39, v39
	v_exp_f32_e32 v28, v28
	v_exp_f32_e32 v29, v29
	v_exp_f32_e32 v30, v30
	v_exp_f32_e32 v31, v31
	v_exp_f32_e32 v20, v20
	v_exp_f32_e32 v21, v21
	v_exp_f32_e32 v22, v22
	v_exp_f32_e32 v23, v23
	v_exp_f32_e32 v12, v12
	v_exp_f32_e32 v13, v13
	v_exp_f32_e32 v14, v14
	v_exp_f32_e32 v15, v15
	v_exp_f32_e32 v4, v4
	v_exp_f32_e32 v5, v5
	v_exp_f32_e32 v6, v6
	v_exp_f32_e32 v7, v7
	v_add_f32_e32 v60, 1.0, v60
	v_add_f32_e32 v61, 1.0, v61
	v_add_f32_e32 v62, 1.0, v62
	v_add_f32_e32 v63, 1.0, v63
	v_add_f32_e32 v52, 1.0, v52
	v_add_f32_e32 v53, 1.0, v53
	v_add_f32_e32 v54, 1.0, v54
	v_add_f32_e32 v55, 1.0, v55
	v_add_f32_e32 v44, 1.0, v44
	v_add_f32_e32 v45, 1.0, v45
	v_add_f32_e32 v46, 1.0, v46
	v_add_f32_e32 v47, 1.0, v47
	v_add_f32_e32 v36, 1.0, v36
	v_add_f32_e32 v37, 1.0, v37
	v_add_f32_e32 v38, 1.0, v38
	v_add_f32_e32 v39, 1.0, v39
	v_add_f32_e32 v28, 1.0, v28
	v_add_f32_e32 v29, 1.0, v29
	v_add_f32_e32 v30, 1.0, v30
	v_add_f32_e32 v31, 1.0, v31
	v_add_f32_e32 v20, 1.0, v20
	v_add_f32_e32 v21, 1.0, v21
	v_add_f32_e32 v22, 1.0, v22
	v_add_f32_e32 v23, 1.0, v23
	v_add_f32_e32 v12, 1.0, v12
	v_add_f32_e32 v13, 1.0, v13
	v_add_f32_e32 v14, 1.0, v14
	v_add_f32_e32 v15, 1.0, v15
	v_add_f32_e32 v4, 1.0, v4
	v_add_f32_e32 v5, 1.0, v5
	v_add_f32_e32 v6, 1.0, v6
	v_add_f32_e32 v7, 1.0, v7
	v_rcp_f32_e32 v60, v60
	v_rcp_f32_e32 v61, v61
	v_rcp_f32_e32 v62, v62
	v_rcp_f32_e32 v63, v63
	v_rcp_f32_e32 v52, v52
	v_rcp_f32_e32 v53, v53
	v_rcp_f32_e32 v54, v54
	v_rcp_f32_e32 v55, v55
	v_rcp_f32_e32 v44, v44
	v_rcp_f32_e32 v45, v45
	v_rcp_f32_e32 v46, v46
	v_rcp_f32_e32 v47, v47
	v_rcp_f32_e32 v36, v36
	v_rcp_f32_e32 v37, v37
	v_rcp_f32_e32 v38, v38
	v_rcp_f32_e32 v39, v39
	v_rcp_f32_e32 v28, v28
	v_rcp_f32_e32 v29, v29
	v_rcp_f32_e32 v30, v30
	v_rcp_f32_e32 v31, v31
	v_rcp_f32_e32 v20, v20
	v_rcp_f32_e32 v21, v21
	v_rcp_f32_e32 v22, v22
	v_rcp_f32_e32 v23, v23
	v_rcp_f32_e32 v12, v12
	v_rcp_f32_e32 v13, v13
	v_rcp_f32_e32 v14, v14
	v_rcp_f32_e32 v15, v15
	v_rcp_f32_e32 v4, v4
	v_rcp_f32_e32 v5, v5
	v_rcp_f32_e32 v6, v6
	v_rcp_f32_e32 v7, v7
	v_pk_add_f32 v[58:59], v[58:59], v[110:111]
	v_pk_add_f32 v[56:57], v[56:57], v[108:109]
	v_pk_add_f32 v[50:51], v[50:51], v[110:111]
	v_pk_add_f32 v[48:49], v[48:49], v[108:109]
	v_pk_add_f32 v[42:43], v[42:43], v[110:111]
	v_pk_add_f32 v[40:41], v[40:41], v[108:109]
	v_pk_add_f32 v[34:35], v[34:35], v[110:111]
	v_pk_add_f32 v[32:33], v[32:33], v[108:109]
	v_pk_add_f32 v[26:27], v[26:27], v[110:111]
	v_pk_add_f32 v[24:25], v[24:25], v[108:109]
	v_pk_add_f32 v[18:19], v[18:19], v[110:111]
	v_pk_add_f32 v[16:17], v[16:17], v[108:109]
	v_pk_add_f32 v[10:11], v[10:11], v[110:111]
	v_pk_add_f32 v[8:9], v[8:9], v[108:109]
	v_pk_add_f32 v[2:3], v[2:3], v[110:111]
	v_pk_add_f32 v[0:1], v[0:1], v[108:109]
	v_pk_mul_f32 v[58:59], v[114:115], v[58:59]
	v_pk_mul_f32 v[56:57], v[112:113], v[56:57]
	v_pk_mul_f32 v[50:51], v[114:115], v[50:51]
	v_pk_mul_f32 v[48:49], v[112:113], v[48:49]
	v_pk_mul_f32 v[42:43], v[114:115], v[42:43]
	v_pk_mul_f32 v[40:41], v[112:113], v[40:41]
	v_pk_mul_f32 v[34:35], v[114:115], v[34:35]
	v_pk_mul_f32 v[32:33], v[112:113], v[32:33]
	v_pk_mul_f32 v[26:27], v[114:115], v[26:27]
	v_pk_mul_f32 v[24:25], v[112:113], v[24:25]
	v_pk_mul_f32 v[18:19], v[114:115], v[18:19]
	v_pk_mul_f32 v[16:17], v[112:113], v[16:17]
	v_pk_mul_f32 v[10:11], v[114:115], v[10:11]
	v_pk_mul_f32 v[8:9], v[112:113], v[8:9]
	v_pk_mul_f32 v[2:3], v[114:115], v[2:3]
	v_pk_mul_f32 v[0:1], v[112:113], v[0:1]
	v_pk_fma_f32 v[58:59], v[58:59], v[62:63], v[142:143]
	v_pk_fma_f32 v[56:57], v[56:57], v[60:61], v[140:141]
	v_pk_fma_f32 v[48:49], v[48:49], v[52:53], v[144:145]
	v_pk_fma_f32 v[50:51], v[50:51], v[54:55], v[146:147]
	v_pk_fma_f32 v[40:41], v[40:41], v[44:45], v[104:105]
	v_pk_fma_f32 v[42:43], v[42:43], v[46:47], v[106:107]
	v_pk_fma_f32 v[32:33], v[32:33], v[36:37], v[96:97]
	v_pk_fma_f32 v[34:35], v[34:35], v[38:39], v[98:99]
	v_pk_fma_f32 v[24:25], v[24:25], v[28:29], v[88:89]
	v_pk_fma_f32 v[26:27], v[26:27], v[30:31], v[90:91]
	v_pk_fma_f32 v[16:17], v[16:17], v[20:21], v[80:81]
	v_pk_fma_f32 v[18:19], v[18:19], v[22:23], v[82:83]
	v_pk_fma_f32 v[8:9], v[8:9], v[12:13], v[72:73]
	v_pk_fma_f32 v[10:11], v[10:11], v[14:15], v[74:75]
	v_pk_fma_f32 v[0:1], v[0:1], v[4:5], v[64:65]
	v_pk_fma_f32 v[2:3], v[2:3], v[6:7], v[66:67]
	global_store_dwordx4 v[174:175], v[56:59], off offset:256
	global_store_dwordx4 v[172:173], v[48:51], off offset:256
	global_store_dwordx4 v[178:179], v[40:43], off offset:256
	global_store_dwordx4 v[176:177], v[32:35], off offset:256
	global_store_dwordx4 v[92:93], v[24:27], off offset:256
	global_store_dwordx4 v[84:85], v[16:19], off offset:256
	global_store_dwordx4 v[76:77], v[8:11], off offset:256
	global_store_dwordx4 v[68:69], v[0:3], off offset:256
	s_cbranch_vccz .LBB0_3269
	s_waitcnt vmcnt(0)
	s_cmpk_gt_u32 s0, 0xff
	s_cbranch_scc1 .LBB0_3280
	s_barrier

.LBB0_3443:
	ds_read_b128 v[148:151], v144
	ds_read_b128 v[152:155], v144 offset:1024
	ds_read_b128 v[156:159], v144 offset:2048
	ds_read_b128 v[160:163], v144 offset:3072
	s_add_u32 s20, s18, 0x100
	s_addc_u32 s21, s19, 0
	s_cmp_eq_u32 s46, 28
	s_cselect_b32 s25, s11, s21
	s_cselect_b32 s24, s40, s20
	s_cselect_b32 s23, s9, s43
	s_cselect_b32 s22, s41, s42
	v_lshl_add_u64 v[196:197], s[18:19], 0, v[134:135]
	s_add_i32 m0, s26, 0xc000
	ds_read_b128 v[164:167], v145
	ds_read_b128 v[168:171], v145 offset:1024
	ds_read_b128 v[172:175], v145 offset:2048
	ds_read_b128 v[176:179], v145 offset:3072
	ds_read_b128 v[180:183], v145 offset:4096
	ds_read_b128 v[184:187], v145 offset:5120
	ds_read_b128 v[188:191], v145 offset:6144
	ds_read_b128 v[192:195], v145 offset:7168
	global_load_lds_dwordx4 v[196:197], off
	v_lshl_add_u64 v[196:197], s[18:19], 0, v[136:137]
	s_add_i32 m0, s26, 0xe000
	s_nop 0
	global_load_lds_dwordx4 v[196:197], off
	s_waitcnt lgkmcnt(8)
	s_barrier
	s_waitcnt lgkmcnt(0)
	s_waitcnt lgkmcnt(0)
	v_mfma_f32_16x16x32_bf16 v[124:127], v[148:151], v[164:167], v[124:127]
	v_mfma_f32_16x16x32_bf16 v[120:123], v[156:159], v[164:167], v[120:123]
	v_mfma_f32_16x16x32_bf16 v[108:111], v[148:151], v[172:175], v[108:111]
	v_mfma_f32_16x16x32_bf16 v[104:107], v[156:159], v[172:175], v[104:107]
	v_mfma_f32_16x16x32_bf16 v[92:95], v[148:151], v[180:183], v[92:95]
	v_mfma_f32_16x16x32_bf16 v[88:91], v[156:159], v[180:183], v[88:91]
	v_mfma_f32_16x16x32_bf16 v[76:79], v[148:151], v[188:191], v[76:79]
	v_mfma_f32_16x16x32_bf16 v[72:75], v[156:159], v[188:191], v[72:75]
	v_mfma_f32_16x16x32_bf16 v[124:127], v[152:155], v[168:171], v[124:127]
	v_mfma_f32_16x16x32_bf16 v[120:123], v[160:163], v[168:171], v[120:123]
	v_mfma_f32_16x16x32_bf16 v[108:111], v[152:155], v[176:179], v[108:111]
	v_mfma_f32_16x16x32_bf16 v[104:107], v[160:163], v[176:179], v[104:107]
	v_mfma_f32_16x16x32_bf16 v[92:95], v[152:155], v[184:187], v[92:95]
	v_mfma_f32_16x16x32_bf16 v[88:91], v[160:163], v[184:187], v[88:91]
	v_mfma_f32_16x16x32_bf16 v[76:79], v[152:155], v[192:195], v[76:79]
	v_mfma_f32_16x16x32_bf16 v[72:75], v[160:163], v[192:195], v[72:75]
	s_barrier
	s_add_i32 s18, s37, s1
	v_lshl_add_u64 v[212:213], s[22:23], 0, v[130:131]
	s_mov_b32 m0, s18
	ds_read_b128 v[196:199], v146
	ds_read_b128 v[200:203], v146 offset:1024
	ds_read_b128 v[204:207], v146 offset:2048
	ds_read_b128 v[208:211], v146 offset:3072
	global_load_lds_dwordx4 v[212:213], off
	v_lshl_add_u64 v[214:215], s[22:23], 0, v[128:129]
	s_add_i32 m0, s18, 0x2000
	s_nop 0
	global_load_lds_dwordx4 v[214:215], off
	s_barrier
	s_waitcnt lgkmcnt(0)
	s_waitcnt lgkmcnt(0)
	v_mfma_f32_16x16x32_bf16 v[116:119], v[196:199], v[164:167], v[116:119]
	v_mfma_f32_16x16x32_bf16 v[112:115], v[204:207], v[164:167], v[112:115]
	v_mfma_f32_16x16x32_bf16 v[100:103], v[196:199], v[172:175], v[100:103]
	v_mfma_f32_16x16x32_bf16 v[96:99], v[204:207], v[172:175], v[96:99]
	v_mfma_f32_16x16x32_bf16 v[84:87], v[196:199], v[180:183], v[84:87]
	v_mfma_f32_16x16x32_bf16 v[80:83], v[204:207], v[180:183], v[80:83]
	v_mfma_f32_16x16x32_bf16 v[68:71], v[196:199], v[188:191], v[68:71]
	v_mfma_f32_16x16x32_bf16 v[64:67], v[204:207], v[188:191], v[64:67]
	v_mfma_f32_16x16x32_bf16 v[116:119], v[200:203], v[168:171], v[116:119]
	v_mfma_f32_16x16x32_bf16 v[112:115], v[208:211], v[168:171], v[112:115]
	v_mfma_f32_16x16x32_bf16 v[100:103], v[200:203], v[176:179], v[100:103]
	v_mfma_f32_16x16x32_bf16 v[96:99], v[208:211], v[176:179], v[96:99]
	v_mfma_f32_16x16x32_bf16 v[84:87], v[200:203], v[184:187], v[84:87]
	v_mfma_f32_16x16x32_bf16 v[80:83], v[208:211], v[184:187], v[80:83]
	v_mfma_f32_16x16x32_bf16 v[68:71], v[200:203], v[192:195], v[68:71]
	v_mfma_f32_16x16x32_bf16 v[64:67], v[208:211], v[192:195], v[64:67]
	s_mov_b32 m0, s26
	v_lshl_add_u64 v[216:217], s[24:25], 0, v[130:131]
	s_barrier
	ds_read_b128 v[164:167], v145 offset:16384
	ds_read_b128 v[168:171], v145 offset:17408
	ds_read_b128 v[172:175], v145 offset:18432
	ds_read_b128 v[176:179], v145 offset:19456
	ds_read_b128 v[180:183], v145 offset:20480
	ds_read_b128 v[184:187], v145 offset:21504
	ds_read_b128 v[188:191], v145 offset:22528
	ds_read_b128 v[192:195], v145 offset:23552
	global_load_lds_dwordx4 v[216:217], off
	v_lshl_add_u64 v[218:219], s[24:25], 0, v[128:129]
	s_mov_b32 m0, s27
	s_nop 0
	global_load_lds_dwordx4 v[218:219], off
	s_barrier
	s_waitcnt lgkmcnt(0)
	s_waitcnt lgkmcnt(0)
	v_mfma_f32_16x16x32_bf16 v[60:63], v[148:151], v[164:167], v[60:63]
	v_mfma_f32_16x16x32_bf16 v[56:59], v[156:159], v[164:167], v[56:59]
	v_mfma_f32_16x16x32_bf16 v[44:47], v[148:151], v[172:175], v[44:47]
	v_mfma_f32_16x16x32_bf16 v[40:43], v[156:159], v[172:175], v[40:43]
	v_mfma_f32_16x16x32_bf16 v[28:31], v[148:151], v[180:183], v[28:31]
	v_mfma_f32_16x16x32_bf16 v[24:27], v[156:159], v[180:183], v[24:27]
	v_mfma_f32_16x16x32_bf16 v[12:15], v[148:151], v[188:191], v[12:15]
	v_mfma_f32_16x16x32_bf16 v[8:11], v[156:159], v[188:191], v[8:11]
	v_mfma_f32_16x16x32_bf16 v[60:63], v[152:155], v[168:171], v[60:63]
	v_mfma_f32_16x16x32_bf16 v[56:59], v[160:163], v[168:171], v[56:59]
	v_mfma_f32_16x16x32_bf16 v[44:47], v[152:155], v[176:179], v[44:47]
	v_mfma_f32_16x16x32_bf16 v[40:43], v[160:163], v[176:179], v[40:43]
	v_mfma_f32_16x16x32_bf16 v[28:31], v[152:155], v[184:187], v[28:31]
	v_mfma_f32_16x16x32_bf16 v[24:27], v[160:163], v[184:187], v[24:27]
	v_mfma_f32_16x16x32_bf16 v[12:15], v[152:155], v[192:195], v[12:15]
	v_mfma_f32_16x16x32_bf16 v[8:11], v[160:163], v[192:195], v[8:11]
	s_barrier
	s_add_u32 s18, s22, 0x80000
	s_addc_u32 s19, s23, 0
	s_add_i32 s47, s38, s1
	v_lshl_add_u64 v[148:149], s[18:19], 0, v[130:131]
	s_mov_b32 m0, s47
	s_nop 0
	global_load_lds_dwordx4 v[148:149], off
	v_lshl_add_u64 v[148:149], s[18:19], 0, v[128:129]
	s_add_i32 m0, s47, 0x2000
	s_nop 0
	global_load_lds_dwordx4 v[148:149], off
	s_waitcnt vmcnt(6)
	s_barrier
	v_mfma_f32_16x16x32_bf16 v[52:55], v[196:199], v[164:167], v[52:55]
	v_mfma_f32_16x16x32_bf16 v[48:51], v[204:207], v[164:167], v[48:51]
	v_mfma_f32_16x16x32_bf16 v[36:39], v[196:199], v[172:175], v[36:39]
	v_mfma_f32_16x16x32_bf16 v[32:35], v[204:207], v[172:175], v[32:35]
	v_mfma_f32_16x16x32_bf16 v[20:23], v[196:199], v[180:183], v[20:23]
	v_mfma_f32_16x16x32_bf16 v[16:19], v[204:207], v[180:183], v[16:19]
	v_mfma_f32_16x16x32_bf16 v[4:7], v[196:199], v[188:191], v[4:7]
	v_mfma_f32_16x16x32_bf16 v[0:3], v[204:207], v[188:191], v[0:3]
	v_mfma_f32_16x16x32_bf16 v[52:55], v[200:203], v[168:171], v[52:55]
	v_mfma_f32_16x16x32_bf16 v[48:51], v[208:211], v[168:171], v[48:51]
	v_mfma_f32_16x16x32_bf16 v[36:39], v[200:203], v[176:179], v[36:39]
	v_mfma_f32_16x16x32_bf16 v[32:35], v[208:211], v[176:179], v[32:35]
	v_mfma_f32_16x16x32_bf16 v[20:23], v[200:203], v[184:187], v[20:23]
	v_mfma_f32_16x16x32_bf16 v[16:19], v[208:211], v[184:187], v[16:19]
	v_mfma_f32_16x16x32_bf16 v[4:7], v[200:203], v[192:195], v[4:7]
	v_mfma_f32_16x16x32_bf16 v[0:3], v[208:211], v[192:195], v[0:3]
	s_add_i32 s47, 0, 0x18000
	v_add_u32_e32 v147, s47, v143
	s_barrier
	ds_read_b128 v[148:151], v147
	ds_read_b128 v[152:155], v147 offset:1024
	ds_read_b128 v[156:159], v147 offset:2048
	ds_read_b128 v[160:163], v147 offset:3072
	s_add_u32 s18, s24, 0x80000
	s_addc_u32 s19, s25, 0
	s_mov_b32 m0, s28
	v_lshl_add_u64 v[196:197], s[18:19], 0, v[130:131]
	ds_read_b128 v[164:167], v145 offset:32768
	ds_read_b128 v[168:171], v145 offset:33792
	ds_read_b128 v[172:175], v145 offset:34816
	ds_read_b128 v[176:179], v145 offset:35840
	ds_read_b128 v[180:183], v145 offset:36864
	ds_read_b128 v[184:187], v145 offset:37888
	ds_read_b128 v[188:191], v145 offset:38912
	ds_read_b128 v[192:195], v145 offset:39936
	global_load_lds_dwordx4 v[196:197], off
	v_lshl_add_u64 v[196:197], s[18:19], 0, v[128:129]
	s_mov_b32 m0, s29
	s_nop 0
	global_load_lds_dwordx4 v[196:197], off
	s_waitcnt lgkmcnt(8)
	s_barrier
	s_waitcnt lgkmcnt(0)
	s_waitcnt lgkmcnt(0)
	v_mfma_f32_16x16x32_bf16 v[124:127], v[148:151], v[164:167], v[124:127]
	v_mfma_f32_16x16x32_bf16 v[120:123], v[156:159], v[164:167], v[120:123]
	v_mfma_f32_16x16x32_bf16 v[108:111], v[148:151], v[172:175], v[108:111]
	v_mfma_f32_16x16x32_bf16 v[104:107], v[156:159], v[172:175], v[104:107]
	v_mfma_f32_16x16x32_bf16 v[92:95], v[148:151], v[180:183], v[92:95]
	v_mfma_f32_16x16x32_bf16 v[88:91], v[156:159], v[180:183], v[88:91]
	v_mfma_f32_16x16x32_bf16 v[76:79], v[148:151], v[188:191], v[76:79]
	v_mfma_f32_16x16x32_bf16 v[72:75], v[156:159], v[188:191], v[72:75]
	v_mfma_f32_16x16x32_bf16 v[124:127], v[152:155], v[168:171], v[124:127]
	v_mfma_f32_16x16x32_bf16 v[120:123], v[160:163], v[168:171], v[120:123]
	v_mfma_f32_16x16x32_bf16 v[108:111], v[152:155], v[176:179], v[108:111]
	v_mfma_f32_16x16x32_bf16 v[104:107], v[160:163], v[176:179], v[104:107]
	v_mfma_f32_16x16x32_bf16 v[92:95], v[152:155], v[184:187], v[92:95]
	v_mfma_f32_16x16x32_bf16 v[88:91], v[160:163], v[184:187], v[88:91]
	v_mfma_f32_16x16x32_bf16 v[76:79], v[152:155], v[192:195], v[76:79]
	v_mfma_f32_16x16x32_bf16 v[72:75], v[160:163], v[192:195], v[72:75]
	s_barrier
	s_add_i32 s24, 0, 0x1c000
	s_add_i32 s18, s47, s1
	v_add_u32_e32 v147, s24, v143
	v_lshl_add_u64 v[212:213], v[212:213], 0, s[6:7]
	s_mov_b32 m0, s18
	ds_read_b128 v[196:199], v147
	ds_read_b128 v[200:203], v147 offset:1024
	ds_read_b128 v[204:207], v147 offset:2048
	ds_read_b128 v[208:211], v147 offset:3072
	global_load_lds_dwordx4 v[212:213], off
	v_lshl_add_u64 v[212:213], v[214:215], 0, s[6:7]
	s_add_i32 m0, s18, 0x2000
	s_nop 0
	global_load_lds_dwordx4 v[212:213], off
	s_barrier
	s_waitcnt lgkmcnt(0)
	s_waitcnt lgkmcnt(0)
	v_mfma_f32_16x16x32_bf16 v[116:119], v[196:199], v[164:167], v[116:119]
	v_mfma_f32_16x16x32_bf16 v[112:115], v[204:207], v[164:167], v[112:115]
	v_mfma_f32_16x16x32_bf16 v[100:103], v[196:199], v[172:175], v[100:103]
	v_mfma_f32_16x16x32_bf16 v[96:99], v[204:207], v[172:175], v[96:99]
	v_mfma_f32_16x16x32_bf16 v[84:87], v[196:199], v[180:183], v[84:87]
	v_mfma_f32_16x16x32_bf16 v[80:83], v[204:207], v[180:183], v[80:83]
	v_mfma_f32_16x16x32_bf16 v[68:71], v[196:199], v[188:191], v[68:71]
	v_mfma_f32_16x16x32_bf16 v[64:67], v[204:207], v[188:191], v[64:67]
	v_mfma_f32_16x16x32_bf16 v[116:119], v[200:203], v[168:171], v[116:119]
	v_mfma_f32_16x16x32_bf16 v[112:115], v[208:211], v[168:171], v[112:115]
	v_mfma_f32_16x16x32_bf16 v[100:103], v[200:203], v[176:179], v[100:103]
	v_mfma_f32_16x16x32_bf16 v[96:99], v[208:211], v[176:179], v[96:99]
	v_mfma_f32_16x16x32_bf16 v[84:87], v[200:203], v[184:187], v[84:87]
	v_mfma_f32_16x16x32_bf16 v[80:83], v[208:211], v[184:187], v[80:83]
	v_mfma_f32_16x16x32_bf16 v[68:71], v[200:203], v[192:195], v[68:71]
	v_mfma_f32_16x16x32_bf16 v[64:67], v[208:211], v[192:195], v[64:67]
	s_mov_b32 m0, s31
	v_lshl_add_u64 v[212:213], v[216:217], 0, s[6:7]
	s_barrier
	ds_read_b128 v[164:167], v145 offset:49152
	ds_read_b128 v[168:171], v145 offset:50176
	ds_read_b128 v[172:175], v145 offset:51200
	ds_read_b128 v[176:179], v145 offset:52224
	ds_read_b128 v[180:183], v145 offset:53248
	ds_read_b128 v[184:187], v145 offset:54272
	ds_read_b128 v[188:191], v145 offset:55296
	ds_read_b128 v[192:195], v145 offset:56320
	global_load_lds_dwordx4 v[212:213], off
	v_lshl_add_u64 v[212:213], v[218:219], 0, s[6:7]
	s_mov_b32 m0, s34
	s_nop 0
	global_load_lds_dwordx4 v[212:213], off
	s_barrier
	s_waitcnt lgkmcnt(0)
	s_waitcnt lgkmcnt(0)
	v_mfma_f32_16x16x32_bf16 v[60:63], v[148:151], v[164:167], v[60:63]
	v_mfma_f32_16x16x32_bf16 v[56:59], v[156:159], v[164:167], v[56:59]
	v_mfma_f32_16x16x32_bf16 v[44:47], v[148:151], v[172:175], v[44:47]
	v_mfma_f32_16x16x32_bf16 v[40:43], v[156:159], v[172:175], v[40:43]
	v_mfma_f32_16x16x32_bf16 v[28:31], v[148:151], v[180:183], v[28:31]
	v_mfma_f32_16x16x32_bf16 v[24:27], v[156:159], v[180:183], v[24:27]
	v_mfma_f32_16x16x32_bf16 v[12:15], v[148:151], v[188:191], v[12:15]
	v_mfma_f32_16x16x32_bf16 v[8:11], v[156:159], v[188:191], v[8:11]
	v_mfma_f32_16x16x32_bf16 v[60:63], v[152:155], v[168:171], v[60:63]
	v_mfma_f32_16x16x32_bf16 v[56:59], v[160:163], v[168:171], v[56:59]
	v_mfma_f32_16x16x32_bf16 v[44:47], v[152:155], v[176:179], v[44:47]
	v_mfma_f32_16x16x32_bf16 v[40:43], v[160:163], v[176:179], v[40:43]
	v_mfma_f32_16x16x32_bf16 v[28:31], v[152:155], v[184:187], v[28:31]
	v_mfma_f32_16x16x32_bf16 v[24:27], v[160:163], v[184:187], v[24:27]
	v_mfma_f32_16x16x32_bf16 v[12:15], v[152:155], v[192:195], v[12:15]
	v_mfma_f32_16x16x32_bf16 v[8:11], v[160:163], v[192:195], v[8:11]
	s_barrier
	s_add_u32 s18, s22, 0x80080
	s_addc_u32 s19, s23, 0
	s_add_i32 s22, s24, s1
	v_lshl_add_u64 v[148:149], s[18:19], 0, v[130:131]
	s_mov_b32 m0, s22
	s_nop 0
	global_load_lds_dwordx4 v[148:149], off
	v_lshl_add_u64 v[148:149], s[18:19], 0, v[128:129]
	s_add_i32 m0, s22, 0x2000
	s_nop 0
	global_load_lds_dwordx4 v[148:149], off
	s_waitcnt vmcnt(6)
	s_barrier
	v_mfma_f32_16x16x32_bf16 v[52:55], v[196:199], v[164:167], v[52:55]
	v_mfma_f32_16x16x32_bf16 v[48:51], v[204:207], v[164:167], v[48:51]
	v_mfma_f32_16x16x32_bf16 v[36:39], v[196:199], v[172:175], v[36:39]
	v_mfma_f32_16x16x32_bf16 v[32:35], v[204:207], v[172:175], v[32:35]
	v_mfma_f32_16x16x32_bf16 v[20:23], v[196:199], v[180:183], v[20:23]
	v_mfma_f32_16x16x32_bf16 v[16:19], v[204:207], v[180:183], v[16:19]
	v_mfma_f32_16x16x32_bf16 v[4:7], v[196:199], v[188:191], v[4:7]
	v_mfma_f32_16x16x32_bf16 v[0:3], v[204:207], v[188:191], v[0:3]
	v_mfma_f32_16x16x32_bf16 v[52:55], v[200:203], v[168:171], v[52:55]
	v_mfma_f32_16x16x32_bf16 v[48:51], v[208:211], v[168:171], v[48:51]
	v_mfma_f32_16x16x32_bf16 v[36:39], v[200:203], v[176:179], v[36:39]
	v_mfma_f32_16x16x32_bf16 v[32:35], v[208:211], v[176:179], v[32:35]
	v_mfma_f32_16x16x32_bf16 v[20:23], v[200:203], v[184:187], v[20:23]
	v_mfma_f32_16x16x32_bf16 v[16:19], v[208:211], v[184:187], v[16:19]
	v_mfma_f32_16x16x32_bf16 v[4:7], v[200:203], v[192:195], v[4:7]
	v_mfma_f32_16x16x32_bf16 v[0:3], v[208:211], v[192:195], v[0:3]
	s_add_i32 s46, s46, 2
	s_add_u32 s42, s42, 0x100
	s_addc_u32 s43, s43, 0
	s_cmp_gt_u32 s46, 29
	s_mov_b64 s[18:19], s[20:21]
	s_barrier
	s_cbranch_scc0 .LBB0_3443
	v_mul_f32_e32 v148, 0xbfb8aa3b, v124
	v_exp_f32_e32 v150, v148
	v_mul_f32_e32 v148, 0xbfb8aa3b, v125
	v_exp_f32_e32 v151, v148
	v_mul_f32_e32 v152, 0xbfb8aa3b, v126
	v_mul_f32_e32 v153, 0xbfb8aa3b, v127
	v_exp_f32_e32 v152, v152
	v_exp_f32_e32 v153, v153
	v_add_f32_e32 v150, 1.0, v150
	v_add_f32_e32 v151, 1.0, v151
	v_rcp_f32_e32 v150, v150
	v_rcp_f32_e32 v151, v151
	v_add_f32_e32 v152, 1.0, v152
	v_add_f32_e32 v153, 1.0, v153
	v_rcp_f32_e32 v152, v152
	v_rcp_f32_e32 v153, v153
	v_pk_mul_f32 v[124:125], v[124:125], v[150:151]
	s_lshl_b32 s9, s17, 7
	v_pk_mul_f32 v[120:121], v[120:121], v[124:125]
	v_pk_mul_f32 v[124:125], v[126:127], v[152:153]
	v_lshl_add_u32 v147, s16, 8, v142
	v_pk_mul_f32 v[122:123], v[122:123], v[124:125]
	v_mul_f32_e32 v124, 0xbfb8aa3b, v116
	v_mul_f32_e32 v125, 0xbfb8aa3b, v117
	s_or_b32 s16, s9, s35
	v_exp_f32_e32 v124, v124
	v_exp_f32_e32 v125, v125
	s_ashr_i32 s17, s16, 31
	v_mad_i64_i32 v[148:149], s[18:19], v147, s39, v[132:133]
	s_lshl_b64 s[16:17], s[16:17], 1
	v_cvt_pk_bf16_f32 v120, v120, v121
	v_cvt_pk_bf16_f32 v121, v122, v123
	v_lshl_add_u64 v[122:123], v[148:149], 0, s[16:17]
	global_store_dwordx2 v[122:123], v[120:121], off
	v_add_f32_e32 v120, 1.0, v124
	v_add_f32_e32 v121, 1.0, v125
	v_mul_f32_e32 v124, 0xbfb8aa3b, v118
	v_mul_f32_e32 v125, 0xbfb8aa3b, v119
	v_exp_f32_e32 v124, v124
	v_exp_f32_e32 v125, v125
	v_rcp_f32_e32 v120, v120
	v_rcp_f32_e32 v121, v121
	v_add_f32_e32 v124, 1.0, v124
	v_add_f32_e32 v125, 1.0, v125
	v_rcp_f32_e32 v124, v124
	v_rcp_f32_e32 v125, v125
	v_pk_mul_f32 v[116:117], v[116:117], v[120:121]
	s_and_b64 vcc, exec, s[4:5]
	v_pk_mul_f32 v[112:113], v[112:113], v[116:117]
	v_pk_mul_f32 v[116:117], v[118:119], v[124:125]
	v_cvt_pk_bf16_f32 v112, v112, v113
	v_pk_mul_f32 v[114:115], v[114:115], v[116:117]
	v_mul_f32_e32 v116, 0xbfb8aa3b, v110
	v_cvt_pk_bf16_f32 v113, v114, v115
	global_store_dwordx2 v[122:123], v[112:113], off offset:128
	v_mul_f32_e32 v113, 0xbfb8aa3b, v108
	v_exp_f32_e32 v114, v113
	v_mul_f32_e32 v113, 0xbfb8aa3b, v109
	v_exp_f32_e32 v115, v113
	v_mul_f32_e32 v117, 0xbfb8aa3b, v111
	v_exp_f32_e32 v116, v116
	v_exp_f32_e32 v117, v117
	v_add_f32_e32 v114, 1.0, v114
	v_add_f32_e32 v115, 1.0, v115
	v_rcp_f32_e32 v114, v114
	v_rcp_f32_e32 v115, v115
	v_add_f32_e32 v116, 1.0, v116
	v_add_f32_e32 v117, 1.0, v117
	v_rcp_f32_e32 v116, v116
	v_rcp_f32_e32 v117, v117
	v_pk_mul_f32 v[108:109], v[108:109], v[114:115]
	v_or_b32_e32 v112, 16, v147
	v_pk_mul_f32 v[104:105], v[104:105], v[108:109]
	v_pk_mul_f32 v[108:109], v[110:111], v[116:117]
	v_mad_i64_i32 v[112:113], s[18:19], v112, s39, v[132:133]
	v_pk_mul_f32 v[106:107], v[106:107], v[108:109]
	v_mul_f32_e32 v108, 0xbfb8aa3b, v100
	v_mul_f32_e32 v109, 0xbfb8aa3b, v101
	v_exp_f32_e32 v108, v108
	v_exp_f32_e32 v109, v109
	v_cvt_pk_bf16_f32 v104, v104, v105
	v_cvt_pk_bf16_f32 v105, v106, v107
	v_lshl_add_u64 v[106:107], v[112:113], 0, s[16:17]
	global_store_dwordx2 v[106:107], v[104:105], off
	v_add_f32_e32 v104, 1.0, v108
	v_add_f32_e32 v105, 1.0, v109
	v_mul_f32_e32 v108, 0xbfb8aa3b, v102
	v_mul_f32_e32 v109, 0xbfb8aa3b, v103
	v_exp_f32_e32 v108, v108
	v_exp_f32_e32 v109, v109
	v_rcp_f32_e32 v104, v104
	v_rcp_f32_e32 v105, v105
	v_add_f32_e32 v108, 1.0, v108
	v_add_f32_e32 v109, 1.0, v109
	v_rcp_f32_e32 v108, v108
	v_rcp_f32_e32 v109, v109
	v_pk_mul_f32 v[100:101], v[100:101], v[104:105]
	s_mov_b64 s[20:21], s[14:15]
	v_pk_mul_f32 v[96:97], v[96:97], v[100:101]
	v_pk_mul_f32 v[100:101], v[102:103], v[108:109]
	v_cvt_pk_bf16_f32 v96, v96, v97
	v_pk_mul_f32 v[98:99], v[98:99], v[100:101]
	v_mul_f32_e32 v100, 0xbfb8aa3b, v94
	v_cvt_pk_bf16_f32 v97, v98, v99
	global_store_dwordx2 v[106:107], v[96:97], off offset:128
	v_mul_f32_e32 v97, 0xbfb8aa3b, v92
	v_exp_f32_e32 v98, v97
	v_mul_f32_e32 v97, 0xbfb8aa3b, v93
	v_exp_f32_e32 v99, v97
	v_mul_f32_e32 v101, 0xbfb8aa3b, v95
	v_exp_f32_e32 v100, v100
	v_exp_f32_e32 v101, v101
	v_add_f32_e32 v98, 1.0, v98
	v_add_f32_e32 v99, 1.0, v99
	v_rcp_f32_e32 v98, v98
	v_rcp_f32_e32 v99, v99
	v_add_f32_e32 v100, 1.0, v100
	v_add_f32_e32 v101, 1.0, v101
	v_rcp_f32_e32 v100, v100
	v_rcp_f32_e32 v101, v101
	v_pk_mul_f32 v[92:93], v[92:93], v[98:99]
	v_or_b32_e32 v96, 32, v147
	v_pk_mul_f32 v[88:89], v[88:89], v[92:93]
	v_pk_mul_f32 v[92:93], v[94:95], v[100:101]
	v_mad_i64_i32 v[96:97], s[18:19], v96, s39, v[132:133]
	v_pk_mul_f32 v[90:91], v[90:91], v[92:93]
	v_mul_f32_e32 v92, 0xbfb8aa3b, v84
	v_mul_f32_e32 v93, 0xbfb8aa3b, v85
	v_exp_f32_e32 v92, v92
	v_exp_f32_e32 v93, v93
	v_cvt_pk_bf16_f32 v88, v88, v89
	v_cvt_pk_bf16_f32 v89, v90, v91
	v_lshl_add_u64 v[90:91], v[96:97], 0, s[16:17]
	global_store_dwordx2 v[90:91], v[88:89], off
	v_add_f32_e32 v88, 1.0, v92
	v_add_f32_e32 v89, 1.0, v93
	v_mul_f32_e32 v92, 0xbfb8aa3b, v86
	v_mul_f32_e32 v93, 0xbfb8aa3b, v87
	v_exp_f32_e32 v92, v92
	v_exp_f32_e32 v93, v93
	v_rcp_f32_e32 v88, v88
	v_rcp_f32_e32 v89, v89
	v_add_f32_e32 v92, 1.0, v92
	v_add_f32_e32 v93, 1.0, v93
	v_rcp_f32_e32 v92, v92
	v_rcp_f32_e32 v93, v93
	v_pk_mul_f32 v[84:85], v[84:85], v[88:89]
	s_nop 0
	v_pk_mul_f32 v[80:81], v[80:81], v[84:85]
	v_pk_mul_f32 v[84:85], v[86:87], v[92:93]
	v_cvt_pk_bf16_f32 v80, v80, v81
	v_pk_mul_f32 v[82:83], v[82:83], v[84:85]
	v_mul_f32_e32 v84, 0xbfb8aa3b, v78
	v_cvt_pk_bf16_f32 v81, v82, v83
	global_store_dwordx2 v[90:91], v[80:81], off offset:128
	v_mul_f32_e32 v81, 0xbfb8aa3b, v76
	v_exp_f32_e32 v82, v81
	v_mul_f32_e32 v81, 0xbfb8aa3b, v77
	v_exp_f32_e32 v83, v81
	v_mul_f32_e32 v85, 0xbfb8aa3b, v79
	v_exp_f32_e32 v84, v84
	v_exp_f32_e32 v85, v85
	v_add_f32_e32 v82, 1.0, v82
	v_add_f32_e32 v83, 1.0, v83
	v_rcp_f32_e32 v82, v82
	v_rcp_f32_e32 v83, v83
	v_add_f32_e32 v84, 1.0, v84
	v_add_f32_e32 v85, 1.0, v85
	v_rcp_f32_e32 v84, v84
	v_rcp_f32_e32 v85, v85
	v_pk_mul_f32 v[76:77], v[76:77], v[82:83]
	v_or_b32_e32 v80, 48, v147
	v_pk_mul_f32 v[72:73], v[72:73], v[76:77]
	v_pk_mul_f32 v[76:77], v[78:79], v[84:85]
	v_mad_i64_i32 v[80:81], s[18:19], v80, s39, v[132:133]
	v_pk_mul_f32 v[74:75], v[74:75], v[76:77]
	v_mul_f32_e32 v76, 0xbfb8aa3b, v68
	v_mul_f32_e32 v77, 0xbfb8aa3b, v69
	v_exp_f32_e32 v76, v76
	v_exp_f32_e32 v77, v77
	v_cvt_pk_bf16_f32 v72, v72, v73
	v_cvt_pk_bf16_f32 v73, v74, v75
	v_lshl_add_u64 v[74:75], v[80:81], 0, s[16:17]
	global_store_dwordx2 v[74:75], v[72:73], off
	v_add_f32_e32 v72, 1.0, v76
	v_add_f32_e32 v73, 1.0, v77
	v_mul_f32_e32 v76, 0xbfb8aa3b, v70
	v_mul_f32_e32 v77, 0xbfb8aa3b, v71
	v_exp_f32_e32 v76, v76
	v_exp_f32_e32 v77, v77
	v_rcp_f32_e32 v72, v72
	v_rcp_f32_e32 v73, v73
	v_add_f32_e32 v76, 1.0, v76
	v_add_f32_e32 v77, 1.0, v77
	v_rcp_f32_e32 v76, v76
	v_rcp_f32_e32 v77, v77
	v_pk_mul_f32 v[68:69], v[68:69], v[72:73]
	s_nop 0
	v_pk_mul_f32 v[64:65], v[64:65], v[68:69]
	v_pk_mul_f32 v[68:69], v[70:71], v[76:77]
	v_cvt_pk_bf16_f32 v64, v64, v65
	v_pk_mul_f32 v[66:67], v[66:67], v[68:69]
	v_mul_f32_e32 v68, 0xbfb8aa3b, v62
	v_cvt_pk_bf16_f32 v65, v66, v67
	global_store_dwordx2 v[74:75], v[64:65], off offset:128
	v_mul_f32_e32 v65, 0xbfb8aa3b, v60
	v_exp_f32_e32 v66, v65
	v_mul_f32_e32 v65, 0xbfb8aa3b, v61
	v_exp_f32_e32 v67, v65
	v_mul_f32_e32 v69, 0xbfb8aa3b, v63
	v_exp_f32_e32 v68, v68
	v_exp_f32_e32 v69, v69
	v_add_f32_e32 v66, 1.0, v66
	v_add_f32_e32 v67, 1.0, v67
	v_rcp_f32_e32 v66, v66
	v_rcp_f32_e32 v67, v67
	v_add_f32_e32 v68, 1.0, v68
	v_add_f32_e32 v69, 1.0, v69
	v_rcp_f32_e32 v68, v68
	v_rcp_f32_e32 v69, v69
	v_pk_mul_f32 v[60:61], v[60:61], v[66:67]
	v_add_u32_e32 v64, 0x80, v147
	v_pk_mul_f32 v[56:57], v[56:57], v[60:61]
	v_pk_mul_f32 v[60:61], v[62:63], v[68:69]
	v_mad_i64_i32 v[64:65], s[18:19], v64, s39, v[132:133]
	v_pk_mul_f32 v[58:59], v[58:59], v[60:61]
	v_mul_f32_e32 v60, 0xbfb8aa3b, v52
	v_mul_f32_e32 v61, 0xbfb8aa3b, v53
	v_exp_f32_e32 v60, v60
	v_exp_f32_e32 v61, v61
	v_cvt_pk_bf16_f32 v56, v56, v57
	v_cvt_pk_bf16_f32 v57, v58, v59
	v_lshl_add_u64 v[58:59], v[64:65], 0, s[16:17]
	global_store_dwordx2 v[58:59], v[56:57], off
	v_add_f32_e32 v56, 1.0, v60
	v_add_f32_e32 v57, 1.0, v61
	v_mul_f32_e32 v60, 0xbfb8aa3b, v54
	v_mul_f32_e32 v61, 0xbfb8aa3b, v55
	v_exp_f32_e32 v60, v60
	v_exp_f32_e32 v61, v61
	v_rcp_f32_e32 v56, v56
	v_rcp_f32_e32 v57, v57
	v_add_f32_e32 v60, 1.0, v60
	v_add_f32_e32 v61, 1.0, v61
	v_rcp_f32_e32 v60, v60
	v_rcp_f32_e32 v61, v61
	v_pk_mul_f32 v[52:53], v[52:53], v[56:57]
	s_nop 0
	v_pk_mul_f32 v[48:49], v[48:49], v[52:53]
	v_pk_mul_f32 v[52:53], v[54:55], v[60:61]
	v_cvt_pk_bf16_f32 v48, v48, v49
	v_pk_mul_f32 v[50:51], v[50:51], v[52:53]
	v_mul_f32_e32 v52, 0xbfb8aa3b, v46
	v_cvt_pk_bf16_f32 v49, v50, v51
	global_store_dwordx2 v[58:59], v[48:49], off offset:128
	v_mul_f32_e32 v49, 0xbfb8aa3b, v44
	v_exp_f32_e32 v50, v49
	v_mul_f32_e32 v49, 0xbfb8aa3b, v45
	v_exp_f32_e32 v51, v49
	v_mul_f32_e32 v53, 0xbfb8aa3b, v47
	v_exp_f32_e32 v52, v52
	v_exp_f32_e32 v53, v53
	v_add_f32_e32 v50, 1.0, v50
	v_add_f32_e32 v51, 1.0, v51
	v_rcp_f32_e32 v50, v50
	v_rcp_f32_e32 v51, v51
	v_add_f32_e32 v52, 1.0, v52
	v_add_f32_e32 v53, 1.0, v53
	v_rcp_f32_e32 v52, v52
	v_rcp_f32_e32 v53, v53
	v_pk_mul_f32 v[44:45], v[44:45], v[50:51]
	v_add_u32_e32 v48, 0x90, v147
	v_pk_mul_f32 v[40:41], v[40:41], v[44:45]
	v_pk_mul_f32 v[44:45], v[46:47], v[52:53]
	v_mad_i64_i32 v[48:49], s[18:19], v48, s39, v[132:133]
	v_pk_mul_f32 v[42:43], v[42:43], v[44:45]
	v_mul_f32_e32 v44, 0xbfb8aa3b, v36
	v_mul_f32_e32 v45, 0xbfb8aa3b, v37
	v_exp_f32_e32 v44, v44
	v_exp_f32_e32 v45, v45
	v_cvt_pk_bf16_f32 v40, v40, v41
	v_cvt_pk_bf16_f32 v41, v42, v43
	v_lshl_add_u64 v[42:43], v[48:49], 0, s[16:17]
	global_store_dwordx2 v[42:43], v[40:41], off
	v_add_f32_e32 v40, 1.0, v44
	v_add_f32_e32 v41, 1.0, v45
	v_mul_f32_e32 v44, 0xbfb8aa3b, v38
	v_mul_f32_e32 v45, 0xbfb8aa3b, v39
	v_exp_f32_e32 v44, v44
	v_exp_f32_e32 v45, v45
	v_rcp_f32_e32 v40, v40
	v_rcp_f32_e32 v41, v41
	v_add_f32_e32 v44, 1.0, v44
	v_add_f32_e32 v45, 1.0, v45
	v_rcp_f32_e32 v44, v44
	v_rcp_f32_e32 v45, v45
	v_pk_mul_f32 v[36:37], v[36:37], v[40:41]
	s_nop 0
	v_pk_mul_f32 v[32:33], v[32:33], v[36:37]
	v_pk_mul_f32 v[36:37], v[38:39], v[44:45]
	v_cvt_pk_bf16_f32 v32, v32, v33
	v_pk_mul_f32 v[34:35], v[34:35], v[36:37]
	v_mul_f32_e32 v36, 0xbfb8aa3b, v30
	v_cvt_pk_bf16_f32 v33, v34, v35
	global_store_dwordx2 v[42:43], v[32:33], off offset:128
	v_mul_f32_e32 v33, 0xbfb8aa3b, v28
	v_exp_f32_e32 v34, v33
	v_mul_f32_e32 v33, 0xbfb8aa3b, v29
	v_exp_f32_e32 v35, v33
	v_mul_f32_e32 v37, 0xbfb8aa3b, v31
	v_exp_f32_e32 v36, v36
	v_exp_f32_e32 v37, v37
	v_add_f32_e32 v34, 1.0, v34
	v_add_f32_e32 v35, 1.0, v35
	v_rcp_f32_e32 v34, v34
	v_rcp_f32_e32 v35, v35
	v_add_f32_e32 v36, 1.0, v36
	v_add_f32_e32 v37, 1.0, v37
	v_rcp_f32_e32 v36, v36
	v_rcp_f32_e32 v37, v37
	v_pk_mul_f32 v[28:29], v[28:29], v[34:35]
	v_add_u32_e32 v32, 0xa0, v147
	v_pk_mul_f32 v[24:25], v[24:25], v[28:29]
	v_pk_mul_f32 v[28:29], v[30:31], v[36:37]
	v_mad_i64_i32 v[32:33], s[18:19], v32, s39, v[132:133]
	v_pk_mul_f32 v[26:27], v[26:27], v[28:29]
	v_mul_f32_e32 v28, 0xbfb8aa3b, v20
	v_mul_f32_e32 v29, 0xbfb8aa3b, v21
	v_exp_f32_e32 v28, v28
	v_exp_f32_e32 v29, v29
	v_cvt_pk_bf16_f32 v24, v24, v25
	v_cvt_pk_bf16_f32 v25, v26, v27
	v_lshl_add_u64 v[26:27], v[32:33], 0, s[16:17]
	global_store_dwordx2 v[26:27], v[24:25], off
	v_add_f32_e32 v24, 1.0, v28
	v_add_f32_e32 v25, 1.0, v29
	v_mul_f32_e32 v28, 0xbfb8aa3b, v22
	v_mul_f32_e32 v29, 0xbfb8aa3b, v23
	v_exp_f32_e32 v28, v28
	v_exp_f32_e32 v29, v29
	v_rcp_f32_e32 v24, v24
	v_rcp_f32_e32 v25, v25
	v_add_f32_e32 v28, 1.0, v28
	v_add_f32_e32 v29, 1.0, v29
	v_rcp_f32_e32 v28, v28
	v_rcp_f32_e32 v29, v29
	v_pk_mul_f32 v[20:21], v[20:21], v[24:25]
	s_nop 0
	v_pk_mul_f32 v[16:17], v[16:17], v[20:21]
	v_pk_mul_f32 v[20:21], v[22:23], v[28:29]
	v_cvt_pk_bf16_f32 v16, v16, v17
	v_pk_mul_f32 v[18:19], v[18:19], v[20:21]
	v_mul_f32_e32 v20, 0xbfb8aa3b, v14
	v_cvt_pk_bf16_f32 v17, v18, v19
	global_store_dwordx2 v[26:27], v[16:17], off offset:128
	v_mul_f32_e32 v17, 0xbfb8aa3b, v12
	v_exp_f32_e32 v18, v17
	v_mul_f32_e32 v17, 0xbfb8aa3b, v13
	v_exp_f32_e32 v19, v17
	v_mul_f32_e32 v21, 0xbfb8aa3b, v15
	v_exp_f32_e32 v20, v20
	v_exp_f32_e32 v21, v21
	v_add_f32_e32 v18, 1.0, v18
	v_add_f32_e32 v19, 1.0, v19
	v_rcp_f32_e32 v18, v18
	v_rcp_f32_e32 v19, v19
	v_add_f32_e32 v20, 1.0, v20
	v_add_f32_e32 v21, 1.0, v21
	v_rcp_f32_e32 v20, v20
	v_rcp_f32_e32 v21, v21
	v_pk_mul_f32 v[12:13], v[12:13], v[18:19]
	v_add_u32_e32 v16, 0xb0, v147
	v_pk_mul_f32 v[8:9], v[8:9], v[12:13]
	v_pk_mul_f32 v[12:13], v[14:15], v[20:21]
	v_mad_i64_i32 v[16:17], s[18:19], v16, s39, v[132:133]
	v_pk_mul_f32 v[10:11], v[10:11], v[12:13]
	v_mul_f32_e32 v12, 0xbfb8aa3b, v4
	v_mul_f32_e32 v13, 0xbfb8aa3b, v5
	v_exp_f32_e32 v12, v12
	v_exp_f32_e32 v13, v13
	v_cvt_pk_bf16_f32 v8, v8, v9
	v_cvt_pk_bf16_f32 v9, v10, v11
	v_lshl_add_u64 v[10:11], v[16:17], 0, s[16:17]
	global_store_dwordx2 v[10:11], v[8:9], off
	v_add_f32_e32 v8, 1.0, v12
	v_add_f32_e32 v9, 1.0, v13
	v_mul_f32_e32 v12, 0xbfb8aa3b, v6
	v_mul_f32_e32 v13, 0xbfb8aa3b, v7
	v_exp_f32_e32 v12, v12
	v_exp_f32_e32 v13, v13
	v_rcp_f32_e32 v8, v8
	v_rcp_f32_e32 v9, v9
	v_add_f32_e32 v12, 1.0, v12
	v_add_f32_e32 v13, 1.0, v13
	v_rcp_f32_e32 v12, v12
	v_rcp_f32_e32 v13, v13
	v_pk_mul_f32 v[4:5], v[4:5], v[8:9]
	s_mov_b32 s17, s8
	v_pk_mul_f32 v[0:1], v[0:1], v[4:5]
	v_pk_mul_f32 v[4:5], v[6:7], v[12:13]
	v_cvt_pk_bf16_f32 v0, v0, v1
	v_pk_mul_f32 v[2:3], v[2:3], v[4:5]
	s_mov_b32 s16, s10
	v_cvt_pk_bf16_f32 v1, v2, v3
	s_mov_b64 s[18:19], s[12:13]
	global_store_dwordx2 v[10:11], v[0:1], off offset:128
	s_cbranch_vccz .LBB0_3440
	s_waitcnt vmcnt(0)
	s_cmpk_gt_u32 s0, 0xff
	s_cbranch_scc1 .LBB0_3447
	s_barrier

.LBB0_3542:
	ds_read_b128 v[128:131], v217
	ds_read_b128 v[132:135], v217 offset:1024
	ds_read_b128 v[136:139], v217 offset:2048
	ds_read_b128 v[140:143], v217 offset:3072
	s_add_u32 s20, s18, 0x100
	s_addc_u32 s21, s19, 0
	s_cmpk_eq_i32 s54, 0x54
	s_cselect_b32 s25, s7, s21
	s_cselect_b32 s24, s6, s20
	s_cselect_b32 s23, s5, s53
	s_cselect_b32 s22, s4, s52
	v_lshl_add_u64 v[188:189], s[18:19], 0, v[168:169]
	s_add_i32 m0, s27, 0xc000
	ds_read_b128 v[144:147], v218
	ds_read_b128 v[148:151], v218 offset:1024
	ds_read_b128 v[152:155], v218 offset:2048
	ds_read_b128 v[156:159], v218 offset:3072
	ds_read_b128 v[160:163], v218 offset:4096
	ds_read_b128 v[176:179], v218 offset:5120
	ds_read_b128 v[180:183], v218 offset:6144
	ds_read_b128 v[184:187], v218 offset:7168
	global_load_lds_dwordx4 v[188:189], off
	v_lshl_add_u64 v[188:189], s[18:19], 0, v[170:171]
	s_add_i32 m0, s27, 0xe000
	s_nop 0
	global_load_lds_dwordx4 v[188:189], off
	s_waitcnt lgkmcnt(8)
	s_barrier
	s_waitcnt lgkmcnt(0)
	s_waitcnt lgkmcnt(0)
	v_mfma_f32_16x16x32_bf16 v[124:127], v[128:131], v[144:147], v[124:127]
	v_mfma_f32_16x16x32_bf16 v[104:107], v[136:139], v[144:147], v[104:107]
	v_mfma_f32_16x16x32_bf16 v[120:123], v[128:131], v[152:155], v[120:123]
	v_mfma_f32_16x16x32_bf16 v[96:99], v[136:139], v[152:155], v[96:99]
	v_mfma_f32_16x16x32_bf16 v[116:119], v[128:131], v[160:163], v[116:119]
	v_mfma_f32_16x16x32_bf16 v[92:95], v[136:139], v[160:163], v[92:95]
	v_mfma_f32_16x16x32_bf16 v[112:115], v[128:131], v[180:183], v[112:115]
	v_mfma_f32_16x16x32_bf16 v[88:91], v[136:139], v[180:183], v[88:91]
	v_mfma_f32_16x16x32_bf16 v[124:127], v[132:135], v[148:151], v[124:127]
	v_mfma_f32_16x16x32_bf16 v[104:107], v[140:143], v[148:151], v[104:107]
	v_mfma_f32_16x16x32_bf16 v[120:123], v[132:135], v[156:159], v[120:123]
	v_mfma_f32_16x16x32_bf16 v[96:99], v[140:143], v[156:159], v[96:99]
	v_mfma_f32_16x16x32_bf16 v[116:119], v[132:135], v[176:179], v[116:119]
	v_mfma_f32_16x16x32_bf16 v[92:95], v[140:143], v[176:179], v[92:95]
	v_mfma_f32_16x16x32_bf16 v[112:115], v[132:135], v[184:187], v[112:115]
	v_mfma_f32_16x16x32_bf16 v[88:91], v[140:143], v[184:187], v[88:91]
	s_barrier
	s_add_i32 s18, s39, s26
	v_lshl_add_u64 v[204:205], s[22:23], 0, v[164:165]
	s_mov_b32 m0, s18
	ds_read_b128 v[188:191], v219
	ds_read_b128 v[192:195], v219 offset:1024
	ds_read_b128 v[196:199], v219 offset:2048
	ds_read_b128 v[200:203], v219 offset:3072
	global_load_lds_dwordx4 v[204:205], off
	v_lshl_add_u64 v[206:207], s[22:23], 0, v[166:167]
	s_add_i32 m0, s18, 0x2000
	s_nop 0
	global_load_lds_dwordx4 v[206:207], off
	s_barrier
	s_waitcnt lgkmcnt(0)
	s_waitcnt lgkmcnt(0)
	v_mfma_f32_16x16x32_bf16 v[72:75], v[188:191], v[144:147], v[72:75]
	v_mfma_f32_16x16x32_bf16 v[44:47], v[196:199], v[144:147], v[44:47]
	v_mfma_f32_16x16x32_bf16 v[64:67], v[188:191], v[152:155], v[64:67]
	v_mfma_f32_16x16x32_bf16 v[40:43], v[196:199], v[152:155], v[40:43]
	v_mfma_f32_16x16x32_bf16 v[56:59], v[188:191], v[160:163], v[56:59]
	v_mfma_f32_16x16x32_bf16 v[36:39], v[196:199], v[160:163], v[36:39]
	v_mfma_f32_16x16x32_bf16 v[48:51], v[188:191], v[180:183], v[48:51]
	v_mfma_f32_16x16x32_bf16 v[28:31], v[196:199], v[180:183], v[28:31]
	v_mfma_f32_16x16x32_bf16 v[72:75], v[192:195], v[148:151], v[72:75]
	v_mfma_f32_16x16x32_bf16 v[44:47], v[200:203], v[148:151], v[44:47]
	v_mfma_f32_16x16x32_bf16 v[64:67], v[192:195], v[156:159], v[64:67]
	v_mfma_f32_16x16x32_bf16 v[40:43], v[200:203], v[156:159], v[40:43]
	v_mfma_f32_16x16x32_bf16 v[56:59], v[192:195], v[176:179], v[56:59]
	v_mfma_f32_16x16x32_bf16 v[36:39], v[200:203], v[176:179], v[36:39]
	v_mfma_f32_16x16x32_bf16 v[48:51], v[192:195], v[184:187], v[48:51]
	v_mfma_f32_16x16x32_bf16 v[28:31], v[200:203], v[184:187], v[28:31]
	s_mov_b32 m0, s27
	v_lshl_add_u64 v[208:209], s[24:25], 0, v[164:165]
	s_barrier
	ds_read_b128 v[144:147], v218 offset:16384
	ds_read_b128 v[148:151], v218 offset:17408
	ds_read_b128 v[152:155], v218 offset:18432
	ds_read_b128 v[156:159], v218 offset:19456
	ds_read_b128 v[160:163], v218 offset:20480
	ds_read_b128 v[176:179], v218 offset:21504
	ds_read_b128 v[180:183], v218 offset:22528
	ds_read_b128 v[184:187], v218 offset:23552
	global_load_lds_dwordx4 v[208:209], off
	v_lshl_add_u64 v[210:211], s[24:25], 0, v[166:167]
	s_mov_b32 m0, s28
	s_nop 0
	global_load_lds_dwordx4 v[210:211], off
	s_barrier
	s_waitcnt lgkmcnt(0)
	s_waitcnt lgkmcnt(0)
	v_mfma_f32_16x16x32_bf16 v[108:111], v[128:131], v[144:147], v[108:111]
	v_mfma_f32_16x16x32_bf16 v[76:79], v[136:139], v[144:147], v[76:79]
	v_mfma_f32_16x16x32_bf16 v[100:103], v[128:131], v[152:155], v[100:103]
	v_mfma_f32_16x16x32_bf16 v[68:71], v[136:139], v[152:155], v[68:71]
	v_mfma_f32_16x16x32_bf16 v[84:87], v[128:131], v[160:163], v[84:87]
	v_mfma_f32_16x16x32_bf16 v[60:63], v[136:139], v[160:163], v[60:63]
	v_mfma_f32_16x16x32_bf16 v[80:83], v[128:131], v[180:183], v[80:83]
	v_mfma_f32_16x16x32_bf16 v[52:55], v[136:139], v[180:183], v[52:55]
	v_mfma_f32_16x16x32_bf16 v[108:111], v[132:135], v[148:151], v[108:111]
	v_mfma_f32_16x16x32_bf16 v[76:79], v[140:143], v[148:151], v[76:79]
	v_mfma_f32_16x16x32_bf16 v[100:103], v[132:135], v[156:159], v[100:103]
	v_mfma_f32_16x16x32_bf16 v[68:71], v[140:143], v[156:159], v[68:71]
	v_mfma_f32_16x16x32_bf16 v[84:87], v[132:135], v[176:179], v[84:87]
	v_mfma_f32_16x16x32_bf16 v[60:63], v[140:143], v[176:179], v[60:63]
	v_mfma_f32_16x16x32_bf16 v[80:83], v[132:135], v[184:187], v[80:83]
	v_mfma_f32_16x16x32_bf16 v[52:55], v[140:143], v[184:187], v[52:55]
	s_barrier
	s_add_u32 s18, s22, 0x160000
	s_addc_u32 s19, s23, 0
	s_add_i32 s55, s40, s26
	v_lshl_add_u64 v[128:129], s[18:19], 0, v[164:165]
	s_mov_b32 m0, s55
	s_nop 0
	global_load_lds_dwordx4 v[128:129], off
	v_lshl_add_u64 v[128:129], s[18:19], 0, v[166:167]
	s_add_i32 m0, s55, 0x2000
	s_nop 0
	global_load_lds_dwordx4 v[128:129], off
	s_waitcnt vmcnt(6)
	s_barrier
	v_mfma_f32_16x16x32_bf16 v[32:35], v[188:191], v[144:147], v[32:35]
	v_mfma_f32_16x16x32_bf16 v[12:15], v[196:199], v[144:147], v[12:15]
	v_mfma_f32_16x16x32_bf16 v[24:27], v[188:191], v[152:155], v[24:27]
	v_mfma_f32_16x16x32_bf16 v[8:11], v[196:199], v[152:155], v[8:11]
	v_mfma_f32_16x16x32_bf16 v[20:23], v[188:191], v[160:163], v[20:23]
	v_mfma_f32_16x16x32_bf16 v[4:7], v[196:199], v[160:163], v[4:7]
	v_mfma_f32_16x16x32_bf16 v[16:19], v[188:191], v[180:183], v[16:19]
	v_mfma_f32_16x16x32_bf16 v[0:3], v[196:199], v[180:183], v[0:3]
	v_mfma_f32_16x16x32_bf16 v[32:35], v[192:195], v[148:151], v[32:35]
	v_mfma_f32_16x16x32_bf16 v[12:15], v[200:203], v[148:151], v[12:15]
	v_mfma_f32_16x16x32_bf16 v[24:27], v[192:195], v[156:159], v[24:27]
	v_mfma_f32_16x16x32_bf16 v[8:11], v[200:203], v[156:159], v[8:11]
	v_mfma_f32_16x16x32_bf16 v[20:23], v[192:195], v[176:179], v[20:23]
	v_mfma_f32_16x16x32_bf16 v[4:7], v[200:203], v[176:179], v[4:7]
	v_mfma_f32_16x16x32_bf16 v[16:19], v[192:195], v[184:187], v[16:19]
	v_mfma_f32_16x16x32_bf16 v[0:3], v[200:203], v[184:187], v[0:3]
	s_add_i32 s55, 0, 0x18000
	v_add_u32_e32 v140, s55, v215
	s_barrier
	ds_read_b128 v[128:131], v140
	ds_read_b128 v[132:135], v140 offset:1024
	ds_read_b128 v[136:139], v140 offset:2048
	ds_read_b128 v[140:143], v140 offset:3072
	s_add_u32 s18, s24, 0x160000
	s_addc_u32 s19, s25, 0
	s_mov_b32 m0, s29
	v_lshl_add_u64 v[188:189], s[18:19], 0, v[164:165]
	ds_read_b128 v[144:147], v218 offset:32768
	ds_read_b128 v[148:151], v218 offset:33792
	ds_read_b128 v[152:155], v218 offset:34816
	ds_read_b128 v[156:159], v218 offset:35840
	ds_read_b128 v[160:163], v218 offset:36864
	ds_read_b128 v[176:179], v218 offset:37888
	ds_read_b128 v[180:183], v218 offset:38912
	ds_read_b128 v[184:187], v218 offset:39936
	global_load_lds_dwordx4 v[188:189], off
	v_lshl_add_u64 v[188:189], s[18:19], 0, v[166:167]
	s_mov_b32 m0, s30
	s_nop 0
	global_load_lds_dwordx4 v[188:189], off
	s_waitcnt lgkmcnt(8)
	s_barrier
	s_waitcnt lgkmcnt(0)
	s_waitcnt lgkmcnt(0)
	v_mfma_f32_16x16x32_bf16 v[124:127], v[128:131], v[144:147], v[124:127]
	v_mfma_f32_16x16x32_bf16 v[104:107], v[136:139], v[144:147], v[104:107]
	v_mfma_f32_16x16x32_bf16 v[120:123], v[128:131], v[152:155], v[120:123]
	v_mfma_f32_16x16x32_bf16 v[96:99], v[136:139], v[152:155], v[96:99]
	v_mfma_f32_16x16x32_bf16 v[116:119], v[128:131], v[160:163], v[116:119]
	v_mfma_f32_16x16x32_bf16 v[92:95], v[136:139], v[160:163], v[92:95]
	v_mfma_f32_16x16x32_bf16 v[112:115], v[128:131], v[180:183], v[112:115]
	v_mfma_f32_16x16x32_bf16 v[88:91], v[136:139], v[180:183], v[88:91]
	v_mfma_f32_16x16x32_bf16 v[124:127], v[132:135], v[148:151], v[124:127]
	v_mfma_f32_16x16x32_bf16 v[104:107], v[140:143], v[148:151], v[104:107]
	v_mfma_f32_16x16x32_bf16 v[120:123], v[132:135], v[156:159], v[120:123]
	v_mfma_f32_16x16x32_bf16 v[96:99], v[140:143], v[156:159], v[96:99]
	v_mfma_f32_16x16x32_bf16 v[116:119], v[132:135], v[176:179], v[116:119]
	v_mfma_f32_16x16x32_bf16 v[92:95], v[140:143], v[176:179], v[92:95]
	v_mfma_f32_16x16x32_bf16 v[112:115], v[132:135], v[184:187], v[112:115]
	v_mfma_f32_16x16x32_bf16 v[88:91], v[140:143], v[184:187], v[88:91]
	s_barrier
	s_add_i32 s24, 0, 0x1c000
	s_add_i32 s18, s55, s26
	v_add_u32_e32 v200, s24, v215
	v_lshl_add_u64 v[204:205], v[204:205], 0, s[10:11]
	s_mov_b32 m0, s18
	ds_read_b128 v[188:191], v200
	ds_read_b128 v[192:195], v200 offset:1024
	ds_read_b128 v[196:199], v200 offset:2048
	ds_read_b128 v[200:203], v200 offset:3072
	global_load_lds_dwordx4 v[204:205], off
	v_lshl_add_u64 v[204:205], v[206:207], 0, s[10:11]
	s_add_i32 m0, s18, 0x2000
	s_nop 0
	global_load_lds_dwordx4 v[204:205], off
	s_barrier
	s_waitcnt lgkmcnt(0)
	s_waitcnt lgkmcnt(0)
	v_mfma_f32_16x16x32_bf16 v[72:75], v[188:191], v[144:147], v[72:75]
	v_mfma_f32_16x16x32_bf16 v[44:47], v[196:199], v[144:147], v[44:47]
	v_mfma_f32_16x16x32_bf16 v[64:67], v[188:191], v[152:155], v[64:67]
	v_mfma_f32_16x16x32_bf16 v[40:43], v[196:199], v[152:155], v[40:43]
	v_mfma_f32_16x16x32_bf16 v[56:59], v[188:191], v[160:163], v[56:59]
	v_mfma_f32_16x16x32_bf16 v[36:39], v[196:199], v[160:163], v[36:39]
	v_mfma_f32_16x16x32_bf16 v[48:51], v[188:191], v[180:183], v[48:51]
	v_mfma_f32_16x16x32_bf16 v[28:31], v[196:199], v[180:183], v[28:31]
	v_mfma_f32_16x16x32_bf16 v[72:75], v[192:195], v[148:151], v[72:75]
	v_mfma_f32_16x16x32_bf16 v[44:47], v[200:203], v[148:151], v[44:47]
	v_mfma_f32_16x16x32_bf16 v[64:67], v[192:195], v[156:159], v[64:67]
	v_mfma_f32_16x16x32_bf16 v[40:43], v[200:203], v[156:159], v[40:43]
	v_mfma_f32_16x16x32_bf16 v[56:59], v[192:195], v[176:179], v[56:59]
	v_mfma_f32_16x16x32_bf16 v[36:39], v[200:203], v[176:179], v[36:39]
	v_mfma_f32_16x16x32_bf16 v[48:51], v[192:195], v[184:187], v[48:51]
	v_mfma_f32_16x16x32_bf16 v[28:31], v[200:203], v[184:187], v[28:31]
	s_mov_b32 m0, s34
	v_lshl_add_u64 v[204:205], v[208:209], 0, s[10:11]
	s_barrier
	ds_read_b128 v[144:147], v218 offset:49152
	ds_read_b128 v[148:151], v218 offset:50176
	ds_read_b128 v[152:155], v218 offset:51200
	ds_read_b128 v[156:159], v218 offset:52224
	ds_read_b128 v[160:163], v218 offset:53248
	ds_read_b128 v[176:179], v218 offset:54272
	ds_read_b128 v[180:183], v218 offset:55296
	ds_read_b128 v[184:187], v218 offset:56320
	global_load_lds_dwordx4 v[204:205], off
	v_lshl_add_u64 v[204:205], v[210:211], 0, s[10:11]
	s_mov_b32 m0, s35
	s_nop 0
	global_load_lds_dwordx4 v[204:205], off
	s_barrier
	s_waitcnt lgkmcnt(0)
	s_waitcnt lgkmcnt(0)
	v_mfma_f32_16x16x32_bf16 v[108:111], v[128:131], v[144:147], v[108:111]
	v_mfma_f32_16x16x32_bf16 v[76:79], v[136:139], v[144:147], v[76:79]
	v_mfma_f32_16x16x32_bf16 v[100:103], v[128:131], v[152:155], v[100:103]
	v_mfma_f32_16x16x32_bf16 v[68:71], v[136:139], v[152:155], v[68:71]
	v_mfma_f32_16x16x32_bf16 v[84:87], v[128:131], v[160:163], v[84:87]
	v_mfma_f32_16x16x32_bf16 v[60:63], v[136:139], v[160:163], v[60:63]
	v_mfma_f32_16x16x32_bf16 v[80:83], v[128:131], v[180:183], v[80:83]
	v_mfma_f32_16x16x32_bf16 v[52:55], v[136:139], v[180:183], v[52:55]
	v_mfma_f32_16x16x32_bf16 v[108:111], v[132:135], v[148:151], v[108:111]
	v_mfma_f32_16x16x32_bf16 v[76:79], v[140:143], v[148:151], v[76:79]
	v_mfma_f32_16x16x32_bf16 v[100:103], v[132:135], v[156:159], v[100:103]
	v_mfma_f32_16x16x32_bf16 v[68:71], v[140:143], v[156:159], v[68:71]
	v_mfma_f32_16x16x32_bf16 v[84:87], v[132:135], v[176:179], v[84:87]
	v_mfma_f32_16x16x32_bf16 v[60:63], v[140:143], v[176:179], v[60:63]
	v_mfma_f32_16x16x32_bf16 v[80:83], v[132:135], v[184:187], v[80:83]
	v_mfma_f32_16x16x32_bf16 v[52:55], v[140:143], v[184:187], v[52:55]
	s_barrier
	s_add_u32 s18, s22, 0x160080
	s_addc_u32 s19, s23, 0
	s_add_i32 s22, s24, s26
	v_lshl_add_u64 v[128:129], s[18:19], 0, v[164:165]
	s_mov_b32 m0, s22
	s_nop 0
	global_load_lds_dwordx4 v[128:129], off
	v_lshl_add_u64 v[128:129], s[18:19], 0, v[166:167]
	s_add_i32 m0, s22, 0x2000
	s_nop 0
	global_load_lds_dwordx4 v[128:129], off
	s_waitcnt vmcnt(6)
	s_barrier
	v_mfma_f32_16x16x32_bf16 v[32:35], v[188:191], v[144:147], v[32:35]
	v_mfma_f32_16x16x32_bf16 v[12:15], v[196:199], v[144:147], v[12:15]
	v_mfma_f32_16x16x32_bf16 v[24:27], v[188:191], v[152:155], v[24:27]
	v_mfma_f32_16x16x32_bf16 v[8:11], v[196:199], v[152:155], v[8:11]
	v_mfma_f32_16x16x32_bf16 v[20:23], v[188:191], v[160:163], v[20:23]
	v_mfma_f32_16x16x32_bf16 v[4:7], v[196:199], v[160:163], v[4:7]
	v_mfma_f32_16x16x32_bf16 v[16:19], v[188:191], v[180:183], v[16:19]
	v_mfma_f32_16x16x32_bf16 v[0:3], v[196:199], v[180:183], v[0:3]
	v_mfma_f32_16x16x32_bf16 v[32:35], v[192:195], v[148:151], v[32:35]
	v_mfma_f32_16x16x32_bf16 v[12:15], v[200:203], v[148:151], v[12:15]
	v_mfma_f32_16x16x32_bf16 v[24:27], v[192:195], v[156:159], v[24:27]
	v_mfma_f32_16x16x32_bf16 v[8:11], v[200:203], v[156:159], v[8:11]
	v_mfma_f32_16x16x32_bf16 v[20:23], v[192:195], v[176:179], v[20:23]
	v_mfma_f32_16x16x32_bf16 v[4:7], v[200:203], v[176:179], v[4:7]
	v_mfma_f32_16x16x32_bf16 v[16:19], v[192:195], v[184:187], v[16:19]
	v_mfma_f32_16x16x32_bf16 v[0:3], v[200:203], v[184:187], v[0:3]
	s_add_i32 s54, s54, 2
	s_add_u32 s52, s52, 0x100
	s_addc_u32 s53, s53, 0
	s_cmpk_gt_u32 s54, 0x55
	s_mov_b64 s[18:19], s[20:21]
	s_barrier
	s_cbranch_scc0 .LBB0_3542
	s_cmp_lt_u32 s50, 32
	v_lshl_add_u32 v144, s50, 8, v214
	v_lshl_or_b32 v128, s51, 8, v216
	s_cselect_b32 s18, s41, 0x6000
	s_cmp_gt_i32 s50, 15
	v_readlane_b32 s48, v240, 22
	v_ashrrev_i32_e32 v145, 31, v144
	v_readlane_b32 s49, v240, 23
	v_readlane_b32 s52, v240, 26
	v_readlane_b32 s53, v240, 27
	v_ashrrev_i32_e32 v129, 31, v128
	v_lshlrev_b64 v[132:133], 13, v[144:145]
	s_mov_b64 s[48:49], s[52:53]
	s_cselect_b32 s18, s18, 0
	v_lshlrev_b64 v[146:147], 2, v[128:129]
	v_lshl_add_u64 v[132:133], s[48:49], 0, v[132:133]
	v_or_b32_e32 v136, 16, v144
	s_lshl_b32 s18, s18, 2
	v_lshl_add_u64 v[176:177], v[132:133], 0, v[146:147]
	v_ashrrev_i32_e32 v137, 31, v136
	v_or_b32_e32 v140, 32, v144
	v_or_b32_e32 v144, 48, v144
	s_add_u32 s18, s37, s18
	v_lshlrev_b64 v[136:137], 13, v[136:137]
	v_ashrrev_i32_e32 v141, 31, v140
	v_ashrrev_i32_e32 v145, 31, v144
	v_add_co_u32_e32 v188, vcc, s42, v176
	s_addc_u32 s19, s38, 0
	v_lshl_add_u64 v[136:137], s[48:49], 0, v[136:137]
	v_lshlrev_b64 v[140:141], 13, v[140:141]
	v_lshlrev_b64 v[144:145], 13, v[144:145]
	v_addc_co_u32_e32 v189, vcc, 0, v177, vcc
	v_lshl_add_u64 v[180:181], s[18:19], 0, v[146:147]
	v_lshl_add_u64 v[178:179], v[136:137], 0, v[146:147]
	v_lshl_add_u64 v[140:141], s[48:49], 0, v[140:141]
	v_lshl_add_u64 v[144:145], s[48:49], 0, v[144:145]
	v_add_co_u32_e32 v192, vcc, s43, v176
	global_load_dwordx4 v[128:131], v[180:181], off
	global_load_dwordx4 v[132:135], v[176:177], off
	global_load_dwordx4 v[136:139], v[178:179], off
	v_lshl_add_u64 v[182:183], v[140:141], 0, v[146:147]
	v_lshl_add_u64 v[184:185], v[144:145], 0, v[146:147]
	v_addc_co_u32_e32 v193, vcc, 0, v177, vcc
	global_load_dwordx4 v[140:143], v[182:183], off
	global_load_dwordx4 v[144:147], v[184:185], off
	global_load_dwordx4 v[160:163], v[188:189], off
	global_load_dwordx4 v[156:159], v[192:193], off
	v_add_co_u32_e32 v190, vcc, s44, v176
	v_pk_add_f32 v[194:195], v[126:127], 0 op_sel_hi:[1,0]
	s_nop 0
	v_addc_co_u32_e32 v191, vcc, 0, v177, vcc
	global_load_dwordx4 v[152:155], v[190:191], off
	v_add_co_u32_e32 v186, vcc, s45, v176
	v_pk_add_f32 v[196:197], v[124:125], 0 op_sel_hi:[1,0]
	s_nop 0
	v_addc_co_u32_e32 v187, vcc, 0, v177, vcc
	global_load_dwordx4 v[148:151], v[186:187], off
	v_pk_add_f32 v[198:199], v[122:123], 0 op_sel_hi:[1,0]
	v_pk_add_f32 v[200:201], v[120:121], 0 op_sel_hi:[1,0]
	v_pk_add_f32 v[202:203], v[118:119], 0 op_sel_hi:[1,0]
	v_pk_add_f32 v[204:205], v[116:117], 0 op_sel_hi:[1,0]
	v_pk_add_f32 v[206:207], v[114:115], 0 op_sel_hi:[1,0]
	v_pk_add_f32 v[208:209], v[112:113], 0 op_sel_hi:[1,0]
	v_pk_add_f32 v[210:211], v[110:111], 0 op_sel_hi:[1,0]
	v_pk_add_f32 v[212:213], v[108:109], 0 op_sel_hi:[1,0]
	v_pk_add_f32 v[126:127], v[102:103], 0 op_sel_hi:[1,0]
	v_pk_add_f32 v[100:101], v[100:101], 0 op_sel_hi:[1,0]
	v_lshl_add_u64 v[102:103], v[176:177], 0, s[12:13]
	global_load_dwordx4 v[108:111], v[176:177], off offset:64
	global_load_dwordx4 v[112:115], v[178:179], off offset:64
	global_load_dwordx4 v[116:119], v[182:183], off offset:64
	global_load_dwordx4 v[120:123], v[184:185], off offset:64
	global_load_dwordx4 v[220:223], v[102:103], off offset:576
	v_lshl_add_u64 v[124:125], v[176:177], 0, s[14:15]
	v_pk_add_f32 v[106:107], v[106:107], 0 op_sel_hi:[1,0]
	v_pk_add_f32 v[104:105], v[104:105], 0 op_sel_hi:[1,0]
	v_pk_add_f32 v[98:99], v[98:99], 0 op_sel_hi:[1,0]
	v_pk_add_f32 v[96:97], v[96:97], 0 op_sel_hi:[1,0]
	v_pk_add_f32 v[74:75], v[74:75], 0 op_sel_hi:[1,0]
	v_pk_add_f32 v[72:73], v[72:73], 0 op_sel_hi:[1,0]
	v_pk_add_f32 v[66:67], v[66:67], 0 op_sel_hi:[1,0]
	v_pk_add_f32 v[64:65], v[64:65], 0 op_sel_hi:[1,0]
	v_pk_add_f32 v[58:59], v[58:59], 0 op_sel_hi:[1,0]
	v_pk_add_f32 v[56:57], v[56:57], 0 op_sel_hi:[1,0]
	v_readlane_b32 s50, v240, 24
	v_readlane_b32 s51, v240, 25
	v_pk_add_f32 v[46:47], v[46:47], 0 op_sel_hi:[1,0]
	v_pk_add_f32 v[44:45], v[44:45], 0 op_sel_hi:[1,0]
	v_pk_add_f32 v[42:43], v[42:43], 0 op_sel_hi:[1,0]
	v_pk_add_f32 v[40:41], v[40:41], 0 op_sel_hi:[1,0]
	v_pk_add_f32 v[38:39], v[38:39], 0 op_sel_hi:[1,0]
	v_pk_add_f32 v[36:37], v[36:37], 0 op_sel_hi:[1,0]
	v_pk_add_f32 v[30:31], v[30:31], 0 op_sel_hi:[1,0]
	v_pk_add_f32 v[28:29], v[28:29], 0 op_sel_hi:[1,0]
	s_mov_b32 s51, s46
	s_mov_b64 s[20:21], s[4:5]
	s_mov_b64 s[18:19], s[6:7]
	s_mov_b32 s50, s47
	s_and_b64 vcc, exec, s[0:1]
	v_readlane_b32 s54, v240, 28
	v_readlane_b32 s55, v240, 29
	v_readlane_b32 s56, v240, 30
	v_readlane_b32 s57, v240, 31
	v_readlane_b32 s58, v240, 32
	v_readlane_b32 s59, v240, 33
	v_readlane_b32 s60, v240, 34
	v_readlane_b32 s61, v240, 35
	v_readlane_b32 s62, v240, 36
	v_readlane_b32 s63, v240, 37
	s_waitcnt vmcnt(0)
	v_pk_fma_f32 v[134:135], v[194:195], v[130:131], v[134:135]
	v_pk_fma_f32 v[132:133], v[196:197], v[128:129], v[132:133]
	v_pk_fma_f32 v[138:139], v[198:199], v[130:131], v[138:139]
	v_pk_fma_f32 v[136:137], v[200:201], v[128:129], v[136:137]
	v_pk_add_f32 v[194:195], v[54:55], 0 op_sel_hi:[1,0]
	v_pk_add_f32 v[196:197], v[52:53], 0 op_sel_hi:[1,0]
	v_pk_fma_f32 v[142:143], v[202:203], v[130:131], v[142:143]
	v_pk_fma_f32 v[140:141], v[204:205], v[128:129], v[140:141]
	v_pk_fma_f32 v[146:147], v[206:207], v[130:131], v[146:147]
	v_pk_fma_f32 v[144:145], v[208:209], v[128:129], v[144:145]
	v_pk_fma_f32 v[162:163], v[210:211], v[130:131], v[162:163]
	v_pk_fma_f32 v[160:161], v[212:213], v[128:129], v[160:161]
	global_store_dwordx4 v[176:177], v[132:135], off
	global_store_dwordx4 v[178:179], v[136:139], off
	global_store_dwordx4 v[182:183], v[140:143], off
	global_store_dwordx4 v[184:185], v[144:147], off
	global_store_dwordx4 v[188:189], v[160:163], off
	v_pk_fma_f32 v[138:139], v[126:127], v[130:131], v[158:159]
	v_pk_fma_f32 v[136:137], v[100:101], v[128:129], v[156:157]
	global_store_dwordx4 v[192:193], v[136:139], off
	v_pk_add_f32 v[126:127], v[86:87], 0 op_sel_hi:[1,0]
	v_lshl_add_u64 v[100:101], v[176:177], 0, s[16:17]
	v_pk_add_f32 v[136:137], v[84:85], 0 op_sel_hi:[1,0]
	v_pk_fma_f32 v[138:139], v[126:127], v[130:131], v[154:155]
	v_pk_fma_f32 v[136:137], v[136:137], v[128:129], v[152:153]
	global_store_dwordx4 v[190:191], v[136:139], off
	v_pk_add_f32 v[126:127], v[82:83], 0 op_sel_hi:[1,0]
	v_lshl_add_u64 v[152:153], v[176:177], 0, s[8:9]
	v_pk_add_f32 v[136:137], v[80:81], 0 op_sel_hi:[1,0]
	v_pk_fma_f32 v[130:131], v[126:127], v[130:131], v[150:151]
	v_pk_fma_f32 v[128:129], v[136:137], v[128:129], v[148:149]
	global_store_dwordx4 v[186:187], v[128:131], off
	global_load_dwordx4 v[132:135], v[124:125], off offset:576
	global_load_dwordx4 v[84:87], v[100:101], off offset:576
	global_load_dwordx4 v[80:83], v[152:153], off offset:576
	s_nop 0
	global_load_dwordx4 v[126:129], v[180:181], off offset:64
	global_load_dwordx4 v[136:139], v[102:103], off offset:64
	global_load_dwordx4 v[140:143], v[124:125], off offset:64
	global_load_dwordx4 v[144:147], v[100:101], off offset:64
	global_load_dwordx4 v[148:151], v[152:153], off offset:64
	v_pk_add_f32 v[130:131], v[94:95], 0 op_sel_hi:[1,0]
	v_pk_add_f32 v[154:155], v[92:93], 0 op_sel_hi:[1,0]
	v_pk_add_f32 v[156:157], v[90:91], 0 op_sel_hi:[1,0]
	v_pk_add_f32 v[158:159], v[88:89], 0 op_sel_hi:[1,0]
	v_pk_add_f32 v[160:161], v[78:79], 0 op_sel_hi:[1,0]
	v_pk_add_f32 v[162:163], v[76:77], 0 op_sel_hi:[1,0]
	v_pk_add_f32 v[186:187], v[70:71], 0 op_sel_hi:[1,0]
	v_pk_add_f32 v[188:189], v[68:69], 0 op_sel_hi:[1,0]
	v_pk_add_f32 v[190:191], v[62:63], 0 op_sel_hi:[1,0]
	v_pk_add_f32 v[192:193], v[60:61], 0 op_sel_hi:[1,0]
	global_load_dwordx4 v[52:55], v[176:177], off offset:512
	global_load_dwordx4 v[60:63], v[102:103], off offset:512
	global_load_dwordx4 v[68:71], v[124:125], off offset:512
	global_load_dwordx4 v[76:79], v[100:101], off offset:512
	global_load_dwordx4 v[88:91], v[152:153], off offset:512
	s_waitcnt vmcnt(0)
	v_pk_fma_f32 v[94:95], v[106:107], v[128:129], v[110:111]
	v_pk_fma_f32 v[92:93], v[104:105], v[126:127], v[108:109]
	v_pk_fma_f32 v[98:99], v[98:99], v[128:129], v[114:115]
	v_pk_fma_f32 v[96:97], v[96:97], v[126:127], v[112:113]
	v_pk_fma_f32 v[106:107], v[130:131], v[128:129], v[118:119]
	v_pk_fma_f32 v[104:105], v[154:155], v[126:127], v[116:117]
	v_pk_fma_f32 v[110:111], v[156:157], v[128:129], v[122:123]
	v_pk_fma_f32 v[108:109], v[158:159], v[126:127], v[120:121]
	v_pk_fma_f32 v[114:115], v[160:161], v[128:129], v[138:139]
	v_pk_fma_f32 v[112:113], v[162:163], v[126:127], v[136:137]
	v_pk_fma_f32 v[118:119], v[186:187], v[128:129], v[142:143]
	v_pk_fma_f32 v[116:117], v[188:189], v[126:127], v[140:141]
	v_pk_fma_f32 v[122:123], v[190:191], v[128:129], v[146:147]
	v_pk_fma_f32 v[120:121], v[192:193], v[126:127], v[144:145]
	v_pk_fma_f32 v[128:129], v[194:195], v[128:129], v[150:151]
	v_pk_fma_f32 v[126:127], v[196:197], v[126:127], v[148:149]
	global_store_dwordx4 v[176:177], v[92:95], off offset:64
	global_store_dwordx4 v[178:179], v[96:99], off offset:64
	global_store_dwordx4 v[182:183], v[104:107], off offset:64
	global_store_dwordx4 v[184:185], v[108:111], off offset:64
	global_store_dwordx4 v[102:103], v[112:115], off offset:64
	global_store_dwordx4 v[124:125], v[116:119], off offset:64
	global_store_dwordx4 v[100:101], v[120:123], off offset:64
	global_store_dwordx4 v[152:153], v[126:129], off offset:64
	global_load_dwordx4 v[92:95], v[180:181], off offset:512
	global_load_dwordx4 v[96:99], v[178:179], off offset:512
	global_load_dwordx4 v[104:107], v[182:183], off offset:512
	global_load_dwordx4 v[108:111], v[184:185], off offset:512
	v_pk_add_f32 v[112:113], v[50:51], 0 op_sel_hi:[1,0]
	v_pk_add_f32 v[114:115], v[48:49], 0 op_sel_hi:[1,0]
	v_pk_add_f32 v[116:117], v[34:35], 0 op_sel_hi:[1,0]
	v_pk_add_f32 v[118:119], v[32:33], 0 op_sel_hi:[1,0]
	v_pk_add_f32 v[120:121], v[26:27], 0 op_sel_hi:[1,0]
	v_pk_add_f32 v[122:123], v[24:25], 0 op_sel_hi:[1,0]
	v_pk_add_f32 v[126:127], v[22:23], 0 op_sel_hi:[1,0]
	v_pk_add_f32 v[128:129], v[20:21], 0 op_sel_hi:[1,0]
	v_pk_add_f32 v[130:131], v[18:19], 0 op_sel_hi:[1,0]
	v_pk_add_f32 v[136:137], v[16:17], 0 op_sel_hi:[1,0]
	global_load_dwordx4 v[16:19], v[176:177], off offset:576
	global_load_dwordx4 v[20:23], v[178:179], off offset:576
	global_load_dwordx4 v[24:27], v[182:183], off offset:576
	global_load_dwordx4 v[32:35], v[184:185], off offset:576
	s_waitcnt vmcnt(0)
	v_pk_fma_f32 v[50:51], v[74:75], v[94:95], v[54:55]
	v_pk_fma_f32 v[48:49], v[72:73], v[92:93], v[52:53]
	v_pk_fma_f32 v[54:55], v[66:67], v[94:95], v[98:99]
	v_pk_fma_f32 v[52:53], v[64:65], v[92:93], v[96:97]
	v_pk_fma_f32 v[58:59], v[58:59], v[94:95], v[106:107]
	v_pk_fma_f32 v[56:57], v[56:57], v[92:93], v[104:105]
	v_pk_fma_f32 v[66:67], v[112:113], v[94:95], v[110:111]
	v_pk_fma_f32 v[64:65], v[114:115], v[92:93], v[108:109]
	v_pk_fma_f32 v[62:63], v[116:117], v[94:95], v[62:63]
	v_pk_fma_f32 v[60:61], v[118:119], v[92:93], v[60:61]
	v_pk_fma_f32 v[70:71], v[120:121], v[94:95], v[70:71]
	v_pk_fma_f32 v[68:69], v[122:123], v[92:93], v[68:69]
	v_pk_fma_f32 v[74:75], v[126:127], v[94:95], v[78:79]
	v_pk_fma_f32 v[72:73], v[128:129], v[92:93], v[76:77]
	v_pk_fma_f32 v[78:79], v[130:131], v[94:95], v[90:91]
	v_pk_fma_f32 v[76:77], v[136:137], v[92:93], v[88:89]
	global_store_dwordx4 v[176:177], v[48:51], off offset:512
	global_store_dwordx4 v[178:179], v[52:55], off offset:512
	global_store_dwordx4 v[182:183], v[56:59], off offset:512
	global_store_dwordx4 v[184:185], v[64:67], off offset:512
	global_store_dwordx4 v[102:103], v[60:63], off offset:512
	global_store_dwordx4 v[124:125], v[68:71], off offset:512
	global_store_dwordx4 v[100:101], v[72:75], off offset:512
	global_store_dwordx4 v[152:153], v[76:79], off offset:512
	global_load_dwordx4 v[48:51], v[180:181], off offset:576
	v_pk_add_f32 v[52:53], v[14:15], 0 op_sel_hi:[1,0]
	v_pk_add_f32 v[54:55], v[12:13], 0 op_sel_hi:[1,0]
	v_pk_add_f32 v[56:57], v[10:11], 0 op_sel_hi:[1,0]
	v_pk_add_f32 v[58:59], v[8:9], 0 op_sel_hi:[1,0]
	v_pk_add_f32 v[60:61], v[6:7], 0 op_sel_hi:[1,0]
	v_pk_add_f32 v[62:63], v[4:5], 0 op_sel_hi:[1,0]
	v_pk_add_f32 v[64:65], v[2:3], 0 op_sel_hi:[1,0]
	v_pk_add_f32 v[66:67], v[0:1], 0 op_sel_hi:[1,0]
	s_waitcnt vmcnt(0)
	v_pk_fma_f32 v[2:3], v[46:47], v[50:51], v[18:19]
	v_pk_fma_f32 v[0:1], v[44:45], v[48:49], v[16:17]
	v_pk_fma_f32 v[6:7], v[42:43], v[50:51], v[22:23]
	v_pk_fma_f32 v[4:5], v[40:41], v[48:49], v[20:21]
	v_pk_fma_f32 v[10:11], v[38:39], v[50:51], v[26:27]
	v_pk_fma_f32 v[8:9], v[36:37], v[48:49], v[24:25]
	v_pk_fma_f32 v[14:15], v[30:31], v[50:51], v[34:35]
	v_pk_fma_f32 v[12:13], v[28:29], v[48:49], v[32:33]
	v_pk_fma_f32 v[18:19], v[52:53], v[50:51], v[222:223]
	v_pk_fma_f32 v[16:17], v[54:55], v[48:49], v[220:221]
	v_pk_fma_f32 v[22:23], v[56:57], v[50:51], v[134:135]
	v_pk_fma_f32 v[20:21], v[58:59], v[48:49], v[132:133]
	v_pk_fma_f32 v[26:27], v[60:61], v[50:51], v[86:87]
	v_pk_fma_f32 v[24:25], v[62:63], v[48:49], v[84:85]
	v_pk_fma_f32 v[30:31], v[64:65], v[50:51], v[82:83]
	v_pk_fma_f32 v[28:29], v[66:67], v[48:49], v[80:81]
	global_store_dwordx4 v[176:177], v[0:3], off offset:576
	global_store_dwordx4 v[178:179], v[4:7], off offset:576
	global_store_dwordx4 v[182:183], v[8:11], off offset:576
	global_store_dwordx4 v[184:185], v[12:15], off offset:576
	global_store_dwordx4 v[102:103], v[16:19], off offset:576
	global_store_dwordx4 v[124:125], v[20:23], off offset:576
	global_store_dwordx4 v[100:101], v[24:27], off offset:576
	global_store_dwordx4 v[152:153], v[28:31], off offset:576
	s_cbranch_vccz .LBB0_3531
	s_waitcnt vmcnt(0)
	s_cmpk_gt_u32 s2, 0xff
	s_cbranch_scc1 .LBB0_3546
	s_barrier
